# epilogue line-swap rotate folded into the select (v_cndmask_b32_dpp), on top of the v54 stack
# baseline (speedup 1.0000x reference)
; __device__ __forceinline__ unsigned pk2(float lo, float hi) { const f32x2 v = {lo, hi}; return __builtin_bit_cast(unsigned, __builtin_convertvector(v, bf16x2_t)); }
; __device__ __forceinline__ u32x4 ror8(u32x4 v) { u32x4 r;
; #pragma unroll
;     for (int i = 0; i < 4; ++i) r[i] = (unsigned)__builtin_amdgcn_mov_dpp((int)v[i], 0x128, 0xf, 0xf, true);
;     return r; }
; __device__ __forceinline__ void store_pair(unsigned char* own, size_t stride8, int hi_off, u32x4 lo, u32x4 hi, bool upper) {
;     const u32x4 tlo = ror8(lo), thi = ror8(hi);
;     const u32x4 A = upper ? thi : lo, B = upper ? hi : tlo;
;     unsigned char* pa = upper ? own - stride8 + hi_off : own;
;     unsigned char* pb = upper ? own + hi_off : own + stride8;
;     *(u32x4*)pa = A; *(u32x4*)pb = B;
; }
;     __device__ __forceinline__ void operator()(const f32x4 (&acc)[2][2][4][2], const Unit& u, int wr, int wc, int fr, int fq) const {
; #pragma unroll
;         for (int ai = 0; ai < 2; ++ai)
; #pragma unroll
;             for (int m = 0; m < 4; ++m) { unsigned char* rowp = (unsigned char*)(H + ((size_t)(u.pm * (FF / 64) + u.pn * 4 + wc) * 256 + (wr * 64 + fr + ai * 128 + m * 16)) * 64 + 8 * fq); u32x4 w[2];
; #pragma unroll
;                 for (int bj = 0; bj < 2; ++bj) { f32x4 v0 = acc[ai][bj][m][0], v1 = acc[ai][bj][m][1];
; #pragma unroll
;                     for (int j = 0; j < 4; ++j) { const float a = fmaxf(v0[j], 0.f), b = fmaxf(v1[j], 0.f); v0[j] = a * a; v1[j] = b * b; }
;                     w[bj].x = pk2(v0[0], v0[1]); w[bj].y = pk2(v0[2], v0[3]); w[bj].z = pk2(v1[0], v1[1]); w[bj].w = pk2(v1[2], v1[3]); }
;                 store_pair(rowp, (size_t)8 * 64 * 2, 64, w[0], w[1], fr >= 8); }
;     }
.LBB0_478:
	s_lshl_b32 s4, s22, 7
	s_lshl_b32 s5, s24, 2
	s_add_i32 s5, s5, s4
	s_or_b32 s4, s5, s49
	s_ashr_i32 s5, s4, 31
	s_lshl_b64 s[4:5], s[4:5], 15
	s_add_u32 s22, s1, s4
	v_max_f32_e32 v126, 0, v126
	v_max_f32_e32 v122, 0, v122
	v_max_f32_e32 v127, 0, v127
	v_max_f32_e32 v123, 0, v123
	v_max_f32_e32 v128, 0, v128
	v_max_f32_e32 v124, 0, v124
	v_max_f32_e32 v129, 0, v129
	v_max_f32_e32 v125, 0, v125
	v_max_f32_e32 v118, 0, v118
	v_max_f32_e32 v114, 0, v114
	v_max_f32_e32 v119, 0, v119
	v_max_f32_e32 v115, 0, v115
	v_max_f32_e32 v120, 0, v120
	v_max_f32_e32 v116, 0, v116
	v_max_f32_e32 v121, 0, v121
	v_max_f32_e32 v117, 0, v117
	s_addc_u32 s23, s33, s5
	v_pk_mul_f32 v[126:127], v[126:127], v[126:127]
	v_pk_mul_f32 v[122:123], v[122:123], v[122:123]
	v_pk_mul_f32 v[128:129], v[128:129], v[128:129]
	v_pk_mul_f32 v[124:125], v[124:125], v[124:125]
	v_pk_mul_f32 v[118:119], v[118:119], v[118:119]
	v_pk_mul_f32 v[114:115], v[114:115], v[114:115]
	v_pk_mul_f32 v[120:121], v[120:121], v[120:121]
	v_pk_mul_f32 v[116:117], v[116:117], v[116:117]
	v_lshl_add_u64 v[164:165], s[22:23], 0, v[144:145]
	v_cvt_pk_bf16_f32 v126, v126, v127
	v_cvt_pk_bf16_f32 v127, v128, v129
	v_cvt_pk_bf16_f32 v128, v122, v123
	v_cvt_pk_bf16_f32 v129, v124, v125
	v_cvt_pk_bf16_f32 v118, v118, v119
	v_cvt_pk_bf16_f32 v119, v120, v121
	v_cvt_pk_bf16_f32 v114, v114, v115
	v_cvt_pk_bf16_f32 v115, v116, v117
	v_lshl_add_u64 v[122:123], v[164:165], 0, v[138:139]
	s_mov_b64 vcc, s[6:7]
	v_mov_b32_dpp v164, v118 row_ror:8 row_mask:0xf bank_mask:0xf bound_ctrl:1
	v_mov_b32_dpp v165, v119 row_ror:8 row_mask:0xf bank_mask:0xf bound_ctrl:1
	v_mov_b32_dpp v166, v114 row_ror:8 row_mask:0xf bank_mask:0xf bound_ctrl:1
	v_mov_b32_dpp v167, v115 row_ror:8 row_mask:0xf bank_mask:0xf bound_ctrl:1
	v_max_f32_e32 v110, 0, v110
	v_max_f32_e32 v106, 0, v106
	v_max_f32_e32 v111, 0, v111
	v_max_f32_e32 v107, 0, v107
	v_max_f32_e32 v112, 0, v112
	v_max_f32_e32 v108, 0, v108
	v_max_f32_e32 v113, 0, v113
	v_max_f32_e32 v109, 0, v109
	v_max_f32_e32 v102, 0, v102
	v_max_f32_e32 v98, 0, v98
	v_max_f32_e32 v103, 0, v103
	v_max_f32_e32 v99, 0, v99
	v_max_f32_e32 v104, 0, v104
	v_max_f32_e32 v100, 0, v100
	v_max_f32_e32 v105, 0, v105
	v_max_f32_e32 v101, 0, v101
	v_lshl_add_u64 v[124:125], v[122:123], 0, v[140:141]
	v_cndmask_b32_dpp v117, v129, v115, vcc row_ror:8 row_mask:0xf bank_mask:0xf bound_ctrl:1
	v_cndmask_b32_dpp v116, v128, v114, vcc row_ror:8 row_mask:0xf bank_mask:0xf bound_ctrl:1
	v_cndmask_b32_dpp v115, v127, v119, vcc row_ror:8 row_mask:0xf bank_mask:0xf bound_ctrl:1
	v_cndmask_b32_dpp v114, v126, v118, vcc row_ror:8 row_mask:0xf bank_mask:0xf bound_ctrl:1
	v_cndmask_b32_e64 v121, v129, v167, s[6:7]
	v_cndmask_b32_e64 v120, v128, v166, s[6:7]
	v_cndmask_b32_e64 v119, v127, v165, s[6:7]
	v_cndmask_b32_e64 v118, v126, v164, s[6:7]
	v_pk_mul_f32 v[110:111], v[110:111], v[110:111]
	v_pk_mul_f32 v[106:107], v[106:107], v[106:107]
	v_pk_mul_f32 v[112:113], v[112:113], v[112:113]
	v_pk_mul_f32 v[108:109], v[108:109], v[108:109]
	v_pk_mul_f32 v[102:103], v[102:103], v[102:103]
	v_pk_mul_f32 v[98:99], v[98:99], v[98:99]
	v_pk_mul_f32 v[104:105], v[104:105], v[104:105]
	v_pk_mul_f32 v[100:101], v[100:101], v[100:101]
	v_lshl_add_u64 v[122:123], v[122:123], 0, v[142:143]
	global_store_dwordx4 v[124:125], v[118:121], off
	global_store_dwordx4 v[122:123], v[114:117], off
	v_cvt_pk_bf16_f32 v110, v110, v111
	v_cvt_pk_bf16_f32 v111, v112, v113
	v_lshl_add_u64 v[114:115], s[22:23], 0, v[146:147]
	v_cvt_pk_bf16_f32 v112, v106, v107
	v_cvt_pk_bf16_f32 v113, v108, v109
	v_cvt_pk_bf16_f32 v102, v102, v103
	v_cvt_pk_bf16_f32 v103, v104, v105
	v_cvt_pk_bf16_f32 v98, v98, v99
	v_cvt_pk_bf16_f32 v99, v100, v101
	v_lshl_add_u64 v[106:107], v[114:115], 0, v[138:139]
	s_mov_b64 vcc, s[6:7]
	v_mov_b32_dpp v114, v102 row_ror:8 row_mask:0xf bank_mask:0xf bound_ctrl:1
	v_mov_b32_dpp v115, v103 row_ror:8 row_mask:0xf bank_mask:0xf bound_ctrl:1
	v_mov_b32_dpp v116, v98 row_ror:8 row_mask:0xf bank_mask:0xf bound_ctrl:1
	v_mov_b32_dpp v117, v99 row_ror:8 row_mask:0xf bank_mask:0xf bound_ctrl:1
	v_max_f32_e32 v94, 0, v94
	v_max_f32_e32 v90, 0, v90
	v_max_f32_e32 v95, 0, v95
	v_max_f32_e32 v91, 0, v91
	v_max_f32_e32 v96, 0, v96
	v_max_f32_e32 v92, 0, v92
	v_max_f32_e32 v97, 0, v97
	v_max_f32_e32 v93, 0, v93
	v_max_f32_e32 v86, 0, v86
	v_max_f32_e32 v82, 0, v82
	v_max_f32_e32 v87, 0, v87
	v_max_f32_e32 v83, 0, v83
	v_max_f32_e32 v88, 0, v88
	v_max_f32_e32 v84, 0, v84
	v_max_f32_e32 v89, 0, v89
	v_max_f32_e32 v85, 0, v85
	v_lshl_add_u64 v[108:109], v[106:107], 0, v[140:141]
	v_cndmask_b32_dpp v101, v113, v99, vcc row_ror:8 row_mask:0xf bank_mask:0xf bound_ctrl:1
	v_cndmask_b32_dpp v100, v112, v98, vcc row_ror:8 row_mask:0xf bank_mask:0xf bound_ctrl:1
	v_cndmask_b32_dpp v99, v111, v103, vcc row_ror:8 row_mask:0xf bank_mask:0xf bound_ctrl:1
	v_cndmask_b32_dpp v98, v110, v102, vcc row_ror:8 row_mask:0xf bank_mask:0xf bound_ctrl:1
	v_cndmask_b32_e64 v105, v113, v117, s[6:7]
	v_cndmask_b32_e64 v104, v112, v116, s[6:7]
	v_cndmask_b32_e64 v103, v111, v115, s[6:7]
	v_cndmask_b32_e64 v102, v110, v114, s[6:7]
	v_pk_mul_f32 v[94:95], v[94:95], v[94:95]
	v_pk_mul_f32 v[90:91], v[90:91], v[90:91]
	v_pk_mul_f32 v[96:97], v[96:97], v[96:97]
	v_pk_mul_f32 v[92:93], v[92:93], v[92:93]
	v_pk_mul_f32 v[86:87], v[86:87], v[86:87]
	v_pk_mul_f32 v[82:83], v[82:83], v[82:83]
	v_pk_mul_f32 v[88:89], v[88:89], v[88:89]
	v_pk_mul_f32 v[84:85], v[84:85], v[84:85]
	v_lshl_add_u64 v[106:107], v[106:107], 0, v[142:143]
	global_store_dwordx4 v[108:109], v[102:105], off
	global_store_dwordx4 v[106:107], v[98:101], off
	v_cvt_pk_bf16_f32 v94, v94, v95
; __device__ __forceinline__ unsigned pk2(float lo, float hi) { const f32x2 v = {lo, hi}; return __builtin_bit_cast(unsigned, __builtin_convertvector(v, bf16x2_t)); }
; __device__ __forceinline__ u32x4 ror8(u32x4 v) { u32x4 r;
; #pragma unroll
;     for (int i = 0; i < 4; ++i) r[i] = (unsigned)__builtin_amdgcn_mov_dpp((int)v[i], 0x128, 0xf, 0xf, true);
;     return r; }
; __device__ __forceinline__ void store_pair(unsigned char* own, size_t stride8, int hi_off, u32x4 lo, u32x4 hi, bool upper) {
;     const u32x4 tlo = ror8(lo), thi = ror8(hi);
;     const u32x4 A = upper ? thi : lo, B = upper ? hi : tlo;
;     unsigned char* pa = upper ? own - stride8 + hi_off : own;
;     unsigned char* pb = upper ? own + hi_off : own + stride8;
;     *(u32x4*)pa = A; *(u32x4*)pb = B;
; }
;     __device__ __forceinline__ void operator()(const f32x4 (&acc)[2][2][4][2], const Unit& u, int wr, int wc, int fr, int fq) const {
; #pragma unroll
;         for (int ai = 0; ai < 2; ++ai)
; #pragma unroll
;             for (int m = 0; m < 4; ++m) { unsigned char* rowp = (unsigned char*)(H + ((size_t)(u.pm * (FF / 64) + u.pn * 4 + wc) * 256 + (wr * 64 + fr + ai * 128 + m * 16)) * 64 + 8 * fq); u32x4 w[2];
; #pragma unroll
;                 for (int bj = 0; bj < 2; ++bj) { f32x4 v0 = acc[ai][bj][m][0], v1 = acc[ai][bj][m][1];
; #pragma unroll
;                     for (int j = 0; j < 4; ++j) { const float a = fmaxf(v0[j], 0.f), b = fmaxf(v1[j], 0.f); v0[j] = a * a; v1[j] = b * b; }
;                     w[bj].x = pk2(v0[0], v0[1]); w[bj].y = pk2(v0[2], v0[3]); w[bj].z = pk2(v1[0], v1[1]); w[bj].w = pk2(v1[2], v1[3]); }
;                 store_pair(rowp, (size_t)8 * 64 * 2, 64, w[0], w[1], fr >= 8); }
;     }
	v_cvt_pk_bf16_f32 v95, v96, v97
	v_lshl_add_u64 v[98:99], s[22:23], 0, v[148:149]
	v_cvt_pk_bf16_f32 v96, v90, v91
	v_cvt_pk_bf16_f32 v97, v92, v93
	v_cvt_pk_bf16_f32 v86, v86, v87
	v_cvt_pk_bf16_f32 v87, v88, v89
	v_cvt_pk_bf16_f32 v82, v82, v83
	v_cvt_pk_bf16_f32 v83, v84, v85
	v_lshl_add_u64 v[90:91], v[98:99], 0, v[138:139]
	s_mov_b64 vcc, s[6:7]
	v_mov_b32_dpp v98, v86 row_ror:8 row_mask:0xf bank_mask:0xf bound_ctrl:1
	v_mov_b32_dpp v99, v87 row_ror:8 row_mask:0xf bank_mask:0xf bound_ctrl:1
	v_mov_b32_dpp v100, v82 row_ror:8 row_mask:0xf bank_mask:0xf bound_ctrl:1
	v_mov_b32_dpp v101, v83 row_ror:8 row_mask:0xf bank_mask:0xf bound_ctrl:1
	v_max_f32_e32 v78, 0, v78
	v_max_f32_e32 v74, 0, v74
	v_max_f32_e32 v79, 0, v79
	v_max_f32_e32 v75, 0, v75
	v_max_f32_e32 v80, 0, v80
	v_max_f32_e32 v76, 0, v76
	v_max_f32_e32 v81, 0, v81
	v_max_f32_e32 v77, 0, v77
	v_max_f32_e32 v70, 0, v70
	v_max_f32_e32 v66, 0, v66
	v_max_f32_e32 v71, 0, v71
	v_max_f32_e32 v67, 0, v67
	v_max_f32_e32 v72, 0, v72
	v_max_f32_e32 v68, 0, v68
	v_max_f32_e32 v73, 0, v73
	v_max_f32_e32 v69, 0, v69
	v_lshl_add_u64 v[92:93], v[90:91], 0, v[140:141]
	v_cndmask_b32_dpp v85, v97, v83, vcc row_ror:8 row_mask:0xf bank_mask:0xf bound_ctrl:1
	v_cndmask_b32_dpp v84, v96, v82, vcc row_ror:8 row_mask:0xf bank_mask:0xf bound_ctrl:1
	v_cndmask_b32_dpp v83, v95, v87, vcc row_ror:8 row_mask:0xf bank_mask:0xf bound_ctrl:1
	v_cndmask_b32_dpp v82, v94, v86, vcc row_ror:8 row_mask:0xf bank_mask:0xf bound_ctrl:1
	v_cndmask_b32_e64 v89, v97, v101, s[6:7]
	v_cndmask_b32_e64 v88, v96, v100, s[6:7]
	v_cndmask_b32_e64 v87, v95, v99, s[6:7]
	v_cndmask_b32_e64 v86, v94, v98, s[6:7]
	v_pk_mul_f32 v[78:79], v[78:79], v[78:79]
	v_pk_mul_f32 v[74:75], v[74:75], v[74:75]
	v_pk_mul_f32 v[80:81], v[80:81], v[80:81]
	v_pk_mul_f32 v[76:77], v[76:77], v[76:77]
	v_pk_mul_f32 v[70:71], v[70:71], v[70:71]
	v_pk_mul_f32 v[66:67], v[66:67], v[66:67]
	v_pk_mul_f32 v[72:73], v[72:73], v[72:73]
	v_pk_mul_f32 v[68:69], v[68:69], v[68:69]
	v_lshl_add_u64 v[90:91], v[90:91], 0, v[142:143]
	global_store_dwordx4 v[92:93], v[86:89], off
	global_store_dwordx4 v[90:91], v[82:85], off
	v_cvt_pk_bf16_f32 v78, v78, v79
	v_cvt_pk_bf16_f32 v79, v80, v81
	v_lshl_add_u64 v[82:83], s[22:23], 0, v[150:151]
	v_cvt_pk_bf16_f32 v80, v74, v75
	v_cvt_pk_bf16_f32 v81, v76, v77
	v_cvt_pk_bf16_f32 v70, v70, v71
	v_cvt_pk_bf16_f32 v71, v72, v73
	v_cvt_pk_bf16_f32 v66, v66, v67
	v_cvt_pk_bf16_f32 v67, v68, v69
	v_lshl_add_u64 v[74:75], v[82:83], 0, v[138:139]
	s_mov_b64 vcc, s[6:7]
	v_mov_b32_dpp v82, v70 row_ror:8 row_mask:0xf bank_mask:0xf bound_ctrl:1
	v_mov_b32_dpp v83, v71 row_ror:8 row_mask:0xf bank_mask:0xf bound_ctrl:1
	v_mov_b32_dpp v84, v66 row_ror:8 row_mask:0xf bank_mask:0xf bound_ctrl:1
	v_mov_b32_dpp v85, v67 row_ror:8 row_mask:0xf bank_mask:0xf bound_ctrl:1
	v_max_f32_e32 v62, 0, v62
	v_max_f32_e32 v58, 0, v58
	v_max_f32_e32 v63, 0, v63
	v_max_f32_e32 v59, 0, v59
	v_max_f32_e32 v64, 0, v64
	v_max_f32_e32 v60, 0, v60
	v_max_f32_e32 v65, 0, v65
	v_max_f32_e32 v61, 0, v61
	v_max_f32_e32 v54, 0, v54
	v_max_f32_e32 v50, 0, v50
	v_max_f32_e32 v55, 0, v55
	v_max_f32_e32 v51, 0, v51
	v_max_f32_e32 v56, 0, v56
	v_max_f32_e32 v52, 0, v52
	v_max_f32_e32 v57, 0, v57
	v_max_f32_e32 v53, 0, v53
	v_lshl_add_u64 v[76:77], v[74:75], 0, v[140:141]
	v_cndmask_b32_dpp v69, v81, v67, vcc row_ror:8 row_mask:0xf bank_mask:0xf bound_ctrl:1
	v_cndmask_b32_dpp v68, v80, v66, vcc row_ror:8 row_mask:0xf bank_mask:0xf bound_ctrl:1
	v_cndmask_b32_dpp v67, v79, v71, vcc row_ror:8 row_mask:0xf bank_mask:0xf bound_ctrl:1
	v_cndmask_b32_dpp v66, v78, v70, vcc row_ror:8 row_mask:0xf bank_mask:0xf bound_ctrl:1
	v_cndmask_b32_e64 v73, v81, v85, s[6:7]
	v_cndmask_b32_e64 v72, v80, v84, s[6:7]
	v_cndmask_b32_e64 v71, v79, v83, s[6:7]
	v_cndmask_b32_e64 v70, v78, v82, s[6:7]
	v_pk_mul_f32 v[62:63], v[62:63], v[62:63]
	v_pk_mul_f32 v[58:59], v[58:59], v[58:59]
	v_pk_mul_f32 v[64:65], v[64:65], v[64:65]
	v_pk_mul_f32 v[60:61], v[60:61], v[60:61]
	v_pk_mul_f32 v[54:55], v[54:55], v[54:55]
	v_pk_mul_f32 v[50:51], v[50:51], v[50:51]
	v_pk_mul_f32 v[56:57], v[56:57], v[56:57]
	v_pk_mul_f32 v[52:53], v[52:53], v[52:53]
	v_lshl_add_u64 v[74:75], v[74:75], 0, v[142:143]
	global_store_dwordx4 v[76:77], v[70:73], off
	global_store_dwordx4 v[74:75], v[66:69], off
	v_cvt_pk_bf16_f32 v62, v62, v63
	v_cvt_pk_bf16_f32 v63, v64, v65
	v_lshl_add_u64 v[66:67], s[22:23], 0, v[152:153]
	v_cvt_pk_bf16_f32 v64, v58, v59
	v_cvt_pk_bf16_f32 v65, v60, v61
	v_cvt_pk_bf16_f32 v54, v54, v55
	v_cvt_pk_bf16_f32 v55, v56, v57
	v_cvt_pk_bf16_f32 v50, v50, v51
	v_cvt_pk_bf16_f32 v51, v52, v53
	v_lshl_add_u64 v[58:59], v[66:67], 0, v[138:139]
	s_mov_b64 vcc, s[6:7]
	v_mov_b32_dpp v66, v54 row_ror:8 row_mask:0xf bank_mask:0xf bound_ctrl:1
	v_mov_b32_dpp v67, v55 row_ror:8 row_mask:0xf bank_mask:0xf bound_ctrl:1
	v_mov_b32_dpp v68, v50 row_ror:8 row_mask:0xf bank_mask:0xf bound_ctrl:1
	v_mov_b32_dpp v69, v51 row_ror:8 row_mask:0xf bank_mask:0xf bound_ctrl:1
	v_max_f32_e32 v46, 0, v46
	v_max_f32_e32 v42, 0, v42
	v_max_f32_e32 v47, 0, v47
	v_max_f32_e32 v43, 0, v43
	v_max_f32_e32 v48, 0, v48
	v_max_f32_e32 v44, 0, v44
	v_max_f32_e32 v49, 0, v49
	v_max_f32_e32 v45, 0, v45
	v_max_f32_e32 v38, 0, v38
	v_max_f32_e32 v34, 0, v34
	v_max_f32_e32 v39, 0, v39
	v_max_f32_e32 v35, 0, v35
	v_max_f32_e32 v40, 0, v40
	v_max_f32_e32 v36, 0, v36
	v_max_f32_e32 v41, 0, v41
	v_max_f32_e32 v37, 0, v37
	v_lshl_add_u64 v[60:61], v[58:59], 0, v[140:141]
	v_cndmask_b32_dpp v53, v65, v51, vcc row_ror:8 row_mask:0xf bank_mask:0xf bound_ctrl:1
	v_cndmask_b32_dpp v52, v64, v50, vcc row_ror:8 row_mask:0xf bank_mask:0xf bound_ctrl:1
; #define PG8_BAR __builtin_amdgcn_s_barrier()
; template <class Epi, class Sched, bool ABLK = false, bool ALIGN_EPI = true, bool SP2 = true, bool BBLK = true>
; __device__ __forceinline__ void gemm_phase(LAS unsigned char* lds, const Gemm g, const Sched& S, const Epi& E) {
;     ...
;         if constexpr (ALIGN_EPI) { if (wr == 0) PG8_BAR; }
;         E(acc, cur, wr, wc, fr, fq); S.done(cur);
;         if (!has_next) break;
; #pragma unroll
;         for (int a = 0; a < 2; ++a)
; #pragma unroll
;             for (int b = 0; b < 2; ++b)
; #pragma unroll
;                 for (int m = 0; m < 4; ++m)
; #pragma unroll
;                     for (int n = 0; n < 2; ++n) acc[a][b][m][n] = (f32x4){0.f, 0.f, 0.f, 0.f};
;         cur = nxt; uA = nuA; tbA = ntbA; cB = nB; ++ui;
;         if constexpr (ALIGN_EPI) { if (wr == 1) PG8_BAR; }
; __device__ __forceinline__ u32x4 ror8(u32x4 v) { u32x4 r;
; #pragma unroll
;     for (int i = 0; i < 4; ++i) r[i] = (unsigned)__builtin_amdgcn_mov_dpp((int)v[i], 0x128, 0xf, 0xf, true);
;     return r; }
; __device__ __forceinline__ void store_pair(unsigned char* own, size_t stride8, int hi_off, u32x4 lo, u32x4 hi, bool upper) {
;     const u32x4 tlo = ror8(lo), thi = ror8(hi);
;     const u32x4 A = upper ? thi : lo, B = upper ? hi : tlo;
;     unsigned char* pa = upper ? own - stride8 + hi_off : own;
;     unsigned char* pb = upper ? own + hi_off : own + stride8;
;     *(u32x4*)pa = A; *(u32x4*)pb = B;
; }
;     __device__ __forceinline__ void operator()(const f32x4 (&acc)[2][2][4][2], const Unit& u, int wr, int wc, int fr, int fq) const {
; #pragma unroll
;         for (int ai = 0; ai < 2; ++ai)
; #pragma unroll
;             for (int m = 0; m < 4; ++m) { unsigned char* rowp = (unsigned char*)(H + ((size_t)(u.pm * (FF / 64) + u.pn * 4 + wc) * 256 + (wr * 64 + fr + ai * 128 + m * 16)) * 64 + 8 * fq); u32x4 w[2];
; #pragma unroll
;                 for (int bj = 0; bj < 2; ++bj) { f32x4 v0 = acc[ai][bj][m][0], v1 = acc[ai][bj][m][1];
; #pragma unroll
;                     for (int j = 0; j < 4; ++j) { const float a = fmaxf(v0[j], 0.f), b = fmaxf(v1[j], 0.f); v0[j] = a * a; v1[j] = b * b; }
;                     w[bj].x = pk2(v0[0], v0[1]); w[bj].y = pk2(v0[2], v0[3]); w[bj].z = pk2(v1[0], v1[1]); w[bj].w = pk2(v1[2], v1[3]); }
;                 store_pair(rowp, (size_t)8 * 64 * 2, 64, w[0], w[1], fr >= 8); }
;     }
	v_cndmask_b32_dpp v51, v63, v55, vcc row_ror:8 row_mask:0xf bank_mask:0xf bound_ctrl:1
	v_cndmask_b32_dpp v50, v62, v54, vcc row_ror:8 row_mask:0xf bank_mask:0xf bound_ctrl:1
	v_cndmask_b32_e64 v57, v65, v69, s[6:7]
	v_cndmask_b32_e64 v56, v64, v68, s[6:7]
	v_cndmask_b32_e64 v55, v63, v67, s[6:7]
	v_cndmask_b32_e64 v54, v62, v66, s[6:7]
	v_pk_mul_f32 v[46:47], v[46:47], v[46:47]
	v_pk_mul_f32 v[42:43], v[42:43], v[42:43]
	v_pk_mul_f32 v[48:49], v[48:49], v[48:49]
	v_pk_mul_f32 v[44:45], v[44:45], v[44:45]
	v_pk_mul_f32 v[38:39], v[38:39], v[38:39]
	v_pk_mul_f32 v[34:35], v[34:35], v[34:35]
	v_pk_mul_f32 v[40:41], v[40:41], v[40:41]
	v_pk_mul_f32 v[36:37], v[36:37], v[36:37]
	v_lshl_add_u64 v[58:59], v[58:59], 0, v[142:143]
	global_store_dwordx4 v[60:61], v[54:57], off
	global_store_dwordx4 v[58:59], v[50:53], off
	v_cvt_pk_bf16_f32 v46, v46, v47
	v_cvt_pk_bf16_f32 v47, v48, v49
	v_lshl_add_u64 v[50:51], s[22:23], 0, v[154:155]
	v_cvt_pk_bf16_f32 v48, v42, v43
	v_cvt_pk_bf16_f32 v49, v44, v45
	v_cvt_pk_bf16_f32 v38, v38, v39
	v_cvt_pk_bf16_f32 v39, v40, v41
	v_cvt_pk_bf16_f32 v34, v34, v35
	v_cvt_pk_bf16_f32 v35, v36, v37
	v_lshl_add_u64 v[42:43], v[50:51], 0, v[138:139]
	s_mov_b64 vcc, s[6:7]
	v_mov_b32_dpp v50, v38 row_ror:8 row_mask:0xf bank_mask:0xf bound_ctrl:1
	v_mov_b32_dpp v51, v39 row_ror:8 row_mask:0xf bank_mask:0xf bound_ctrl:1
	v_mov_b32_dpp v52, v34 row_ror:8 row_mask:0xf bank_mask:0xf bound_ctrl:1
	v_mov_b32_dpp v53, v35 row_ror:8 row_mask:0xf bank_mask:0xf bound_ctrl:1
	v_max_f32_e32 v30, 0, v30
	v_max_f32_e32 v26, 0, v26
	v_max_f32_e32 v31, 0, v31
	v_max_f32_e32 v27, 0, v27
	v_max_f32_e32 v32, 0, v32
	v_max_f32_e32 v28, 0, v28
	v_max_f32_e32 v33, 0, v33
	v_max_f32_e32 v29, 0, v29
	v_max_f32_e32 v22, 0, v22
	v_max_f32_e32 v18, 0, v18
	v_max_f32_e32 v23, 0, v23
	v_max_f32_e32 v19, 0, v19
	v_max_f32_e32 v24, 0, v24
	v_max_f32_e32 v20, 0, v20
	v_max_f32_e32 v25, 0, v25
	v_max_f32_e32 v21, 0, v21
	v_lshl_add_u64 v[44:45], v[42:43], 0, v[140:141]
	v_cndmask_b32_dpp v37, v49, v35, vcc row_ror:8 row_mask:0xf bank_mask:0xf bound_ctrl:1
	v_cndmask_b32_dpp v36, v48, v34, vcc row_ror:8 row_mask:0xf bank_mask:0xf bound_ctrl:1
	v_cndmask_b32_dpp v35, v47, v39, vcc row_ror:8 row_mask:0xf bank_mask:0xf bound_ctrl:1
	v_cndmask_b32_dpp v34, v46, v38, vcc row_ror:8 row_mask:0xf bank_mask:0xf bound_ctrl:1
	v_cndmask_b32_e64 v41, v49, v53, s[6:7]
	v_cndmask_b32_e64 v40, v48, v52, s[6:7]
	v_cndmask_b32_e64 v39, v47, v51, s[6:7]
	v_cndmask_b32_e64 v38, v46, v50, s[6:7]
	v_pk_mul_f32 v[30:31], v[30:31], v[30:31]
	v_pk_mul_f32 v[26:27], v[26:27], v[26:27]
	v_pk_mul_f32 v[32:33], v[32:33], v[32:33]
	v_pk_mul_f32 v[28:29], v[28:29], v[28:29]
	v_pk_mul_f32 v[22:23], v[22:23], v[22:23]
	v_pk_mul_f32 v[18:19], v[18:19], v[18:19]
	v_pk_mul_f32 v[24:25], v[24:25], v[24:25]
	v_pk_mul_f32 v[20:21], v[20:21], v[20:21]
	v_lshl_add_u64 v[42:43], v[42:43], 0, v[142:143]
	global_store_dwordx4 v[44:45], v[38:41], off
	global_store_dwordx4 v[42:43], v[34:37], off
	v_cvt_pk_bf16_f32 v30, v30, v31
	v_cvt_pk_bf16_f32 v31, v32, v33
	v_lshl_add_u64 v[34:35], s[22:23], 0, v[156:157]
	v_cvt_pk_bf16_f32 v32, v26, v27
	v_cvt_pk_bf16_f32 v33, v28, v29
	v_cvt_pk_bf16_f32 v22, v22, v23
	v_cvt_pk_bf16_f32 v23, v24, v25
	v_cvt_pk_bf16_f32 v18, v18, v19
	v_cvt_pk_bf16_f32 v19, v20, v21
	v_lshl_add_u64 v[26:27], v[34:35], 0, v[138:139]
	s_mov_b64 vcc, s[6:7]
	v_mov_b32_dpp v34, v22 row_ror:8 row_mask:0xf bank_mask:0xf bound_ctrl:1
	v_mov_b32_dpp v35, v23 row_ror:8 row_mask:0xf bank_mask:0xf bound_ctrl:1
	v_mov_b32_dpp v36, v18 row_ror:8 row_mask:0xf bank_mask:0xf bound_ctrl:1
	v_mov_b32_dpp v37, v19 row_ror:8 row_mask:0xf bank_mask:0xf bound_ctrl:1
	v_max_f32_e32 v14, 0, v14
	v_max_f32_e32 v10, 0, v10
	v_max_f32_e32 v15, 0, v15
	v_max_f32_e32 v11, 0, v11
	v_max_f32_e32 v16, 0, v16
	v_max_f32_e32 v12, 0, v12
	v_max_f32_e32 v17, 0, v17
	v_max_f32_e32 v13, 0, v13
	v_max_f32_e32 v6, 0, v6
	v_max_f32_e32 v2, 0, v2
	v_max_f32_e32 v7, 0, v7
	v_max_f32_e32 v3, 0, v3
	v_max_f32_e32 v8, 0, v8
	v_max_f32_e32 v4, 0, v4
	v_max_f32_e32 v9, 0, v9
	v_max_f32_e32 v5, 0, v5
	v_lshl_add_u64 v[28:29], v[26:27], 0, v[140:141]
	v_cndmask_b32_dpp v21, v33, v19, vcc row_ror:8 row_mask:0xf bank_mask:0xf bound_ctrl:1
	v_cndmask_b32_dpp v20, v32, v18, vcc row_ror:8 row_mask:0xf bank_mask:0xf bound_ctrl:1
	v_cndmask_b32_dpp v19, v31, v23, vcc row_ror:8 row_mask:0xf bank_mask:0xf bound_ctrl:1
	v_cndmask_b32_dpp v18, v30, v22, vcc row_ror:8 row_mask:0xf bank_mask:0xf bound_ctrl:1
	v_cndmask_b32_e64 v25, v33, v37, s[6:7]
	v_cndmask_b32_e64 v24, v32, v36, s[6:7]
	v_cndmask_b32_e64 v23, v31, v35, s[6:7]
	v_cndmask_b32_e64 v22, v30, v34, s[6:7]
	v_pk_mul_f32 v[14:15], v[14:15], v[14:15]
	v_pk_mul_f32 v[10:11], v[10:11], v[10:11]
	v_pk_mul_f32 v[16:17], v[16:17], v[16:17]
	v_pk_mul_f32 v[12:13], v[12:13], v[12:13]
	v_pk_mul_f32 v[6:7], v[6:7], v[6:7]
	v_pk_mul_f32 v[2:3], v[2:3], v[2:3]
	v_pk_mul_f32 v[8:9], v[8:9], v[8:9]
	v_pk_mul_f32 v[4:5], v[4:5], v[4:5]
	v_lshl_add_u64 v[26:27], v[26:27], 0, v[142:143]
	global_store_dwordx4 v[28:29], v[22:25], off
	global_store_dwordx4 v[26:27], v[18:21], off
	v_cvt_pk_bf16_f32 v14, v14, v15
	v_cvt_pk_bf16_f32 v15, v16, v17
	v_lshl_add_u64 v[18:19], s[22:23], 0, v[158:159]
	v_cvt_pk_bf16_f32 v16, v10, v11
	v_cvt_pk_bf16_f32 v17, v12, v13
	v_cvt_pk_bf16_f32 v6, v6, v7
	v_cvt_pk_bf16_f32 v7, v8, v9
	v_cvt_pk_bf16_f32 v2, v2, v3
	v_cvt_pk_bf16_f32 v3, v4, v5
	v_lshl_add_u64 v[10:11], v[18:19], 0, v[138:139]
	s_mov_b64 vcc, s[6:7]
	v_mov_b32_dpp v18, v6 row_ror:8 row_mask:0xf bank_mask:0xf bound_ctrl:1
	v_mov_b32_dpp v19, v7 row_ror:8 row_mask:0xf bank_mask:0xf bound_ctrl:1
	v_mov_b32_dpp v20, v2 row_ror:8 row_mask:0xf bank_mask:0xf bound_ctrl:1
	v_mov_b32_dpp v21, v3 row_ror:8 row_mask:0xf bank_mask:0xf bound_ctrl:1
	v_lshl_add_u64 v[12:13], v[10:11], 0, v[140:141]
	v_cndmask_b32_dpp v5, v17, v3, vcc row_ror:8 row_mask:0xf bank_mask:0xf bound_ctrl:1
	v_cndmask_b32_dpp v4, v16, v2, vcc row_ror:8 row_mask:0xf bank_mask:0xf bound_ctrl:1
	v_cndmask_b32_dpp v3, v15, v7, vcc row_ror:8 row_mask:0xf bank_mask:0xf bound_ctrl:1
	v_cndmask_b32_dpp v2, v14, v6, vcc row_ror:8 row_mask:0xf bank_mask:0xf bound_ctrl:1
	v_cndmask_b32_e64 v9, v17, v21, s[6:7]
	v_cndmask_b32_e64 v8, v16, v20, s[6:7]
	v_cndmask_b32_e64 v7, v15, v19, s[6:7]
	v_cndmask_b32_e64 v6, v14, v18, s[6:7]
	s_andn2_b64 vcc, exec, s[18:19]
	s_mov_b64 s[4:5], -1
	v_lshl_add_u64 v[10:11], v[10:11], 0, v[142:143]
	global_store_dwordx4 v[12:13], v[6:9], off
	global_store_dwordx4 v[10:11], v[2:5], off
	s_cbranch_vccnz .LBB0_471
	s_andn2_b64 vcc, exec, s[2:3]
	s_cbranch_vccnz .LBB0_470
	s_barrier
	s_branch .LBB0_470

; __device__ __forceinline__ unsigned pk2(float lo, float hi) { const f32x2 v = {lo, hi}; return __builtin_bit_cast(unsigned, __builtin_convertvector(v, bf16x2_t)); }
; __device__ __forceinline__ u32x4 ror8(u32x4 v) { u32x4 r;
; #pragma unroll
;     for (int i = 0; i < 4; ++i) r[i] = (unsigned)__builtin_amdgcn_mov_dpp((int)v[i], 0x128, 0xf, 0xf, true);
;     return r; }
; __device__ __forceinline__ void store_pair(unsigned char* own, size_t stride8, int hi_off, u32x4 lo, u32x4 hi, bool upper) {
;     const u32x4 tlo = ror8(lo), thi = ror8(hi);
;     const u32x4 A = upper ? thi : lo, B = upper ? hi : tlo;
;     unsigned char* pa = upper ? own - stride8 + hi_off : own;
;     unsigned char* pb = upper ? own + hi_off : own + stride8;
;     *(u32x4*)pa = A; *(u32x4*)pb = B;
; }
;     __device__ __forceinline__ void operator()(const f32x4 (&acc)[2][2][4][2], const Unit& u, int wr, int wc, int fr, int fq) const {
;         const int row0 = u.pm * 256 + wr * 64 + fr, col0 = u.pn * 256 + wc * 64 + 8 * fq;
;         bf16_t* base = u.part == 0 ? Z + (size_t)row0 * D + col0 : P + ((size_t)(u.part - 1) * MS + (row0 - MP)) * D + col0;
; #pragma unroll
;         for (int ai = 0; ai < 2; ++ai)
; #pragma unroll
;             for (int m = 0; m < 4; ++m) { u32x4 w[2];
; #pragma unroll
;                 for (int bj = 0; bj < 2; ++bj) { const f32x4 v0 = acc[ai][bj][m][0], v1 = acc[ai][bj][m][1]; w[bj].x = pk2(v0[0], v0[1]); w[bj].y = pk2(v0[2], v0[3]); w[bj].z = pk2(v1[0], v1[1]); w[bj].w = pk2(v1[2], v1[3]); }
;                 store_pair((unsigned char*)(base + (size_t)(ai * 128 + m * 16) * D), (size_t)8 * D * 2, 64, w[0], w[1], fr >= 8); }
;     }
.LBB0_543:
	v_lshl_add_u32 v143, s62, 8, v1
	v_add_u32_e32 v144, 0xffffe000, v143
	v_sub_co_u32_e64 v142, vcc, s58, 1
	v_mov_b32_e32 v145, s17
	s_nop 0
	v_cndmask_b32_e32 v144, v144, v143, vcc
	v_ashrrev_i32_e32 v143, 31, v142
	v_lshlrev_b64 v[142:143], 23, v[142:143]
	v_lshl_add_u64 v[142:143], s[10:11], 0, v[142:143]
	v_cndmask_b32_e32 v143, v143, v145, vcc
	v_mov_b32_e32 v145, s16
	v_cndmask_b32_e32 v142, v142, v145, vcc
	v_ashrrev_i32_e32 v145, 31, v144
	v_lshl_or_b32 v152, s78, 8, v147
	v_lshlrev_b64 v[144:145], 12, v[144:145]
	v_lshl_add_u64 v[142:143], v[142:143], 0, v[144:145]
	v_ashrrev_i32_e32 v153, 31, v152
	v_cvt_pk_bf16_f32 v126, v126, v127
	v_cvt_pk_bf16_f32 v127, v128, v129
	v_cvt_pk_bf16_f32 v128, v122, v123
	v_cvt_pk_bf16_f32 v124, v124, v125
	v_cvt_pk_bf16_f32 v118, v118, v119
	v_cvt_pk_bf16_f32 v119, v120, v121
	v_cvt_pk_bf16_f32 v114, v114, v115
	v_cvt_pk_bf16_f32 v115, v116, v117
	v_lshl_add_u64 v[142:143], v[152:153], 1, v[142:143]
	s_mov_b64 vcc, s[6:7]
	v_mov_b32_dpp v125, v118 row_ror:8 row_mask:0xf bank_mask:0xf bound_ctrl:1
	v_mov_b32_dpp v129, v119 row_ror:8 row_mask:0xf bank_mask:0xf bound_ctrl:1
	v_mov_b32_dpp v144, v114 row_ror:8 row_mask:0xf bank_mask:0xf bound_ctrl:1
	v_mov_b32_dpp v145, v115 row_ror:8 row_mask:0xf bank_mask:0xf bound_ctrl:1
	v_lshl_add_u64 v[122:123], v[142:143], 0, v[134:135]
	v_cndmask_b32_dpp v117, v124, v115, vcc row_ror:8 row_mask:0xf bank_mask:0xf bound_ctrl:1
	v_cndmask_b32_dpp v116, v128, v114, vcc row_ror:8 row_mask:0xf bank_mask:0xf bound_ctrl:1
	v_cndmask_b32_dpp v115, v127, v119, vcc row_ror:8 row_mask:0xf bank_mask:0xf bound_ctrl:1
	v_cndmask_b32_dpp v114, v126, v118, vcc row_ror:8 row_mask:0xf bank_mask:0xf bound_ctrl:1
	v_cndmask_b32_e64 v121, v124, v145, s[6:7]
	v_cndmask_b32_e64 v120, v128, v144, s[6:7]
	v_cndmask_b32_e64 v119, v127, v129, s[6:7]
	v_cndmask_b32_e64 v118, v126, v125, s[6:7]
	v_cvt_pk_bf16_f32 v110, v110, v111
	v_cvt_pk_bf16_f32 v111, v112, v113
	v_cvt_pk_bf16_f32 v112, v106, v107
	v_cvt_pk_bf16_f32 v113, v108, v109
	v_cvt_pk_bf16_f32 v102, v102, v103
	v_cvt_pk_bf16_f32 v103, v104, v105
	v_cvt_pk_bf16_f32 v98, v98, v99
	v_cvt_pk_bf16_f32 v99, v100, v101
	v_lshl_add_u64 v[124:125], v[142:143], 0, v[136:137]
	global_store_dwordx4 v[122:123], v[118:121], off
	global_store_dwordx4 v[124:125], v[114:117], off
	v_lshl_add_u64 v[106:107], v[142:143], 0, s[14:15]
	s_mov_b64 vcc, s[6:7]
	v_mov_b32_dpp v114, v102 row_ror:8 row_mask:0xf bank_mask:0xf bound_ctrl:1
	v_mov_b32_dpp v115, v103 row_ror:8 row_mask:0xf bank_mask:0xf bound_ctrl:1
	v_mov_b32_dpp v116, v98 row_ror:8 row_mask:0xf bank_mask:0xf bound_ctrl:1
	v_mov_b32_dpp v117, v99 row_ror:8 row_mask:0xf bank_mask:0xf bound_ctrl:1
	v_lshl_add_u64 v[108:109], v[106:107], 0, v[134:135]
	v_cndmask_b32_dpp v101, v113, v99, vcc row_ror:8 row_mask:0xf bank_mask:0xf bound_ctrl:1
	v_cndmask_b32_dpp v100, v112, v98, vcc row_ror:8 row_mask:0xf bank_mask:0xf bound_ctrl:1
	v_cndmask_b32_dpp v99, v111, v103, vcc row_ror:8 row_mask:0xf bank_mask:0xf bound_ctrl:1
	v_cndmask_b32_dpp v98, v110, v102, vcc row_ror:8 row_mask:0xf bank_mask:0xf bound_ctrl:1
	v_cndmask_b32_e64 v105, v113, v117, s[6:7]
	v_cndmask_b32_e64 v104, v112, v116, s[6:7]
	v_cndmask_b32_e64 v103, v111, v115, s[6:7]
	v_cndmask_b32_e64 v102, v110, v114, s[6:7]
	v_cvt_pk_bf16_f32 v94, v94, v95
	v_cvt_pk_bf16_f32 v95, v96, v97
	v_cvt_pk_bf16_f32 v96, v90, v91
	v_cvt_pk_bf16_f32 v97, v92, v93
	v_cvt_pk_bf16_f32 v86, v86, v87
	v_cvt_pk_bf16_f32 v87, v88, v89
	v_cvt_pk_bf16_f32 v82, v82, v83
	v_cvt_pk_bf16_f32 v83, v84, v85
	v_lshl_add_u64 v[106:107], v[106:107], 0, v[136:137]
	global_store_dwordx4 v[108:109], v[102:105], off
	global_store_dwordx4 v[106:107], v[98:101], off
	v_lshl_add_u64 v[90:91], v[142:143], 0, s[18:19]
	s_mov_b64 vcc, s[6:7]
	v_mov_b32_dpp v98, v86 row_ror:8 row_mask:0xf bank_mask:0xf bound_ctrl:1
	v_mov_b32_dpp v99, v87 row_ror:8 row_mask:0xf bank_mask:0xf bound_ctrl:1
	v_mov_b32_dpp v100, v82 row_ror:8 row_mask:0xf bank_mask:0xf bound_ctrl:1
	v_mov_b32_dpp v101, v83 row_ror:8 row_mask:0xf bank_mask:0xf bound_ctrl:1
	v_lshl_add_u64 v[92:93], v[90:91], 0, v[134:135]
	v_cndmask_b32_dpp v85, v97, v83, vcc row_ror:8 row_mask:0xf bank_mask:0xf bound_ctrl:1
	v_cndmask_b32_dpp v84, v96, v82, vcc row_ror:8 row_mask:0xf bank_mask:0xf bound_ctrl:1
	v_cndmask_b32_dpp v83, v95, v87, vcc row_ror:8 row_mask:0xf bank_mask:0xf bound_ctrl:1
	v_cndmask_b32_dpp v82, v94, v86, vcc row_ror:8 row_mask:0xf bank_mask:0xf bound_ctrl:1
	v_cndmask_b32_e64 v89, v97, v101, s[6:7]
	v_cndmask_b32_e64 v88, v96, v100, s[6:7]
	v_cndmask_b32_e64 v87, v95, v99, s[6:7]
	v_cndmask_b32_e64 v86, v94, v98, s[6:7]
	v_cvt_pk_bf16_f32 v78, v78, v79
	v_cvt_pk_bf16_f32 v79, v80, v81
	v_cvt_pk_bf16_f32 v80, v74, v75
	v_cvt_pk_bf16_f32 v81, v76, v77
	v_cvt_pk_bf16_f32 v70, v70, v71
	v_cvt_pk_bf16_f32 v71, v72, v73
	v_cvt_pk_bf16_f32 v66, v66, v67
	v_cvt_pk_bf16_f32 v67, v68, v69
	v_lshl_add_u64 v[90:91], v[90:91], 0, v[136:137]
	global_store_dwordx4 v[92:93], v[86:89], off
	global_store_dwordx4 v[90:91], v[82:85], off
	v_lshl_add_u64 v[74:75], v[142:143], 0, s[20:21]
	s_mov_b64 vcc, s[6:7]
	v_mov_b32_dpp v82, v70 row_ror:8 row_mask:0xf bank_mask:0xf bound_ctrl:1
	v_mov_b32_dpp v83, v71 row_ror:8 row_mask:0xf bank_mask:0xf bound_ctrl:1
	v_mov_b32_dpp v84, v66 row_ror:8 row_mask:0xf bank_mask:0xf bound_ctrl:1
	v_mov_b32_dpp v85, v67 row_ror:8 row_mask:0xf bank_mask:0xf bound_ctrl:1
	v_lshl_add_u64 v[76:77], v[74:75], 0, v[134:135]
	v_cndmask_b32_dpp v69, v81, v67, vcc row_ror:8 row_mask:0xf bank_mask:0xf bound_ctrl:1
	v_cndmask_b32_dpp v68, v80, v66, vcc row_ror:8 row_mask:0xf bank_mask:0xf bound_ctrl:1
; #define PG8_BAR __builtin_amdgcn_s_barrier()
; template <class Epi, class Sched, bool ABLK = false, bool ALIGN_EPI = true, bool SP2 = true, bool BBLK = true>
; __device__ __forceinline__ void gemm_phase(LAS unsigned char* lds, const Gemm g, const Sched& S, const Epi& E) {
;     ...
;         if constexpr (ALIGN_EPI) { if (wr == 0) PG8_BAR; }
;         E(acc, cur, wr, wc, fr, fq); S.done(cur);
;         if (!has_next) break;
; #pragma unroll
;         for (int a = 0; a < 2; ++a)
; #pragma unroll
;             for (int b = 0; b < 2; ++b)
; #pragma unroll
;                 for (int m = 0; m < 4; ++m)
; #pragma unroll
;                     for (int n = 0; n < 2; ++n) acc[a][b][m][n] = (f32x4){0.f, 0.f, 0.f, 0.f};
;         cur = nxt; uA = nuA; tbA = ntbA; cB = nB; ++ui;
;         if constexpr (ALIGN_EPI) { if (wr == 1) PG8_BAR; }
; __device__ __forceinline__ u32x4 ror8(u32x4 v) { u32x4 r;
; #pragma unroll
;     for (int i = 0; i < 4; ++i) r[i] = (unsigned)__builtin_amdgcn_mov_dpp((int)v[i], 0x128, 0xf, 0xf, true);
;     return r; }
; __device__ __forceinline__ void store_pair(unsigned char* own, size_t stride8, int hi_off, u32x4 lo, u32x4 hi, bool upper) {
;     const u32x4 tlo = ror8(lo), thi = ror8(hi);
;     const u32x4 A = upper ? thi : lo, B = upper ? hi : tlo;
;     unsigned char* pa = upper ? own - stride8 + hi_off : own;
;     unsigned char* pb = upper ? own + hi_off : own + stride8;
;     *(u32x4*)pa = A; *(u32x4*)pb = B;
; }
;     __device__ __forceinline__ void operator()(const f32x4 (&acc)[2][2][4][2], const Unit& u, int wr, int wc, int fr, int fq) const {
;         const int row0 = u.pm * 256 + wr * 64 + fr, col0 = u.pn * 256 + wc * 64 + 8 * fq;
;         bf16_t* base = u.part == 0 ? Z + (size_t)row0 * D + col0 : P + ((size_t)(u.part - 1) * MS + (row0 - MP)) * D + col0;
; #pragma unroll
;         for (int ai = 0; ai < 2; ++ai)
; #pragma unroll
;             for (int m = 0; m < 4; ++m) { u32x4 w[2];
; #pragma unroll
;                 for (int bj = 0; bj < 2; ++bj) { const f32x4 v0 = acc[ai][bj][m][0], v1 = acc[ai][bj][m][1]; w[bj].x = pk2(v0[0], v0[1]); w[bj].y = pk2(v0[2], v0[3]); w[bj].z = pk2(v1[0], v1[1]); w[bj].w = pk2(v1[2], v1[3]); }
;                 store_pair((unsigned char*)(base + (size_t)(ai * 128 + m * 16) * D), (size_t)8 * D * 2, 64, w[0], w[1], fr >= 8); }
;     }
	v_cndmask_b32_dpp v67, v79, v71, vcc row_ror:8 row_mask:0xf bank_mask:0xf bound_ctrl:1
	v_cndmask_b32_dpp v66, v78, v70, vcc row_ror:8 row_mask:0xf bank_mask:0xf bound_ctrl:1
	v_cndmask_b32_e64 v73, v81, v85, s[6:7]
	v_cndmask_b32_e64 v72, v80, v84, s[6:7]
	v_cndmask_b32_e64 v71, v79, v83, s[6:7]
	v_cndmask_b32_e64 v70, v78, v82, s[6:7]
	v_cvt_pk_bf16_f32 v62, v62, v63
	v_cvt_pk_bf16_f32 v63, v64, v65
	v_cvt_pk_bf16_f32 v64, v58, v59
	v_cvt_pk_bf16_f32 v65, v60, v61
	v_cvt_pk_bf16_f32 v54, v54, v55
	v_cvt_pk_bf16_f32 v55, v56, v57
	v_cvt_pk_bf16_f32 v50, v50, v51
	v_cvt_pk_bf16_f32 v51, v52, v53
	v_lshl_add_u64 v[74:75], v[74:75], 0, v[136:137]
	global_store_dwordx4 v[76:77], v[70:73], off
	global_store_dwordx4 v[74:75], v[66:69], off
	v_lshl_add_u64 v[58:59], v[142:143], 0, s[22:23]
	s_mov_b64 vcc, s[6:7]
	v_mov_b32_dpp v66, v54 row_ror:8 row_mask:0xf bank_mask:0xf bound_ctrl:1
	v_mov_b32_dpp v67, v55 row_ror:8 row_mask:0xf bank_mask:0xf bound_ctrl:1
	v_mov_b32_dpp v68, v50 row_ror:8 row_mask:0xf bank_mask:0xf bound_ctrl:1
	v_mov_b32_dpp v69, v51 row_ror:8 row_mask:0xf bank_mask:0xf bound_ctrl:1
	v_lshl_add_u64 v[60:61], v[58:59], 0, v[134:135]
	v_cndmask_b32_dpp v53, v65, v51, vcc row_ror:8 row_mask:0xf bank_mask:0xf bound_ctrl:1
	v_cndmask_b32_dpp v52, v64, v50, vcc row_ror:8 row_mask:0xf bank_mask:0xf bound_ctrl:1
	v_cndmask_b32_dpp v51, v63, v55, vcc row_ror:8 row_mask:0xf bank_mask:0xf bound_ctrl:1
	v_cndmask_b32_dpp v50, v62, v54, vcc row_ror:8 row_mask:0xf bank_mask:0xf bound_ctrl:1
	v_cndmask_b32_e64 v57, v65, v69, s[6:7]
	v_cndmask_b32_e64 v56, v64, v68, s[6:7]
	v_cndmask_b32_e64 v55, v63, v67, s[6:7]
	v_cndmask_b32_e64 v54, v62, v66, s[6:7]
	v_cvt_pk_bf16_f32 v46, v46, v47
	v_cvt_pk_bf16_f32 v47, v48, v49
	v_cvt_pk_bf16_f32 v48, v42, v43
	v_cvt_pk_bf16_f32 v49, v44, v45
	v_cvt_pk_bf16_f32 v38, v38, v39
	v_cvt_pk_bf16_f32 v39, v40, v41
	v_cvt_pk_bf16_f32 v34, v34, v35
	v_cvt_pk_bf16_f32 v35, v36, v37
	v_lshl_add_u64 v[58:59], v[58:59], 0, v[136:137]
	global_store_dwordx4 v[60:61], v[54:57], off
	global_store_dwordx4 v[58:59], v[50:53], off
	v_lshl_add_u64 v[42:43], v[142:143], 0, s[24:25]
	s_mov_b64 vcc, s[6:7]
	v_mov_b32_dpp v50, v38 row_ror:8 row_mask:0xf bank_mask:0xf bound_ctrl:1
	v_mov_b32_dpp v51, v39 row_ror:8 row_mask:0xf bank_mask:0xf bound_ctrl:1
	v_mov_b32_dpp v52, v34 row_ror:8 row_mask:0xf bank_mask:0xf bound_ctrl:1
	v_mov_b32_dpp v53, v35 row_ror:8 row_mask:0xf bank_mask:0xf bound_ctrl:1
	v_lshl_add_u64 v[44:45], v[42:43], 0, v[134:135]
	v_cndmask_b32_dpp v37, v49, v35, vcc row_ror:8 row_mask:0xf bank_mask:0xf bound_ctrl:1
	v_cndmask_b32_dpp v36, v48, v34, vcc row_ror:8 row_mask:0xf bank_mask:0xf bound_ctrl:1
	v_cndmask_b32_dpp v35, v47, v39, vcc row_ror:8 row_mask:0xf bank_mask:0xf bound_ctrl:1
	v_cndmask_b32_dpp v34, v46, v38, vcc row_ror:8 row_mask:0xf bank_mask:0xf bound_ctrl:1
	v_cndmask_b32_e64 v41, v49, v53, s[6:7]
	v_cndmask_b32_e64 v40, v48, v52, s[6:7]
	v_cndmask_b32_e64 v39, v47, v51, s[6:7]
	v_cndmask_b32_e64 v38, v46, v50, s[6:7]
	v_cvt_pk_bf16_f32 v30, v30, v31
	v_cvt_pk_bf16_f32 v31, v32, v33
	v_cvt_pk_bf16_f32 v32, v26, v27
	v_cvt_pk_bf16_f32 v33, v28, v29
	v_cvt_pk_bf16_f32 v22, v22, v23
	v_cvt_pk_bf16_f32 v23, v24, v25
	v_cvt_pk_bf16_f32 v18, v18, v19
	v_cvt_pk_bf16_f32 v19, v20, v21
	v_lshl_add_u64 v[42:43], v[42:43], 0, v[136:137]
	global_store_dwordx4 v[44:45], v[38:41], off
	global_store_dwordx4 v[42:43], v[34:37], off
	v_lshl_add_u64 v[26:27], v[142:143], 0, s[26:27]
	s_mov_b64 vcc, s[6:7]
	v_mov_b32_dpp v34, v22 row_ror:8 row_mask:0xf bank_mask:0xf bound_ctrl:1
	v_mov_b32_dpp v35, v23 row_ror:8 row_mask:0xf bank_mask:0xf bound_ctrl:1
	v_mov_b32_dpp v36, v18 row_ror:8 row_mask:0xf bank_mask:0xf bound_ctrl:1
	v_mov_b32_dpp v37, v19 row_ror:8 row_mask:0xf bank_mask:0xf bound_ctrl:1
	v_lshl_add_u64 v[28:29], v[26:27], 0, v[134:135]
	v_cndmask_b32_dpp v21, v33, v19, vcc row_ror:8 row_mask:0xf bank_mask:0xf bound_ctrl:1
	v_cndmask_b32_dpp v20, v32, v18, vcc row_ror:8 row_mask:0xf bank_mask:0xf bound_ctrl:1
	v_cndmask_b32_dpp v19, v31, v23, vcc row_ror:8 row_mask:0xf bank_mask:0xf bound_ctrl:1
	v_cndmask_b32_dpp v18, v30, v22, vcc row_ror:8 row_mask:0xf bank_mask:0xf bound_ctrl:1
	v_cndmask_b32_e64 v25, v33, v37, s[6:7]
	v_cndmask_b32_e64 v24, v32, v36, s[6:7]
	v_cndmask_b32_e64 v23, v31, v35, s[6:7]
	v_cndmask_b32_e64 v22, v30, v34, s[6:7]
	v_cvt_pk_bf16_f32 v14, v14, v15
	v_cvt_pk_bf16_f32 v15, v16, v17
	v_cvt_pk_bf16_f32 v16, v10, v11
	v_cvt_pk_bf16_f32 v17, v12, v13
	v_cvt_pk_bf16_f32 v6, v6, v7
	v_cvt_pk_bf16_f32 v7, v8, v9
	v_cvt_pk_bf16_f32 v2, v2, v3
	v_cvt_pk_bf16_f32 v3, v4, v5
	v_lshl_add_u64 v[26:27], v[26:27], 0, v[136:137]
	global_store_dwordx4 v[28:29], v[22:25], off
	global_store_dwordx4 v[26:27], v[18:21], off
	v_lshl_add_u64 v[10:11], v[142:143], 0, s[28:29]
	s_mov_b64 vcc, s[6:7]
	v_mov_b32_dpp v18, v6 row_ror:8 row_mask:0xf bank_mask:0xf bound_ctrl:1
	v_mov_b32_dpp v19, v7 row_ror:8 row_mask:0xf bank_mask:0xf bound_ctrl:1
	v_mov_b32_dpp v20, v2 row_ror:8 row_mask:0xf bank_mask:0xf bound_ctrl:1
	v_mov_b32_dpp v21, v3 row_ror:8 row_mask:0xf bank_mask:0xf bound_ctrl:1
	v_lshl_add_u64 v[12:13], v[10:11], 0, v[134:135]
	v_cndmask_b32_dpp v5, v17, v3, vcc row_ror:8 row_mask:0xf bank_mask:0xf bound_ctrl:1
	v_cndmask_b32_dpp v4, v16, v2, vcc row_ror:8 row_mask:0xf bank_mask:0xf bound_ctrl:1
	v_cndmask_b32_dpp v3, v15, v7, vcc row_ror:8 row_mask:0xf bank_mask:0xf bound_ctrl:1
	v_cndmask_b32_dpp v2, v14, v6, vcc row_ror:8 row_mask:0xf bank_mask:0xf bound_ctrl:1
	v_cndmask_b32_e64 v9, v17, v21, s[6:7]
	v_cndmask_b32_e64 v8, v16, v20, s[6:7]
	v_cndmask_b32_e64 v7, v15, v19, s[6:7]
	v_cndmask_b32_e64 v6, v14, v18, s[6:7]
	s_and_b64 vcc, exec, s[8:9]
	s_mov_b64 s[8:9], -1
	v_lshl_add_u64 v[10:11], v[10:11], 0, v[136:137]
	global_store_dwordx4 v[12:13], v[6:9], off
	global_store_dwordx4 v[10:11], v[2:5], off
	s_cbranch_vccnz .LBB0_538
	s_andn2_b64 vcc, exec, s[2:3]
	s_cbranch_vccnz .LBB0_537
	s_barrier
	s_branch .LBB0_537

; __device__ __forceinline__ unsigned pk2(float lo, float hi) { const f32x2 v = {lo, hi}; return __builtin_bit_cast(unsigned, __builtin_convertvector(v, bf16x2_t)); }
; __device__ __forceinline__ void store_pair(unsigned char* own, size_t stride8, int hi_off, u32x4 lo, u32x4 hi, bool upper) {
;     const u32x4 tlo = ror8(lo), thi = ror8(hi);
;     const u32x4 A = upper ? thi : lo, B = upper ? hi : tlo;
;     unsigned char* pa = upper ? own - stride8 + hi_off : own;
;     unsigned char* pb = upper ? own + hi_off : own + stride8;
;     *(u32x4*)pa = A; *(u32x4*)pb = B;
; }
;     __device__ __forceinline__ void operator()(const f32x4 (&acc)[2][2][4][2], const Unit& u, int wr, int wc, int fr, int fq) const {
;         const int t = u.pn >> 3; const int colt = (u.pn & 7) * 256;
;         const int col0 = colt + wc * 64 + 8 * fq;
;         bf16_t* base = QKV + (size_t)t * M * D;
;         float* fdst = nullptr;
;         if (t >= 1) {
;             if (u.pm < 32) { if ((u.pm & 7) >= 6) { const int n = u.pm >> 3; fdst = out + (t == 1 ? O_KP : O_VP) + ((size_t)n * 512 + (size_t)((u.pm & 7) - 6) * 256) * D; } }
;             else fdst = out + (t == 1 ? O_KS : O_VS) + (size_t)(u.pm - 32) * 256 * D;
;         }
; #pragma unroll
;         for (int ai = 0; ai < 2; ++ai)
; #pragma unroll
;             for (int m = 0; m < 4; ++m) { const int rl = wr * 64 + fr + ai * 128 + m * 16; u32x4 w[2];
; #pragma unroll
;                 for (int bj = 0; bj < 2; ++bj) { const f32x4 v0 = acc[ai][bj][m][0], v1 = acc[ai][bj][m][1];
;                     w[bj].x = pk2(v0[0], v0[1]); w[bj].y = pk2(v0[2], v0[3]); w[bj].z = pk2(v1[0], v1[1]); w[bj].w = pk2(v1[2], v1[3]);
;                     if (fdst) { float* fp = fdst + (size_t)rl * D + col0 + bj * 32; *(f32x4*)fp = v0; *(f32x4*)(fp + 4) = v1; } }
;                 store_pair((unsigned char*)(base + (size_t)(u.pm * 256 + rl) * D + col0), (size_t)8 * D * 2, 64, w[0], w[1], fr >= 8); }
;     }
.LBB0_682:
	s_mul_hi_i32 s2, s15, 0x2800000
	s_mul_i32 s15, s15, 0x2800000
	s_add_u32 s4, s1, s15
	s_addc_u32 s5, s33, s2
	s_lshl_b32 s2, s24, 8
	v_cvt_pk_bf16_f32 v128, v128, v129
	v_cvt_pk_bf16_f32 v129, v118, v119
	v_cvt_pk_bf16_f32 v119, v116, v117
	v_add_u32_e32 v116, s2, v140
	v_lshlrev_b32_e32 v138, 1, v161
	v_ashrrev_i32_e32 v117, 31, v116
	v_cvt_pk_bf16_f32 v165, v126, v127
	v_cvt_pk_bf16_f32 v122, v122, v123
	v_cvt_pk_bf16_f32 v120, v120, v121
	v_cvt_pk_bf16_f32 v118, v114, v115
	v_lshl_add_u64 v[114:115], s[4:5], 0, v[138:139]
	v_lshlrev_b64 v[116:117], 12, v[116:117]
	v_cvt_pk_bf16_f32 v123, v124, v125
	v_lshl_add_u64 v[124:125], v[114:115], 0, v[116:117]
	s_mov_b64 vcc, s[6:7]
	v_mov_b32_dpp v161, v129 row_ror:8 row_mask:0xf bank_mask:0xf bound_ctrl:1
	v_mov_b32_dpp v169, v120 row_ror:8 row_mask:0xf bank_mask:0xf bound_ctrl:1
	v_mov_b32_dpp v173, v118 row_ror:8 row_mask:0xf bank_mask:0xf bound_ctrl:1
	v_mov_b32_dpp v182, v119 row_ror:8 row_mask:0xf bank_mask:0xf bound_ctrl:1
	v_mov_b32_dpp v138, v123 row_ror:8 row_mask:0xf bank_mask:0xf bound_ctrl:1
	v_lshl_add_u64 v[126:127], v[124:125], 0, v[142:143]
	v_cndmask_b32_dpp v118, v122, v118, vcc row_ror:8 row_mask:0xf bank_mask:0xf bound_ctrl:1
	v_cndmask_b32_dpp v117, v128, v120, vcc row_ror:8 row_mask:0xf bank_mask:0xf bound_ctrl:1
	v_cndmask_b32_dpp v116, v165, v129, vcc row_ror:8 row_mask:0xf bank_mask:0xf bound_ctrl:1
	v_cndmask_b32_e64 v123, v123, v182, s[6:7]
	v_cndmask_b32_e64 v122, v122, v173, s[6:7]
	v_cndmask_b32_e64 v121, v128, v169, s[6:7]
	v_cndmask_b32_e64 v120, v165, v161, s[6:7]
	v_cndmask_b32_e64 v119, v138, v119, s[6:7]
	v_lshl_add_u64 v[124:125], v[124:125], 0, v[144:145]
	global_store_dwordx4 v[126:127], v[120:123], off
	global_store_dwordx4 v[124:125], v[116:119], off
	s_and_b64 vcc, exec, s[8:9]
	s_nop 0
	v_lshl_add_u64 v[116:117], v[180:181], 0, v[150:151]
	s_cbranch_vccnz .LBB0_684
	global_store_dwordx4 v[116:117], v[110:113], off
	global_store_dwordx4 v[116:117], v[106:109], off offset:16

; __device__ __forceinline__ unsigned pk2(float lo, float hi) { const f32x2 v = {lo, hi}; return __builtin_bit_cast(unsigned, __builtin_convertvector(v, bf16x2_t)); }
; __device__ __forceinline__ void store_pair(unsigned char* own, size_t stride8, int hi_off, u32x4 lo, u32x4 hi, bool upper) {
;     const u32x4 tlo = ror8(lo), thi = ror8(hi);
;     const u32x4 A = upper ? thi : lo, B = upper ? hi : tlo;
;     unsigned char* pa = upper ? own - stride8 + hi_off : own;
;     unsigned char* pb = upper ? own + hi_off : own + stride8;
;     *(u32x4*)pa = A; *(u32x4*)pb = B;
; }
;     __device__ __forceinline__ void operator()(const f32x4 (&acc)[2][2][4][2], const Unit& u, int wr, int wc, int fr, int fq) const {
;         const int t = u.pn >> 3; const int colt = (u.pn & 7) * 256;
;         const int col0 = colt + wc * 64 + 8 * fq;
;         bf16_t* base = QKV + (size_t)t * M * D;
;         float* fdst = nullptr;
;         if (t >= 1) {
;             if (u.pm < 32) { if ((u.pm & 7) >= 6) { const int n = u.pm >> 3; fdst = out + (t == 1 ? O_KP : O_VP) + ((size_t)n * 512 + (size_t)((u.pm & 7) - 6) * 256) * D; } }
;             else fdst = out + (t == 1 ? O_KS : O_VS) + (size_t)(u.pm - 32) * 256 * D;
;         }
; #pragma unroll
;         for (int ai = 0; ai < 2; ++ai)
; #pragma unroll
;             for (int m = 0; m < 4; ++m) { const int rl = wr * 64 + fr + ai * 128 + m * 16; u32x4 w[2];
; #pragma unroll
;                 for (int bj = 0; bj < 2; ++bj) { const f32x4 v0 = acc[ai][bj][m][0], v1 = acc[ai][bj][m][1];
;                     w[bj].x = pk2(v0[0], v0[1]); w[bj].y = pk2(v0[2], v0[3]); w[bj].z = pk2(v1[0], v1[1]); w[bj].w = pk2(v1[2], v1[3]);
;                     if (fdst) { float* fp = fdst + (size_t)rl * D + col0 + bj * 32; *(f32x4*)fp = v0; *(f32x4*)(fp + 4) = v1; } }
;                 store_pair((unsigned char*)(base + (size_t)(u.pm * 256 + rl) * D + col0), (size_t)8 * D * 2, 64, w[0], w[1], fr >= 8); }
;     }
.LBB0_686:
	s_nop 0
	v_cvt_pk_bf16_f32 v102, v102, v103
	v_cvt_pk_bf16_f32 v103, v104, v105
	v_cvt_pk_bf16_f32 v104, v98, v99
	v_add_u32_e32 v98, s2, v148
	v_ashrrev_i32_e32 v99, 31, v98
	v_cvt_pk_bf16_f32 v100, v100, v101
	v_cvt_pk_bf16_f32 v110, v110, v111
	v_cvt_pk_bf16_f32 v111, v112, v113
	v_cvt_pk_bf16_f32 v112, v106, v107
	v_cvt_pk_bf16_f32 v105, v108, v109
	v_lshlrev_b64 v[98:99], 12, v[98:99]
	v_lshl_add_u64 v[106:107], v[114:115], 0, v[98:99]
	s_mov_b64 vcc, s[6:7]
	v_mov_b32_dpp v116, v102 row_ror:8 row_mask:0xf bank_mask:0xf bound_ctrl:1
	v_mov_b32_dpp v117, v103 row_ror:8 row_mask:0xf bank_mask:0xf bound_ctrl:1
	v_mov_b32_dpp v118, v104 row_ror:8 row_mask:0xf bank_mask:0xf bound_ctrl:1
	v_mov_b32_dpp v119, v100 row_ror:8 row_mask:0xf bank_mask:0xf bound_ctrl:1
	v_lshl_add_u64 v[108:109], v[106:107], 0, v[142:143]
	v_cndmask_b32_dpp v101, v105, v100, vcc row_ror:8 row_mask:0xf bank_mask:0xf bound_ctrl:1
	v_cndmask_b32_dpp v100, v112, v104, vcc row_ror:8 row_mask:0xf bank_mask:0xf bound_ctrl:1
	v_cndmask_b32_dpp v99, v111, v103, vcc row_ror:8 row_mask:0xf bank_mask:0xf bound_ctrl:1
	v_cndmask_b32_dpp v98, v110, v102, vcc row_ror:8 row_mask:0xf bank_mask:0xf bound_ctrl:1
	v_cndmask_b32_e64 v105, v105, v119, s[6:7]
	v_cndmask_b32_e64 v104, v112, v118, s[6:7]
	v_cndmask_b32_e64 v103, v111, v117, s[6:7]
	v_cndmask_b32_e64 v102, v110, v116, s[6:7]
	v_lshl_add_u64 v[106:107], v[106:107], 0, v[144:145]
	global_store_dwordx4 v[108:109], v[102:105], off
	global_store_dwordx4 v[106:107], v[98:101], off
	s_and_b64 vcc, exec, s[8:9]
	s_nop 0
	v_lshl_add_u64 v[98:99], v[180:181], 0, v[154:155]
	s_cbranch_vccnz .LBB0_688
	global_store_dwordx4 v[98:99], v[94:97], off
	global_store_dwordx4 v[98:99], v[90:93], off offset:16

; __device__ __forceinline__ unsigned pk2(float lo, float hi) { const f32x2 v = {lo, hi}; return __builtin_bit_cast(unsigned, __builtin_convertvector(v, bf16x2_t)); }
; __device__ __forceinline__ void store_pair(unsigned char* own, size_t stride8, int hi_off, u32x4 lo, u32x4 hi, bool upper) {
;     const u32x4 tlo = ror8(lo), thi = ror8(hi);
;     const u32x4 A = upper ? thi : lo, B = upper ? hi : tlo;
;     unsigned char* pa = upper ? own - stride8 + hi_off : own;
;     unsigned char* pb = upper ? own + hi_off : own + stride8;
;     *(u32x4*)pa = A; *(u32x4*)pb = B;
; }
;     __device__ __forceinline__ void operator()(const f32x4 (&acc)[2][2][4][2], const Unit& u, int wr, int wc, int fr, int fq) const {
;         const int t = u.pn >> 3; const int colt = (u.pn & 7) * 256;
;         const int col0 = colt + wc * 64 + 8 * fq;
;         bf16_t* base = QKV + (size_t)t * M * D;
;         float* fdst = nullptr;
;         if (t >= 1) {
;             if (u.pm < 32) { if ((u.pm & 7) >= 6) { const int n = u.pm >> 3; fdst = out + (t == 1 ? O_KP : O_VP) + ((size_t)n * 512 + (size_t)((u.pm & 7) - 6) * 256) * D; } }
;             else fdst = out + (t == 1 ? O_KS : O_VS) + (size_t)(u.pm - 32) * 256 * D;
;         }
; #pragma unroll
;         for (int ai = 0; ai < 2; ++ai)
; #pragma unroll
;             for (int m = 0; m < 4; ++m) { const int rl = wr * 64 + fr + ai * 128 + m * 16; u32x4 w[2];
; #pragma unroll
;                 for (int bj = 0; bj < 2; ++bj) { const f32x4 v0 = acc[ai][bj][m][0], v1 = acc[ai][bj][m][1];
;                     w[bj].x = pk2(v0[0], v0[1]); w[bj].y = pk2(v0[2], v0[3]); w[bj].z = pk2(v1[0], v1[1]); w[bj].w = pk2(v1[2], v1[3]);
;                     if (fdst) { float* fp = fdst + (size_t)rl * D + col0 + bj * 32; *(f32x4*)fp = v0; *(f32x4*)(fp + 4) = v1; } }
;                 store_pair((unsigned char*)(base + (size_t)(u.pm * 256 + rl) * D + col0), (size_t)8 * D * 2, 64, w[0], w[1], fr >= 8); }
;     }
.LBB0_690:
	s_nop 0
	v_cvt_pk_bf16_f32 v86, v86, v87
	v_cvt_pk_bf16_f32 v87, v88, v89
	v_cvt_pk_bf16_f32 v88, v82, v83
	v_add_u32_e32 v82, s2, v152
	v_ashrrev_i32_e32 v83, 31, v82
	v_cvt_pk_bf16_f32 v84, v84, v85
	v_cvt_pk_bf16_f32 v94, v94, v95
	v_cvt_pk_bf16_f32 v95, v96, v97
	v_cvt_pk_bf16_f32 v96, v90, v91
	v_cvt_pk_bf16_f32 v89, v92, v93
	v_lshlrev_b64 v[82:83], 12, v[82:83]
	v_lshl_add_u64 v[90:91], v[114:115], 0, v[82:83]
	s_mov_b64 vcc, s[6:7]
	v_mov_b32_dpp v98, v86 row_ror:8 row_mask:0xf bank_mask:0xf bound_ctrl:1
	v_mov_b32_dpp v99, v87 row_ror:8 row_mask:0xf bank_mask:0xf bound_ctrl:1
	v_mov_b32_dpp v100, v88 row_ror:8 row_mask:0xf bank_mask:0xf bound_ctrl:1
	v_mov_b32_dpp v101, v84 row_ror:8 row_mask:0xf bank_mask:0xf bound_ctrl:1
	v_lshl_add_u64 v[92:93], v[90:91], 0, v[142:143]
	v_cndmask_b32_dpp v85, v89, v84, vcc row_ror:8 row_mask:0xf bank_mask:0xf bound_ctrl:1
	v_cndmask_b32_dpp v84, v96, v88, vcc row_ror:8 row_mask:0xf bank_mask:0xf bound_ctrl:1
	v_cndmask_b32_dpp v83, v95, v87, vcc row_ror:8 row_mask:0xf bank_mask:0xf bound_ctrl:1
	v_cndmask_b32_dpp v82, v94, v86, vcc row_ror:8 row_mask:0xf bank_mask:0xf bound_ctrl:1
	v_cndmask_b32_e64 v89, v89, v101, s[6:7]
	v_cndmask_b32_e64 v88, v96, v100, s[6:7]
	v_cndmask_b32_e64 v87, v95, v99, s[6:7]
	v_cndmask_b32_e64 v86, v94, v98, s[6:7]
	v_lshl_add_u64 v[90:91], v[90:91], 0, v[144:145]
	global_store_dwordx4 v[92:93], v[86:89], off
	global_store_dwordx4 v[90:91], v[82:85], off
	s_and_b64 vcc, exec, s[8:9]
	s_nop 0
	v_lshl_add_u64 v[82:83], v[180:181], 0, v[158:159]
	s_cbranch_vccnz .LBB0_692
	global_store_dwordx4 v[82:83], v[78:81], off
	global_store_dwordx4 v[82:83], v[74:77], off offset:16

; __device__ __forceinline__ unsigned pk2(float lo, float hi) { const f32x2 v = {lo, hi}; return __builtin_bit_cast(unsigned, __builtin_convertvector(v, bf16x2_t)); }
; __device__ __forceinline__ void store_pair(unsigned char* own, size_t stride8, int hi_off, u32x4 lo, u32x4 hi, bool upper) {
;     const u32x4 tlo = ror8(lo), thi = ror8(hi);
;     const u32x4 A = upper ? thi : lo, B = upper ? hi : tlo;
;     unsigned char* pa = upper ? own - stride8 + hi_off : own;
;     unsigned char* pb = upper ? own + hi_off : own + stride8;
;     *(u32x4*)pa = A; *(u32x4*)pb = B;
; }
;     __device__ __forceinline__ void operator()(const f32x4 (&acc)[2][2][4][2], const Unit& u, int wr, int wc, int fr, int fq) const {
;         const int t = u.pn >> 3; const int colt = (u.pn & 7) * 256;
;         const int col0 = colt + wc * 64 + 8 * fq;
;         bf16_t* base = QKV + (size_t)t * M * D;
;         float* fdst = nullptr;
;         if (t >= 1) {
;             if (u.pm < 32) { if ((u.pm & 7) >= 6) { const int n = u.pm >> 3; fdst = out + (t == 1 ? O_KP : O_VP) + ((size_t)n * 512 + (size_t)((u.pm & 7) - 6) * 256) * D; } }
;             else fdst = out + (t == 1 ? O_KS : O_VS) + (size_t)(u.pm - 32) * 256 * D;
;         }
; #pragma unroll
;         for (int ai = 0; ai < 2; ++ai)
; #pragma unroll
;             for (int m = 0; m < 4; ++m) { const int rl = wr * 64 + fr + ai * 128 + m * 16; u32x4 w[2];
; #pragma unroll
;                 for (int bj = 0; bj < 2; ++bj) { const f32x4 v0 = acc[ai][bj][m][0], v1 = acc[ai][bj][m][1];
;                     w[bj].x = pk2(v0[0], v0[1]); w[bj].y = pk2(v0[2], v0[3]); w[bj].z = pk2(v1[0], v1[1]); w[bj].w = pk2(v1[2], v1[3]);
;                     if (fdst) { float* fp = fdst + (size_t)rl * D + col0 + bj * 32; *(f32x4*)fp = v0; *(f32x4*)(fp + 4) = v1; } }
;                 store_pair((unsigned char*)(base + (size_t)(u.pm * 256 + rl) * D + col0), (size_t)8 * D * 2, 64, w[0], w[1], fr >= 8); }
;     }
.LBB0_694:
	s_nop 0
	v_cvt_pk_bf16_f32 v70, v70, v71
	v_cvt_pk_bf16_f32 v71, v72, v73
	v_cvt_pk_bf16_f32 v72, v66, v67
	v_add_u32_e32 v66, s2, v156
	v_ashrrev_i32_e32 v67, 31, v66
	v_cvt_pk_bf16_f32 v68, v68, v69
	v_cvt_pk_bf16_f32 v78, v78, v79
	v_cvt_pk_bf16_f32 v79, v80, v81
	v_cvt_pk_bf16_f32 v80, v74, v75
	v_cvt_pk_bf16_f32 v73, v76, v77
	v_lshlrev_b64 v[66:67], 12, v[66:67]
	v_lshl_add_u64 v[74:75], v[114:115], 0, v[66:67]
	s_mov_b64 vcc, s[6:7]
	v_mov_b32_dpp v82, v70 row_ror:8 row_mask:0xf bank_mask:0xf bound_ctrl:1
	v_mov_b32_dpp v83, v71 row_ror:8 row_mask:0xf bank_mask:0xf bound_ctrl:1
	v_mov_b32_dpp v84, v72 row_ror:8 row_mask:0xf bank_mask:0xf bound_ctrl:1
	v_mov_b32_dpp v85, v68 row_ror:8 row_mask:0xf bank_mask:0xf bound_ctrl:1
	v_lshl_add_u64 v[76:77], v[74:75], 0, v[142:143]
	v_cndmask_b32_dpp v69, v73, v68, vcc row_ror:8 row_mask:0xf bank_mask:0xf bound_ctrl:1
	v_cndmask_b32_dpp v68, v80, v72, vcc row_ror:8 row_mask:0xf bank_mask:0xf bound_ctrl:1
	v_cndmask_b32_dpp v67, v79, v71, vcc row_ror:8 row_mask:0xf bank_mask:0xf bound_ctrl:1
	v_cndmask_b32_dpp v66, v78, v70, vcc row_ror:8 row_mask:0xf bank_mask:0xf bound_ctrl:1
	v_cndmask_b32_e64 v73, v73, v85, s[6:7]
	v_cndmask_b32_e64 v72, v80, v84, s[6:7]
	v_cndmask_b32_e64 v71, v79, v83, s[6:7]
	v_cndmask_b32_e64 v70, v78, v82, s[6:7]
	v_lshl_add_u64 v[74:75], v[74:75], 0, v[144:145]
	global_store_dwordx4 v[76:77], v[70:73], off
	global_store_dwordx4 v[74:75], v[66:69], off
	s_and_b64 vcc, exec, s[8:9]
	s_nop 0
	v_lshl_add_u64 v[66:67], v[180:181], 0, v[162:163]
	s_cbranch_vccnz .LBB0_696
	global_store_dwordx4 v[66:67], v[62:65], off
	global_store_dwordx4 v[66:67], v[58:61], off offset:16

; __device__ __forceinline__ unsigned pk2(float lo, float hi) { const f32x2 v = {lo, hi}; return __builtin_bit_cast(unsigned, __builtin_convertvector(v, bf16x2_t)); }
; __device__ __forceinline__ void store_pair(unsigned char* own, size_t stride8, int hi_off, u32x4 lo, u32x4 hi, bool upper) {
;     const u32x4 tlo = ror8(lo), thi = ror8(hi);
;     const u32x4 A = upper ? thi : lo, B = upper ? hi : tlo;
;     unsigned char* pa = upper ? own - stride8 + hi_off : own;
;     unsigned char* pb = upper ? own + hi_off : own + stride8;
;     *(u32x4*)pa = A; *(u32x4*)pb = B;
; }
;     __device__ __forceinline__ void operator()(const f32x4 (&acc)[2][2][4][2], const Unit& u, int wr, int wc, int fr, int fq) const {
;         const int t = u.pn >> 3; const int colt = (u.pn & 7) * 256;
;         const int col0 = colt + wc * 64 + 8 * fq;
;         bf16_t* base = QKV + (size_t)t * M * D;
;         float* fdst = nullptr;
;         if (t >= 1) {
;             if (u.pm < 32) { if ((u.pm & 7) >= 6) { const int n = u.pm >> 3; fdst = out + (t == 1 ? O_KP : O_VP) + ((size_t)n * 512 + (size_t)((u.pm & 7) - 6) * 256) * D; } }
;             else fdst = out + (t == 1 ? O_KS : O_VS) + (size_t)(u.pm - 32) * 256 * D;
;         }
; #pragma unroll
;         for (int ai = 0; ai < 2; ++ai)
; #pragma unroll
;             for (int m = 0; m < 4; ++m) { const int rl = wr * 64 + fr + ai * 128 + m * 16; u32x4 w[2];
; #pragma unroll
;                 for (int bj = 0; bj < 2; ++bj) { const f32x4 v0 = acc[ai][bj][m][0], v1 = acc[ai][bj][m][1];
;                     w[bj].x = pk2(v0[0], v0[1]); w[bj].y = pk2(v0[2], v0[3]); w[bj].z = pk2(v1[0], v1[1]); w[bj].w = pk2(v1[2], v1[3]);
;                     if (fdst) { float* fp = fdst + (size_t)rl * D + col0 + bj * 32; *(f32x4*)fp = v0; *(f32x4*)(fp + 4) = v1; } }
;                 store_pair((unsigned char*)(base + (size_t)(u.pm * 256 + rl) * D + col0), (size_t)8 * D * 2, 64, w[0], w[1], fr >= 8); }
;     }
.LBB0_698:
	s_nop 0
	v_cvt_pk_bf16_f32 v54, v54, v55
	v_cvt_pk_bf16_f32 v55, v56, v57
	v_cvt_pk_bf16_f32 v56, v50, v51
	v_add_u32_e32 v50, s2, v160
	v_ashrrev_i32_e32 v51, 31, v50
	v_cvt_pk_bf16_f32 v52, v52, v53
	v_cvt_pk_bf16_f32 v62, v62, v63
	v_cvt_pk_bf16_f32 v63, v64, v65
	v_cvt_pk_bf16_f32 v64, v58, v59
	v_cvt_pk_bf16_f32 v57, v60, v61
	v_lshlrev_b64 v[50:51], 12, v[50:51]
	v_lshl_add_u64 v[58:59], v[114:115], 0, v[50:51]
	s_mov_b64 vcc, s[6:7]
	v_mov_b32_dpp v66, v54 row_ror:8 row_mask:0xf bank_mask:0xf bound_ctrl:1
	v_mov_b32_dpp v67, v55 row_ror:8 row_mask:0xf bank_mask:0xf bound_ctrl:1
	v_mov_b32_dpp v68, v56 row_ror:8 row_mask:0xf bank_mask:0xf bound_ctrl:1
	v_mov_b32_dpp v69, v52 row_ror:8 row_mask:0xf bank_mask:0xf bound_ctrl:1
	v_lshl_add_u64 v[60:61], v[58:59], 0, v[142:143]
	v_cndmask_b32_dpp v53, v57, v52, vcc row_ror:8 row_mask:0xf bank_mask:0xf bound_ctrl:1
	v_cndmask_b32_dpp v52, v64, v56, vcc row_ror:8 row_mask:0xf bank_mask:0xf bound_ctrl:1
	v_cndmask_b32_dpp v51, v63, v55, vcc row_ror:8 row_mask:0xf bank_mask:0xf bound_ctrl:1
	v_cndmask_b32_dpp v50, v62, v54, vcc row_ror:8 row_mask:0xf bank_mask:0xf bound_ctrl:1
	v_cndmask_b32_e64 v57, v57, v69, s[6:7]
	v_cndmask_b32_e64 v56, v64, v68, s[6:7]
	v_cndmask_b32_e64 v55, v63, v67, s[6:7]
	v_cndmask_b32_e64 v54, v62, v66, s[6:7]
	v_lshl_add_u64 v[58:59], v[58:59], 0, v[144:145]
	global_store_dwordx4 v[60:61], v[54:57], off
	global_store_dwordx4 v[58:59], v[50:53], off
	s_and_b64 vcc, exec, s[8:9]
	s_nop 0
	v_lshl_add_u64 v[50:51], v[180:181], 0, v[166:167]
	s_cbranch_vccnz .LBB0_700
	global_store_dwordx4 v[50:51], v[46:49], off
	global_store_dwordx4 v[50:51], v[42:45], off offset:16

; __device__ __forceinline__ unsigned pk2(float lo, float hi) { const f32x2 v = {lo, hi}; return __builtin_bit_cast(unsigned, __builtin_convertvector(v, bf16x2_t)); }
; __device__ __forceinline__ void store_pair(unsigned char* own, size_t stride8, int hi_off, u32x4 lo, u32x4 hi, bool upper) {
;     const u32x4 tlo = ror8(lo), thi = ror8(hi);
;     const u32x4 A = upper ? thi : lo, B = upper ? hi : tlo;
;     unsigned char* pa = upper ? own - stride8 + hi_off : own;
;     unsigned char* pb = upper ? own + hi_off : own + stride8;
;     *(u32x4*)pa = A; *(u32x4*)pb = B;
; }
;     __device__ __forceinline__ void operator()(const f32x4 (&acc)[2][2][4][2], const Unit& u, int wr, int wc, int fr, int fq) const {
;         const int t = u.pn >> 3; const int colt = (u.pn & 7) * 256;
;         const int col0 = colt + wc * 64 + 8 * fq;
;         bf16_t* base = QKV + (size_t)t * M * D;
;         float* fdst = nullptr;
;         if (t >= 1) {
;             if (u.pm < 32) { if ((u.pm & 7) >= 6) { const int n = u.pm >> 3; fdst = out + (t == 1 ? O_KP : O_VP) + ((size_t)n * 512 + (size_t)((u.pm & 7) - 6) * 256) * D; } }
;             else fdst = out + (t == 1 ? O_KS : O_VS) + (size_t)(u.pm - 32) * 256 * D;
;         }
; #pragma unroll
;         for (int ai = 0; ai < 2; ++ai)
; #pragma unroll
;             for (int m = 0; m < 4; ++m) { const int rl = wr * 64 + fr + ai * 128 + m * 16; u32x4 w[2];
; #pragma unroll
;                 for (int bj = 0; bj < 2; ++bj) { const f32x4 v0 = acc[ai][bj][m][0], v1 = acc[ai][bj][m][1];
;                     w[bj].x = pk2(v0[0], v0[1]); w[bj].y = pk2(v0[2], v0[3]); w[bj].z = pk2(v1[0], v1[1]); w[bj].w = pk2(v1[2], v1[3]);
;                     if (fdst) { float* fp = fdst + (size_t)rl * D + col0 + bj * 32; *(f32x4*)fp = v0; *(f32x4*)(fp + 4) = v1; } }
;                 store_pair((unsigned char*)(base + (size_t)(u.pm * 256 + rl) * D + col0), (size_t)8 * D * 2, 64, w[0], w[1], fr >= 8); }
;     }
.LBB0_702:
	s_nop 0
	v_cvt_pk_bf16_f32 v38, v38, v39
	v_cvt_pk_bf16_f32 v39, v40, v41
	v_cvt_pk_bf16_f32 v40, v34, v35
	v_add_u32_e32 v34, s2, v164
	v_ashrrev_i32_e32 v35, 31, v34
	v_cvt_pk_bf16_f32 v36, v36, v37
	v_cvt_pk_bf16_f32 v46, v46, v47
	v_cvt_pk_bf16_f32 v47, v48, v49
	v_cvt_pk_bf16_f32 v48, v42, v43
	v_cvt_pk_bf16_f32 v41, v44, v45
	v_lshlrev_b64 v[34:35], 12, v[34:35]
	v_lshl_add_u64 v[42:43], v[114:115], 0, v[34:35]
	s_mov_b64 vcc, s[6:7]
	v_mov_b32_dpp v50, v38 row_ror:8 row_mask:0xf bank_mask:0xf bound_ctrl:1
	v_mov_b32_dpp v51, v39 row_ror:8 row_mask:0xf bank_mask:0xf bound_ctrl:1
	v_mov_b32_dpp v52, v40 row_ror:8 row_mask:0xf bank_mask:0xf bound_ctrl:1
	v_mov_b32_dpp v53, v36 row_ror:8 row_mask:0xf bank_mask:0xf bound_ctrl:1
	v_lshl_add_u64 v[44:45], v[42:43], 0, v[142:143]
	v_cndmask_b32_dpp v37, v41, v36, vcc row_ror:8 row_mask:0xf bank_mask:0xf bound_ctrl:1
	v_cndmask_b32_dpp v36, v48, v40, vcc row_ror:8 row_mask:0xf bank_mask:0xf bound_ctrl:1
	v_cndmask_b32_dpp v35, v47, v39, vcc row_ror:8 row_mask:0xf bank_mask:0xf bound_ctrl:1
	v_cndmask_b32_dpp v34, v46, v38, vcc row_ror:8 row_mask:0xf bank_mask:0xf bound_ctrl:1
	v_cndmask_b32_e64 v41, v41, v53, s[6:7]
	v_cndmask_b32_e64 v40, v48, v52, s[6:7]
	v_cndmask_b32_e64 v39, v47, v51, s[6:7]
	v_cndmask_b32_e64 v38, v46, v50, s[6:7]
	v_lshl_add_u64 v[42:43], v[42:43], 0, v[144:145]
	global_store_dwordx4 v[44:45], v[38:41], off
	global_store_dwordx4 v[42:43], v[34:37], off
	s_and_b64 vcc, exec, s[8:9]
	s_nop 0
	v_lshl_add_u64 v[34:35], v[180:181], 0, v[170:171]
	s_cbranch_vccnz .LBB0_704
	global_store_dwordx4 v[34:35], v[30:33], off
	global_store_dwordx4 v[34:35], v[26:29], off offset:16

; #define PG8_BAR __builtin_amdgcn_s_barrier()
; template <class Epi, class Sched, bool ABLK = false, bool ALIGN_EPI = true, bool SP2 = true, bool BBLK = true>
; __device__ __forceinline__ void gemm_phase(LAS unsigned char* lds, const Gemm g, const Sched& S, const Epi& E) {
;     ...
;         if constexpr (ALIGN_EPI) { if (wr == 0) PG8_BAR; }
;         E(acc, cur, wr, wc, fr, fq); S.done(cur);
;         if (!has_next) break;
; #pragma unroll
;         for (int a = 0; a < 2; ++a)
; #pragma unroll
;             for (int b = 0; b < 2; ++b)
; #pragma unroll
;                 for (int m = 0; m < 4; ++m)
; #pragma unroll
; __device__ __forceinline__ void store_pair(unsigned char* own, size_t stride8, int hi_off, u32x4 lo, u32x4 hi, bool upper) {
;     const u32x4 tlo = ror8(lo), thi = ror8(hi);
;     const u32x4 A = upper ? thi : lo, B = upper ? hi : tlo;
;     unsigned char* pa = upper ? own - stride8 + hi_off : own;
;     unsigned char* pb = upper ? own + hi_off : own + stride8;
;     *(u32x4*)pa = A; *(u32x4*)pb = B;
; }
;     __device__ __forceinline__ void operator()(const f32x4 (&acc)[2][2][4][2], const Unit& u, int wr, int wc, int fr, int fq) const {
;         const int t = u.pn >> 3; const int colt = (u.pn & 7) * 256;
;         const int col0 = colt + wc * 64 + 8 * fq;
;         bf16_t* base = QKV + (size_t)t * M * D;
;         float* fdst = nullptr;
;         if (t >= 1) {
;             if (u.pm < 32) { if ((u.pm & 7) >= 6) { const int n = u.pm >> 3; fdst = out + (t == 1 ? O_KP : O_VP) + ((size_t)n * 512 + (size_t)((u.pm & 7) - 6) * 256) * D; } }
;             else fdst = out + (t == 1 ? O_KS : O_VS) + (size_t)(u.pm - 32) * 256 * D;
;         }
; #pragma unroll
;         for (int ai = 0; ai < 2; ++ai)
; #pragma unroll
;             for (int m = 0; m < 4; ++m) { const int rl = wr * 64 + fr + ai * 128 + m * 16; u32x4 w[2];
; #pragma unroll
;                 for (int bj = 0; bj < 2; ++bj) { const f32x4 v0 = acc[ai][bj][m][0], v1 = acc[ai][bj][m][1];
;                     w[bj].x = pk2(v0[0], v0[1]); w[bj].y = pk2(v0[2], v0[3]); w[bj].z = pk2(v1[0], v1[1]); w[bj].w = pk2(v1[2], v1[3]);
;                     if (fdst) { float* fp = fdst + (size_t)rl * D + col0 + bj * 32; *(f32x4*)fp = v0; *(f32x4*)(fp + 4) = v1; } }
;                 store_pair((unsigned char*)(base + (size_t)(u.pm * 256 + rl) * D + col0), (size_t)8 * D * 2, 64, w[0], w[1], fr >= 8); }
;     }
.LBB0_706:
	s_nop 0
	v_cvt_pk_bf16_f32 v22, v22, v23
	v_cvt_pk_bf16_f32 v23, v24, v25
	v_cvt_pk_bf16_f32 v24, v18, v19
	v_add_u32_e32 v18, s2, v168
	v_ashrrev_i32_e32 v19, 31, v18
	v_cvt_pk_bf16_f32 v20, v20, v21
	v_cvt_pk_bf16_f32 v30, v30, v31
	v_cvt_pk_bf16_f32 v31, v32, v33
	v_cvt_pk_bf16_f32 v32, v26, v27
	v_cvt_pk_bf16_f32 v25, v28, v29
	v_lshlrev_b64 v[18:19], 12, v[18:19]
	v_lshl_add_u64 v[26:27], v[114:115], 0, v[18:19]
	s_mov_b64 vcc, s[6:7]
	v_mov_b32_dpp v34, v22 row_ror:8 row_mask:0xf bank_mask:0xf bound_ctrl:1
	v_mov_b32_dpp v35, v23 row_ror:8 row_mask:0xf bank_mask:0xf bound_ctrl:1
	v_mov_b32_dpp v36, v24 row_ror:8 row_mask:0xf bank_mask:0xf bound_ctrl:1
	v_mov_b32_dpp v37, v20 row_ror:8 row_mask:0xf bank_mask:0xf bound_ctrl:1
	v_lshl_add_u64 v[28:29], v[26:27], 0, v[142:143]
	v_cndmask_b32_dpp v21, v25, v20, vcc row_ror:8 row_mask:0xf bank_mask:0xf bound_ctrl:1
	v_cndmask_b32_dpp v20, v32, v24, vcc row_ror:8 row_mask:0xf bank_mask:0xf bound_ctrl:1
	v_cndmask_b32_dpp v19, v31, v23, vcc row_ror:8 row_mask:0xf bank_mask:0xf bound_ctrl:1
	v_cndmask_b32_dpp v18, v30, v22, vcc row_ror:8 row_mask:0xf bank_mask:0xf bound_ctrl:1
	v_cndmask_b32_e64 v25, v25, v37, s[6:7]
	v_cndmask_b32_e64 v24, v32, v36, s[6:7]
	v_cndmask_b32_e64 v23, v31, v35, s[6:7]
	v_cndmask_b32_e64 v22, v30, v34, s[6:7]
	v_lshl_add_u64 v[26:27], v[26:27], 0, v[144:145]
	s_and_b64 vcc, exec, s[8:9]
	global_store_dwordx4 v[28:29], v[22:25], off
	global_store_dwordx4 v[26:27], v[18:21], off
	s_cbranch_vccnz .LBB0_708
	s_nop 0
	v_lshl_add_u64 v[18:19], v[180:181], 0, v[174:175]
	global_store_dwordx4 v[18:19], v[14:17], off
	global_store_dwordx4 v[18:19], v[10:13], off offset:16
	global_store_dwordx4 v[18:19], v[6:9], off offset:128
	global_store_dwordx4 v[18:19], v[2:5], off offset:144
.LBB0_708:
	s_nop 0
	v_cvt_pk_bf16_f32 v6, v6, v7
	v_cvt_pk_bf16_f32 v7, v8, v9
	v_cvt_pk_bf16_f32 v8, v2, v3
	v_add_u32_e32 v2, s2, v172
	v_ashrrev_i32_e32 v3, 31, v2
	v_cvt_pk_bf16_f32 v4, v4, v5
	v_cvt_pk_bf16_f32 v14, v14, v15
	v_cvt_pk_bf16_f32 v15, v16, v17
	v_cvt_pk_bf16_f32 v16, v10, v11
	v_cvt_pk_bf16_f32 v17, v12, v13
	v_lshlrev_b64 v[2:3], 12, v[2:3]
	v_lshl_add_u64 v[10:11], v[114:115], 0, v[2:3]
	s_mov_b64 vcc, s[6:7]
	v_mov_b32_dpp v18, v6 row_ror:8 row_mask:0xf bank_mask:0xf bound_ctrl:1
	v_mov_b32_dpp v19, v7 row_ror:8 row_mask:0xf bank_mask:0xf bound_ctrl:1
	v_mov_b32_dpp v20, v8 row_ror:8 row_mask:0xf bank_mask:0xf bound_ctrl:1
	v_mov_b32_dpp v21, v4 row_ror:8 row_mask:0xf bank_mask:0xf bound_ctrl:1
	v_lshl_add_u64 v[12:13], v[10:11], 0, v[142:143]
	v_cndmask_b32_dpp v5, v17, v4, vcc row_ror:8 row_mask:0xf bank_mask:0xf bound_ctrl:1
	v_cndmask_b32_dpp v4, v16, v8, vcc row_ror:8 row_mask:0xf bank_mask:0xf bound_ctrl:1
	v_cndmask_b32_dpp v3, v15, v7, vcc row_ror:8 row_mask:0xf bank_mask:0xf bound_ctrl:1
	v_cndmask_b32_dpp v2, v14, v6, vcc row_ror:8 row_mask:0xf bank_mask:0xf bound_ctrl:1
	v_cndmask_b32_e64 v9, v17, v21, s[6:7]
	v_cndmask_b32_e64 v8, v16, v20, s[6:7]
	v_cndmask_b32_e64 v7, v15, v19, s[6:7]
	v_cndmask_b32_e64 v6, v14, v18, s[6:7]
	s_andn2_b64 vcc, exec, s[20:21]
	s_mov_b64 s[4:5], -1
	v_lshl_add_u64 v[10:11], v[10:11], 0, v[144:145]
	global_store_dwordx4 v[12:13], v[6:9], off
	global_store_dwordx4 v[10:11], v[2:5], off
	s_cbranch_vccnz .LBB0_664
	s_andn2_b64 vcc, exec, s[10:11]
	s_cbranch_vccnz .LBB0_663
	s_barrier
	s_branch .LBB0_663

; __device__ __forceinline__ unsigned pk2(float lo, float hi) { const f32x2 v = {lo, hi}; return __builtin_bit_cast(unsigned, __builtin_convertvector(v, bf16x2_t)); }
; __device__ __forceinline__ u32x4 ror8(u32x4 v) { u32x4 r;
; #pragma unroll
;     for (int i = 0; i < 4; ++i) r[i] = (unsigned)__builtin_amdgcn_mov_dpp((int)v[i], 0x128, 0xf, 0xf, true);
;     return r; }
; __device__ __forceinline__ void store_pair(unsigned char* own, size_t stride8, int hi_off, u32x4 lo, u32x4 hi, bool upper) {
;     const u32x4 tlo = ror8(lo), thi = ror8(hi);
;     const u32x4 A = upper ? thi : lo, B = upper ? hi : tlo;
;     unsigned char* pa = upper ? own - stride8 + hi_off : own;
;     unsigned char* pb = upper ? own + hi_off : own + stride8;
;     *(u32x4*)pa = A; *(u32x4*)pb = B;
; }
;     __device__ __forceinline__ void operator()(const f32x4 (&acc)[2][2][4][2], const Unit& u, int wr, int wc, int fr, int fq) const {
;         const int row0 = u.pm * 256 + wr * 64 + fr, col0 = u.pn * 256 + wc * 64 + 8 * fq;
;         bf16_t* base = u.part == 0 ? Z + (size_t)row0 * D + col0 : P + ((size_t)(u.part - 1) * MS + (row0 - MP)) * D + col0;
; #pragma unroll
;         for (int ai = 0; ai < 2; ++ai)
; #pragma unroll
;             for (int m = 0; m < 4; ++m) { u32x4 w[2];
; #pragma unroll
;                 for (int bj = 0; bj < 2; ++bj) { const f32x4 v0 = acc[ai][bj][m][0], v1 = acc[ai][bj][m][1]; w[bj].x = pk2(v0[0], v0[1]); w[bj].y = pk2(v0[2], v0[3]); w[bj].z = pk2(v1[0], v1[1]); w[bj].w = pk2(v1[2], v1[3]); }
;                 store_pair((unsigned char*)(base + (size_t)(ai * 128 + m * 16) * D), (size_t)8 * D * 2, 64, w[0], w[1], fr >= 8); }
;     }
.LBB0_1041:
	v_lshl_add_u32 v147, s47, 8, v150
	v_add_u32_e32 v148, 0xffffe000, v147
	v_sub_co_u32_e64 v146, vcc, s43, 1
	v_mov_b32_e32 v149, s54
	s_nop 0
	v_cndmask_b32_e32 v148, v148, v147, vcc
	v_ashrrev_i32_e32 v147, 31, v146
	v_lshlrev_b64 v[146:147], 23, v[146:147]
	v_lshl_add_u64 v[146:147], s[12:13], 0, v[146:147]
	v_cndmask_b32_e32 v147, v147, v149, vcc
	v_mov_b32_e32 v149, s52
	v_cndmask_b32_e32 v146, v146, v149, vcc
	v_ashrrev_i32_e32 v149, 31, v148
	v_lshl_or_b32 v156, s78, 8, v152
	v_lshlrev_b64 v[148:149], 12, v[148:149]
	v_lshl_add_u64 v[146:147], v[146:147], 0, v[148:149]
	v_ashrrev_i32_e32 v157, 31, v156
	v_cvt_pk_bf16_f32 v126, v126, v127
	v_cvt_pk_bf16_f32 v127, v128, v129
	v_cvt_pk_bf16_f32 v128, v122, v123
	v_cvt_pk_bf16_f32 v124, v124, v125
	v_cvt_pk_bf16_f32 v118, v118, v119
	v_cvt_pk_bf16_f32 v119, v120, v121
	v_cvt_pk_bf16_f32 v114, v114, v115
	v_cvt_pk_bf16_f32 v115, v116, v117
	v_lshl_add_u64 v[146:147], v[156:157], 1, v[146:147]
	s_mov_b64 vcc, s[6:7]
	v_mov_b32_dpp v125, v118 row_ror:8 row_mask:0xf bank_mask:0xf bound_ctrl:1
	v_mov_b32_dpp v129, v119 row_ror:8 row_mask:0xf bank_mask:0xf bound_ctrl:1
	v_mov_b32_dpp v148, v114 row_ror:8 row_mask:0xf bank_mask:0xf bound_ctrl:1
	v_mov_b32_dpp v149, v115 row_ror:8 row_mask:0xf bank_mask:0xf bound_ctrl:1
	v_lshl_add_u64 v[122:123], v[146:147], 0, v[138:139]
	v_cndmask_b32_dpp v117, v124, v115, vcc row_ror:8 row_mask:0xf bank_mask:0xf bound_ctrl:1
	v_cndmask_b32_dpp v116, v128, v114, vcc row_ror:8 row_mask:0xf bank_mask:0xf bound_ctrl:1
	v_cndmask_b32_dpp v115, v127, v119, vcc row_ror:8 row_mask:0xf bank_mask:0xf bound_ctrl:1
	v_cndmask_b32_dpp v114, v126, v118, vcc row_ror:8 row_mask:0xf bank_mask:0xf bound_ctrl:1
	v_cndmask_b32_e64 v121, v124, v149, s[6:7]
	v_cndmask_b32_e64 v120, v128, v148, s[6:7]
	v_cndmask_b32_e64 v119, v127, v129, s[6:7]
	v_cndmask_b32_e64 v118, v126, v125, s[6:7]
	v_cvt_pk_bf16_f32 v110, v110, v111
	v_cvt_pk_bf16_f32 v111, v112, v113
	v_cvt_pk_bf16_f32 v112, v106, v107
	v_cvt_pk_bf16_f32 v113, v108, v109
	v_cvt_pk_bf16_f32 v102, v102, v103
	v_cvt_pk_bf16_f32 v103, v104, v105
	v_cvt_pk_bf16_f32 v98, v98, v99
	v_cvt_pk_bf16_f32 v99, v100, v101
	s_mov_b64 s[4:5], 0x10000
	v_lshl_add_u64 v[124:125], v[146:147], 0, v[140:141]
	global_store_dwordx4 v[122:123], v[118:121], off
	global_store_dwordx4 v[124:125], v[114:117], off
	v_lshl_add_u64 v[106:107], v[146:147], 0, s[4:5]
	s_mov_b64 vcc, s[6:7]
	v_mov_b32_dpp v114, v102 row_ror:8 row_mask:0xf bank_mask:0xf bound_ctrl:1
	v_mov_b32_dpp v115, v103 row_ror:8 row_mask:0xf bank_mask:0xf bound_ctrl:1
	v_mov_b32_dpp v116, v98 row_ror:8 row_mask:0xf bank_mask:0xf bound_ctrl:1
	v_mov_b32_dpp v117, v99 row_ror:8 row_mask:0xf bank_mask:0xf bound_ctrl:1
	v_lshl_add_u64 v[108:109], v[106:107], 0, v[138:139]
	v_cndmask_b32_dpp v101, v113, v99, vcc row_ror:8 row_mask:0xf bank_mask:0xf bound_ctrl:1
	v_cndmask_b32_dpp v100, v112, v98, vcc row_ror:8 row_mask:0xf bank_mask:0xf bound_ctrl:1
	v_cndmask_b32_dpp v99, v111, v103, vcc row_ror:8 row_mask:0xf bank_mask:0xf bound_ctrl:1
	v_cndmask_b32_dpp v98, v110, v102, vcc row_ror:8 row_mask:0xf bank_mask:0xf bound_ctrl:1
	v_cndmask_b32_e64 v105, v113, v117, s[6:7]
	v_cndmask_b32_e64 v104, v112, v116, s[6:7]
	v_cndmask_b32_e64 v103, v111, v115, s[6:7]
	v_cndmask_b32_e64 v102, v110, v114, s[6:7]
	v_cvt_pk_bf16_f32 v94, v94, v95
	v_cvt_pk_bf16_f32 v95, v96, v97
	v_cvt_pk_bf16_f32 v96, v90, v91
	v_cvt_pk_bf16_f32 v97, v92, v93
	v_cvt_pk_bf16_f32 v86, v86, v87
	v_cvt_pk_bf16_f32 v87, v88, v89
	v_cvt_pk_bf16_f32 v82, v82, v83
	v_cvt_pk_bf16_f32 v83, v84, v85
	s_mov_b64 s[4:5], 0x20000
	v_lshl_add_u64 v[106:107], v[106:107], 0, v[140:141]
	global_store_dwordx4 v[108:109], v[102:105], off
	global_store_dwordx4 v[106:107], v[98:101], off
	v_lshl_add_u64 v[90:91], v[146:147], 0, s[4:5]
	s_mov_b64 vcc, s[6:7]
	v_mov_b32_dpp v98, v86 row_ror:8 row_mask:0xf bank_mask:0xf bound_ctrl:1
	v_mov_b32_dpp v99, v87 row_ror:8 row_mask:0xf bank_mask:0xf bound_ctrl:1
	v_mov_b32_dpp v100, v82 row_ror:8 row_mask:0xf bank_mask:0xf bound_ctrl:1
	v_mov_b32_dpp v101, v83 row_ror:8 row_mask:0xf bank_mask:0xf bound_ctrl:1
	v_lshl_add_u64 v[92:93], v[90:91], 0, v[138:139]
	v_cndmask_b32_dpp v85, v97, v83, vcc row_ror:8 row_mask:0xf bank_mask:0xf bound_ctrl:1
	v_cndmask_b32_dpp v84, v96, v82, vcc row_ror:8 row_mask:0xf bank_mask:0xf bound_ctrl:1
	v_cndmask_b32_dpp v83, v95, v87, vcc row_ror:8 row_mask:0xf bank_mask:0xf bound_ctrl:1
	v_cndmask_b32_dpp v82, v94, v86, vcc row_ror:8 row_mask:0xf bank_mask:0xf bound_ctrl:1
	v_cndmask_b32_e64 v89, v97, v101, s[6:7]
	v_cndmask_b32_e64 v88, v96, v100, s[6:7]
	v_cndmask_b32_e64 v87, v95, v99, s[6:7]
	v_cndmask_b32_e64 v86, v94, v98, s[6:7]
	v_cvt_pk_bf16_f32 v78, v78, v79
	v_cvt_pk_bf16_f32 v79, v80, v81
	v_cvt_pk_bf16_f32 v80, v74, v75
	v_cvt_pk_bf16_f32 v81, v76, v77
	v_cvt_pk_bf16_f32 v70, v70, v71
	v_cvt_pk_bf16_f32 v71, v72, v73
	v_cvt_pk_bf16_f32 v66, v66, v67
	v_cvt_pk_bf16_f32 v67, v68, v69
	s_mov_b64 s[4:5], 0x30000
	v_lshl_add_u64 v[90:91], v[90:91], 0, v[140:141]
	global_store_dwordx4 v[92:93], v[86:89], off
	global_store_dwordx4 v[90:91], v[82:85], off
	v_lshl_add_u64 v[74:75], v[146:147], 0, s[4:5]
	s_mov_b64 vcc, s[6:7]
	v_mov_b32_dpp v82, v70 row_ror:8 row_mask:0xf bank_mask:0xf bound_ctrl:1
	v_mov_b32_dpp v83, v71 row_ror:8 row_mask:0xf bank_mask:0xf bound_ctrl:1
	v_mov_b32_dpp v84, v66 row_ror:8 row_mask:0xf bank_mask:0xf bound_ctrl:1
	v_mov_b32_dpp v85, v67 row_ror:8 row_mask:0xf bank_mask:0xf bound_ctrl:1
	v_lshl_add_u64 v[76:77], v[74:75], 0, v[138:139]
	v_cndmask_b32_dpp v69, v81, v67, vcc row_ror:8 row_mask:0xf bank_mask:0xf bound_ctrl:1
; __device__ __forceinline__ unsigned pk2(float lo, float hi) { const f32x2 v = {lo, hi}; return __builtin_bit_cast(unsigned, __builtin_convertvector(v, bf16x2_t)); }
; __device__ __forceinline__ u32x4 ror8(u32x4 v) { u32x4 r;
; #pragma unroll
;     for (int i = 0; i < 4; ++i) r[i] = (unsigned)__builtin_amdgcn_mov_dpp((int)v[i], 0x128, 0xf, 0xf, true);
;     return r; }
; __device__ __forceinline__ void store_pair(unsigned char* own, size_t stride8, int hi_off, u32x4 lo, u32x4 hi, bool upper) {
;     const u32x4 tlo = ror8(lo), thi = ror8(hi);
;     const u32x4 A = upper ? thi : lo, B = upper ? hi : tlo;
;     unsigned char* pa = upper ? own - stride8 + hi_off : own;
;     unsigned char* pb = upper ? own + hi_off : own + stride8;
;     *(u32x4*)pa = A; *(u32x4*)pb = B;
; }
;     __device__ __forceinline__ void operator()(const f32x4 (&acc)[2][2][4][2], const Unit& u, int wr, int wc, int fr, int fq) const {
;         const int row0 = u.pm * 256 + wr * 64 + fr, col0 = u.pn * 256 + wc * 64 + 8 * fq;
;         bf16_t* base = u.part == 0 ? Z + (size_t)row0 * D + col0 : P + ((size_t)(u.part - 1) * MS + (row0 - MP)) * D + col0;
; #pragma unroll
;         for (int ai = 0; ai < 2; ++ai)
; #pragma unroll
;             for (int m = 0; m < 4; ++m) { u32x4 w[2];
; #pragma unroll
;                 for (int bj = 0; bj < 2; ++bj) { const f32x4 v0 = acc[ai][bj][m][0], v1 = acc[ai][bj][m][1]; w[bj].x = pk2(v0[0], v0[1]); w[bj].y = pk2(v0[2], v0[3]); w[bj].z = pk2(v1[0], v1[1]); w[bj].w = pk2(v1[2], v1[3]); }
;                 store_pair((unsigned char*)(base + (size_t)(ai * 128 + m * 16) * D), (size_t)8 * D * 2, 64, w[0], w[1], fr >= 8); }
;     }
	v_cndmask_b32_dpp v68, v80, v66, vcc row_ror:8 row_mask:0xf bank_mask:0xf bound_ctrl:1
	v_cndmask_b32_dpp v67, v79, v71, vcc row_ror:8 row_mask:0xf bank_mask:0xf bound_ctrl:1
	v_cndmask_b32_dpp v66, v78, v70, vcc row_ror:8 row_mask:0xf bank_mask:0xf bound_ctrl:1
	v_cndmask_b32_e64 v73, v81, v85, s[6:7]
	v_cndmask_b32_e64 v72, v80, v84, s[6:7]
	v_cndmask_b32_e64 v71, v79, v83, s[6:7]
	v_cndmask_b32_e64 v70, v78, v82, s[6:7]
	v_cvt_pk_bf16_f32 v62, v62, v63
	v_cvt_pk_bf16_f32 v63, v64, v65
	v_cvt_pk_bf16_f32 v64, v58, v59
	v_cvt_pk_bf16_f32 v65, v60, v61
	v_cvt_pk_bf16_f32 v54, v54, v55
	v_cvt_pk_bf16_f32 v55, v56, v57
	v_cvt_pk_bf16_f32 v50, v50, v51
	v_cvt_pk_bf16_f32 v51, v52, v53
	s_mov_b64 s[4:5], 0x80000
	v_lshl_add_u64 v[74:75], v[74:75], 0, v[140:141]
	global_store_dwordx4 v[76:77], v[70:73], off
	global_store_dwordx4 v[74:75], v[66:69], off
	v_lshl_add_u64 v[58:59], v[146:147], 0, s[4:5]
	s_mov_b64 vcc, s[6:7]
	v_mov_b32_dpp v66, v54 row_ror:8 row_mask:0xf bank_mask:0xf bound_ctrl:1
	v_mov_b32_dpp v67, v55 row_ror:8 row_mask:0xf bank_mask:0xf bound_ctrl:1
	v_mov_b32_dpp v68, v50 row_ror:8 row_mask:0xf bank_mask:0xf bound_ctrl:1
	v_mov_b32_dpp v69, v51 row_ror:8 row_mask:0xf bank_mask:0xf bound_ctrl:1
	v_lshl_add_u64 v[60:61], v[58:59], 0, v[138:139]
	v_cndmask_b32_dpp v53, v65, v51, vcc row_ror:8 row_mask:0xf bank_mask:0xf bound_ctrl:1
	v_cndmask_b32_dpp v52, v64, v50, vcc row_ror:8 row_mask:0xf bank_mask:0xf bound_ctrl:1
	v_cndmask_b32_dpp v51, v63, v55, vcc row_ror:8 row_mask:0xf bank_mask:0xf bound_ctrl:1
	v_cndmask_b32_dpp v50, v62, v54, vcc row_ror:8 row_mask:0xf bank_mask:0xf bound_ctrl:1
	v_cndmask_b32_e64 v57, v65, v69, s[6:7]
	v_cndmask_b32_e64 v56, v64, v68, s[6:7]
	v_cndmask_b32_e64 v55, v63, v67, s[6:7]
	v_cndmask_b32_e64 v54, v62, v66, s[6:7]
	v_cvt_pk_bf16_f32 v46, v46, v47
	v_cvt_pk_bf16_f32 v47, v48, v49
	v_cvt_pk_bf16_f32 v48, v42, v43
	v_cvt_pk_bf16_f32 v49, v44, v45
	v_cvt_pk_bf16_f32 v38, v38, v39
	v_cvt_pk_bf16_f32 v39, v40, v41
	v_cvt_pk_bf16_f32 v34, v34, v35
	v_cvt_pk_bf16_f32 v35, v36, v37
	s_mov_b64 s[4:5], 0x90000
	v_lshl_add_u64 v[58:59], v[58:59], 0, v[140:141]
	global_store_dwordx4 v[60:61], v[54:57], off
	global_store_dwordx4 v[58:59], v[50:53], off
	v_lshl_add_u64 v[42:43], v[146:147], 0, s[4:5]
	s_mov_b64 vcc, s[6:7]
	v_mov_b32_dpp v50, v38 row_ror:8 row_mask:0xf bank_mask:0xf bound_ctrl:1
	v_mov_b32_dpp v51, v39 row_ror:8 row_mask:0xf bank_mask:0xf bound_ctrl:1
	v_mov_b32_dpp v52, v34 row_ror:8 row_mask:0xf bank_mask:0xf bound_ctrl:1
	v_mov_b32_dpp v53, v35 row_ror:8 row_mask:0xf bank_mask:0xf bound_ctrl:1
	v_lshl_add_u64 v[44:45], v[42:43], 0, v[138:139]
	v_cndmask_b32_dpp v37, v49, v35, vcc row_ror:8 row_mask:0xf bank_mask:0xf bound_ctrl:1
	v_cndmask_b32_dpp v36, v48, v34, vcc row_ror:8 row_mask:0xf bank_mask:0xf bound_ctrl:1
	v_cndmask_b32_dpp v35, v47, v39, vcc row_ror:8 row_mask:0xf bank_mask:0xf bound_ctrl:1
	v_cndmask_b32_dpp v34, v46, v38, vcc row_ror:8 row_mask:0xf bank_mask:0xf bound_ctrl:1
	v_cndmask_b32_e64 v41, v49, v53, s[6:7]
	v_cndmask_b32_e64 v40, v48, v52, s[6:7]
	v_cndmask_b32_e64 v39, v47, v51, s[6:7]
	v_cndmask_b32_e64 v38, v46, v50, s[6:7]
	v_cvt_pk_bf16_f32 v30, v30, v31
	v_cvt_pk_bf16_f32 v31, v32, v33
	v_cvt_pk_bf16_f32 v32, v26, v27
	v_cvt_pk_bf16_f32 v33, v28, v29
	v_cvt_pk_bf16_f32 v22, v22, v23
	v_cvt_pk_bf16_f32 v23, v24, v25
	v_cvt_pk_bf16_f32 v18, v18, v19
	v_cvt_pk_bf16_f32 v19, v20, v21
	s_mov_b64 s[4:5], 0xa0000
	v_lshl_add_u64 v[42:43], v[42:43], 0, v[140:141]
	global_store_dwordx4 v[44:45], v[38:41], off
	global_store_dwordx4 v[42:43], v[34:37], off
	v_lshl_add_u64 v[26:27], v[146:147], 0, s[4:5]
	s_mov_b64 vcc, s[6:7]
	v_mov_b32_dpp v34, v22 row_ror:8 row_mask:0xf bank_mask:0xf bound_ctrl:1
	v_mov_b32_dpp v35, v23 row_ror:8 row_mask:0xf bank_mask:0xf bound_ctrl:1
	v_mov_b32_dpp v36, v18 row_ror:8 row_mask:0xf bank_mask:0xf bound_ctrl:1
	v_mov_b32_dpp v37, v19 row_ror:8 row_mask:0xf bank_mask:0xf bound_ctrl:1
	v_lshl_add_u64 v[28:29], v[26:27], 0, v[138:139]
	v_cndmask_b32_dpp v21, v33, v19, vcc row_ror:8 row_mask:0xf bank_mask:0xf bound_ctrl:1
	v_cndmask_b32_dpp v20, v32, v18, vcc row_ror:8 row_mask:0xf bank_mask:0xf bound_ctrl:1
	v_cndmask_b32_dpp v19, v31, v23, vcc row_ror:8 row_mask:0xf bank_mask:0xf bound_ctrl:1
	v_cndmask_b32_dpp v18, v30, v22, vcc row_ror:8 row_mask:0xf bank_mask:0xf bound_ctrl:1
	v_cndmask_b32_e64 v25, v33, v37, s[6:7]
	v_cndmask_b32_e64 v24, v32, v36, s[6:7]
	v_cndmask_b32_e64 v23, v31, v35, s[6:7]
	v_cndmask_b32_e64 v22, v30, v34, s[6:7]
	v_cvt_pk_bf16_f32 v14, v14, v15
	v_cvt_pk_bf16_f32 v15, v16, v17
	v_cvt_pk_bf16_f32 v16, v10, v11
	v_cvt_pk_bf16_f32 v17, v12, v13
	v_cvt_pk_bf16_f32 v6, v6, v7
	v_cvt_pk_bf16_f32 v7, v8, v9
	v_cvt_pk_bf16_f32 v2, v2, v3
	v_cvt_pk_bf16_f32 v3, v4, v5
	s_mov_b64 s[4:5], 0xb0000
	v_lshl_add_u64 v[26:27], v[26:27], 0, v[140:141]
	global_store_dwordx4 v[28:29], v[22:25], off
	global_store_dwordx4 v[26:27], v[18:21], off
	v_lshl_add_u64 v[10:11], v[146:147], 0, s[4:5]
	s_mov_b64 vcc, s[6:7]
	v_mov_b32_dpp v18, v6 row_ror:8 row_mask:0xf bank_mask:0xf bound_ctrl:1
	v_mov_b32_dpp v19, v7 row_ror:8 row_mask:0xf bank_mask:0xf bound_ctrl:1
	v_mov_b32_dpp v20, v2 row_ror:8 row_mask:0xf bank_mask:0xf bound_ctrl:1
	v_mov_b32_dpp v21, v3 row_ror:8 row_mask:0xf bank_mask:0xf bound_ctrl:1
	v_lshl_add_u64 v[12:13], v[10:11], 0, v[138:139]
	v_cndmask_b32_dpp v5, v17, v3, vcc row_ror:8 row_mask:0xf bank_mask:0xf bound_ctrl:1
	v_cndmask_b32_dpp v4, v16, v2, vcc row_ror:8 row_mask:0xf bank_mask:0xf bound_ctrl:1
	v_cndmask_b32_dpp v3, v15, v7, vcc row_ror:8 row_mask:0xf bank_mask:0xf bound_ctrl:1
	v_cndmask_b32_dpp v2, v14, v6, vcc row_ror:8 row_mask:0xf bank_mask:0xf bound_ctrl:1
	v_cndmask_b32_e64 v9, v17, v21, s[6:7]
	v_cndmask_b32_e64 v8, v16, v20, s[6:7]
	v_cndmask_b32_e64 v7, v15, v19, s[6:7]
	v_cndmask_b32_e64 v6, v14, v18, s[6:7]
	s_and_b64 vcc, exec, s[8:9]
	s_mov_b64 s[8:9], -1
	v_lshl_add_u64 v[10:11], v[10:11], 0, v[140:141]
	global_store_dwordx4 v[12:13], v[6:9], off
	global_store_dwordx4 v[10:11], v[2:5], off
	s_cbranch_vccnz .LBB0_1036
	s_andn2_b64 vcc, exec, s[2:3]
	s_cbranch_vccnz .LBB0_1035
	s_barrier
	s_branch .LBB0_1035

; __device__ __forceinline__ unsigned pk2(float lo, float hi) { const f32x2 v = {lo, hi}; return __builtin_bit_cast(unsigned, __builtin_convertvector(v, bf16x2_t)); }
; __device__ __forceinline__ u32x4 ror8(u32x4 v) { u32x4 r;
; #pragma unroll
;     for (int i = 0; i < 4; ++i) r[i] = (unsigned)__builtin_amdgcn_mov_dpp((int)v[i], 0x128, 0xf, 0xf, true);
;     return r; }
; __device__ __forceinline__ void store_pair(unsigned char* own, size_t stride8, int hi_off, u32x4 lo, u32x4 hi, bool upper) {
;     const u32x4 tlo = ror8(lo), thi = ror8(hi);
;     const u32x4 A = upper ? thi : lo, B = upper ? hi : tlo;
;     unsigned char* pa = upper ? own - stride8 + hi_off : own;
;     unsigned char* pb = upper ? own + hi_off : own + stride8;
;     *(u32x4*)pa = A; *(u32x4*)pb = B;
; }
;     __device__ __forceinline__ void operator()(const f32x4 (&acc)[2][2][4][2], const Unit& u, int wr, int wc, int fr, int fq) const {
; #pragma unroll
;         for (int ai = 0; ai < 2; ++ai)
; #pragma unroll
;             for (int m = 0; m < 4; ++m) { unsigned char* rowp = (unsigned char*)(H + ((size_t)(u.pm * (FF / 64) + u.pn * 4 + wc) * 256 + (wr * 64 + fr + ai * 128 + m * 16)) * 64 + 8 * fq); u32x4 w[2];
; #pragma unroll
;                 for (int bj = 0; bj < 2; ++bj) { f32x4 v0 = acc[ai][bj][m][0], v1 = acc[ai][bj][m][1];
; #pragma unroll
;                     for (int j = 0; j < 4; ++j) { const float a = fmaxf(v0[j], 0.f), b = fmaxf(v1[j], 0.f); v0[j] = a * a; v1[j] = b * b; }
;                     w[bj].x = pk2(v0[0], v0[1]); w[bj].y = pk2(v0[2], v0[3]); w[bj].z = pk2(v1[0], v1[1]); w[bj].w = pk2(v1[2], v1[3]); }
;                 store_pair(rowp, (size_t)8 * 64 * 2, 64, w[0], w[1], fr >= 8); }
;     }
.LBB0_1167:
	s_lshl_b32 s4, s22, 7
	s_lshl_b32 s5, s24, 2
	s_add_i32 s5, s5, s4
	s_or_b32 s4, s5, s47
	s_ashr_i32 s5, s4, 31
	s_lshl_b64 s[4:5], s[4:5], 15
	s_add_u32 s22, s1, s4
	v_max_f32_e32 v126, 0, v126
	v_max_f32_e32 v122, 0, v122
	v_max_f32_e32 v127, 0, v127
	v_max_f32_e32 v123, 0, v123
	v_max_f32_e32 v128, 0, v128
	v_max_f32_e32 v124, 0, v124
	v_max_f32_e32 v129, 0, v129
	v_max_f32_e32 v125, 0, v125
	v_max_f32_e32 v118, 0, v118
	v_max_f32_e32 v114, 0, v114
	v_max_f32_e32 v119, 0, v119
	v_max_f32_e32 v115, 0, v115
	v_max_f32_e32 v120, 0, v120
	v_max_f32_e32 v116, 0, v116
	v_max_f32_e32 v121, 0, v121
	v_max_f32_e32 v117, 0, v117
	s_addc_u32 s23, s33, s5
	v_pk_mul_f32 v[126:127], v[126:127], v[126:127]
	v_pk_mul_f32 v[122:123], v[122:123], v[122:123]
	v_pk_mul_f32 v[128:129], v[128:129], v[128:129]
	v_pk_mul_f32 v[124:125], v[124:125], v[124:125]
	v_pk_mul_f32 v[118:119], v[118:119], v[118:119]
	v_pk_mul_f32 v[114:115], v[114:115], v[114:115]
	v_pk_mul_f32 v[120:121], v[120:121], v[120:121]
	v_pk_mul_f32 v[116:117], v[116:117], v[116:117]
	v_lshl_add_u64 v[164:165], s[22:23], 0, v[144:145]
	v_cvt_pk_bf16_f32 v126, v126, v127
	v_cvt_pk_bf16_f32 v127, v128, v129
	v_cvt_pk_bf16_f32 v128, v122, v123
	v_cvt_pk_bf16_f32 v129, v124, v125
	v_cvt_pk_bf16_f32 v118, v118, v119
	v_cvt_pk_bf16_f32 v119, v120, v121
	v_cvt_pk_bf16_f32 v114, v114, v115
	v_cvt_pk_bf16_f32 v115, v116, v117
	v_lshl_add_u64 v[122:123], v[164:165], 0, v[138:139]
	s_mov_b64 vcc, s[8:9]
	v_mov_b32_dpp v164, v118 row_ror:8 row_mask:0xf bank_mask:0xf bound_ctrl:1
	v_mov_b32_dpp v165, v119 row_ror:8 row_mask:0xf bank_mask:0xf bound_ctrl:1
	v_mov_b32_dpp v166, v114 row_ror:8 row_mask:0xf bank_mask:0xf bound_ctrl:1
	v_mov_b32_dpp v167, v115 row_ror:8 row_mask:0xf bank_mask:0xf bound_ctrl:1
	v_max_f32_e32 v110, 0, v110
	v_max_f32_e32 v106, 0, v106
	v_max_f32_e32 v111, 0, v111
	v_max_f32_e32 v107, 0, v107
	v_max_f32_e32 v112, 0, v112
	v_max_f32_e32 v108, 0, v108
	v_max_f32_e32 v113, 0, v113
	v_max_f32_e32 v109, 0, v109
	v_max_f32_e32 v102, 0, v102
	v_max_f32_e32 v98, 0, v98
	v_max_f32_e32 v103, 0, v103
	v_max_f32_e32 v99, 0, v99
	v_max_f32_e32 v104, 0, v104
	v_max_f32_e32 v100, 0, v100
	v_max_f32_e32 v105, 0, v105
	v_max_f32_e32 v101, 0, v101
	v_lshl_add_u64 v[124:125], v[122:123], 0, v[140:141]
	v_cndmask_b32_dpp v117, v129, v115, vcc row_ror:8 row_mask:0xf bank_mask:0xf bound_ctrl:1
	v_cndmask_b32_dpp v116, v128, v114, vcc row_ror:8 row_mask:0xf bank_mask:0xf bound_ctrl:1
	v_cndmask_b32_dpp v115, v127, v119, vcc row_ror:8 row_mask:0xf bank_mask:0xf bound_ctrl:1
	v_cndmask_b32_dpp v114, v126, v118, vcc row_ror:8 row_mask:0xf bank_mask:0xf bound_ctrl:1
	v_cndmask_b32_e64 v121, v129, v167, s[8:9]
	v_cndmask_b32_e64 v120, v128, v166, s[8:9]
	v_cndmask_b32_e64 v119, v127, v165, s[8:9]
	v_cndmask_b32_e64 v118, v126, v164, s[8:9]
	v_pk_mul_f32 v[110:111], v[110:111], v[110:111]
	v_pk_mul_f32 v[106:107], v[106:107], v[106:107]
	v_pk_mul_f32 v[112:113], v[112:113], v[112:113]
	v_pk_mul_f32 v[108:109], v[108:109], v[108:109]
	v_pk_mul_f32 v[102:103], v[102:103], v[102:103]
	v_pk_mul_f32 v[98:99], v[98:99], v[98:99]
	v_pk_mul_f32 v[104:105], v[104:105], v[104:105]
	v_pk_mul_f32 v[100:101], v[100:101], v[100:101]
	v_lshl_add_u64 v[122:123], v[122:123], 0, v[142:143]
	global_store_dwordx4 v[124:125], v[118:121], off
	global_store_dwordx4 v[122:123], v[114:117], off
	v_cvt_pk_bf16_f32 v110, v110, v111
	v_cvt_pk_bf16_f32 v111, v112, v113
	v_lshl_add_u64 v[114:115], s[22:23], 0, v[146:147]
	v_cvt_pk_bf16_f32 v112, v106, v107
	v_cvt_pk_bf16_f32 v113, v108, v109
	v_cvt_pk_bf16_f32 v102, v102, v103
	v_cvt_pk_bf16_f32 v103, v104, v105
	v_cvt_pk_bf16_f32 v98, v98, v99
	v_cvt_pk_bf16_f32 v99, v100, v101
	v_lshl_add_u64 v[106:107], v[114:115], 0, v[138:139]
	s_mov_b64 vcc, s[8:9]
	v_mov_b32_dpp v114, v102 row_ror:8 row_mask:0xf bank_mask:0xf bound_ctrl:1
	v_mov_b32_dpp v115, v103 row_ror:8 row_mask:0xf bank_mask:0xf bound_ctrl:1
	v_mov_b32_dpp v116, v98 row_ror:8 row_mask:0xf bank_mask:0xf bound_ctrl:1
	v_mov_b32_dpp v117, v99 row_ror:8 row_mask:0xf bank_mask:0xf bound_ctrl:1
	v_max_f32_e32 v94, 0, v94
	v_max_f32_e32 v90, 0, v90
	v_max_f32_e32 v95, 0, v95
	v_max_f32_e32 v91, 0, v91
	v_max_f32_e32 v96, 0, v96
	v_max_f32_e32 v92, 0, v92
	v_max_f32_e32 v97, 0, v97
	v_max_f32_e32 v93, 0, v93
	v_max_f32_e32 v86, 0, v86
	v_max_f32_e32 v82, 0, v82
	v_max_f32_e32 v87, 0, v87
	v_max_f32_e32 v83, 0, v83
	v_max_f32_e32 v88, 0, v88
	v_max_f32_e32 v84, 0, v84
	v_max_f32_e32 v89, 0, v89
	v_max_f32_e32 v85, 0, v85
	v_lshl_add_u64 v[108:109], v[106:107], 0, v[140:141]
	v_cndmask_b32_dpp v101, v113, v99, vcc row_ror:8 row_mask:0xf bank_mask:0xf bound_ctrl:1
	v_cndmask_b32_dpp v100, v112, v98, vcc row_ror:8 row_mask:0xf bank_mask:0xf bound_ctrl:1
	v_cndmask_b32_dpp v99, v111, v103, vcc row_ror:8 row_mask:0xf bank_mask:0xf bound_ctrl:1
	v_cndmask_b32_dpp v98, v110, v102, vcc row_ror:8 row_mask:0xf bank_mask:0xf bound_ctrl:1
	v_cndmask_b32_e64 v105, v113, v117, s[8:9]
	v_cndmask_b32_e64 v104, v112, v116, s[8:9]
	v_cndmask_b32_e64 v103, v111, v115, s[8:9]
	v_cndmask_b32_e64 v102, v110, v114, s[8:9]
	v_pk_mul_f32 v[94:95], v[94:95], v[94:95]
	v_pk_mul_f32 v[90:91], v[90:91], v[90:91]
	v_pk_mul_f32 v[96:97], v[96:97], v[96:97]
	v_pk_mul_f32 v[92:93], v[92:93], v[92:93]
	v_pk_mul_f32 v[86:87], v[86:87], v[86:87]
	v_pk_mul_f32 v[82:83], v[82:83], v[82:83]
	v_pk_mul_f32 v[88:89], v[88:89], v[88:89]
	v_pk_mul_f32 v[84:85], v[84:85], v[84:85]
	v_lshl_add_u64 v[106:107], v[106:107], 0, v[142:143]
	global_store_dwordx4 v[108:109], v[102:105], off
	global_store_dwordx4 v[106:107], v[98:101], off
	v_cvt_pk_bf16_f32 v94, v94, v95
; __device__ __forceinline__ unsigned pk2(float lo, float hi) { const f32x2 v = {lo, hi}; return __builtin_bit_cast(unsigned, __builtin_convertvector(v, bf16x2_t)); }
; __device__ __forceinline__ u32x4 ror8(u32x4 v) { u32x4 r;
; #pragma unroll
;     for (int i = 0; i < 4; ++i) r[i] = (unsigned)__builtin_amdgcn_mov_dpp((int)v[i], 0x128, 0xf, 0xf, true);
;     return r; }
; __device__ __forceinline__ void store_pair(unsigned char* own, size_t stride8, int hi_off, u32x4 lo, u32x4 hi, bool upper) {
;     const u32x4 tlo = ror8(lo), thi = ror8(hi);
;     const u32x4 A = upper ? thi : lo, B = upper ? hi : tlo;
;     unsigned char* pa = upper ? own - stride8 + hi_off : own;
;     unsigned char* pb = upper ? own + hi_off : own + stride8;
;     *(u32x4*)pa = A; *(u32x4*)pb = B;
; }
;     __device__ __forceinline__ void operator()(const f32x4 (&acc)[2][2][4][2], const Unit& u, int wr, int wc, int fr, int fq) const {
; #pragma unroll
;         for (int ai = 0; ai < 2; ++ai)
; #pragma unroll
;             for (int m = 0; m < 4; ++m) { unsigned char* rowp = (unsigned char*)(H + ((size_t)(u.pm * (FF / 64) + u.pn * 4 + wc) * 256 + (wr * 64 + fr + ai * 128 + m * 16)) * 64 + 8 * fq); u32x4 w[2];
; #pragma unroll
;                 for (int bj = 0; bj < 2; ++bj) { f32x4 v0 = acc[ai][bj][m][0], v1 = acc[ai][bj][m][1];
; #pragma unroll
;                     for (int j = 0; j < 4; ++j) { const float a = fmaxf(v0[j], 0.f), b = fmaxf(v1[j], 0.f); v0[j] = a * a; v1[j] = b * b; }
;                     w[bj].x = pk2(v0[0], v0[1]); w[bj].y = pk2(v0[2], v0[3]); w[bj].z = pk2(v1[0], v1[1]); w[bj].w = pk2(v1[2], v1[3]); }
;                 store_pair(rowp, (size_t)8 * 64 * 2, 64, w[0], w[1], fr >= 8); }
;     }
	v_cvt_pk_bf16_f32 v95, v96, v97
	v_lshl_add_u64 v[98:99], s[22:23], 0, v[148:149]
	v_cvt_pk_bf16_f32 v96, v90, v91
	v_cvt_pk_bf16_f32 v97, v92, v93
	v_cvt_pk_bf16_f32 v86, v86, v87
	v_cvt_pk_bf16_f32 v87, v88, v89
	v_cvt_pk_bf16_f32 v82, v82, v83
	v_cvt_pk_bf16_f32 v83, v84, v85
	v_lshl_add_u64 v[90:91], v[98:99], 0, v[138:139]
	s_mov_b64 vcc, s[8:9]
	v_mov_b32_dpp v98, v86 row_ror:8 row_mask:0xf bank_mask:0xf bound_ctrl:1
	v_mov_b32_dpp v99, v87 row_ror:8 row_mask:0xf bank_mask:0xf bound_ctrl:1
	v_mov_b32_dpp v100, v82 row_ror:8 row_mask:0xf bank_mask:0xf bound_ctrl:1
	v_mov_b32_dpp v101, v83 row_ror:8 row_mask:0xf bank_mask:0xf bound_ctrl:1
	v_max_f32_e32 v78, 0, v78
	v_max_f32_e32 v74, 0, v74
	v_max_f32_e32 v79, 0, v79
	v_max_f32_e32 v75, 0, v75
	v_max_f32_e32 v80, 0, v80
	v_max_f32_e32 v76, 0, v76
	v_max_f32_e32 v81, 0, v81
	v_max_f32_e32 v77, 0, v77
	v_max_f32_e32 v70, 0, v70
	v_max_f32_e32 v66, 0, v66
	v_max_f32_e32 v71, 0, v71
	v_max_f32_e32 v67, 0, v67
	v_max_f32_e32 v72, 0, v72
	v_max_f32_e32 v68, 0, v68
	v_max_f32_e32 v73, 0, v73
	v_max_f32_e32 v69, 0, v69
	v_lshl_add_u64 v[92:93], v[90:91], 0, v[140:141]
	v_cndmask_b32_dpp v85, v97, v83, vcc row_ror:8 row_mask:0xf bank_mask:0xf bound_ctrl:1
	v_cndmask_b32_dpp v84, v96, v82, vcc row_ror:8 row_mask:0xf bank_mask:0xf bound_ctrl:1
	v_cndmask_b32_dpp v83, v95, v87, vcc row_ror:8 row_mask:0xf bank_mask:0xf bound_ctrl:1
	v_cndmask_b32_dpp v82, v94, v86, vcc row_ror:8 row_mask:0xf bank_mask:0xf bound_ctrl:1
	v_cndmask_b32_e64 v89, v97, v101, s[8:9]
	v_cndmask_b32_e64 v88, v96, v100, s[8:9]
	v_cndmask_b32_e64 v87, v95, v99, s[8:9]
	v_cndmask_b32_e64 v86, v94, v98, s[8:9]
	v_pk_mul_f32 v[78:79], v[78:79], v[78:79]
	v_pk_mul_f32 v[74:75], v[74:75], v[74:75]
	v_pk_mul_f32 v[80:81], v[80:81], v[80:81]
	v_pk_mul_f32 v[76:77], v[76:77], v[76:77]
	v_pk_mul_f32 v[70:71], v[70:71], v[70:71]
	v_pk_mul_f32 v[66:67], v[66:67], v[66:67]
	v_pk_mul_f32 v[72:73], v[72:73], v[72:73]
	v_pk_mul_f32 v[68:69], v[68:69], v[68:69]
	v_lshl_add_u64 v[90:91], v[90:91], 0, v[142:143]
	global_store_dwordx4 v[92:93], v[86:89], off
	global_store_dwordx4 v[90:91], v[82:85], off
	v_cvt_pk_bf16_f32 v78, v78, v79
	v_cvt_pk_bf16_f32 v79, v80, v81
	v_lshl_add_u64 v[82:83], s[22:23], 0, v[150:151]
	v_cvt_pk_bf16_f32 v80, v74, v75
	v_cvt_pk_bf16_f32 v81, v76, v77
	v_cvt_pk_bf16_f32 v70, v70, v71
	v_cvt_pk_bf16_f32 v71, v72, v73
	v_cvt_pk_bf16_f32 v66, v66, v67
	v_cvt_pk_bf16_f32 v67, v68, v69
	v_lshl_add_u64 v[74:75], v[82:83], 0, v[138:139]
	s_mov_b64 vcc, s[8:9]
	v_mov_b32_dpp v82, v70 row_ror:8 row_mask:0xf bank_mask:0xf bound_ctrl:1
	v_mov_b32_dpp v83, v71 row_ror:8 row_mask:0xf bank_mask:0xf bound_ctrl:1
	v_mov_b32_dpp v84, v66 row_ror:8 row_mask:0xf bank_mask:0xf bound_ctrl:1
	v_mov_b32_dpp v85, v67 row_ror:8 row_mask:0xf bank_mask:0xf bound_ctrl:1
	v_max_f32_e32 v62, 0, v62
	v_max_f32_e32 v58, 0, v58
	v_max_f32_e32 v63, 0, v63
	v_max_f32_e32 v59, 0, v59
	v_max_f32_e32 v64, 0, v64
	v_max_f32_e32 v60, 0, v60
	v_max_f32_e32 v65, 0, v65
	v_max_f32_e32 v61, 0, v61
	v_max_f32_e32 v54, 0, v54
	v_max_f32_e32 v50, 0, v50
	v_max_f32_e32 v55, 0, v55
	v_max_f32_e32 v51, 0, v51
	v_max_f32_e32 v56, 0, v56
	v_max_f32_e32 v52, 0, v52
	v_max_f32_e32 v57, 0, v57
	v_max_f32_e32 v53, 0, v53
	v_lshl_add_u64 v[76:77], v[74:75], 0, v[140:141]
	v_cndmask_b32_dpp v69, v81, v67, vcc row_ror:8 row_mask:0xf bank_mask:0xf bound_ctrl:1
	v_cndmask_b32_dpp v68, v80, v66, vcc row_ror:8 row_mask:0xf bank_mask:0xf bound_ctrl:1
	v_cndmask_b32_dpp v67, v79, v71, vcc row_ror:8 row_mask:0xf bank_mask:0xf bound_ctrl:1
	v_cndmask_b32_dpp v66, v78, v70, vcc row_ror:8 row_mask:0xf bank_mask:0xf bound_ctrl:1
	v_cndmask_b32_e64 v73, v81, v85, s[8:9]
	v_cndmask_b32_e64 v72, v80, v84, s[8:9]
	v_cndmask_b32_e64 v71, v79, v83, s[8:9]
	v_cndmask_b32_e64 v70, v78, v82, s[8:9]
	v_pk_mul_f32 v[62:63], v[62:63], v[62:63]
	v_pk_mul_f32 v[58:59], v[58:59], v[58:59]
	v_pk_mul_f32 v[64:65], v[64:65], v[64:65]
	v_pk_mul_f32 v[60:61], v[60:61], v[60:61]
	v_pk_mul_f32 v[54:55], v[54:55], v[54:55]
	v_pk_mul_f32 v[50:51], v[50:51], v[50:51]
	v_pk_mul_f32 v[56:57], v[56:57], v[56:57]
	v_pk_mul_f32 v[52:53], v[52:53], v[52:53]
	v_lshl_add_u64 v[74:75], v[74:75], 0, v[142:143]
	global_store_dwordx4 v[76:77], v[70:73], off
	global_store_dwordx4 v[74:75], v[66:69], off
	v_cvt_pk_bf16_f32 v62, v62, v63
	v_cvt_pk_bf16_f32 v63, v64, v65
	v_lshl_add_u64 v[66:67], s[22:23], 0, v[152:153]
	v_cvt_pk_bf16_f32 v64, v58, v59
	v_cvt_pk_bf16_f32 v65, v60, v61
	v_cvt_pk_bf16_f32 v54, v54, v55
	v_cvt_pk_bf16_f32 v55, v56, v57
	v_cvt_pk_bf16_f32 v50, v50, v51
	v_cvt_pk_bf16_f32 v51, v52, v53
	v_lshl_add_u64 v[58:59], v[66:67], 0, v[138:139]
	s_mov_b64 vcc, s[8:9]
	v_mov_b32_dpp v66, v54 row_ror:8 row_mask:0xf bank_mask:0xf bound_ctrl:1
	v_mov_b32_dpp v67, v55 row_ror:8 row_mask:0xf bank_mask:0xf bound_ctrl:1
	v_mov_b32_dpp v68, v50 row_ror:8 row_mask:0xf bank_mask:0xf bound_ctrl:1
	v_mov_b32_dpp v69, v51 row_ror:8 row_mask:0xf bank_mask:0xf bound_ctrl:1
	v_max_f32_e32 v46, 0, v46
	v_max_f32_e32 v42, 0, v42
	v_max_f32_e32 v47, 0, v47
	v_max_f32_e32 v43, 0, v43
	v_max_f32_e32 v48, 0, v48
	v_max_f32_e32 v44, 0, v44
	v_max_f32_e32 v49, 0, v49
	v_max_f32_e32 v45, 0, v45
	v_max_f32_e32 v38, 0, v38
	v_max_f32_e32 v34, 0, v34
	v_max_f32_e32 v39, 0, v39
	v_max_f32_e32 v35, 0, v35
	v_max_f32_e32 v40, 0, v40
	v_max_f32_e32 v36, 0, v36
	v_max_f32_e32 v41, 0, v41
	v_max_f32_e32 v37, 0, v37
	v_lshl_add_u64 v[60:61], v[58:59], 0, v[140:141]
	v_cndmask_b32_dpp v53, v65, v51, vcc row_ror:8 row_mask:0xf bank_mask:0xf bound_ctrl:1
	v_cndmask_b32_dpp v52, v64, v50, vcc row_ror:8 row_mask:0xf bank_mask:0xf bound_ctrl:1
; __device__ __forceinline__ unsigned pk2(float lo, float hi) { const f32x2 v = {lo, hi}; return __builtin_bit_cast(unsigned, __builtin_convertvector(v, bf16x2_t)); }
; __device__ __forceinline__ u32x4 ror8(u32x4 v) { u32x4 r;
; #pragma unroll
;     for (int i = 0; i < 4; ++i) r[i] = (unsigned)__builtin_amdgcn_mov_dpp((int)v[i], 0x128, 0xf, 0xf, true);
;     return r; }
; __device__ __forceinline__ void store_pair(unsigned char* own, size_t stride8, int hi_off, u32x4 lo, u32x4 hi, bool upper) {
;     const u32x4 tlo = ror8(lo), thi = ror8(hi);
;     const u32x4 A = upper ? thi : lo, B = upper ? hi : tlo;
;     unsigned char* pa = upper ? own - stride8 + hi_off : own;
;     unsigned char* pb = upper ? own + hi_off : own + stride8;
;     *(u32x4*)pa = A; *(u32x4*)pb = B;
; }
;     __device__ __forceinline__ void operator()(const f32x4 (&acc)[2][2][4][2], const Unit& u, int wr, int wc, int fr, int fq) const {
; #pragma unroll
;         for (int ai = 0; ai < 2; ++ai)
; #pragma unroll
;             for (int m = 0; m < 4; ++m) { unsigned char* rowp = (unsigned char*)(H + ((size_t)(u.pm * (FF / 64) + u.pn * 4 + wc) * 256 + (wr * 64 + fr + ai * 128 + m * 16)) * 64 + 8 * fq); u32x4 w[2];
; #pragma unroll
;                 for (int bj = 0; bj < 2; ++bj) { f32x4 v0 = acc[ai][bj][m][0], v1 = acc[ai][bj][m][1];
; #pragma unroll
;                     for (int j = 0; j < 4; ++j) { const float a = fmaxf(v0[j], 0.f), b = fmaxf(v1[j], 0.f); v0[j] = a * a; v1[j] = b * b; }
;                     w[bj].x = pk2(v0[0], v0[1]); w[bj].y = pk2(v0[2], v0[3]); w[bj].z = pk2(v1[0], v1[1]); w[bj].w = pk2(v1[2], v1[3]); }
;                 store_pair(rowp, (size_t)8 * 64 * 2, 64, w[0], w[1], fr >= 8); }
;     }
	v_cndmask_b32_dpp v51, v63, v55, vcc row_ror:8 row_mask:0xf bank_mask:0xf bound_ctrl:1
	v_cndmask_b32_dpp v50, v62, v54, vcc row_ror:8 row_mask:0xf bank_mask:0xf bound_ctrl:1
	v_cndmask_b32_e64 v57, v65, v69, s[8:9]
	v_cndmask_b32_e64 v56, v64, v68, s[8:9]
	v_cndmask_b32_e64 v55, v63, v67, s[8:9]
	v_cndmask_b32_e64 v54, v62, v66, s[8:9]
	v_pk_mul_f32 v[46:47], v[46:47], v[46:47]
	v_pk_mul_f32 v[42:43], v[42:43], v[42:43]
	v_pk_mul_f32 v[48:49], v[48:49], v[48:49]
	v_pk_mul_f32 v[44:45], v[44:45], v[44:45]
	v_pk_mul_f32 v[38:39], v[38:39], v[38:39]
	v_pk_mul_f32 v[34:35], v[34:35], v[34:35]
	v_pk_mul_f32 v[40:41], v[40:41], v[40:41]
	v_pk_mul_f32 v[36:37], v[36:37], v[36:37]
	v_lshl_add_u64 v[58:59], v[58:59], 0, v[142:143]
	global_store_dwordx4 v[60:61], v[54:57], off
	global_store_dwordx4 v[58:59], v[50:53], off
	v_cvt_pk_bf16_f32 v46, v46, v47
	v_cvt_pk_bf16_f32 v47, v48, v49
	v_lshl_add_u64 v[50:51], s[22:23], 0, v[154:155]
	v_cvt_pk_bf16_f32 v48, v42, v43
	v_cvt_pk_bf16_f32 v49, v44, v45
	v_cvt_pk_bf16_f32 v38, v38, v39
	v_cvt_pk_bf16_f32 v39, v40, v41
	v_cvt_pk_bf16_f32 v34, v34, v35
	v_cvt_pk_bf16_f32 v35, v36, v37
	v_lshl_add_u64 v[42:43], v[50:51], 0, v[138:139]
	s_mov_b64 vcc, s[8:9]
	v_mov_b32_dpp v50, v38 row_ror:8 row_mask:0xf bank_mask:0xf bound_ctrl:1
	v_mov_b32_dpp v51, v39 row_ror:8 row_mask:0xf bank_mask:0xf bound_ctrl:1
	v_mov_b32_dpp v52, v34 row_ror:8 row_mask:0xf bank_mask:0xf bound_ctrl:1
	v_mov_b32_dpp v53, v35 row_ror:8 row_mask:0xf bank_mask:0xf bound_ctrl:1
	v_max_f32_e32 v30, 0, v30
	v_max_f32_e32 v26, 0, v26
	v_max_f32_e32 v31, 0, v31
	v_max_f32_e32 v27, 0, v27
	v_max_f32_e32 v32, 0, v32
	v_max_f32_e32 v28, 0, v28
	v_max_f32_e32 v33, 0, v33
	v_max_f32_e32 v29, 0, v29
	v_max_f32_e32 v22, 0, v22
	v_max_f32_e32 v18, 0, v18
	v_max_f32_e32 v23, 0, v23
	v_max_f32_e32 v19, 0, v19
	v_max_f32_e32 v24, 0, v24
	v_max_f32_e32 v20, 0, v20
	v_max_f32_e32 v25, 0, v25
	v_max_f32_e32 v21, 0, v21
	v_lshl_add_u64 v[44:45], v[42:43], 0, v[140:141]
	v_cndmask_b32_dpp v37, v49, v35, vcc row_ror:8 row_mask:0xf bank_mask:0xf bound_ctrl:1
	v_cndmask_b32_dpp v36, v48, v34, vcc row_ror:8 row_mask:0xf bank_mask:0xf bound_ctrl:1
	v_cndmask_b32_dpp v35, v47, v39, vcc row_ror:8 row_mask:0xf bank_mask:0xf bound_ctrl:1
	v_cndmask_b32_dpp v34, v46, v38, vcc row_ror:8 row_mask:0xf bank_mask:0xf bound_ctrl:1
	v_cndmask_b32_e64 v41, v49, v53, s[8:9]
	v_cndmask_b32_e64 v40, v48, v52, s[8:9]
	v_cndmask_b32_e64 v39, v47, v51, s[8:9]
	v_cndmask_b32_e64 v38, v46, v50, s[8:9]
	v_pk_mul_f32 v[30:31], v[30:31], v[30:31]
	v_pk_mul_f32 v[26:27], v[26:27], v[26:27]
	v_pk_mul_f32 v[32:33], v[32:33], v[32:33]
	v_pk_mul_f32 v[28:29], v[28:29], v[28:29]
	v_pk_mul_f32 v[22:23], v[22:23], v[22:23]
	v_pk_mul_f32 v[18:19], v[18:19], v[18:19]
	v_pk_mul_f32 v[24:25], v[24:25], v[24:25]
	v_pk_mul_f32 v[20:21], v[20:21], v[20:21]
	v_lshl_add_u64 v[42:43], v[42:43], 0, v[142:143]
	global_store_dwordx4 v[44:45], v[38:41], off
	global_store_dwordx4 v[42:43], v[34:37], off
	v_cvt_pk_bf16_f32 v30, v30, v31
	v_cvt_pk_bf16_f32 v31, v32, v33
	v_lshl_add_u64 v[34:35], s[22:23], 0, v[156:157]
	v_cvt_pk_bf16_f32 v32, v26, v27
	v_cvt_pk_bf16_f32 v33, v28, v29
	v_cvt_pk_bf16_f32 v22, v22, v23
	v_cvt_pk_bf16_f32 v23, v24, v25
	v_cvt_pk_bf16_f32 v18, v18, v19
	v_cvt_pk_bf16_f32 v19, v20, v21
	v_lshl_add_u64 v[26:27], v[34:35], 0, v[138:139]
	s_mov_b64 vcc, s[8:9]
	v_mov_b32_dpp v34, v22 row_ror:8 row_mask:0xf bank_mask:0xf bound_ctrl:1
	v_mov_b32_dpp v35, v23 row_ror:8 row_mask:0xf bank_mask:0xf bound_ctrl:1
	v_mov_b32_dpp v36, v18 row_ror:8 row_mask:0xf bank_mask:0xf bound_ctrl:1
	v_mov_b32_dpp v37, v19 row_ror:8 row_mask:0xf bank_mask:0xf bound_ctrl:1
	v_max_f32_e32 v14, 0, v14
	v_max_f32_e32 v10, 0, v10
	v_max_f32_e32 v15, 0, v15
	v_max_f32_e32 v11, 0, v11
	v_max_f32_e32 v16, 0, v16
	v_max_f32_e32 v12, 0, v12
	v_max_f32_e32 v17, 0, v17
	v_max_f32_e32 v13, 0, v13
	v_max_f32_e32 v6, 0, v6
	v_max_f32_e32 v2, 0, v2
	v_max_f32_e32 v7, 0, v7
	v_max_f32_e32 v3, 0, v3
	v_max_f32_e32 v8, 0, v8
	v_max_f32_e32 v4, 0, v4
	v_max_f32_e32 v9, 0, v9
	v_max_f32_e32 v5, 0, v5
	v_lshl_add_u64 v[28:29], v[26:27], 0, v[140:141]
	v_cndmask_b32_dpp v21, v33, v19, vcc row_ror:8 row_mask:0xf bank_mask:0xf bound_ctrl:1
	v_cndmask_b32_dpp v20, v32, v18, vcc row_ror:8 row_mask:0xf bank_mask:0xf bound_ctrl:1
	v_cndmask_b32_dpp v19, v31, v23, vcc row_ror:8 row_mask:0xf bank_mask:0xf bound_ctrl:1
	v_cndmask_b32_dpp v18, v30, v22, vcc row_ror:8 row_mask:0xf bank_mask:0xf bound_ctrl:1
	v_cndmask_b32_e64 v25, v33, v37, s[8:9]
	v_cndmask_b32_e64 v24, v32, v36, s[8:9]
	v_cndmask_b32_e64 v23, v31, v35, s[8:9]
	v_cndmask_b32_e64 v22, v30, v34, s[8:9]
	v_pk_mul_f32 v[14:15], v[14:15], v[14:15]
	v_pk_mul_f32 v[10:11], v[10:11], v[10:11]
	v_pk_mul_f32 v[16:17], v[16:17], v[16:17]
	v_pk_mul_f32 v[12:13], v[12:13], v[12:13]
	v_pk_mul_f32 v[6:7], v[6:7], v[6:7]
	v_pk_mul_f32 v[2:3], v[2:3], v[2:3]
	v_pk_mul_f32 v[8:9], v[8:9], v[8:9]
	v_pk_mul_f32 v[4:5], v[4:5], v[4:5]
	v_lshl_add_u64 v[26:27], v[26:27], 0, v[142:143]
	global_store_dwordx4 v[28:29], v[22:25], off
	global_store_dwordx4 v[26:27], v[18:21], off
	v_cvt_pk_bf16_f32 v14, v14, v15
	v_cvt_pk_bf16_f32 v15, v16, v17
	v_lshl_add_u64 v[18:19], s[22:23], 0, v[158:159]
	v_cvt_pk_bf16_f32 v16, v10, v11
	v_cvt_pk_bf16_f32 v17, v12, v13
	v_cvt_pk_bf16_f32 v6, v6, v7
	v_cvt_pk_bf16_f32 v7, v8, v9
	v_cvt_pk_bf16_f32 v2, v2, v3
	v_cvt_pk_bf16_f32 v3, v4, v5
	v_lshl_add_u64 v[10:11], v[18:19], 0, v[138:139]
	s_mov_b64 vcc, s[8:9]
	v_mov_b32_dpp v18, v6 row_ror:8 row_mask:0xf bank_mask:0xf bound_ctrl:1
	v_mov_b32_dpp v19, v7 row_ror:8 row_mask:0xf bank_mask:0xf bound_ctrl:1
	v_mov_b32_dpp v20, v2 row_ror:8 row_mask:0xf bank_mask:0xf bound_ctrl:1
	v_mov_b32_dpp v21, v3 row_ror:8 row_mask:0xf bank_mask:0xf bound_ctrl:1
	v_lshl_add_u64 v[12:13], v[10:11], 0, v[140:141]
	v_cndmask_b32_dpp v5, v17, v3, vcc row_ror:8 row_mask:0xf bank_mask:0xf bound_ctrl:1
	v_cndmask_b32_dpp v4, v16, v2, vcc row_ror:8 row_mask:0xf bank_mask:0xf bound_ctrl:1
	v_cndmask_b32_dpp v3, v15, v7, vcc row_ror:8 row_mask:0xf bank_mask:0xf bound_ctrl:1
	v_cndmask_b32_dpp v2, v14, v6, vcc row_ror:8 row_mask:0xf bank_mask:0xf bound_ctrl:1
	v_cndmask_b32_e64 v9, v17, v21, s[8:9]
	v_cndmask_b32_e64 v8, v16, v20, s[8:9]
	v_cndmask_b32_e64 v7, v15, v19, s[8:9]
	v_cndmask_b32_e64 v6, v14, v18, s[8:9]
	s_andn2_b64 vcc, exec, s[18:19]
	s_mov_b64 s[4:5], -1
	v_lshl_add_u64 v[10:11], v[10:11], 0, v[142:143]
	global_store_dwordx4 v[12:13], v[6:9], off
	global_store_dwordx4 v[10:11], v[2:5], off
	s_cbranch_vccnz .LBB0_1160
	s_andn2_b64 vcc, exec, s[2:3]
	s_cbranch_vccnz .LBB0_1159
	s_barrier
	s_branch .LBB0_1159

; __device__ __forceinline__ unsigned pk2(float lo, float hi) { const f32x2 v = {lo, hi}; return __builtin_bit_cast(unsigned, __builtin_convertvector(v, bf16x2_t)); }
; __device__ __forceinline__ u32x4 ror8(u32x4 v) { u32x4 r;
; #pragma unroll
;     for (int i = 0; i < 4; ++i) r[i] = (unsigned)__builtin_amdgcn_mov_dpp((int)v[i], 0x128, 0xf, 0xf, true);
;     return r; }
; __device__ __forceinline__ void store_pair(unsigned char* own, size_t stride8, int hi_off, u32x4 lo, u32x4 hi, bool upper) {
;     const u32x4 tlo = ror8(lo), thi = ror8(hi);
;     const u32x4 A = upper ? thi : lo, B = upper ? hi : tlo;
;     unsigned char* pa = upper ? own - stride8 + hi_off : own;
;     unsigned char* pb = upper ? own + hi_off : own + stride8;
;     *(u32x4*)pa = A; *(u32x4*)pb = B;
; }
;     __device__ __forceinline__ void operator()(const f32x4 (&acc)[2][2][4][2], const Unit& u, int wr, int wc, int fr, int fq) const {
;         const int row0 = u.pm * 256 + wr * 64 + fr, col0 = u.pn * 256 + wc * 64 + 8 * fq;
;         bf16_t* base = u.part == 0 ? Z + (size_t)row0 * D + col0 : P + ((size_t)(u.part - 1) * MS + (row0 - MP)) * D + col0;
; #pragma unroll
;         for (int ai = 0; ai < 2; ++ai)
; #pragma unroll
;             for (int m = 0; m < 4; ++m) { u32x4 w[2];
; #pragma unroll
;                 for (int bj = 0; bj < 2; ++bj) { const f32x4 v0 = acc[ai][bj][m][0], v1 = acc[ai][bj][m][1]; w[bj].x = pk2(v0[0], v0[1]); w[bj].y = pk2(v0[2], v0[3]); w[bj].z = pk2(v1[0], v1[1]); w[bj].w = pk2(v1[2], v1[3]); }
;                 store_pair((unsigned char*)(base + (size_t)(ai * 128 + m * 16) * D), (size_t)8 * D * 2, 64, w[0], w[1], fr >= 8); }
;     }
.LBB0_1232:
	v_lshl_add_u32 v143, s45, 8, v146
	v_add_u32_e32 v144, 0xffffe000, v143
	v_sub_co_u32_e64 v142, vcc, s43, 1
	v_mov_b32_e32 v145, s54
	s_nop 0
	v_cndmask_b32_e32 v144, v144, v143, vcc
	v_ashrrev_i32_e32 v143, 31, v142
	v_lshlrev_b64 v[142:143], 23, v[142:143]
	v_lshl_add_u64 v[142:143], s[12:13], 0, v[142:143]
	v_cndmask_b32_e32 v143, v143, v145, vcc
	v_mov_b32_e32 v145, s52
	v_cndmask_b32_e32 v142, v142, v145, vcc
	v_ashrrev_i32_e32 v145, 31, v144
	v_lshl_or_b32 v152, s78, 8, v148
	v_lshlrev_b64 v[144:145], 12, v[144:145]
	v_lshl_add_u64 v[142:143], v[142:143], 0, v[144:145]
	v_ashrrev_i32_e32 v153, 31, v152
	v_cvt_pk_bf16_f32 v126, v126, v127
	v_cvt_pk_bf16_f32 v127, v128, v129
	v_cvt_pk_bf16_f32 v128, v122, v123
	v_cvt_pk_bf16_f32 v124, v124, v125
	v_cvt_pk_bf16_f32 v118, v118, v119
	v_cvt_pk_bf16_f32 v119, v120, v121
	v_cvt_pk_bf16_f32 v114, v114, v115
	v_cvt_pk_bf16_f32 v115, v116, v117
	v_lshl_add_u64 v[142:143], v[152:153], 1, v[142:143]
	s_mov_b64 vcc, s[8:9]
	v_mov_b32_dpp v125, v118 row_ror:8 row_mask:0xf bank_mask:0xf bound_ctrl:1
	v_mov_b32_dpp v129, v119 row_ror:8 row_mask:0xf bank_mask:0xf bound_ctrl:1
	v_mov_b32_dpp v144, v114 row_ror:8 row_mask:0xf bank_mask:0xf bound_ctrl:1
	v_mov_b32_dpp v145, v115 row_ror:8 row_mask:0xf bank_mask:0xf bound_ctrl:1
	v_lshl_add_u64 v[122:123], v[142:143], 0, v[134:135]
	v_cndmask_b32_dpp v117, v124, v115, vcc row_ror:8 row_mask:0xf bank_mask:0xf bound_ctrl:1
	v_cndmask_b32_dpp v116, v128, v114, vcc row_ror:8 row_mask:0xf bank_mask:0xf bound_ctrl:1
	v_cndmask_b32_dpp v115, v127, v119, vcc row_ror:8 row_mask:0xf bank_mask:0xf bound_ctrl:1
	v_cndmask_b32_dpp v114, v126, v118, vcc row_ror:8 row_mask:0xf bank_mask:0xf bound_ctrl:1
	v_cndmask_b32_e64 v121, v124, v145, s[8:9]
	v_cndmask_b32_e64 v120, v128, v144, s[8:9]
	v_cndmask_b32_e64 v119, v127, v129, s[8:9]
	v_cndmask_b32_e64 v118, v126, v125, s[8:9]
	v_cvt_pk_bf16_f32 v110, v110, v111
	v_cvt_pk_bf16_f32 v111, v112, v113
	v_cvt_pk_bf16_f32 v112, v106, v107
	v_cvt_pk_bf16_f32 v113, v108, v109
	v_cvt_pk_bf16_f32 v102, v102, v103
	v_cvt_pk_bf16_f32 v103, v104, v105
	v_cvt_pk_bf16_f32 v98, v98, v99
	v_cvt_pk_bf16_f32 v99, v100, v101
	s_mov_b64 s[4:5], 0x10000
	v_lshl_add_u64 v[124:125], v[142:143], 0, v[136:137]
	global_store_dwordx4 v[122:123], v[118:121], off
	global_store_dwordx4 v[124:125], v[114:117], off
	v_lshl_add_u64 v[106:107], v[142:143], 0, s[4:5]
	s_mov_b64 vcc, s[8:9]
	v_mov_b32_dpp v114, v102 row_ror:8 row_mask:0xf bank_mask:0xf bound_ctrl:1
	v_mov_b32_dpp v115, v103 row_ror:8 row_mask:0xf bank_mask:0xf bound_ctrl:1
	v_mov_b32_dpp v116, v98 row_ror:8 row_mask:0xf bank_mask:0xf bound_ctrl:1
	v_mov_b32_dpp v117, v99 row_ror:8 row_mask:0xf bank_mask:0xf bound_ctrl:1
	v_lshl_add_u64 v[108:109], v[106:107], 0, v[134:135]
	v_cndmask_b32_dpp v101, v113, v99, vcc row_ror:8 row_mask:0xf bank_mask:0xf bound_ctrl:1
	v_cndmask_b32_dpp v100, v112, v98, vcc row_ror:8 row_mask:0xf bank_mask:0xf bound_ctrl:1
	v_cndmask_b32_dpp v99, v111, v103, vcc row_ror:8 row_mask:0xf bank_mask:0xf bound_ctrl:1
	v_cndmask_b32_dpp v98, v110, v102, vcc row_ror:8 row_mask:0xf bank_mask:0xf bound_ctrl:1
	v_cndmask_b32_e64 v105, v113, v117, s[8:9]
	v_cndmask_b32_e64 v104, v112, v116, s[8:9]
	v_cndmask_b32_e64 v103, v111, v115, s[8:9]
	v_cndmask_b32_e64 v102, v110, v114, s[8:9]
	v_cvt_pk_bf16_f32 v94, v94, v95
	v_cvt_pk_bf16_f32 v95, v96, v97
	v_cvt_pk_bf16_f32 v96, v90, v91
	v_cvt_pk_bf16_f32 v97, v92, v93
	v_cvt_pk_bf16_f32 v86, v86, v87
	v_cvt_pk_bf16_f32 v87, v88, v89
	v_cvt_pk_bf16_f32 v82, v82, v83
	v_cvt_pk_bf16_f32 v83, v84, v85
	s_mov_b64 s[4:5], 0x20000
	v_lshl_add_u64 v[106:107], v[106:107], 0, v[136:137]
	global_store_dwordx4 v[108:109], v[102:105], off
	global_store_dwordx4 v[106:107], v[98:101], off
	v_lshl_add_u64 v[90:91], v[142:143], 0, s[4:5]
	s_mov_b64 vcc, s[8:9]
	v_mov_b32_dpp v98, v86 row_ror:8 row_mask:0xf bank_mask:0xf bound_ctrl:1
	v_mov_b32_dpp v99, v87 row_ror:8 row_mask:0xf bank_mask:0xf bound_ctrl:1
	v_mov_b32_dpp v100, v82 row_ror:8 row_mask:0xf bank_mask:0xf bound_ctrl:1
	v_mov_b32_dpp v101, v83 row_ror:8 row_mask:0xf bank_mask:0xf bound_ctrl:1
	v_lshl_add_u64 v[92:93], v[90:91], 0, v[134:135]
	v_cndmask_b32_dpp v85, v97, v83, vcc row_ror:8 row_mask:0xf bank_mask:0xf bound_ctrl:1
	v_cndmask_b32_dpp v84, v96, v82, vcc row_ror:8 row_mask:0xf bank_mask:0xf bound_ctrl:1
	v_cndmask_b32_dpp v83, v95, v87, vcc row_ror:8 row_mask:0xf bank_mask:0xf bound_ctrl:1
	v_cndmask_b32_dpp v82, v94, v86, vcc row_ror:8 row_mask:0xf bank_mask:0xf bound_ctrl:1
	v_cndmask_b32_e64 v89, v97, v101, s[8:9]
	v_cndmask_b32_e64 v88, v96, v100, s[8:9]
	v_cndmask_b32_e64 v87, v95, v99, s[8:9]
	v_cndmask_b32_e64 v86, v94, v98, s[8:9]
	v_cvt_pk_bf16_f32 v78, v78, v79
	v_cvt_pk_bf16_f32 v79, v80, v81
	v_cvt_pk_bf16_f32 v80, v74, v75
	v_cvt_pk_bf16_f32 v81, v76, v77
	v_cvt_pk_bf16_f32 v70, v70, v71
	v_cvt_pk_bf16_f32 v71, v72, v73
	v_cvt_pk_bf16_f32 v66, v66, v67
	v_cvt_pk_bf16_f32 v67, v68, v69
	s_mov_b64 s[4:5], 0x30000
	v_lshl_add_u64 v[90:91], v[90:91], 0, v[136:137]
	global_store_dwordx4 v[92:93], v[86:89], off
	global_store_dwordx4 v[90:91], v[82:85], off
	v_lshl_add_u64 v[74:75], v[142:143], 0, s[4:5]
	s_mov_b64 vcc, s[8:9]
	v_mov_b32_dpp v82, v70 row_ror:8 row_mask:0xf bank_mask:0xf bound_ctrl:1
	v_mov_b32_dpp v83, v71 row_ror:8 row_mask:0xf bank_mask:0xf bound_ctrl:1
	v_mov_b32_dpp v84, v66 row_ror:8 row_mask:0xf bank_mask:0xf bound_ctrl:1
	v_mov_b32_dpp v85, v67 row_ror:8 row_mask:0xf bank_mask:0xf bound_ctrl:1
	v_lshl_add_u64 v[76:77], v[74:75], 0, v[134:135]
	v_cndmask_b32_dpp v69, v81, v67, vcc row_ror:8 row_mask:0xf bank_mask:0xf bound_ctrl:1
; __device__ __forceinline__ unsigned pk2(float lo, float hi) { const f32x2 v = {lo, hi}; return __builtin_bit_cast(unsigned, __builtin_convertvector(v, bf16x2_t)); }
; __device__ __forceinline__ u32x4 ror8(u32x4 v) { u32x4 r;
; #pragma unroll
;     for (int i = 0; i < 4; ++i) r[i] = (unsigned)__builtin_amdgcn_mov_dpp((int)v[i], 0x128, 0xf, 0xf, true);
;     return r; }
; __device__ __forceinline__ void store_pair(unsigned char* own, size_t stride8, int hi_off, u32x4 lo, u32x4 hi, bool upper) {
;     const u32x4 tlo = ror8(lo), thi = ror8(hi);
;     const u32x4 A = upper ? thi : lo, B = upper ? hi : tlo;
;     unsigned char* pa = upper ? own - stride8 + hi_off : own;
;     unsigned char* pb = upper ? own + hi_off : own + stride8;
;     *(u32x4*)pa = A; *(u32x4*)pb = B;
; }
;     __device__ __forceinline__ void operator()(const f32x4 (&acc)[2][2][4][2], const Unit& u, int wr, int wc, int fr, int fq) const {
;         const int row0 = u.pm * 256 + wr * 64 + fr, col0 = u.pn * 256 + wc * 64 + 8 * fq;
;         bf16_t* base = u.part == 0 ? Z + (size_t)row0 * D + col0 : P + ((size_t)(u.part - 1) * MS + (row0 - MP)) * D + col0;
; #pragma unroll
;         for (int ai = 0; ai < 2; ++ai)
; #pragma unroll
;             for (int m = 0; m < 4; ++m) { u32x4 w[2];
; #pragma unroll
;                 for (int bj = 0; bj < 2; ++bj) { const f32x4 v0 = acc[ai][bj][m][0], v1 = acc[ai][bj][m][1]; w[bj].x = pk2(v0[0], v0[1]); w[bj].y = pk2(v0[2], v0[3]); w[bj].z = pk2(v1[0], v1[1]); w[bj].w = pk2(v1[2], v1[3]); }
;                 store_pair((unsigned char*)(base + (size_t)(ai * 128 + m * 16) * D), (size_t)8 * D * 2, 64, w[0], w[1], fr >= 8); }
;     }
	v_cndmask_b32_dpp v68, v80, v66, vcc row_ror:8 row_mask:0xf bank_mask:0xf bound_ctrl:1
	v_cndmask_b32_dpp v67, v79, v71, vcc row_ror:8 row_mask:0xf bank_mask:0xf bound_ctrl:1
	v_cndmask_b32_dpp v66, v78, v70, vcc row_ror:8 row_mask:0xf bank_mask:0xf bound_ctrl:1
	v_cndmask_b32_e64 v73, v81, v85, s[8:9]
	v_cndmask_b32_e64 v72, v80, v84, s[8:9]
	v_cndmask_b32_e64 v71, v79, v83, s[8:9]
	v_cndmask_b32_e64 v70, v78, v82, s[8:9]
	v_cvt_pk_bf16_f32 v62, v62, v63
	v_cvt_pk_bf16_f32 v63, v64, v65
	v_cvt_pk_bf16_f32 v64, v58, v59
	v_cvt_pk_bf16_f32 v65, v60, v61
	v_cvt_pk_bf16_f32 v54, v54, v55
	v_cvt_pk_bf16_f32 v55, v56, v57
	v_cvt_pk_bf16_f32 v50, v50, v51
	v_cvt_pk_bf16_f32 v51, v52, v53
	s_mov_b64 s[4:5], 0x80000
	v_lshl_add_u64 v[74:75], v[74:75], 0, v[136:137]
	global_store_dwordx4 v[76:77], v[70:73], off
	global_store_dwordx4 v[74:75], v[66:69], off
	v_lshl_add_u64 v[58:59], v[142:143], 0, s[4:5]
	s_mov_b64 vcc, s[8:9]
	v_mov_b32_dpp v66, v54 row_ror:8 row_mask:0xf bank_mask:0xf bound_ctrl:1
	v_mov_b32_dpp v67, v55 row_ror:8 row_mask:0xf bank_mask:0xf bound_ctrl:1
	v_mov_b32_dpp v68, v50 row_ror:8 row_mask:0xf bank_mask:0xf bound_ctrl:1
	v_mov_b32_dpp v69, v51 row_ror:8 row_mask:0xf bank_mask:0xf bound_ctrl:1
	v_lshl_add_u64 v[60:61], v[58:59], 0, v[134:135]
	v_cndmask_b32_dpp v53, v65, v51, vcc row_ror:8 row_mask:0xf bank_mask:0xf bound_ctrl:1
	v_cndmask_b32_dpp v52, v64, v50, vcc row_ror:8 row_mask:0xf bank_mask:0xf bound_ctrl:1
	v_cndmask_b32_dpp v51, v63, v55, vcc row_ror:8 row_mask:0xf bank_mask:0xf bound_ctrl:1
	v_cndmask_b32_dpp v50, v62, v54, vcc row_ror:8 row_mask:0xf bank_mask:0xf bound_ctrl:1
	v_cndmask_b32_e64 v57, v65, v69, s[8:9]
	v_cndmask_b32_e64 v56, v64, v68, s[8:9]
	v_cndmask_b32_e64 v55, v63, v67, s[8:9]
	v_cndmask_b32_e64 v54, v62, v66, s[8:9]
	v_cvt_pk_bf16_f32 v46, v46, v47
	v_cvt_pk_bf16_f32 v47, v48, v49
	v_cvt_pk_bf16_f32 v48, v42, v43
	v_cvt_pk_bf16_f32 v49, v44, v45
	v_cvt_pk_bf16_f32 v38, v38, v39
	v_cvt_pk_bf16_f32 v39, v40, v41
	v_cvt_pk_bf16_f32 v34, v34, v35
	v_cvt_pk_bf16_f32 v35, v36, v37
	s_mov_b64 s[4:5], 0x90000
	v_lshl_add_u64 v[58:59], v[58:59], 0, v[136:137]
	global_store_dwordx4 v[60:61], v[54:57], off
	global_store_dwordx4 v[58:59], v[50:53], off
	v_lshl_add_u64 v[42:43], v[142:143], 0, s[4:5]
	s_mov_b64 vcc, s[8:9]
	v_mov_b32_dpp v50, v38 row_ror:8 row_mask:0xf bank_mask:0xf bound_ctrl:1
	v_mov_b32_dpp v51, v39 row_ror:8 row_mask:0xf bank_mask:0xf bound_ctrl:1
	v_mov_b32_dpp v52, v34 row_ror:8 row_mask:0xf bank_mask:0xf bound_ctrl:1
	v_mov_b32_dpp v53, v35 row_ror:8 row_mask:0xf bank_mask:0xf bound_ctrl:1
	v_lshl_add_u64 v[44:45], v[42:43], 0, v[134:135]
	v_cndmask_b32_dpp v37, v49, v35, vcc row_ror:8 row_mask:0xf bank_mask:0xf bound_ctrl:1
	v_cndmask_b32_dpp v36, v48, v34, vcc row_ror:8 row_mask:0xf bank_mask:0xf bound_ctrl:1
	v_cndmask_b32_dpp v35, v47, v39, vcc row_ror:8 row_mask:0xf bank_mask:0xf bound_ctrl:1
	v_cndmask_b32_dpp v34, v46, v38, vcc row_ror:8 row_mask:0xf bank_mask:0xf bound_ctrl:1
	v_cndmask_b32_e64 v41, v49, v53, s[8:9]
	v_cndmask_b32_e64 v40, v48, v52, s[8:9]
	v_cndmask_b32_e64 v39, v47, v51, s[8:9]
	v_cndmask_b32_e64 v38, v46, v50, s[8:9]
	v_cvt_pk_bf16_f32 v30, v30, v31
	v_cvt_pk_bf16_f32 v31, v32, v33
	v_cvt_pk_bf16_f32 v32, v26, v27
	v_cvt_pk_bf16_f32 v33, v28, v29
	v_cvt_pk_bf16_f32 v22, v22, v23
	v_cvt_pk_bf16_f32 v23, v24, v25
	v_cvt_pk_bf16_f32 v18, v18, v19
	v_cvt_pk_bf16_f32 v19, v20, v21
	s_mov_b64 s[4:5], 0xa0000
	v_lshl_add_u64 v[42:43], v[42:43], 0, v[136:137]
	global_store_dwordx4 v[44:45], v[38:41], off
	global_store_dwordx4 v[42:43], v[34:37], off
	v_lshl_add_u64 v[26:27], v[142:143], 0, s[4:5]
	s_mov_b64 vcc, s[8:9]
	v_mov_b32_dpp v34, v22 row_ror:8 row_mask:0xf bank_mask:0xf bound_ctrl:1
	v_mov_b32_dpp v35, v23 row_ror:8 row_mask:0xf bank_mask:0xf bound_ctrl:1
	v_mov_b32_dpp v36, v18 row_ror:8 row_mask:0xf bank_mask:0xf bound_ctrl:1
	v_mov_b32_dpp v37, v19 row_ror:8 row_mask:0xf bank_mask:0xf bound_ctrl:1
	v_lshl_add_u64 v[28:29], v[26:27], 0, v[134:135]
	v_cndmask_b32_dpp v21, v33, v19, vcc row_ror:8 row_mask:0xf bank_mask:0xf bound_ctrl:1
	v_cndmask_b32_dpp v20, v32, v18, vcc row_ror:8 row_mask:0xf bank_mask:0xf bound_ctrl:1
	v_cndmask_b32_dpp v19, v31, v23, vcc row_ror:8 row_mask:0xf bank_mask:0xf bound_ctrl:1
	v_cndmask_b32_dpp v18, v30, v22, vcc row_ror:8 row_mask:0xf bank_mask:0xf bound_ctrl:1
	v_cndmask_b32_e64 v25, v33, v37, s[8:9]
	v_cndmask_b32_e64 v24, v32, v36, s[8:9]
	v_cndmask_b32_e64 v23, v31, v35, s[8:9]
	v_cndmask_b32_e64 v22, v30, v34, s[8:9]
	v_cvt_pk_bf16_f32 v14, v14, v15
	v_cvt_pk_bf16_f32 v15, v16, v17
	v_cvt_pk_bf16_f32 v16, v10, v11
	v_cvt_pk_bf16_f32 v17, v12, v13
	v_cvt_pk_bf16_f32 v6, v6, v7
	v_cvt_pk_bf16_f32 v7, v8, v9
	v_cvt_pk_bf16_f32 v2, v2, v3
	v_cvt_pk_bf16_f32 v3, v4, v5
	v_lshl_add_u64 v[26:27], v[26:27], 0, v[136:137]
	global_store_dwordx4 v[28:29], v[22:25], off
	global_store_dwordx4 v[26:27], v[18:21], off
	v_lshl_add_u64 v[10:11], v[142:143], 0, s[14:15]
	s_mov_b64 vcc, s[8:9]
	v_mov_b32_dpp v18, v6 row_ror:8 row_mask:0xf bank_mask:0xf bound_ctrl:1
	v_mov_b32_dpp v19, v7 row_ror:8 row_mask:0xf bank_mask:0xf bound_ctrl:1
	v_mov_b32_dpp v20, v2 row_ror:8 row_mask:0xf bank_mask:0xf bound_ctrl:1
	v_mov_b32_dpp v21, v3 row_ror:8 row_mask:0xf bank_mask:0xf bound_ctrl:1
	v_lshl_add_u64 v[12:13], v[10:11], 0, v[134:135]
	v_cndmask_b32_dpp v5, v17, v3, vcc row_ror:8 row_mask:0xf bank_mask:0xf bound_ctrl:1
	v_cndmask_b32_dpp v4, v16, v2, vcc row_ror:8 row_mask:0xf bank_mask:0xf bound_ctrl:1
	v_cndmask_b32_dpp v3, v15, v7, vcc row_ror:8 row_mask:0xf bank_mask:0xf bound_ctrl:1
	v_cndmask_b32_dpp v2, v14, v6, vcc row_ror:8 row_mask:0xf bank_mask:0xf bound_ctrl:1
	v_cndmask_b32_e64 v9, v17, v21, s[8:9]
	v_cndmask_b32_e64 v8, v16, v20, s[8:9]
	v_cndmask_b32_e64 v7, v15, v19, s[8:9]
	v_cndmask_b32_e64 v6, v14, v18, s[8:9]
	s_and_b64 vcc, exec, s[10:11]
	s_mov_b64 s[10:11], -1
	v_lshl_add_u64 v[10:11], v[10:11], 0, v[136:137]
	global_store_dwordx4 v[12:13], v[6:9], off
	global_store_dwordx4 v[10:11], v[2:5], off
	s_cbranch_vccnz .LBB0_1227
	s_andn2_b64 vcc, exec, s[2:3]
	s_cbranch_vccnz .LBB0_1226
	s_barrier
	s_branch .LBB0_1226

; __device__ __forceinline__ u32x4 ror8(u32x4 v) { u32x4 r;
; #pragma unroll
;     for (int i = 0; i < 4; ++i) r[i] = (unsigned)__builtin_amdgcn_mov_dpp((int)v[i], 0x128, 0xf, 0xf, true);
;     return r; }
; __device__ __forceinline__ void store_pair(unsigned char* own, size_t stride8, int hi_off, u32x4 lo, u32x4 hi, bool upper) {
;     const u32x4 tlo = ror8(lo), thi = ror8(hi);
;     const u32x4 A = upper ? thi : lo, B = upper ? hi : tlo;
;     unsigned char* pa = upper ? own - stride8 + hi_off : own;
;     __device__ __forceinline__ void operator()(const f32x4 (&acc)[2][2][4][2], const Unit& u, int wr, int wc, int fr, int fq) const {
;         const int t = u.pn >> 3; const int colt = (u.pn & 7) * 256;
;         const int row0 = u.pm * 256 + wr * 64 + fr, col0 = colt + wc * 64 + 8 * fq;
;         if (t == 1) {
;             f32x4 l[2][2];
; #pragma unroll
;             for (int bj = 0; bj < 2; ++bj) { l[bj][0] = 1.0f - *(const f32x4*)(lb + col0 + bj * 32); l[bj][1] = 1.0f - *(const f32x4*)(lb + col0 + bj * 32 + 4); }
; #pragma unroll
;             for (int ai = 0; ai < 2; ++ai)
; #pragma unroll
;                 for (int m = 0; m < 4; ++m) { u32x4 w[2];
; #pragma unroll
;                     for (int bj = 0; bj < 2; ++bj) { f32x4 v0 = acc[ai][bj][m][0], v1 = acc[ai][bj][m][1];
; #pragma unroll
;                         for (int j = 0; j < 4; ++j) { v0[j] = l[bj][0][j] * sigmoidf_(-v0[j]); v1[j] = l[bj][1][j] * sigmoidf_(-v1[j]); }
;                         w[bj].x = pkh2(v0[0], v0[1]); w[bj].y = pkh2(v0[2], v0[3]); w[bj].z = pkh2(v1[0], v1[1]); w[bj].w = pkh2(v1[2], v1[3]); }
;                     store_pair((unsigned char*)(F + (size_t)(row0 + ai * 128 + m * 16) * D + col0), (size_t)8 * D * 2, 64, w[0], w[1], fr >= 8); }
;         } else {
;             bf16_t* base = QIG + (size_t)(t == 0 ? 0 : t - 1) * M * D;
; #pragma unroll
;             for (int ai = 0; ai < 2; ++ai)
; #pragma unroll
;                 for (int m = 0; m < 4; ++m) { u32x4 w[2];
; #pragma unroll
;                     for (int bj = 0; bj < 2; ++bj) { const f32x4 v0 = acc[ai][bj][m][0], v1 = acc[ai][bj][m][1]; w[bj].x = pk2(v0[0], v0[1]); w[bj].y = pk2(v0[2], v0[3]); w[bj].z = pk2(v1[0], v1[1]); w[bj].w = pk2(v1[2], v1[3]); }
;                     store_pair((unsigned char*)(base + (size_t)(row0 + ai * 128 + m * 16) * D + col0), (size_t)8 * D * 2, 64, w[0], w[1], fr >= 8); }
.LBB0_1358:
	s_lshl_b32 s4, s30, 8
	s_and_b32 s4, s4, 0x700
	v_lshl_add_u32 v158, s34, 8, v160
	s_ashr_i32 s21, s30, 3
	v_or_b32_e32 v150, s4, v162
	v_or_b32_e32 v156, 16, v158
	v_or_b32_e32 v154, 32, v158
	v_or_b32_e32 v152, 48, v158
	s_mov_b64 s[4:5], -1
	s_cmp_lg_u32 s21, 1
	v_lshlrev_b32_e32 v138, 1, v150
	v_ashrrev_i32_e32 v159, 31, v158
	v_ashrrev_i32_e32 v157, 31, v156
	v_ashrrev_i32_e32 v155, 31, v154
	v_ashrrev_i32_e32 v153, 31, v152
	s_cbranch_scc0 .LBB0_1361
	s_add_i32 s21, s21, -1
	s_cmp_gt_u32 s30, 7
	s_cselect_b32 s4, s21, 0
	s_mul_hi_i32 s5, s4, 0x2800000
	s_mul_i32 s4, s4, 0x2800000
	s_add_u32 s4, s62, s4
	s_addc_u32 s5, s83, s5
	v_lshl_add_u64 v[174:175], s[4:5], 0, v[138:139]
	v_cvt_pk_bf16_f32 v151, v126, v127
	v_cvt_pk_bf16_f32 v170, v128, v129
	v_cvt_pk_bf16_f32 v171, v122, v123
	v_cvt_pk_bf16_f32 v172, v124, v125
	v_cvt_pk_bf16_f32 v166, v118, v119
	v_cvt_pk_bf16_f32 v167, v120, v121
	v_cvt_pk_bf16_f32 v168, v114, v115
	v_cvt_pk_bf16_f32 v169, v116, v117
	v_lshlrev_b64 v[148:149], 12, v[158:159]
	v_lshl_add_u64 v[148:149], v[174:175], 0, v[148:149]
	s_mov_b64 vcc, s[8:9]
	v_mov_b32_dpp v181, v166 row_ror:8 row_mask:0xf bank_mask:0xf bound_ctrl:1
	v_mov_b32_dpp v182, v167 row_ror:8 row_mask:0xf bank_mask:0xf bound_ctrl:1
	v_mov_b32_dpp v183, v168 row_ror:8 row_mask:0xf bank_mask:0xf bound_ctrl:1
	v_mov_b32_dpp v184, v169 row_ror:8 row_mask:0xf bank_mask:0xf bound_ctrl:1
	v_lshl_add_u64 v[176:177], v[148:149], 0, v[140:141]
	v_cndmask_b32_dpp v169, v172, v169, vcc row_ror:8 row_mask:0xf bank_mask:0xf bound_ctrl:1
	v_cndmask_b32_dpp v168, v171, v168, vcc row_ror:8 row_mask:0xf bank_mask:0xf bound_ctrl:1
	v_cndmask_b32_dpp v167, v170, v167, vcc row_ror:8 row_mask:0xf bank_mask:0xf bound_ctrl:1
	v_cndmask_b32_dpp v166, v151, v166, vcc row_ror:8 row_mask:0xf bank_mask:0xf bound_ctrl:1
	v_cndmask_b32_e64 v173, v172, v184, s[8:9]
	v_cndmask_b32_e64 v172, v171, v183, s[8:9]
	v_cndmask_b32_e64 v171, v170, v182, s[8:9]
	v_cndmask_b32_e64 v170, v151, v181, s[8:9]
	v_lshl_add_u64 v[178:179], v[148:149], 0, v[142:143]
	global_store_dwordx4 v[176:177], v[170:173], off
	global_store_dwordx4 v[178:179], v[166:169], off
	v_cvt_pk_bf16_f32 v151, v110, v111
	v_cvt_pk_bf16_f32 v170, v112, v113
	v_cvt_pk_bf16_f32 v171, v106, v107
	v_cvt_pk_bf16_f32 v172, v108, v109
	v_cvt_pk_bf16_f32 v173, v102, v103
	v_cvt_pk_bf16_f32 v180, v104, v105
	v_cvt_pk_bf16_f32 v168, v98, v99
	v_cvt_pk_bf16_f32 v169, v100, v101
	v_lshlrev_b64 v[166:167], 12, v[156:157]
	v_lshl_add_u64 v[176:177], v[174:175], 0, v[166:167]
	s_mov_b64 vcc, s[8:9]
	v_mov_b32_dpp v183, v173 row_ror:8 row_mask:0xf bank_mask:0xf bound_ctrl:1
	v_mov_b32_dpp v184, v180 row_ror:8 row_mask:0xf bank_mask:0xf bound_ctrl:1
	v_mov_b32_dpp v185, v168 row_ror:8 row_mask:0xf bank_mask:0xf bound_ctrl:1
	v_mov_b32_dpp v186, v169 row_ror:8 row_mask:0xf bank_mask:0xf bound_ctrl:1
	v_lshl_add_u64 v[178:179], v[176:177], 0, v[140:141]
	v_cndmask_b32_dpp v169, v172, v169, vcc row_ror:8 row_mask:0xf bank_mask:0xf bound_ctrl:1
	v_cndmask_b32_dpp v168, v171, v168, vcc row_ror:8 row_mask:0xf bank_mask:0xf bound_ctrl:1
	v_cndmask_b32_dpp v167, v170, v180, vcc row_ror:8 row_mask:0xf bank_mask:0xf bound_ctrl:1
	v_cndmask_b32_dpp v166, v151, v173, vcc row_ror:8 row_mask:0xf bank_mask:0xf bound_ctrl:1
	v_cndmask_b32_e64 v173, v172, v186, s[8:9]
	v_cndmask_b32_e64 v172, v171, v185, s[8:9]
	v_cndmask_b32_e64 v171, v170, v184, s[8:9]
	v_cndmask_b32_e64 v170, v151, v183, s[8:9]
	v_lshl_add_u64 v[176:177], v[176:177], 0, v[142:143]
	global_store_dwordx4 v[178:179], v[170:173], off
	global_store_dwordx4 v[176:177], v[166:169], off
	v_cvt_pk_bf16_f32 v151, v94, v95
	v_cvt_pk_bf16_f32 v170, v96, v97
	v_cvt_pk_bf16_f32 v171, v90, v91
	v_cvt_pk_bf16_f32 v172, v92, v93
	v_cvt_pk_bf16_f32 v173, v86, v87
	v_cvt_pk_bf16_f32 v180, v88, v89
	v_cvt_pk_bf16_f32 v168, v82, v83
	v_cvt_pk_bf16_f32 v169, v84, v85
	v_lshlrev_b64 v[166:167], 12, v[154:155]
	v_lshl_add_u64 v[176:177], v[174:175], 0, v[166:167]
	s_mov_b64 vcc, s[8:9]
	v_mov_b32_dpp v183, v173 row_ror:8 row_mask:0xf bank_mask:0xf bound_ctrl:1
	v_mov_b32_dpp v184, v180 row_ror:8 row_mask:0xf bank_mask:0xf bound_ctrl:1
	v_mov_b32_dpp v185, v168 row_ror:8 row_mask:0xf bank_mask:0xf bound_ctrl:1
	v_mov_b32_dpp v186, v169 row_ror:8 row_mask:0xf bank_mask:0xf bound_ctrl:1
	v_lshl_add_u64 v[178:179], v[176:177], 0, v[140:141]
	v_cndmask_b32_dpp v169, v172, v169, vcc row_ror:8 row_mask:0xf bank_mask:0xf bound_ctrl:1
	v_cndmask_b32_dpp v168, v171, v168, vcc row_ror:8 row_mask:0xf bank_mask:0xf bound_ctrl:1
	v_cndmask_b32_dpp v167, v170, v180, vcc row_ror:8 row_mask:0xf bank_mask:0xf bound_ctrl:1
	v_cndmask_b32_dpp v166, v151, v173, vcc row_ror:8 row_mask:0xf bank_mask:0xf bound_ctrl:1
	v_cndmask_b32_e64 v173, v172, v186, s[8:9]
	v_cndmask_b32_e64 v172, v171, v185, s[8:9]
	v_cndmask_b32_e64 v171, v170, v184, s[8:9]
	v_cndmask_b32_e64 v170, v151, v183, s[8:9]
	v_lshl_add_u64 v[176:177], v[176:177], 0, v[142:143]
	global_store_dwordx4 v[178:179], v[170:173], off
	global_store_dwordx4 v[176:177], v[166:169], off
	v_cvt_pk_bf16_f32 v151, v78, v79
	v_cvt_pk_bf16_f32 v170, v80, v81
	v_cvt_pk_bf16_f32 v171, v74, v75
	v_cvt_pk_bf16_f32 v172, v76, v77
	v_cvt_pk_bf16_f32 v173, v70, v71
	v_cvt_pk_bf16_f32 v178, v72, v73
	v_cvt_pk_bf16_f32 v168, v66, v67
	v_cvt_pk_bf16_f32 v169, v68, v69
	v_lshlrev_b64 v[166:167], 12, v[152:153]
	v_lshl_add_u64 v[174:175], v[174:175], 0, v[166:167]
	s_mov_b64 vcc, s[8:9]
	v_mov_b32_dpp v181, v173 row_ror:8 row_mask:0xf bank_mask:0xf bound_ctrl:1
	v_mov_b32_dpp v182, v178 row_ror:8 row_mask:0xf bank_mask:0xf bound_ctrl:1
; __device__ __forceinline__ u32x4 ror8(u32x4 v) { u32x4 r;
; #pragma unroll
;     for (int i = 0; i < 4; ++i) r[i] = (unsigned)__builtin_amdgcn_mov_dpp((int)v[i], 0x128, 0xf, 0xf, true);
;     return r; }
; __device__ __forceinline__ void store_pair(unsigned char* own, size_t stride8, int hi_off, u32x4 lo, u32x4 hi, bool upper) {
;     const u32x4 tlo = ror8(lo), thi = ror8(hi);
;     const u32x4 A = upper ? thi : lo, B = upper ? hi : tlo;
;     unsigned char* pa = upper ? own - stride8 + hi_off : own;
;     __device__ __forceinline__ void operator()(const f32x4 (&acc)[2][2][4][2], const Unit& u, int wr, int wc, int fr, int fq) const {
;         const int t = u.pn >> 3; const int colt = (u.pn & 7) * 256;
;         const int row0 = u.pm * 256 + wr * 64 + fr, col0 = colt + wc * 64 + 8 * fq;
;         if (t == 1) {
;             f32x4 l[2][2];
; #pragma unroll
;             for (int bj = 0; bj < 2; ++bj) { l[bj][0] = 1.0f - *(const f32x4*)(lb + col0 + bj * 32); l[bj][1] = 1.0f - *(const f32x4*)(lb + col0 + bj * 32 + 4); }
; #pragma unroll
;             for (int ai = 0; ai < 2; ++ai)
; #pragma unroll
;                 for (int m = 0; m < 4; ++m) { u32x4 w[2];
; #pragma unroll
;                     for (int bj = 0; bj < 2; ++bj) { f32x4 v0 = acc[ai][bj][m][0], v1 = acc[ai][bj][m][1];
; #pragma unroll
;                         for (int j = 0; j < 4; ++j) { v0[j] = l[bj][0][j] * sigmoidf_(-v0[j]); v1[j] = l[bj][1][j] * sigmoidf_(-v1[j]); }
;                         w[bj].x = pkh2(v0[0], v0[1]); w[bj].y = pkh2(v0[2], v0[3]); w[bj].z = pkh2(v1[0], v1[1]); w[bj].w = pkh2(v1[2], v1[3]); }
;                     store_pair((unsigned char*)(F + (size_t)(row0 + ai * 128 + m * 16) * D + col0), (size_t)8 * D * 2, 64, w[0], w[1], fr >= 8); }
;         } else {
;             bf16_t* base = QIG + (size_t)(t == 0 ? 0 : t - 1) * M * D;
; #pragma unroll
;             for (int ai = 0; ai < 2; ++ai)
; #pragma unroll
;                 for (int m = 0; m < 4; ++m) { u32x4 w[2];
; #pragma unroll
;                     for (int bj = 0; bj < 2; ++bj) { const f32x4 v0 = acc[ai][bj][m][0], v1 = acc[ai][bj][m][1]; w[bj].x = pk2(v0[0], v0[1]); w[bj].y = pk2(v0[2], v0[3]); w[bj].z = pk2(v1[0], v1[1]); w[bj].w = pk2(v1[2], v1[3]); }
;                     store_pair((unsigned char*)(base + (size_t)(row0 + ai * 128 + m * 16) * D + col0), (size_t)8 * D * 2, 64, w[0], w[1], fr >= 8); }
	v_mov_b32_dpp v183, v168 row_ror:8 row_mask:0xf bank_mask:0xf bound_ctrl:1
	v_mov_b32_dpp v184, v169 row_ror:8 row_mask:0xf bank_mask:0xf bound_ctrl:1
	v_lshl_add_u64 v[176:177], v[174:175], 0, v[140:141]
	v_cndmask_b32_dpp v169, v172, v169, vcc row_ror:8 row_mask:0xf bank_mask:0xf bound_ctrl:1
	v_cndmask_b32_dpp v168, v171, v168, vcc row_ror:8 row_mask:0xf bank_mask:0xf bound_ctrl:1
	v_cndmask_b32_dpp v167, v170, v178, vcc row_ror:8 row_mask:0xf bank_mask:0xf bound_ctrl:1
	v_cndmask_b32_dpp v166, v151, v173, vcc row_ror:8 row_mask:0xf bank_mask:0xf bound_ctrl:1
	v_cndmask_b32_e64 v173, v172, v184, s[8:9]
	v_cndmask_b32_e64 v172, v171, v183, s[8:9]
	v_cndmask_b32_e64 v171, v170, v182, s[8:9]
	v_cndmask_b32_e64 v170, v151, v181, s[8:9]
	v_lshl_add_u64 v[174:175], v[174:175], 0, v[142:143]
	global_store_dwordx4 v[176:177], v[170:173], off
	global_store_dwordx4 v[174:175], v[166:169], off
	v_cvt_pk_bf16_f32 v151, v62, v63
	v_cvt_pk_bf16_f32 v170, v64, v65
	v_cvt_pk_bf16_f32 v171, v58, v59
	v_cvt_pk_bf16_f32 v172, v60, v61
	v_cvt_pk_bf16_f32 v166, v54, v55
	v_cvt_pk_bf16_f32 v167, v56, v57
	v_cvt_pk_bf16_f32 v168, v50, v51
	v_cvt_pk_bf16_f32 v169, v52, v53
	v_lshl_add_u64 v[174:175], v[148:149], 0, s[6:7]
	s_mov_b64 vcc, s[8:9]
	v_mov_b32_dpp v181, v166 row_ror:8 row_mask:0xf bank_mask:0xf bound_ctrl:1
	v_mov_b32_dpp v182, v167 row_ror:8 row_mask:0xf bank_mask:0xf bound_ctrl:1
	v_mov_b32_dpp v183, v168 row_ror:8 row_mask:0xf bank_mask:0xf bound_ctrl:1
	v_mov_b32_dpp v184, v169 row_ror:8 row_mask:0xf bank_mask:0xf bound_ctrl:1
	v_lshl_add_u64 v[176:177], v[174:175], 0, v[140:141]
	v_cndmask_b32_dpp v169, v172, v169, vcc row_ror:8 row_mask:0xf bank_mask:0xf bound_ctrl:1
	v_cndmask_b32_dpp v168, v171, v168, vcc row_ror:8 row_mask:0xf bank_mask:0xf bound_ctrl:1
	v_cndmask_b32_dpp v167, v170, v167, vcc row_ror:8 row_mask:0xf bank_mask:0xf bound_ctrl:1
	v_cndmask_b32_dpp v166, v151, v166, vcc row_ror:8 row_mask:0xf bank_mask:0xf bound_ctrl:1
	v_cndmask_b32_e64 v173, v172, v184, s[8:9]
	v_cndmask_b32_e64 v172, v171, v183, s[8:9]
	v_cndmask_b32_e64 v171, v170, v182, s[8:9]
	v_cndmask_b32_e64 v170, v151, v181, s[8:9]
	v_lshl_add_u64 v[174:175], v[174:175], 0, v[142:143]
	global_store_dwordx4 v[176:177], v[170:173], off
	global_store_dwordx4 v[174:175], v[166:169], off
	v_cvt_pk_bf16_f32 v151, v46, v47
	v_cvt_pk_bf16_f32 v170, v48, v49
	v_cvt_pk_bf16_f32 v171, v42, v43
	v_cvt_pk_bf16_f32 v172, v44, v45
	v_cvt_pk_bf16_f32 v166, v38, v39
	v_cvt_pk_bf16_f32 v167, v40, v41
	v_cvt_pk_bf16_f32 v168, v34, v35
	v_cvt_pk_bf16_f32 v169, v36, v37
	v_lshl_add_u64 v[174:175], v[148:149], 0, s[14:15]
	s_mov_b64 vcc, s[8:9]
	v_mov_b32_dpp v181, v166 row_ror:8 row_mask:0xf bank_mask:0xf bound_ctrl:1
	v_mov_b32_dpp v182, v167 row_ror:8 row_mask:0xf bank_mask:0xf bound_ctrl:1
	v_mov_b32_dpp v183, v168 row_ror:8 row_mask:0xf bank_mask:0xf bound_ctrl:1
	v_mov_b32_dpp v184, v169 row_ror:8 row_mask:0xf bank_mask:0xf bound_ctrl:1
	v_lshl_add_u64 v[176:177], v[174:175], 0, v[140:141]
	v_cndmask_b32_dpp v169, v172, v169, vcc row_ror:8 row_mask:0xf bank_mask:0xf bound_ctrl:1
	v_cndmask_b32_dpp v168, v171, v168, vcc row_ror:8 row_mask:0xf bank_mask:0xf bound_ctrl:1
	v_cndmask_b32_dpp v167, v170, v167, vcc row_ror:8 row_mask:0xf bank_mask:0xf bound_ctrl:1
	v_cndmask_b32_dpp v166, v151, v166, vcc row_ror:8 row_mask:0xf bank_mask:0xf bound_ctrl:1
	v_cndmask_b32_e64 v173, v172, v184, s[8:9]
	v_cndmask_b32_e64 v172, v171, v183, s[8:9]
	v_cndmask_b32_e64 v171, v170, v182, s[8:9]
	v_cndmask_b32_e64 v170, v151, v181, s[8:9]
	v_lshl_add_u64 v[174:175], v[174:175], 0, v[142:143]
	global_store_dwordx4 v[176:177], v[170:173], off
	global_store_dwordx4 v[174:175], v[166:169], off
	v_cvt_pk_bf16_f32 v151, v30, v31
	v_cvt_pk_bf16_f32 v170, v32, v33
	v_cvt_pk_bf16_f32 v171, v26, v27
	v_cvt_pk_bf16_f32 v172, v28, v29
	v_cvt_pk_bf16_f32 v166, v22, v23
	v_cvt_pk_bf16_f32 v167, v24, v25
	v_cvt_pk_bf16_f32 v168, v18, v19
	v_cvt_pk_bf16_f32 v169, v20, v21
	v_lshl_add_u64 v[174:175], v[148:149], 0, s[16:17]
	s_mov_b64 vcc, s[8:9]
	v_mov_b32_dpp v181, v166 row_ror:8 row_mask:0xf bank_mask:0xf bound_ctrl:1
	v_mov_b32_dpp v182, v167 row_ror:8 row_mask:0xf bank_mask:0xf bound_ctrl:1
	v_mov_b32_dpp v183, v168 row_ror:8 row_mask:0xf bank_mask:0xf bound_ctrl:1
	v_mov_b32_dpp v184, v169 row_ror:8 row_mask:0xf bank_mask:0xf bound_ctrl:1
	v_lshl_add_u64 v[176:177], v[174:175], 0, v[140:141]
	v_cndmask_b32_dpp v169, v172, v169, vcc row_ror:8 row_mask:0xf bank_mask:0xf bound_ctrl:1
	v_cndmask_b32_dpp v168, v171, v168, vcc row_ror:8 row_mask:0xf bank_mask:0xf bound_ctrl:1
	v_cndmask_b32_dpp v167, v170, v167, vcc row_ror:8 row_mask:0xf bank_mask:0xf bound_ctrl:1
	v_cndmask_b32_dpp v166, v151, v166, vcc row_ror:8 row_mask:0xf bank_mask:0xf bound_ctrl:1
	v_cndmask_b32_e64 v173, v172, v184, s[8:9]
	v_cndmask_b32_e64 v172, v171, v183, s[8:9]
	v_cndmask_b32_e64 v171, v170, v182, s[8:9]
	v_cndmask_b32_e64 v170, v151, v181, s[8:9]
	v_lshl_add_u64 v[174:175], v[174:175], 0, v[142:143]
	global_store_dwordx4 v[176:177], v[170:173], off
	global_store_dwordx4 v[174:175], v[166:169], off
	v_cvt_pk_bf16_f32 v151, v14, v15
	v_cvt_pk_bf16_f32 v170, v16, v17
	v_cvt_pk_bf16_f32 v166, v6, v7
	v_cvt_pk_bf16_f32 v167, v8, v9
	v_cvt_pk_bf16_f32 v168, v2, v3
	v_cvt_pk_bf16_f32 v169, v4, v5
	v_cvt_pk_bf16_f32 v171, v10, v11
	v_cvt_pk_bf16_f32 v172, v12, v13
	v_lshl_add_u64 v[148:149], v[148:149], 0, s[18:19]
	s_mov_b64 vcc, s[8:9]
	v_mov_b32_dpp v179, v166 row_ror:8 row_mask:0xf bank_mask:0xf bound_ctrl:1
	v_mov_b32_dpp v180, v167 row_ror:8 row_mask:0xf bank_mask:0xf bound_ctrl:1
	v_mov_b32_dpp v181, v168 row_ror:8 row_mask:0xf bank_mask:0xf bound_ctrl:1
	v_mov_b32_dpp v182, v169 row_ror:8 row_mask:0xf bank_mask:0xf bound_ctrl:1
	v_mov_b32_dpp v176, v170 row_ror:8 row_mask:0xf bank_mask:0xf bound_ctrl:1
	v_mov_b32_dpp v177, v171 row_ror:8 row_mask:0xf bank_mask:0xf bound_ctrl:1
	v_mov_b32_dpp v178, v172 row_ror:8 row_mask:0xf bank_mask:0xf bound_ctrl:1
	v_lshl_add_u64 v[174:175], v[148:149], 0, v[140:141]
	v_cndmask_b32_dpp v166, v151, v166, vcc row_ror:8 row_mask:0xf bank_mask:0xf bound_ctrl:1
	v_cndmask_b32_e64 v173, v172, v182, s[8:9]
	v_cndmask_b32_e64 v172, v171, v181, s[8:9]
	v_cndmask_b32_e64 v171, v170, v180, s[8:9]
	v_cndmask_b32_e64 v170, v151, v179, s[8:9]
	v_cndmask_b32_e64 v169, v178, v169, s[8:9]
	v_cndmask_b32_e64 v168, v177, v168, s[8:9]
	v_cndmask_b32_e64 v167, v176, v167, s[8:9]
	v_lshl_add_u64 v[148:149], v[148:149], 0, v[142:143]
	global_store_dwordx4 v[174:175], v[170:173], off
	global_store_dwordx4 v[148:149], v[166:169], off
	s_cbranch_execz .LBB0_1362

; __device__ __forceinline__ unsigned pkh2(float lo, float hi) { const f32x2 v = {lo, hi}; return __builtin_bit_cast(unsigned, __builtin_convertvector(v, f16x2_t)); }
; __device__ __forceinline__ float sigmoidf_(float x) { return __builtin_amdgcn_rcpf(1.0f + __expf(-x)); }
; __device__ __forceinline__ u32x4 ror8(u32x4 v) { u32x4 r;
; #pragma unroll
;     for (int i = 0; i < 4; ++i) r[i] = (unsigned)__builtin_amdgcn_mov_dpp((int)v[i], 0x128, 0xf, 0xf, true);
;     return r; }
; __device__ __forceinline__ void store_pair(unsigned char* own, size_t stride8, int hi_off, u32x4 lo, u32x4 hi, bool upper) {
;     const u32x4 tlo = ror8(lo), thi = ror8(hi);
;     const u32x4 A = upper ? thi : lo, B = upper ? hi : tlo;
;     unsigned char* pa = upper ? own - stride8 + hi_off : own;
;     unsigned char* pb = upper ? own + hi_off : own + stride8;
;     *(u32x4*)pa = A; *(u32x4*)pb = B;
; }
;     __device__ __forceinline__ void operator()(const f32x4 (&acc)[2][2][4][2], const Unit& u, int wr, int wc, int fr, int fq) const {
;     ...
;         if (t == 1) {
;             f32x4 l[2][2];
; #pragma unroll
;             for (int bj = 0; bj < 2; ++bj) { l[bj][0] = 1.0f - *(const f32x4*)(lb + col0 + bj * 32); l[bj][1] = 1.0f - *(const f32x4*)(lb + col0 + bj * 32 + 4); }
; #pragma unroll
;             for (int ai = 0; ai < 2; ++ai)
; #pragma unroll
;                 for (int m = 0; m < 4; ++m) { u32x4 w[2];
; #pragma unroll
;                     for (int bj = 0; bj < 2; ++bj) { f32x4 v0 = acc[ai][bj][m][0], v1 = acc[ai][bj][m][1];
; #pragma unroll
;                         for (int j = 0; j < 4; ++j) { v0[j] = l[bj][0][j] * sigmoidf_(-v0[j]); v1[j] = l[bj][1][j] * sigmoidf_(-v1[j]); }
;                         w[bj].x = pkh2(v0[0], v0[1]); w[bj].y = pkh2(v0[2], v0[3]); w[bj].z = pkh2(v1[0], v1[1]); w[bj].w = pkh2(v1[2], v1[3]); }
;                     store_pair((unsigned char*)(F + (size_t)(row0 + ai * 128 + m * 16) * D + col0), (size_t)8 * D * 2, 64, w[0], w[1], fr >= 8); }
.LBB0_1362:
	v_lshlrev_b32_e32 v174, 2, v150
	global_load_dwordx4 v[148:151], v174, s[10:11]
	global_load_dwordx4 v[166:169], v174, s[10:11] offset:16
	global_load_dwordx4 v[170:173], v174, s[10:11] offset:128
	s_nop 0
	global_load_dwordx4 v[174:177], v174, s[10:11] offset:144
	v_mul_f32_e32 v126, 0x3fb8aa3b, v126
	v_mul_f32_e32 v127, 0x3fb8aa3b, v127
	v_exp_f32_e32 v126, v126
	v_exp_f32_e32 v127, v127
	v_mul_f32_e32 v120, 0x3fb8aa3b, v120
	v_mul_f32_e32 v116, 0x3fb8aa3b, v116
	v_exp_f32_e32 v120, v120
	v_mul_f32_e32 v124, 0x3fb8aa3b, v124
	v_exp_f32_e32 v116, v116
	v_add_f32_e32 v126, 1.0, v126
	v_add_f32_e32 v127, 1.0, v127
	v_exp_f32_e32 v124, v124
	v_rcp_f32_e32 v178, v126
	v_rcp_f32_e32 v179, v127
	v_add_f32_e32 v120, 1.0, v120
	v_mul_f32_e32 v122, 0x3fb8aa3b, v122
	v_mul_f32_e32 v123, 0x3fb8aa3b, v123
	v_mul_f32_e32 v128, 0x3fb8aa3b, v128
	v_mul_f32_e32 v129, 0x3fb8aa3b, v129
	v_mul_f32_e32 v118, 0x3fb8aa3b, v118
	v_mul_f32_e32 v119, 0x3fb8aa3b, v119
	v_add_f32_e32 v190, 1.0, v116
	v_rcp_f32_e32 v116, v120
	v_mul_f32_e32 v120, 0x3fb8aa3b, v121
	v_mul_f32_e32 v114, 0x3fb8aa3b, v114
	v_mul_f32_e32 v115, 0x3fb8aa3b, v115
	v_exp_f32_e32 v122, v122
	v_exp_f32_e32 v123, v123
	v_exp_f32_e32 v128, v128
	v_exp_f32_e32 v129, v129
	v_exp_f32_e32 v118, v118
	v_exp_f32_e32 v119, v119
	v_add_f32_e32 v124, 1.0, v124
	v_exp_f32_e32 v121, v120
	v_mul_f32_e32 v117, 0x3fb8aa3b, v117
	v_mul_f32_e32 v125, 0x3fb8aa3b, v125
	v_exp_f32_e32 v114, v114
	v_exp_f32_e32 v115, v115
	v_rcp_f32_e32 v184, v124
	v_exp_f32_e32 v125, v125
	v_add_f32_e32 v122, 1.0, v122
	v_add_f32_e32 v123, 1.0, v123
	v_add_f32_e32 v128, 1.0, v128
	v_add_f32_e32 v129, 1.0, v129
	v_add_f32_e32 v118, 1.0, v118
	v_add_f32_e32 v119, 1.0, v119
	v_add_f32_e32 v114, 1.0, v114
	v_add_f32_e32 v115, 1.0, v115
	v_rcp_f32_e32 v180, v122
	v_rcp_f32_e32 v181, v123
	v_rcp_f32_e32 v182, v128
	v_rcp_f32_e32 v183, v129
	v_rcp_f32_e32 v186, v118
	v_rcp_f32_e32 v187, v119
	v_add_f32_e32 v125, 1.0, v125
	v_rcp_f32_e32 v188, v114
	v_rcp_f32_e32 v189, v115
	v_rcp_f32_e32 v120, v190
	v_rcp_f32_e32 v185, v125
	v_mul_f32_e32 v110, 0x3fb8aa3b, v110
	v_mul_f32_e32 v106, 0x3fb8aa3b, v106
	v_exp_f32_e32 v110, v110
	v_mul_f32_e32 v111, 0x3fb8aa3b, v111
	v_mul_f32_e32 v107, 0x3fb8aa3b, v107
	v_exp_f32_e32 v111, v111
	v_mul_f32_e32 v112, 0x3fb8aa3b, v112
	v_mul_f32_e32 v108, 0x3fb8aa3b, v108
	v_exp_f32_e32 v112, v112
	v_mul_f32_e32 v113, 0x3fb8aa3b, v113
	v_mul_f32_e32 v109, 0x3fb8aa3b, v109
	v_exp_f32_e32 v113, v113
	v_mul_f32_e32 v102, 0x3fb8aa3b, v102
	v_mul_f32_e32 v98, 0x3fb8aa3b, v98
	v_exp_f32_e32 v102, v102
	v_mul_f32_e32 v103, 0x3fb8aa3b, v103
	v_mul_f32_e32 v99, 0x3fb8aa3b, v99
	s_waitcnt vmcnt(0)
	v_sub_f32_e32 v149, 1.0, v149
	v_sub_f32_e32 v148, 1.0, v148
	v_sub_f32_e32 v127, 1.0, v151
	v_sub_f32_e32 v126, 1.0, v150
	v_sub_f32_e32 v151, 1.0, v167
	v_sub_f32_e32 v150, 1.0, v166
	v_pk_mul_f32 v[166:167], v[178:179], v[148:149]
	v_sub_f32_e32 v124, 1.0, v174
	v_cvt_pk_f16_f32 v174, v166, v167
	v_exp_f32_e32 v166, v117
	v_add_f32_e32 v117, 1.0, v121
	v_rcp_f32_e32 v117, v117
	v_sub_f32_e32 v115, 1.0, v173
	v_add_f32_e32 v121, 1.0, v166
	v_rcp_f32_e32 v121, v121
	v_sub_f32_e32 v114, 1.0, v172
	v_sub_f32_e32 v123, 1.0, v171
	v_sub_f32_e32 v122, 1.0, v170
	v_sub_f32_e32 v129, 1.0, v169
	v_sub_f32_e32 v128, 1.0, v168
	v_sub_f32_e32 v119, 1.0, v177
	v_sub_f32_e32 v118, 1.0, v176
	v_sub_f32_e32 v125, 1.0, v175
	v_pk_mul_f32 v[168:169], v[180:181], v[150:151]
	v_pk_mul_f32 v[170:171], v[182:183], v[126:127]
	v_pk_mul_f32 v[166:167], v[186:187], v[122:123]
	v_pk_mul_f32 v[116:117], v[116:117], v[114:115]
	v_cvt_pk_f16_f32 v170, v170, v171
	v_cvt_pk_f16_f32 v171, v168, v169
	v_pk_mul_f32 v[168:169], v[188:189], v[124:125]
	v_pk_mul_f32 v[120:121], v[120:121], v[118:119]
	v_cvt_pk_f16_f32 v166, v166, v167
	v_cvt_pk_f16_f32 v167, v116, v117
	v_lshlrev_b64 v[116:117], 12, v[158:159]
	v_pk_mul_f32 v[172:173], v[184:185], v[128:129]
	v_cvt_pk_f16_f32 v168, v168, v169
	v_cvt_pk_f16_f32 v169, v120, v121
	v_lshl_add_u64 v[116:117], s[90:91], 0, v[116:117]
	v_cvt_pk_f16_f32 v172, v172, v173
	v_lshl_add_u64 v[116:117], v[116:117], 0, v[138:139]
	s_mov_b64 vcc, s[8:9]
	v_mov_b32_dpp v176, v166 row_ror:8 row_mask:0xf bank_mask:0xf bound_ctrl:1
	v_mov_b32_dpp v177, v167 row_ror:8 row_mask:0xf bank_mask:0xf bound_ctrl:1
	v_mov_b32_dpp v178, v168 row_ror:8 row_mask:0xf bank_mask:0xf bound_ctrl:1
	v_mov_b32_dpp v179, v169 row_ror:8 row_mask:0xf bank_mask:0xf bound_ctrl:1
	v_mov_b32_dpp v159, v170 row_ror:8 row_mask:0xf bank_mask:0xf bound_ctrl:1
	v_mov_b32_dpp v175, v172 row_ror:8 row_mask:0xf bank_mask:0xf bound_ctrl:1
	v_lshl_add_u64 v[120:121], v[116:117], 0, v[140:141]
	v_cndmask_b32_dpp v168, v171, v168, vcc row_ror:8 row_mask:0xf bank_mask:0xf bound_ctrl:1
	v_cndmask_b32_e64 v173, v172, v179, s[8:9]
	v_cndmask_b32_e64 v172, v171, v178, s[8:9]
	v_cndmask_b32_e64 v171, v170, v177, s[8:9]
	v_cndmask_b32_e64 v170, v174, v176, s[8:9]
	global_store_dwordx4 v[120:121], v[170:173], off
	v_exp_f32_e32 v120, v106
	v_add_f32_e32 v106, 1.0, v110
	v_rcp_f32_e32 v106, v106
	v_exp_f32_e32 v103, v103
	v_add_f32_e32 v110, 1.0, v120
	v_exp_f32_e32 v120, v107
	v_add_f32_e32 v107, 1.0, v111
	v_rcp_f32_e32 v107, v107
	v_mul_f32_e32 v104, 0x3fb8aa3b, v104
	v_add_f32_e32 v111, 1.0, v120
	v_exp_f32_e32 v120, v108
	v_add_f32_e32 v108, 1.0, v112
	v_pk_mul_f32 v[106:107], v[106:107], v[148:149]
	v_mul_f32_e32 v100, 0x3fb8aa3b, v100
	v_add_f32_e32 v112, 1.0, v120
	v_exp_f32_e32 v120, v109
	v_add_f32_e32 v109, 1.0, v113
	v_exp_f32_e32 v104, v104
	v_mul_f32_e32 v105, 0x3fb8aa3b, v105
	v_add_f32_e32 v113, 1.0, v120
	v_cvt_pk_f16_f32 v120, v106, v107
; __device__ __forceinline__ unsigned pkh2(float lo, float hi) { const f32x2 v = {lo, hi}; return __builtin_bit_cast(unsigned, __builtin_convertvector(v, f16x2_t)); }
; __device__ __forceinline__ float sigmoidf_(float x) { return __builtin_amdgcn_rcpf(1.0f + __expf(-x)); }
; __device__ __forceinline__ u32x4 ror8(u32x4 v) { u32x4 r;
; #pragma unroll
;     for (int i = 0; i < 4; ++i) r[i] = (unsigned)__builtin_amdgcn_mov_dpp((int)v[i], 0x128, 0xf, 0xf, true);
;     return r; }
; __device__ __forceinline__ void store_pair(unsigned char* own, size_t stride8, int hi_off, u32x4 lo, u32x4 hi, bool upper) {
;     const u32x4 tlo = ror8(lo), thi = ror8(hi);
;     const u32x4 A = upper ? thi : lo, B = upper ? hi : tlo;
;     unsigned char* pa = upper ? own - stride8 + hi_off : own;
;     unsigned char* pb = upper ? own + hi_off : own + stride8;
;     *(u32x4*)pa = A; *(u32x4*)pb = B;
; }
;     __device__ __forceinline__ void operator()(const f32x4 (&acc)[2][2][4][2], const Unit& u, int wr, int wc, int fr, int fq) const {
;     ...
;         if (t == 1) {
;             f32x4 l[2][2];
; #pragma unroll
;             for (int bj = 0; bj < 2; ++bj) { l[bj][0] = 1.0f - *(const f32x4*)(lb + col0 + bj * 32); l[bj][1] = 1.0f - *(const f32x4*)(lb + col0 + bj * 32 + 4); }
; #pragma unroll
;             for (int ai = 0; ai < 2; ++ai)
; #pragma unroll
;                 for (int m = 0; m < 4; ++m) { u32x4 w[2];
; #pragma unroll
;                     for (int bj = 0; bj < 2; ++bj) { f32x4 v0 = acc[ai][bj][m][0], v1 = acc[ai][bj][m][1];
; #pragma unroll
;                         for (int j = 0; j < 4; ++j) { v0[j] = l[bj][0][j] * sigmoidf_(-v0[j]); v1[j] = l[bj][1][j] * sigmoidf_(-v1[j]); }
;                         w[bj].x = pkh2(v0[0], v0[1]); w[bj].y = pkh2(v0[2], v0[3]); w[bj].z = pkh2(v1[0], v1[1]); w[bj].w = pkh2(v1[2], v1[3]); }
;                     store_pair((unsigned char*)(F + (size_t)(row0 + ai * 128 + m * 16) * D + col0), (size_t)8 * D * 2, 64, w[0], w[1], fr >= 8); }
	v_exp_f32_e32 v106, v98
	v_add_f32_e32 v98, 1.0, v102
	v_mul_f32_e32 v101, 0x3fb8aa3b, v101
	v_exp_f32_e32 v105, v105
	v_add_f32_e32 v102, 1.0, v106
	v_exp_f32_e32 v106, v99
	v_add_f32_e32 v99, 1.0, v103
	v_rcp_f32_e32 v110, v110
	v_rcp_f32_e32 v111, v111
	v_add_f32_e32 v103, 1.0, v106
	v_exp_f32_e32 v106, v100
	v_add_f32_e32 v100, 1.0, v104
	v_rcp_f32_e32 v112, v112
	v_rcp_f32_e32 v113, v113
	v_add_f32_e32 v104, 1.0, v106
	v_exp_f32_e32 v106, v101
	v_rcp_f32_e32 v98, v98
	v_rcp_f32_e32 v99, v99
	v_rcp_f32_e32 v108, v108
	v_rcp_f32_e32 v109, v109
	v_add_f32_e32 v101, 1.0, v105
	v_add_f32_e32 v105, 1.0, v106
	v_rcp_f32_e32 v102, v102
	v_rcp_f32_e32 v103, v103
	v_rcp_f32_e32 v100, v100
	v_rcp_f32_e32 v104, v104
	v_rcp_f32_e32 v101, v101
	v_rcp_f32_e32 v105, v105
	v_pk_mul_f32 v[110:111], v[110:111], v[150:151]
	v_pk_mul_f32 v[112:113], v[112:113], v[128:129]
	v_pk_mul_f32 v[98:99], v[98:99], v[122:123]
	v_pk_mul_f32 v[108:109], v[108:109], v[126:127]
	v_cvt_pk_f16_f32 v110, v110, v111
	v_cvt_pk_f16_f32 v111, v112, v113
	v_cvt_pk_f16_f32 v112, v98, v99
	v_lshlrev_b64 v[98:99], 12, v[156:157]
	v_cvt_pk_f16_f32 v121, v108, v109
	v_pk_mul_f32 v[102:103], v[102:103], v[124:125]
	v_pk_mul_f32 v[100:101], v[100:101], v[114:115]
	v_pk_mul_f32 v[104:105], v[104:105], v[118:119]
	v_lshl_add_u64 v[98:99], s[90:91], 0, v[98:99]
	v_cvt_pk_f16_f32 v113, v100, v101
	v_cvt_pk_f16_f32 v100, v102, v103
	v_cvt_pk_f16_f32 v101, v104, v105
	v_lshl_add_u64 v[106:107], v[98:99], 0, v[138:139]
	s_mov_b64 vcc, s[8:9]
	v_mov_b32_dpp v104, v100 row_ror:8 row_mask:0xf bank_mask:0xf bound_ctrl:1
	v_mov_b32_dpp v105, v101 row_ror:8 row_mask:0xf bank_mask:0xf bound_ctrl:1
	v_lshl_add_u64 v[108:109], v[106:107], 0, v[140:141]
	v_cndmask_b32_dpp v101, v111, v101, vcc row_ror:8 row_mask:0xf bank_mask:0xf bound_ctrl:1
	v_cndmask_b32_dpp v100, v110, v100, vcc row_ror:8 row_mask:0xf bank_mask:0xf bound_ctrl:1
	v_cndmask_b32_dpp v99, v121, v113, vcc row_ror:8 row_mask:0xf bank_mask:0xf bound_ctrl:1
	v_cndmask_b32_dpp v98, v120, v112, vcc row_ror:8 row_mask:0xf bank_mask:0xf bound_ctrl:1
	v_lshl_add_u64 v[106:107], v[106:107], 0, v[142:143]
	v_mul_f32_e32 v95, 0x3fb8aa3b, v95
	v_mul_f32_e32 v91, 0x3fb8aa3b, v91
	global_store_dwordx4 v[106:107], v[98:101], off
	v_exp_f32_e32 v95, v95
	v_mul_f32_e32 v94, 0x3fb8aa3b, v94
	v_exp_f32_e32 v98, v91
	v_exp_f32_e32 v94, v94
	v_mul_f32_e32 v96, 0x3fb8aa3b, v96
	v_mul_f32_e32 v92, 0x3fb8aa3b, v92
	v_mov_b32_dpp v156, v112 row_ror:8 row_mask:0xf bank_mask:0xf bound_ctrl:1
	v_mov_b32_dpp v157, v113 row_ror:8 row_mask:0xf bank_mask:0xf bound_ctrl:1
	v_add_f32_e32 v91, 1.0, v95
	v_add_f32_e32 v95, 1.0, v98
	v_exp_f32_e32 v96, v96
	v_exp_f32_e32 v98, v92
	v_cndmask_b32_e64 v105, v111, v105, s[8:9]
	v_cndmask_b32_e64 v104, v110, v104, s[8:9]
	v_cndmask_b32_e64 v103, v121, v157, s[8:9]
	v_cndmask_b32_e64 v102, v120, v156, s[8:9]
	v_mul_f32_e32 v90, 0x3fb8aa3b, v90
	global_store_dwordx4 v[108:109], v[102:105], off
	v_rcp_f32_e32 v91, v91
	v_mul_f32_e32 v97, 0x3fb8aa3b, v97
	v_exp_f32_e32 v102, v90
	v_add_f32_e32 v90, 1.0, v94
	v_rcp_f32_e32 v90, v90
	v_mul_f32_e32 v93, 0x3fb8aa3b, v93
	v_add_f32_e32 v92, 1.0, v96
	v_add_f32_e32 v96, 1.0, v98
	v_exp_f32_e32 v97, v97
	v_exp_f32_e32 v98, v93
	v_pk_mul_f32 v[90:91], v[90:91], v[148:149]
	v_mul_f32_e32 v86, 0x3fb8aa3b, v86
	v_mul_f32_e32 v82, 0x3fb8aa3b, v82
	v_add_f32_e32 v93, 1.0, v97
	v_add_f32_e32 v97, 1.0, v98
	v_cvt_pk_f16_f32 v98, v90, v91
	v_exp_f32_e32 v86, v86
	v_exp_f32_e32 v90, v82
	v_mul_f32_e32 v87, 0x3fb8aa3b, v87
	v_mul_f32_e32 v83, 0x3fb8aa3b, v83
	v_add_f32_e32 v82, 1.0, v86
	v_add_f32_e32 v86, 1.0, v90
	v_exp_f32_e32 v87, v87
	v_exp_f32_e32 v90, v83
	v_mul_f32_e32 v88, 0x3fb8aa3b, v88
	v_mul_f32_e32 v84, 0x3fb8aa3b, v84
	v_add_f32_e32 v83, 1.0, v87
	v_add_f32_e32 v87, 1.0, v90
	v_exp_f32_e32 v88, v88
	v_exp_f32_e32 v90, v84
	v_mul_f32_e32 v89, 0x3fb8aa3b, v89
	v_mul_f32_e32 v85, 0x3fb8aa3b, v85
	v_add_f32_e32 v84, 1.0, v88
	v_add_f32_e32 v88, 1.0, v90
	v_exp_f32_e32 v89, v89
	v_exp_f32_e32 v90, v85
	v_add_f32_e32 v94, 1.0, v102
	v_rcp_f32_e32 v94, v94
	v_rcp_f32_e32 v95, v95
	v_rcp_f32_e32 v96, v96
	v_rcp_f32_e32 v97, v97
	v_rcp_f32_e32 v82, v82
	v_rcp_f32_e32 v83, v83
	v_rcp_f32_e32 v92, v92
	v_rcp_f32_e32 v93, v93
	v_add_f32_e32 v85, 1.0, v89
	v_add_f32_e32 v89, 1.0, v90
	v_rcp_f32_e32 v86, v86
	v_rcp_f32_e32 v87, v87
	v_rcp_f32_e32 v84, v84
	v_rcp_f32_e32 v88, v88
	v_rcp_f32_e32 v85, v85
	v_rcp_f32_e32 v89, v89
	v_pk_mul_f32 v[94:95], v[94:95], v[150:151]
	v_pk_mul_f32 v[96:97], v[96:97], v[128:129]
	v_pk_mul_f32 v[82:83], v[82:83], v[122:123]
	v_pk_mul_f32 v[92:93], v[92:93], v[126:127]
	v_cvt_pk_f16_f32 v94, v94, v95
	v_cvt_pk_f16_f32 v95, v96, v97
	v_cvt_pk_f16_f32 v96, v82, v83
	v_lshlrev_b64 v[82:83], 12, v[154:155]
	v_cvt_pk_f16_f32 v99, v92, v93
	v_pk_mul_f32 v[86:87], v[86:87], v[124:125]
	v_pk_mul_f32 v[84:85], v[84:85], v[114:115]
	v_pk_mul_f32 v[88:89], v[88:89], v[118:119]
	v_lshl_add_u64 v[82:83], s[90:91], 0, v[82:83]
	v_cvt_pk_f16_f32 v97, v84, v85
	v_cvt_pk_f16_f32 v84, v86, v87
	v_cvt_pk_f16_f32 v85, v88, v89
	v_lshl_add_u64 v[90:91], v[82:83], 0, v[138:139]
	s_mov_b64 vcc, s[8:9]
	v_mov_b32_dpp v88, v84 row_ror:8 row_mask:0xf bank_mask:0xf bound_ctrl:1
	v_mov_b32_dpp v89, v85 row_ror:8 row_mask:0xf bank_mask:0xf bound_ctrl:1
	v_lshl_add_u64 v[92:93], v[90:91], 0, v[140:141]
	v_cndmask_b32_dpp v85, v95, v85, vcc row_ror:8 row_mask:0xf bank_mask:0xf bound_ctrl:1
	v_cndmask_b32_dpp v84, v94, v84, vcc row_ror:8 row_mask:0xf bank_mask:0xf bound_ctrl:1
	v_cndmask_b32_dpp v83, v99, v97, vcc row_ror:8 row_mask:0xf bank_mask:0xf bound_ctrl:1
; __device__ __forceinline__ unsigned pkh2(float lo, float hi) { const f32x2 v = {lo, hi}; return __builtin_bit_cast(unsigned, __builtin_convertvector(v, f16x2_t)); }
; __device__ __forceinline__ float sigmoidf_(float x) { return __builtin_amdgcn_rcpf(1.0f + __expf(-x)); }
; __device__ __forceinline__ u32x4 ror8(u32x4 v) { u32x4 r;
; #pragma unroll
;     for (int i = 0; i < 4; ++i) r[i] = (unsigned)__builtin_amdgcn_mov_dpp((int)v[i], 0x128, 0xf, 0xf, true);
;     return r; }
; __device__ __forceinline__ void store_pair(unsigned char* own, size_t stride8, int hi_off, u32x4 lo, u32x4 hi, bool upper) {
;     const u32x4 tlo = ror8(lo), thi = ror8(hi);
;     const u32x4 A = upper ? thi : lo, B = upper ? hi : tlo;
;     unsigned char* pa = upper ? own - stride8 + hi_off : own;
;     unsigned char* pb = upper ? own + hi_off : own + stride8;
;     *(u32x4*)pa = A; *(u32x4*)pb = B;
; }
;     __device__ __forceinline__ void operator()(const f32x4 (&acc)[2][2][4][2], const Unit& u, int wr, int wc, int fr, int fq) const {
;     ...
;         if (t == 1) {
;             f32x4 l[2][2];
; #pragma unroll
;             for (int bj = 0; bj < 2; ++bj) { l[bj][0] = 1.0f - *(const f32x4*)(lb + col0 + bj * 32); l[bj][1] = 1.0f - *(const f32x4*)(lb + col0 + bj * 32 + 4); }
; #pragma unroll
;             for (int ai = 0; ai < 2; ++ai)
; #pragma unroll
;                 for (int m = 0; m < 4; ++m) { u32x4 w[2];
; #pragma unroll
;                     for (int bj = 0; bj < 2; ++bj) { f32x4 v0 = acc[ai][bj][m][0], v1 = acc[ai][bj][m][1];
; #pragma unroll
;                         for (int j = 0; j < 4; ++j) { v0[j] = l[bj][0][j] * sigmoidf_(-v0[j]); v1[j] = l[bj][1][j] * sigmoidf_(-v1[j]); }
;                         w[bj].x = pkh2(v0[0], v0[1]); w[bj].y = pkh2(v0[2], v0[3]); w[bj].z = pkh2(v1[0], v1[1]); w[bj].w = pkh2(v1[2], v1[3]); }
;                     store_pair((unsigned char*)(F + (size_t)(row0 + ai * 128 + m * 16) * D + col0), (size_t)8 * D * 2, 64, w[0], w[1], fr >= 8); }
	v_cndmask_b32_dpp v82, v98, v96, vcc row_ror:8 row_mask:0xf bank_mask:0xf bound_ctrl:1
	v_lshl_add_u64 v[90:91], v[90:91], 0, v[142:143]
	v_mul_f32_e32 v79, 0x3fb8aa3b, v79
	v_mul_f32_e32 v75, 0x3fb8aa3b, v75
	global_store_dwordx4 v[90:91], v[82:85], off
	v_exp_f32_e32 v79, v79
	v_mul_f32_e32 v78, 0x3fb8aa3b, v78
	v_exp_f32_e32 v82, v75
	v_exp_f32_e32 v78, v78
	v_mul_f32_e32 v80, 0x3fb8aa3b, v80
	v_mul_f32_e32 v76, 0x3fb8aa3b, v76
	v_mov_b32_dpp v100, v96 row_ror:8 row_mask:0xf bank_mask:0xf bound_ctrl:1
	v_mov_b32_dpp v101, v97 row_ror:8 row_mask:0xf bank_mask:0xf bound_ctrl:1
	v_add_f32_e32 v75, 1.0, v79
	v_add_f32_e32 v79, 1.0, v82
	v_exp_f32_e32 v80, v80
	v_exp_f32_e32 v82, v76
	v_cndmask_b32_e64 v89, v95, v89, s[8:9]
	v_cndmask_b32_e64 v88, v94, v88, s[8:9]
	v_cndmask_b32_e64 v87, v99, v101, s[8:9]
	v_cndmask_b32_e64 v86, v98, v100, s[8:9]
	v_mul_f32_e32 v74, 0x3fb8aa3b, v74
	global_store_dwordx4 v[92:93], v[86:89], off
	v_rcp_f32_e32 v75, v75
	v_mul_f32_e32 v81, 0x3fb8aa3b, v81
	v_exp_f32_e32 v86, v74
	v_add_f32_e32 v74, 1.0, v78
	v_rcp_f32_e32 v74, v74
	v_mul_f32_e32 v77, 0x3fb8aa3b, v77
	v_add_f32_e32 v76, 1.0, v80
	v_add_f32_e32 v80, 1.0, v82
	v_exp_f32_e32 v81, v81
	v_exp_f32_e32 v82, v77
	v_pk_mul_f32 v[74:75], v[74:75], v[148:149]
	v_mul_f32_e32 v70, 0x3fb8aa3b, v70
	v_mul_f32_e32 v66, 0x3fb8aa3b, v66
	v_add_f32_e32 v77, 1.0, v81
	v_add_f32_e32 v81, 1.0, v82
	v_cvt_pk_f16_f32 v82, v74, v75
	v_exp_f32_e32 v70, v70
	v_exp_f32_e32 v74, v66
	v_mul_f32_e32 v71, 0x3fb8aa3b, v71
	v_mul_f32_e32 v67, 0x3fb8aa3b, v67
	v_add_f32_e32 v66, 1.0, v70
	v_add_f32_e32 v70, 1.0, v74
	v_exp_f32_e32 v71, v71
	v_exp_f32_e32 v74, v67
	v_mul_f32_e32 v72, 0x3fb8aa3b, v72
	v_mul_f32_e32 v68, 0x3fb8aa3b, v68
	v_add_f32_e32 v67, 1.0, v71
	v_add_f32_e32 v71, 1.0, v74
	v_exp_f32_e32 v72, v72
	v_exp_f32_e32 v74, v68
	v_mul_f32_e32 v73, 0x3fb8aa3b, v73
	v_mul_f32_e32 v69, 0x3fb8aa3b, v69
	v_add_f32_e32 v68, 1.0, v72
	v_add_f32_e32 v72, 1.0, v74
	v_exp_f32_e32 v73, v73
	v_exp_f32_e32 v74, v69
	v_add_f32_e32 v78, 1.0, v86
	v_rcp_f32_e32 v78, v78
	v_rcp_f32_e32 v79, v79
	v_rcp_f32_e32 v80, v80
	v_rcp_f32_e32 v81, v81
	v_rcp_f32_e32 v66, v66
	v_rcp_f32_e32 v67, v67
	v_rcp_f32_e32 v76, v76
	v_rcp_f32_e32 v77, v77
	v_add_f32_e32 v69, 1.0, v73
	v_add_f32_e32 v73, 1.0, v74
	v_rcp_f32_e32 v70, v70
	v_rcp_f32_e32 v71, v71
	v_rcp_f32_e32 v68, v68
	v_rcp_f32_e32 v72, v72
	v_rcp_f32_e32 v69, v69
	v_rcp_f32_e32 v73, v73
	v_pk_mul_f32 v[78:79], v[78:79], v[150:151]
	v_pk_mul_f32 v[80:81], v[80:81], v[128:129]
	v_pk_mul_f32 v[66:67], v[66:67], v[122:123]
	v_pk_mul_f32 v[76:77], v[76:77], v[126:127]
	v_cvt_pk_f16_f32 v78, v78, v79
	v_cvt_pk_f16_f32 v79, v80, v81
	v_cvt_pk_f16_f32 v80, v66, v67
	v_lshlrev_b64 v[66:67], 12, v[152:153]
	v_cvt_pk_f16_f32 v83, v76, v77
	v_pk_mul_f32 v[70:71], v[70:71], v[124:125]
	v_pk_mul_f32 v[68:69], v[68:69], v[114:115]
	v_pk_mul_f32 v[72:73], v[72:73], v[118:119]
	v_lshl_add_u64 v[66:67], s[90:91], 0, v[66:67]
	v_cvt_pk_f16_f32 v81, v68, v69
	v_cvt_pk_f16_f32 v68, v70, v71
	v_cvt_pk_f16_f32 v69, v72, v73
	v_lshl_add_u64 v[74:75], v[66:67], 0, v[138:139]
	s_mov_b64 vcc, s[8:9]
	v_mov_b32_dpp v72, v68 row_ror:8 row_mask:0xf bank_mask:0xf bound_ctrl:1
	v_mov_b32_dpp v73, v69 row_ror:8 row_mask:0xf bank_mask:0xf bound_ctrl:1
	v_lshl_add_u64 v[76:77], v[74:75], 0, v[140:141]
	v_cndmask_b32_dpp v69, v79, v69, vcc row_ror:8 row_mask:0xf bank_mask:0xf bound_ctrl:1
	v_cndmask_b32_dpp v68, v78, v68, vcc row_ror:8 row_mask:0xf bank_mask:0xf bound_ctrl:1
	v_cndmask_b32_dpp v67, v83, v81, vcc row_ror:8 row_mask:0xf bank_mask:0xf bound_ctrl:1
	v_cndmask_b32_dpp v66, v82, v80, vcc row_ror:8 row_mask:0xf bank_mask:0xf bound_ctrl:1
	v_lshl_add_u64 v[74:75], v[74:75], 0, v[142:143]
	v_mul_f32_e32 v63, 0x3fb8aa3b, v63
	v_mul_f32_e32 v59, 0x3fb8aa3b, v59
	global_store_dwordx4 v[74:75], v[66:69], off
	v_exp_f32_e32 v63, v63
	v_mul_f32_e32 v62, 0x3fb8aa3b, v62
	v_exp_f32_e32 v66, v59
	v_exp_f32_e32 v62, v62
	v_mul_f32_e32 v64, 0x3fb8aa3b, v64
	v_mul_f32_e32 v60, 0x3fb8aa3b, v60
	v_mov_b32_dpp v84, v80 row_ror:8 row_mask:0xf bank_mask:0xf bound_ctrl:1
	v_mov_b32_dpp v85, v81 row_ror:8 row_mask:0xf bank_mask:0xf bound_ctrl:1
	v_add_f32_e32 v59, 1.0, v63
	v_add_f32_e32 v63, 1.0, v66
	v_exp_f32_e32 v64, v64
	v_exp_f32_e32 v66, v60
	v_cndmask_b32_e64 v73, v79, v73, s[8:9]
	v_cndmask_b32_e64 v72, v78, v72, s[8:9]
	v_cndmask_b32_e64 v71, v83, v85, s[8:9]
	v_cndmask_b32_e64 v70, v82, v84, s[8:9]
	v_mul_f32_e32 v58, 0x3fb8aa3b, v58
	global_store_dwordx4 v[76:77], v[70:73], off
	v_rcp_f32_e32 v59, v59
	v_mul_f32_e32 v65, 0x3fb8aa3b, v65
	v_exp_f32_e32 v70, v58
	v_add_f32_e32 v58, 1.0, v62
	v_rcp_f32_e32 v58, v58
	v_mul_f32_e32 v61, 0x3fb8aa3b, v61
	v_add_f32_e32 v60, 1.0, v64
	v_add_f32_e32 v64, 1.0, v66
	v_exp_f32_e32 v65, v65
	v_exp_f32_e32 v66, v61
	v_pk_mul_f32 v[58:59], v[58:59], v[148:149]
	v_mul_f32_e32 v54, 0x3fb8aa3b, v54
	v_mul_f32_e32 v50, 0x3fb8aa3b, v50
	v_add_f32_e32 v61, 1.0, v65
	v_add_f32_e32 v65, 1.0, v66
	v_cvt_pk_f16_f32 v66, v58, v59
	v_exp_f32_e32 v54, v54
	v_exp_f32_e32 v58, v50
	v_mul_f32_e32 v55, 0x3fb8aa3b, v55
	v_mul_f32_e32 v51, 0x3fb8aa3b, v51
	v_add_f32_e32 v50, 1.0, v54
	v_add_f32_e32 v54, 1.0, v58
	v_exp_f32_e32 v55, v55
	v_exp_f32_e32 v58, v51
	v_mul_f32_e32 v56, 0x3fb8aa3b, v56
	v_mul_f32_e32 v52, 0x3fb8aa3b, v52
	v_add_f32_e32 v51, 1.0, v55
	v_add_f32_e32 v55, 1.0, v58
	v_exp_f32_e32 v56, v56
	v_exp_f32_e32 v58, v52
	v_mul_f32_e32 v57, 0x3fb8aa3b, v57
	v_mul_f32_e32 v53, 0x3fb8aa3b, v53
	v_add_f32_e32 v52, 1.0, v56
	v_add_f32_e32 v56, 1.0, v58
	v_exp_f32_e32 v57, v57
	v_exp_f32_e32 v58, v53
	v_add_f32_e32 v62, 1.0, v70
	v_rcp_f32_e32 v62, v62
; __device__ __forceinline__ unsigned pkh2(float lo, float hi) { const f32x2 v = {lo, hi}; return __builtin_bit_cast(unsigned, __builtin_convertvector(v, f16x2_t)); }
; __device__ __forceinline__ float sigmoidf_(float x) { return __builtin_amdgcn_rcpf(1.0f + __expf(-x)); }
; __device__ __forceinline__ u32x4 ror8(u32x4 v) { u32x4 r;
; #pragma unroll
;     for (int i = 0; i < 4; ++i) r[i] = (unsigned)__builtin_amdgcn_mov_dpp((int)v[i], 0x128, 0xf, 0xf, true);
;     return r; }
; __device__ __forceinline__ void store_pair(unsigned char* own, size_t stride8, int hi_off, u32x4 lo, u32x4 hi, bool upper) {
;     const u32x4 tlo = ror8(lo), thi = ror8(hi);
;     const u32x4 A = upper ? thi : lo, B = upper ? hi : tlo;
;     unsigned char* pa = upper ? own - stride8 + hi_off : own;
;     unsigned char* pb = upper ? own + hi_off : own + stride8;
;     *(u32x4*)pa = A; *(u32x4*)pb = B;
; }
;     __device__ __forceinline__ void operator()(const f32x4 (&acc)[2][2][4][2], const Unit& u, int wr, int wc, int fr, int fq) const {
;     ...
;         if (t == 1) {
;             f32x4 l[2][2];
; #pragma unroll
;             for (int bj = 0; bj < 2; ++bj) { l[bj][0] = 1.0f - *(const f32x4*)(lb + col0 + bj * 32); l[bj][1] = 1.0f - *(const f32x4*)(lb + col0 + bj * 32 + 4); }
; #pragma unroll
;             for (int ai = 0; ai < 2; ++ai)
; #pragma unroll
;                 for (int m = 0; m < 4; ++m) { u32x4 w[2];
; #pragma unroll
;                     for (int bj = 0; bj < 2; ++bj) { f32x4 v0 = acc[ai][bj][m][0], v1 = acc[ai][bj][m][1];
; #pragma unroll
;                         for (int j = 0; j < 4; ++j) { v0[j] = l[bj][0][j] * sigmoidf_(-v0[j]); v1[j] = l[bj][1][j] * sigmoidf_(-v1[j]); }
;                         w[bj].x = pkh2(v0[0], v0[1]); w[bj].y = pkh2(v0[2], v0[3]); w[bj].z = pkh2(v1[0], v1[1]); w[bj].w = pkh2(v1[2], v1[3]); }
;                     store_pair((unsigned char*)(F + (size_t)(row0 + ai * 128 + m * 16) * D + col0), (size_t)8 * D * 2, 64, w[0], w[1], fr >= 8); }
	v_rcp_f32_e32 v63, v63
	v_rcp_f32_e32 v60, v60
	v_rcp_f32_e32 v64, v64
	v_rcp_f32_e32 v61, v61
	v_rcp_f32_e32 v65, v65
	v_add_f32_e32 v53, 1.0, v57
	v_add_f32_e32 v57, 1.0, v58
	v_rcp_f32_e32 v50, v50
	v_rcp_f32_e32 v54, v54
	v_rcp_f32_e32 v51, v51
	v_rcp_f32_e32 v55, v55
	v_rcp_f32_e32 v52, v52
	v_rcp_f32_e32 v56, v56
	v_rcp_f32_e32 v53, v53
	v_rcp_f32_e32 v57, v57
	v_pk_mul_f32 v[62:63], v[62:63], v[150:151]
	v_pk_mul_f32 v[60:61], v[60:61], v[126:127]
	v_pk_mul_f32 v[64:65], v[64:65], v[128:129]
	v_cvt_pk_f16_f32 v67, v60, v61
	v_cvt_pk_f16_f32 v62, v62, v63
	v_cvt_pk_f16_f32 v63, v64, v65
	v_pk_mul_f32 v[50:51], v[50:51], v[122:123]
	v_pk_mul_f32 v[54:55], v[54:55], v[124:125]
	v_pk_mul_f32 v[52:53], v[52:53], v[114:115]
	v_pk_mul_f32 v[56:57], v[56:57], v[118:119]
	v_cvt_pk_f16_f32 v50, v50, v51
	v_cvt_pk_f16_f32 v51, v52, v53
	v_cvt_pk_f16_f32 v52, v54, v55
	v_cvt_pk_f16_f32 v53, v56, v57
	v_lshl_add_u64 v[58:59], v[116:117], 0, s[6:7]
	s_mov_b64 vcc, s[8:9]
	v_mov_b32_dpp v64, v50 row_ror:8 row_mask:0xf bank_mask:0xf bound_ctrl:1
	v_mov_b32_dpp v65, v51 row_ror:8 row_mask:0xf bank_mask:0xf bound_ctrl:1
	v_mov_b32_dpp v68, v52 row_ror:8 row_mask:0xf bank_mask:0xf bound_ctrl:1
	v_mov_b32_dpp v69, v53 row_ror:8 row_mask:0xf bank_mask:0xf bound_ctrl:1
	v_lshl_add_u64 v[60:61], v[58:59], 0, v[140:141]
	v_cndmask_b32_dpp v53, v63, v53, vcc row_ror:8 row_mask:0xf bank_mask:0xf bound_ctrl:1
	v_cndmask_b32_dpp v52, v62, v52, vcc row_ror:8 row_mask:0xf bank_mask:0xf bound_ctrl:1
	v_cndmask_b32_dpp v51, v67, v51, vcc row_ror:8 row_mask:0xf bank_mask:0xf bound_ctrl:1
	v_cndmask_b32_dpp v50, v66, v50, vcc row_ror:8 row_mask:0xf bank_mask:0xf bound_ctrl:1
	v_lshl_add_u64 v[58:59], v[58:59], 0, v[142:143]
	v_mul_f32_e32 v47, 0x3fb8aa3b, v47
	v_mul_f32_e32 v43, 0x3fb8aa3b, v43
	global_store_dwordx4 v[58:59], v[50:53], off
	v_exp_f32_e32 v47, v47
	v_mul_f32_e32 v46, 0x3fb8aa3b, v46
	v_exp_f32_e32 v50, v43
	v_exp_f32_e32 v46, v46
	v_mul_f32_e32 v48, 0x3fb8aa3b, v48
	v_mul_f32_e32 v44, 0x3fb8aa3b, v44
	v_add_f32_e32 v43, 1.0, v47
	v_add_f32_e32 v47, 1.0, v50
	v_exp_f32_e32 v48, v48
	v_exp_f32_e32 v50, v44
	v_cndmask_b32_e64 v57, v63, v69, s[8:9]
	v_cndmask_b32_e64 v56, v62, v68, s[8:9]
	v_cndmask_b32_e64 v55, v67, v65, s[8:9]
	v_cndmask_b32_e64 v54, v66, v64, s[8:9]
	v_mul_f32_e32 v42, 0x3fb8aa3b, v42
	global_store_dwordx4 v[60:61], v[54:57], off
	v_rcp_f32_e32 v43, v43
	v_mul_f32_e32 v49, 0x3fb8aa3b, v49
	v_exp_f32_e32 v54, v42
	v_add_f32_e32 v42, 1.0, v46
	v_rcp_f32_e32 v42, v42
	v_mul_f32_e32 v45, 0x3fb8aa3b, v45
	v_add_f32_e32 v44, 1.0, v48
	v_add_f32_e32 v48, 1.0, v50
	v_exp_f32_e32 v49, v49
	v_exp_f32_e32 v50, v45
	v_pk_mul_f32 v[42:43], v[42:43], v[148:149]
	v_mul_f32_e32 v38, 0x3fb8aa3b, v38
	v_mul_f32_e32 v34, 0x3fb8aa3b, v34
	v_add_f32_e32 v45, 1.0, v49
	v_add_f32_e32 v49, 1.0, v50
	v_cvt_pk_f16_f32 v50, v42, v43
	v_exp_f32_e32 v38, v38
	v_exp_f32_e32 v42, v34
	v_mul_f32_e32 v39, 0x3fb8aa3b, v39
	v_mul_f32_e32 v35, 0x3fb8aa3b, v35
	v_add_f32_e32 v34, 1.0, v38
	v_add_f32_e32 v38, 1.0, v42
	v_exp_f32_e32 v39, v39
	v_exp_f32_e32 v42, v35
	v_mul_f32_e32 v40, 0x3fb8aa3b, v40
	v_mul_f32_e32 v36, 0x3fb8aa3b, v36
	v_add_f32_e32 v35, 1.0, v39
	v_add_f32_e32 v39, 1.0, v42
	v_exp_f32_e32 v40, v40
	v_exp_f32_e32 v42, v36
	v_mul_f32_e32 v41, 0x3fb8aa3b, v41
	v_mul_f32_e32 v37, 0x3fb8aa3b, v37
	v_add_f32_e32 v36, 1.0, v40
	v_add_f32_e32 v40, 1.0, v42
	v_exp_f32_e32 v41, v41
	v_exp_f32_e32 v42, v37
	v_add_f32_e32 v46, 1.0, v54
	v_rcp_f32_e32 v46, v46
	v_rcp_f32_e32 v47, v47
	v_rcp_f32_e32 v44, v44
	v_rcp_f32_e32 v48, v48
	v_rcp_f32_e32 v45, v45
	v_rcp_f32_e32 v49, v49
	v_add_f32_e32 v37, 1.0, v41
	v_add_f32_e32 v41, 1.0, v42
	v_rcp_f32_e32 v34, v34
	v_rcp_f32_e32 v38, v38
	v_rcp_f32_e32 v35, v35
	v_rcp_f32_e32 v39, v39
	v_rcp_f32_e32 v36, v36
	v_rcp_f32_e32 v40, v40
	v_rcp_f32_e32 v37, v37
	v_rcp_f32_e32 v41, v41
	v_pk_mul_f32 v[46:47], v[46:47], v[150:151]
	v_pk_mul_f32 v[44:45], v[44:45], v[126:127]
	v_pk_mul_f32 v[48:49], v[48:49], v[128:129]
	v_cvt_pk_f16_f32 v51, v44, v45
	v_cvt_pk_f16_f32 v46, v46, v47
	v_cvt_pk_f16_f32 v47, v48, v49
	v_pk_mul_f32 v[34:35], v[34:35], v[122:123]
	v_pk_mul_f32 v[38:39], v[38:39], v[124:125]
	v_pk_mul_f32 v[36:37], v[36:37], v[114:115]
	v_pk_mul_f32 v[40:41], v[40:41], v[118:119]
	v_cvt_pk_f16_f32 v34, v34, v35
	v_cvt_pk_f16_f32 v35, v36, v37
	v_cvt_pk_f16_f32 v36, v38, v39
	v_cvt_pk_f16_f32 v37, v40, v41
	v_lshl_add_u64 v[42:43], v[116:117], 0, s[14:15]
	s_mov_b64 vcc, s[8:9]
	v_mov_b32_dpp v48, v34 row_ror:8 row_mask:0xf bank_mask:0xf bound_ctrl:1
	v_mov_b32_dpp v49, v35 row_ror:8 row_mask:0xf bank_mask:0xf bound_ctrl:1
	v_mov_b32_dpp v52, v36 row_ror:8 row_mask:0xf bank_mask:0xf bound_ctrl:1
	v_mov_b32_dpp v53, v37 row_ror:8 row_mask:0xf bank_mask:0xf bound_ctrl:1
	v_lshl_add_u64 v[44:45], v[42:43], 0, v[140:141]
	v_cndmask_b32_dpp v37, v47, v37, vcc row_ror:8 row_mask:0xf bank_mask:0xf bound_ctrl:1
	v_cndmask_b32_dpp v36, v46, v36, vcc row_ror:8 row_mask:0xf bank_mask:0xf bound_ctrl:1
	v_cndmask_b32_dpp v35, v51, v35, vcc row_ror:8 row_mask:0xf bank_mask:0xf bound_ctrl:1
	v_cndmask_b32_dpp v34, v50, v34, vcc row_ror:8 row_mask:0xf bank_mask:0xf bound_ctrl:1
	v_lshl_add_u64 v[42:43], v[42:43], 0, v[142:143]
	v_mul_f32_e32 v31, 0x3fb8aa3b, v31
	v_mul_f32_e32 v27, 0x3fb8aa3b, v27
	global_store_dwordx4 v[42:43], v[34:37], off
	v_exp_f32_e32 v31, v31
	v_mul_f32_e32 v30, 0x3fb8aa3b, v30
	v_exp_f32_e32 v34, v27
	v_exp_f32_e32 v30, v30
	v_mul_f32_e32 v32, 0x3fb8aa3b, v32
	v_mul_f32_e32 v28, 0x3fb8aa3b, v28
	v_add_f32_e32 v27, 1.0, v31
	v_add_f32_e32 v31, 1.0, v34
	v_exp_f32_e32 v32, v32
	v_exp_f32_e32 v34, v28
; __device__ __forceinline__ unsigned pkh2(float lo, float hi) { const f32x2 v = {lo, hi}; return __builtin_bit_cast(unsigned, __builtin_convertvector(v, f16x2_t)); }
; __device__ __forceinline__ float sigmoidf_(float x) { return __builtin_amdgcn_rcpf(1.0f + __expf(-x)); }
; __device__ __forceinline__ u32x4 ror8(u32x4 v) { u32x4 r;
; #pragma unroll
;     for (int i = 0; i < 4; ++i) r[i] = (unsigned)__builtin_amdgcn_mov_dpp((int)v[i], 0x128, 0xf, 0xf, true);
;     return r; }
; __device__ __forceinline__ void store_pair(unsigned char* own, size_t stride8, int hi_off, u32x4 lo, u32x4 hi, bool upper) {
;     const u32x4 tlo = ror8(lo), thi = ror8(hi);
;     const u32x4 A = upper ? thi : lo, B = upper ? hi : tlo;
;     unsigned char* pa = upper ? own - stride8 + hi_off : own;
;     unsigned char* pb = upper ? own + hi_off : own + stride8;
;     *(u32x4*)pa = A; *(u32x4*)pb = B;
; }
;     __device__ __forceinline__ void operator()(const f32x4 (&acc)[2][2][4][2], const Unit& u, int wr, int wc, int fr, int fq) const {
;     ...
;         if (t == 1) {
;             f32x4 l[2][2];
; #pragma unroll
;             for (int bj = 0; bj < 2; ++bj) { l[bj][0] = 1.0f - *(const f32x4*)(lb + col0 + bj * 32); l[bj][1] = 1.0f - *(const f32x4*)(lb + col0 + bj * 32 + 4); }
; #pragma unroll
;             for (int ai = 0; ai < 2; ++ai)
; #pragma unroll
;                 for (int m = 0; m < 4; ++m) { u32x4 w[2];
; #pragma unroll
;                     for (int bj = 0; bj < 2; ++bj) { f32x4 v0 = acc[ai][bj][m][0], v1 = acc[ai][bj][m][1];
; #pragma unroll
;                         for (int j = 0; j < 4; ++j) { v0[j] = l[bj][0][j] * sigmoidf_(-v0[j]); v1[j] = l[bj][1][j] * sigmoidf_(-v1[j]); }
;                         w[bj].x = pkh2(v0[0], v0[1]); w[bj].y = pkh2(v0[2], v0[3]); w[bj].z = pkh2(v1[0], v1[1]); w[bj].w = pkh2(v1[2], v1[3]); }
;                     store_pair((unsigned char*)(F + (size_t)(row0 + ai * 128 + m * 16) * D + col0), (size_t)8 * D * 2, 64, w[0], w[1], fr >= 8); }
	v_cndmask_b32_e64 v41, v47, v53, s[8:9]
	v_cndmask_b32_e64 v40, v46, v52, s[8:9]
	v_cndmask_b32_e64 v39, v51, v49, s[8:9]
	v_cndmask_b32_e64 v38, v50, v48, s[8:9]
	v_mul_f32_e32 v26, 0x3fb8aa3b, v26
	global_store_dwordx4 v[44:45], v[38:41], off
	v_rcp_f32_e32 v27, v27
	v_mul_f32_e32 v33, 0x3fb8aa3b, v33
	v_exp_f32_e32 v38, v26
	v_add_f32_e32 v26, 1.0, v30
	v_rcp_f32_e32 v26, v26
	v_mul_f32_e32 v29, 0x3fb8aa3b, v29
	v_add_f32_e32 v28, 1.0, v32
	v_add_f32_e32 v32, 1.0, v34
	v_exp_f32_e32 v33, v33
	v_exp_f32_e32 v34, v29
	v_pk_mul_f32 v[26:27], v[26:27], v[148:149]
	v_mul_f32_e32 v22, 0x3fb8aa3b, v22
	v_mul_f32_e32 v18, 0x3fb8aa3b, v18
	v_add_f32_e32 v29, 1.0, v33
	v_add_f32_e32 v33, 1.0, v34
	v_cvt_pk_f16_f32 v34, v26, v27
	v_exp_f32_e32 v22, v22
	v_exp_f32_e32 v26, v18
	v_mul_f32_e32 v23, 0x3fb8aa3b, v23
	v_mul_f32_e32 v19, 0x3fb8aa3b, v19
	v_add_f32_e32 v18, 1.0, v22
	v_add_f32_e32 v22, 1.0, v26
	v_exp_f32_e32 v23, v23
	v_exp_f32_e32 v26, v19
	v_mul_f32_e32 v24, 0x3fb8aa3b, v24
	v_mul_f32_e32 v20, 0x3fb8aa3b, v20
	v_add_f32_e32 v19, 1.0, v23
	v_add_f32_e32 v23, 1.0, v26
	v_exp_f32_e32 v24, v24
	v_exp_f32_e32 v26, v20
	v_mul_f32_e32 v25, 0x3fb8aa3b, v25
	v_mul_f32_e32 v21, 0x3fb8aa3b, v21
	v_add_f32_e32 v20, 1.0, v24
	v_add_f32_e32 v24, 1.0, v26
	v_exp_f32_e32 v25, v25
	v_exp_f32_e32 v26, v21
	v_add_f32_e32 v30, 1.0, v38
	v_rcp_f32_e32 v30, v30
	v_rcp_f32_e32 v31, v31
	v_rcp_f32_e32 v28, v28
	v_rcp_f32_e32 v32, v32
	v_rcp_f32_e32 v29, v29
	v_rcp_f32_e32 v33, v33
	v_add_f32_e32 v21, 1.0, v25
	v_add_f32_e32 v25, 1.0, v26
	v_rcp_f32_e32 v18, v18
	v_rcp_f32_e32 v22, v22
	v_rcp_f32_e32 v19, v19
	v_rcp_f32_e32 v23, v23
	v_rcp_f32_e32 v20, v20
	v_rcp_f32_e32 v24, v24
	v_rcp_f32_e32 v21, v21
	v_rcp_f32_e32 v25, v25
	v_pk_mul_f32 v[30:31], v[30:31], v[150:151]
	v_pk_mul_f32 v[28:29], v[28:29], v[126:127]
	v_pk_mul_f32 v[32:33], v[32:33], v[128:129]
	v_cvt_pk_f16_f32 v35, v28, v29
	v_cvt_pk_f16_f32 v30, v30, v31
	v_cvt_pk_f16_f32 v31, v32, v33
	v_pk_mul_f32 v[18:19], v[18:19], v[122:123]
	v_pk_mul_f32 v[22:23], v[22:23], v[124:125]
	v_pk_mul_f32 v[20:21], v[20:21], v[114:115]
	v_pk_mul_f32 v[24:25], v[24:25], v[118:119]
	v_cvt_pk_f16_f32 v18, v18, v19
	v_cvt_pk_f16_f32 v19, v20, v21
	v_cvt_pk_f16_f32 v20, v22, v23
	v_cvt_pk_f16_f32 v21, v24, v25
	v_lshl_add_u64 v[26:27], v[116:117], 0, s[16:17]
	s_mov_b64 vcc, s[8:9]
	v_mov_b32_dpp v32, v18 row_ror:8 row_mask:0xf bank_mask:0xf bound_ctrl:1
	v_mov_b32_dpp v33, v19 row_ror:8 row_mask:0xf bank_mask:0xf bound_ctrl:1
	v_mov_b32_dpp v36, v20 row_ror:8 row_mask:0xf bank_mask:0xf bound_ctrl:1
	v_mov_b32_dpp v37, v21 row_ror:8 row_mask:0xf bank_mask:0xf bound_ctrl:1
	v_lshl_add_u64 v[28:29], v[26:27], 0, v[140:141]
	v_cndmask_b32_dpp v21, v31, v21, vcc row_ror:8 row_mask:0xf bank_mask:0xf bound_ctrl:1
	v_cndmask_b32_dpp v20, v30, v20, vcc row_ror:8 row_mask:0xf bank_mask:0xf bound_ctrl:1
	v_cndmask_b32_dpp v19, v35, v19, vcc row_ror:8 row_mask:0xf bank_mask:0xf bound_ctrl:1
	v_cndmask_b32_dpp v18, v34, v18, vcc row_ror:8 row_mask:0xf bank_mask:0xf bound_ctrl:1
	v_lshl_add_u64 v[26:27], v[26:27], 0, v[142:143]
	v_mul_f32_e32 v15, 0x3fb8aa3b, v15
	v_mul_f32_e32 v11, 0x3fb8aa3b, v11
	global_store_dwordx4 v[26:27], v[18:21], off
	v_exp_f32_e32 v15, v15
	v_mul_f32_e32 v14, 0x3fb8aa3b, v14
	v_exp_f32_e32 v18, v11
	v_exp_f32_e32 v14, v14
	v_mul_f32_e32 v16, 0x3fb8aa3b, v16
	v_mul_f32_e32 v12, 0x3fb8aa3b, v12
	v_add_f32_e32 v11, 1.0, v15
	v_add_f32_e32 v15, 1.0, v18
	v_exp_f32_e32 v16, v16
	v_exp_f32_e32 v18, v12
	v_cndmask_b32_e64 v25, v31, v37, s[8:9]
; __device__ __forceinline__ unsigned pkh2(float lo, float hi) { const f32x2 v = {lo, hi}; return __builtin_bit_cast(unsigned, __builtin_convertvector(v, f16x2_t)); }
; __device__ __forceinline__ float sigmoidf_(float x) { return __builtin_amdgcn_rcpf(1.0f + __expf(-x)); }
; __device__ __forceinline__ u32x4 ror8(u32x4 v) { u32x4 r;
; #pragma unroll
;     for (int i = 0; i < 4; ++i) r[i] = (unsigned)__builtin_amdgcn_mov_dpp((int)v[i], 0x128, 0xf, 0xf, true);
;     return r; }
; __device__ __forceinline__ void store_pair(unsigned char* own, size_t stride8, int hi_off, u32x4 lo, u32x4 hi, bool upper) {
;     const u32x4 tlo = ror8(lo), thi = ror8(hi);
;     const u32x4 A = upper ? thi : lo, B = upper ? hi : tlo;
;     unsigned char* pa = upper ? own - stride8 + hi_off : own;
;     unsigned char* pb = upper ? own + hi_off : own + stride8;
;     *(u32x4*)pa = A; *(u32x4*)pb = B;
; }
;     __device__ __forceinline__ void operator()(const f32x4 (&acc)[2][2][4][2], const Unit& u, int wr, int wc, int fr, int fq) const {
;     ...
;         if (t == 1) {
;             f32x4 l[2][2];
; #pragma unroll
;             for (int bj = 0; bj < 2; ++bj) { l[bj][0] = 1.0f - *(const f32x4*)(lb + col0 + bj * 32); l[bj][1] = 1.0f - *(const f32x4*)(lb + col0 + bj * 32 + 4); }
; #pragma unroll
;             for (int ai = 0; ai < 2; ++ai)
; #pragma unroll
;                 for (int m = 0; m < 4; ++m) { u32x4 w[2];
; #pragma unroll
;                     for (int bj = 0; bj < 2; ++bj) { f32x4 v0 = acc[ai][bj][m][0], v1 = acc[ai][bj][m][1];
; #pragma unroll
;                         for (int j = 0; j < 4; ++j) { v0[j] = l[bj][0][j] * sigmoidf_(-v0[j]); v1[j] = l[bj][1][j] * sigmoidf_(-v1[j]); }
;                         w[bj].x = pkh2(v0[0], v0[1]); w[bj].y = pkh2(v0[2], v0[3]); w[bj].z = pkh2(v1[0], v1[1]); w[bj].w = pkh2(v1[2], v1[3]); }
;                     store_pair((unsigned char*)(F + (size_t)(row0 + ai * 128 + m * 16) * D + col0), (size_t)8 * D * 2, 64, w[0], w[1], fr >= 8); }
	v_cndmask_b32_e64 v24, v30, v36, s[8:9]
	v_cndmask_b32_e64 v23, v35, v33, s[8:9]
	v_cndmask_b32_e64 v22, v34, v32, s[8:9]
	v_mul_f32_e32 v10, 0x3fb8aa3b, v10
	global_store_dwordx4 v[28:29], v[22:25], off
	v_rcp_f32_e32 v11, v11
	v_mul_f32_e32 v17, 0x3fb8aa3b, v17
	v_exp_f32_e32 v22, v10
	v_add_f32_e32 v10, 1.0, v14
	v_rcp_f32_e32 v10, v10
	v_mul_f32_e32 v13, 0x3fb8aa3b, v13
	v_add_f32_e32 v12, 1.0, v16
	v_add_f32_e32 v16, 1.0, v18
	v_exp_f32_e32 v17, v17
	v_exp_f32_e32 v18, v13
	v_pk_mul_f32 v[10:11], v[10:11], v[148:149]
	v_mul_f32_e32 v6, 0x3fb8aa3b, v6
	v_mul_f32_e32 v2, 0x3fb8aa3b, v2
	v_add_f32_e32 v13, 1.0, v17
	v_add_f32_e32 v17, 1.0, v18
	v_cvt_pk_f16_f32 v18, v10, v11
	v_exp_f32_e32 v6, v6
	v_exp_f32_e32 v10, v2
	v_mul_f32_e32 v7, 0x3fb8aa3b, v7
	v_mul_f32_e32 v3, 0x3fb8aa3b, v3
	v_add_f32_e32 v2, 1.0, v6
	v_add_f32_e32 v6, 1.0, v10
	v_exp_f32_e32 v7, v7
	v_exp_f32_e32 v10, v3
	v_mul_f32_e32 v8, 0x3fb8aa3b, v8
	v_mul_f32_e32 v4, 0x3fb8aa3b, v4
	v_add_f32_e32 v3, 1.0, v7
	v_add_f32_e32 v7, 1.0, v10
	v_exp_f32_e32 v8, v8
	v_exp_f32_e32 v10, v4
	v_mul_f32_e32 v9, 0x3fb8aa3b, v9
	v_mul_f32_e32 v5, 0x3fb8aa3b, v5
	v_add_f32_e32 v4, 1.0, v8
	v_add_f32_e32 v8, 1.0, v10
	v_exp_f32_e32 v9, v9
	v_exp_f32_e32 v10, v5
	v_add_f32_e32 v14, 1.0, v22
	v_rcp_f32_e32 v14, v14
	v_add_f32_e32 v5, 1.0, v9
	v_add_f32_e32 v9, 1.0, v10
	v_rcp_f32_e32 v15, v15
	v_rcp_f32_e32 v12, v12
	v_rcp_f32_e32 v16, v16
	v_rcp_f32_e32 v13, v13
	v_rcp_f32_e32 v17, v17
	v_rcp_f32_e32 v2, v2
	v_rcp_f32_e32 v6, v6
	v_rcp_f32_e32 v3, v3
	v_rcp_f32_e32 v7, v7
	v_rcp_f32_e32 v4, v4
	v_rcp_f32_e32 v8, v8
	v_rcp_f32_e32 v5, v5
	v_rcp_f32_e32 v9, v9
	v_pk_mul_f32 v[14:15], v[14:15], v[150:151]
	v_pk_mul_f32 v[12:13], v[12:13], v[126:127]
	v_pk_mul_f32 v[16:17], v[16:17], v[128:129]
	v_pk_mul_f32 v[2:3], v[2:3], v[122:123]
	v_pk_mul_f32 v[6:7], v[6:7], v[124:125]
	v_pk_mul_f32 v[4:5], v[4:5], v[114:115]
	v_pk_mul_f32 v[8:9], v[8:9], v[118:119]
	v_cvt_pk_f16_f32 v19, v12, v13
	v_cvt_pk_f16_f32 v14, v14, v15
	v_cvt_pk_f16_f32 v15, v16, v17
	v_cvt_pk_f16_f32 v2, v2, v3
	v_cvt_pk_f16_f32 v3, v4, v5
	v_cvt_pk_f16_f32 v4, v6, v7
	v_cvt_pk_f16_f32 v5, v8, v9
	s_mov_b64 vcc, s[8:9]
	v_lshl_add_u64 v[10:11], v[116:117], 0, s[18:19]
	v_mov_b32_dpp v16, v2 row_ror:8 row_mask:0xf bank_mask:0xf bound_ctrl:1
	v_mov_b32_dpp v17, v3 row_ror:8 row_mask:0xf bank_mask:0xf bound_ctrl:1
	v_mov_b32_dpp v20, v4 row_ror:8 row_mask:0xf bank_mask:0xf bound_ctrl:1
	v_mov_b32_dpp v21, v5 row_ror:8 row_mask:0xf bank_mask:0xf bound_ctrl:1
	v_cndmask_b32_e64 v169, v175, v169, s[8:9]
	v_cndmask_b32_e64 v167, v159, v167, s[8:9]
	v_cndmask_b32_dpp v166, v174, v166, vcc row_ror:8 row_mask:0xf bank_mask:0xf bound_ctrl:1
	v_lshl_add_u64 v[158:159], v[116:117], 0, v[142:143]
	v_lshl_add_u64 v[12:13], v[10:11], 0, v[140:141]
	v_cndmask_b32_dpp v5, v15, v5, vcc row_ror:8 row_mask:0xf bank_mask:0xf bound_ctrl:1
	v_cndmask_b32_dpp v4, v14, v4, vcc row_ror:8 row_mask:0xf bank_mask:0xf bound_ctrl:1
	v_cndmask_b32_dpp v3, v19, v3, vcc row_ror:8 row_mask:0xf bank_mask:0xf bound_ctrl:1
	v_cndmask_b32_dpp v2, v18, v2, vcc row_ror:8 row_mask:0xf bank_mask:0xf bound_ctrl:1
	v_cndmask_b32_e64 v9, v15, v21, s[8:9]
	v_cndmask_b32_e64 v8, v14, v20, s[8:9]
	v_cndmask_b32_e64 v7, v19, v17, s[8:9]
	v_cndmask_b32_e64 v6, v18, v16, s[8:9]
	global_store_dwordx4 v[158:159], v[166:169], off
	v_lshl_add_u64 v[10:11], v[10:11], 0, v[142:143]
	global_store_dwordx4 v[12:13], v[6:9], off
	global_store_dwordx4 v[10:11], v[2:5], off
	s_andn2_b64 vcc, exec, s[26:27]
	s_mov_b64 s[4:5], -1
	s_cbranch_vccnz .LBB0_1351

; __device__ __forceinline__ unsigned pk2(float lo, float hi) { const f32x2 v = {lo, hi}; return __builtin_bit_cast(unsigned, __builtin_convertvector(v, bf16x2_t)); }
; __device__ __forceinline__ u32x4 ror8(u32x4 v) { u32x4 r;
; #pragma unroll
;     for (int i = 0; i < 4; ++i) r[i] = (unsigned)__builtin_amdgcn_mov_dpp((int)v[i], 0x128, 0xf, 0xf, true);
;     return r; }
; __device__ __forceinline__ void store_pair(unsigned char* own, size_t stride8, int hi_off, u32x4 lo, u32x4 hi, bool upper) {
;     const u32x4 tlo = ror8(lo), thi = ror8(hi);
;     const u32x4 A = upper ? thi : lo, B = upper ? hi : tlo;
;     unsigned char* pa = upper ? own - stride8 + hi_off : own;
;     unsigned char* pb = upper ? own + hi_off : own + stride8;
;     *(u32x4*)pa = A; *(u32x4*)pb = B;
; }
;     __device__ __forceinline__ void operator()(const f32x4 (&acc)[2][2][4][2], const Unit& u, int wr, int wc, int fr, int fq) const {
;         const int row0 = u.pm * 256 + wr * 64 + fr, col0 = u.pn * 256 + wc * 64 + 8 * fq;
;         bf16_t* base = u.part == 0 ? Z + (size_t)row0 * D + col0 : P + ((size_t)(u.part - 1) * MS + (row0 - MP)) * D + col0;
; #pragma unroll
;         for (int ai = 0; ai < 2; ++ai)
; #pragma unroll
;             for (int m = 0; m < 4; ++m) { u32x4 w[2];
; #pragma unroll
;                 for (int bj = 0; bj < 2; ++bj) { const f32x4 v0 = acc[ai][bj][m][0], v1 = acc[ai][bj][m][1]; w[bj].x = pk2(v0[0], v0[1]); w[bj].y = pk2(v0[2], v0[3]); w[bj].z = pk2(v1[0], v1[1]); w[bj].w = pk2(v1[2], v1[3]); }
;                 store_pair((unsigned char*)(base + (size_t)(ai * 128 + m * 16) * D), (size_t)8 * D * 2, 64, w[0], w[1], fr >= 8); }
;     }
.LBB0_1719:
	v_lshl_add_u32 v147, s48, 8, v1
	v_add_u32_e32 v148, 0xffffe000, v147
	v_sub_co_u32_e64 v146, vcc, s46, 1
	v_mov_b32_e32 v149, s91
	s_nop 0
	v_cndmask_b32_e32 v148, v148, v147, vcc
	v_ashrrev_i32_e32 v147, 31, v146
	v_lshlrev_b64 v[146:147], 23, v[146:147]
	v_lshl_add_u64 v[146:147], s[12:13], 0, v[146:147]
	v_cndmask_b32_e32 v147, v147, v149, vcc
	v_mov_b32_e32 v149, s90
	v_cndmask_b32_e32 v146, v146, v149, vcc
	v_ashrrev_i32_e32 v149, 31, v148
	v_lshl_or_b32 v156, s78, 8, v151
	v_lshlrev_b64 v[148:149], 12, v[148:149]
	v_lshl_add_u64 v[146:147], v[146:147], 0, v[148:149]
	v_ashrrev_i32_e32 v157, 31, v156
	v_cvt_pk_bf16_f32 v126, v126, v127
	v_cvt_pk_bf16_f32 v127, v128, v129
	v_cvt_pk_bf16_f32 v128, v122, v123
	v_cvt_pk_bf16_f32 v124, v124, v125
	v_cvt_pk_bf16_f32 v118, v118, v119
	v_cvt_pk_bf16_f32 v119, v120, v121
	v_cvt_pk_bf16_f32 v114, v114, v115
	v_cvt_pk_bf16_f32 v115, v116, v117
	v_lshl_add_u64 v[146:147], v[156:157], 1, v[146:147]
	s_mov_b64 vcc, s[8:9]
	v_mov_b32_dpp v125, v118 row_ror:8 row_mask:0xf bank_mask:0xf bound_ctrl:1
	v_mov_b32_dpp v129, v119 row_ror:8 row_mask:0xf bank_mask:0xf bound_ctrl:1
	v_mov_b32_dpp v148, v114 row_ror:8 row_mask:0xf bank_mask:0xf bound_ctrl:1
	v_mov_b32_dpp v149, v115 row_ror:8 row_mask:0xf bank_mask:0xf bound_ctrl:1
	v_lshl_add_u64 v[122:123], v[146:147], 0, v[138:139]
	v_cndmask_b32_dpp v117, v124, v115, vcc row_ror:8 row_mask:0xf bank_mask:0xf bound_ctrl:1
	v_cndmask_b32_dpp v116, v128, v114, vcc row_ror:8 row_mask:0xf bank_mask:0xf bound_ctrl:1
	v_cndmask_b32_dpp v115, v127, v119, vcc row_ror:8 row_mask:0xf bank_mask:0xf bound_ctrl:1
	v_cndmask_b32_dpp v114, v126, v118, vcc row_ror:8 row_mask:0xf bank_mask:0xf bound_ctrl:1
	v_cndmask_b32_e64 v121, v124, v149, s[8:9]
	v_cndmask_b32_e64 v120, v128, v148, s[8:9]
	v_cndmask_b32_e64 v119, v127, v129, s[8:9]
	v_cndmask_b32_e64 v118, v126, v125, s[8:9]
	v_cvt_pk_bf16_f32 v110, v110, v111
	v_cvt_pk_bf16_f32 v111, v112, v113
	v_cvt_pk_bf16_f32 v112, v106, v107
	v_cvt_pk_bf16_f32 v113, v108, v109
	v_cvt_pk_bf16_f32 v102, v102, v103
	v_cvt_pk_bf16_f32 v103, v104, v105
	v_cvt_pk_bf16_f32 v98, v98, v99
	v_cvt_pk_bf16_f32 v99, v100, v101
	s_mov_b64 s[4:5], 0x10000
	v_lshl_add_u64 v[124:125], v[146:147], 0, v[140:141]
	global_store_dwordx4 v[122:123], v[118:121], off
	global_store_dwordx4 v[124:125], v[114:117], off
	v_lshl_add_u64 v[106:107], v[146:147], 0, s[4:5]
	s_mov_b64 vcc, s[8:9]
	v_mov_b32_dpp v114, v102 row_ror:8 row_mask:0xf bank_mask:0xf bound_ctrl:1
	v_mov_b32_dpp v115, v103 row_ror:8 row_mask:0xf bank_mask:0xf bound_ctrl:1
	v_mov_b32_dpp v116, v98 row_ror:8 row_mask:0xf bank_mask:0xf bound_ctrl:1
	v_mov_b32_dpp v117, v99 row_ror:8 row_mask:0xf bank_mask:0xf bound_ctrl:1
	v_lshl_add_u64 v[108:109], v[106:107], 0, v[138:139]
	v_cndmask_b32_dpp v101, v113, v99, vcc row_ror:8 row_mask:0xf bank_mask:0xf bound_ctrl:1
	v_cndmask_b32_dpp v100, v112, v98, vcc row_ror:8 row_mask:0xf bank_mask:0xf bound_ctrl:1
	v_cndmask_b32_dpp v99, v111, v103, vcc row_ror:8 row_mask:0xf bank_mask:0xf bound_ctrl:1
	v_cndmask_b32_dpp v98, v110, v102, vcc row_ror:8 row_mask:0xf bank_mask:0xf bound_ctrl:1
	v_cndmask_b32_e64 v105, v113, v117, s[8:9]
	v_cndmask_b32_e64 v104, v112, v116, s[8:9]
	v_cndmask_b32_e64 v103, v111, v115, s[8:9]
	v_cndmask_b32_e64 v102, v110, v114, s[8:9]
	v_cvt_pk_bf16_f32 v94, v94, v95
	v_cvt_pk_bf16_f32 v95, v96, v97
	v_cvt_pk_bf16_f32 v96, v90, v91
	v_cvt_pk_bf16_f32 v97, v92, v93
	v_cvt_pk_bf16_f32 v86, v86, v87
	v_cvt_pk_bf16_f32 v87, v88, v89
	v_cvt_pk_bf16_f32 v82, v82, v83
	v_cvt_pk_bf16_f32 v83, v84, v85
	s_mov_b64 s[4:5], 0x20000
	v_lshl_add_u64 v[106:107], v[106:107], 0, v[140:141]
	global_store_dwordx4 v[108:109], v[102:105], off
	global_store_dwordx4 v[106:107], v[98:101], off
	v_lshl_add_u64 v[90:91], v[146:147], 0, s[4:5]
	s_mov_b64 vcc, s[8:9]
	v_mov_b32_dpp v98, v86 row_ror:8 row_mask:0xf bank_mask:0xf bound_ctrl:1
	v_mov_b32_dpp v99, v87 row_ror:8 row_mask:0xf bank_mask:0xf bound_ctrl:1
	v_mov_b32_dpp v100, v82 row_ror:8 row_mask:0xf bank_mask:0xf bound_ctrl:1
	v_mov_b32_dpp v101, v83 row_ror:8 row_mask:0xf bank_mask:0xf bound_ctrl:1
	v_lshl_add_u64 v[92:93], v[90:91], 0, v[138:139]
	v_cndmask_b32_dpp v85, v97, v83, vcc row_ror:8 row_mask:0xf bank_mask:0xf bound_ctrl:1
	v_cndmask_b32_dpp v84, v96, v82, vcc row_ror:8 row_mask:0xf bank_mask:0xf bound_ctrl:1
	v_cndmask_b32_dpp v83, v95, v87, vcc row_ror:8 row_mask:0xf bank_mask:0xf bound_ctrl:1
	v_cndmask_b32_dpp v82, v94, v86, vcc row_ror:8 row_mask:0xf bank_mask:0xf bound_ctrl:1
	v_cndmask_b32_e64 v89, v97, v101, s[8:9]
	v_cndmask_b32_e64 v88, v96, v100, s[8:9]
	v_cndmask_b32_e64 v87, v95, v99, s[8:9]
	v_cndmask_b32_e64 v86, v94, v98, s[8:9]
	v_cvt_pk_bf16_f32 v78, v78, v79
	v_cvt_pk_bf16_f32 v79, v80, v81
	v_cvt_pk_bf16_f32 v80, v74, v75
	v_cvt_pk_bf16_f32 v81, v76, v77
	v_cvt_pk_bf16_f32 v70, v70, v71
	v_cvt_pk_bf16_f32 v71, v72, v73
	v_cvt_pk_bf16_f32 v66, v66, v67
	v_cvt_pk_bf16_f32 v67, v68, v69
	s_mov_b64 s[4:5], 0x30000
	v_lshl_add_u64 v[90:91], v[90:91], 0, v[140:141]
	global_store_dwordx4 v[92:93], v[86:89], off
	global_store_dwordx4 v[90:91], v[82:85], off
	v_lshl_add_u64 v[74:75], v[146:147], 0, s[4:5]
	s_mov_b64 vcc, s[8:9]
	v_mov_b32_dpp v82, v70 row_ror:8 row_mask:0xf bank_mask:0xf bound_ctrl:1
	v_mov_b32_dpp v83, v71 row_ror:8 row_mask:0xf bank_mask:0xf bound_ctrl:1
	v_mov_b32_dpp v84, v66 row_ror:8 row_mask:0xf bank_mask:0xf bound_ctrl:1
	v_mov_b32_dpp v85, v67 row_ror:8 row_mask:0xf bank_mask:0xf bound_ctrl:1
	v_lshl_add_u64 v[76:77], v[74:75], 0, v[138:139]
	v_cndmask_b32_dpp v69, v81, v67, vcc row_ror:8 row_mask:0xf bank_mask:0xf bound_ctrl:1
; __device__ __forceinline__ unsigned pk2(float lo, float hi) { const f32x2 v = {lo, hi}; return __builtin_bit_cast(unsigned, __builtin_convertvector(v, bf16x2_t)); }
; __device__ __forceinline__ u32x4 ror8(u32x4 v) { u32x4 r;
; #pragma unroll
;     for (int i = 0; i < 4; ++i) r[i] = (unsigned)__builtin_amdgcn_mov_dpp((int)v[i], 0x128, 0xf, 0xf, true);
;     return r; }
; __device__ __forceinline__ void store_pair(unsigned char* own, size_t stride8, int hi_off, u32x4 lo, u32x4 hi, bool upper) {
;     const u32x4 tlo = ror8(lo), thi = ror8(hi);
;     const u32x4 A = upper ? thi : lo, B = upper ? hi : tlo;
;     unsigned char* pa = upper ? own - stride8 + hi_off : own;
;     unsigned char* pb = upper ? own + hi_off : own + stride8;
;     *(u32x4*)pa = A; *(u32x4*)pb = B;
; }
;     __device__ __forceinline__ void operator()(const f32x4 (&acc)[2][2][4][2], const Unit& u, int wr, int wc, int fr, int fq) const {
;         const int row0 = u.pm * 256 + wr * 64 + fr, col0 = u.pn * 256 + wc * 64 + 8 * fq;
;         bf16_t* base = u.part == 0 ? Z + (size_t)row0 * D + col0 : P + ((size_t)(u.part - 1) * MS + (row0 - MP)) * D + col0;
; #pragma unroll
;         for (int ai = 0; ai < 2; ++ai)
; #pragma unroll
;             for (int m = 0; m < 4; ++m) { u32x4 w[2];
; #pragma unroll
;                 for (int bj = 0; bj < 2; ++bj) { const f32x4 v0 = acc[ai][bj][m][0], v1 = acc[ai][bj][m][1]; w[bj].x = pk2(v0[0], v0[1]); w[bj].y = pk2(v0[2], v0[3]); w[bj].z = pk2(v1[0], v1[1]); w[bj].w = pk2(v1[2], v1[3]); }
;                 store_pair((unsigned char*)(base + (size_t)(ai * 128 + m * 16) * D), (size_t)8 * D * 2, 64, w[0], w[1], fr >= 8); }
;     }
	v_cndmask_b32_dpp v68, v80, v66, vcc row_ror:8 row_mask:0xf bank_mask:0xf bound_ctrl:1
	v_cndmask_b32_dpp v67, v79, v71, vcc row_ror:8 row_mask:0xf bank_mask:0xf bound_ctrl:1
	v_cndmask_b32_dpp v66, v78, v70, vcc row_ror:8 row_mask:0xf bank_mask:0xf bound_ctrl:1
	v_cndmask_b32_e64 v73, v81, v85, s[8:9]
	v_cndmask_b32_e64 v72, v80, v84, s[8:9]
	v_cndmask_b32_e64 v71, v79, v83, s[8:9]
	v_cndmask_b32_e64 v70, v78, v82, s[8:9]
	v_cvt_pk_bf16_f32 v62, v62, v63
	v_cvt_pk_bf16_f32 v63, v64, v65
	v_cvt_pk_bf16_f32 v64, v58, v59
	v_cvt_pk_bf16_f32 v65, v60, v61
	v_cvt_pk_bf16_f32 v54, v54, v55
	v_cvt_pk_bf16_f32 v55, v56, v57
	v_cvt_pk_bf16_f32 v50, v50, v51
	v_cvt_pk_bf16_f32 v51, v52, v53
	s_mov_b64 s[4:5], 0x80000
	v_lshl_add_u64 v[74:75], v[74:75], 0, v[140:141]
	global_store_dwordx4 v[76:77], v[70:73], off
	global_store_dwordx4 v[74:75], v[66:69], off
	v_lshl_add_u64 v[58:59], v[146:147], 0, s[4:5]
	s_mov_b64 vcc, s[8:9]
	v_mov_b32_dpp v66, v54 row_ror:8 row_mask:0xf bank_mask:0xf bound_ctrl:1
	v_mov_b32_dpp v67, v55 row_ror:8 row_mask:0xf bank_mask:0xf bound_ctrl:1
	v_mov_b32_dpp v68, v50 row_ror:8 row_mask:0xf bank_mask:0xf bound_ctrl:1
	v_mov_b32_dpp v69, v51 row_ror:8 row_mask:0xf bank_mask:0xf bound_ctrl:1
	v_lshl_add_u64 v[60:61], v[58:59], 0, v[138:139]
	v_cndmask_b32_dpp v53, v65, v51, vcc row_ror:8 row_mask:0xf bank_mask:0xf bound_ctrl:1
	v_cndmask_b32_dpp v52, v64, v50, vcc row_ror:8 row_mask:0xf bank_mask:0xf bound_ctrl:1
	v_cndmask_b32_dpp v51, v63, v55, vcc row_ror:8 row_mask:0xf bank_mask:0xf bound_ctrl:1
	v_cndmask_b32_dpp v50, v62, v54, vcc row_ror:8 row_mask:0xf bank_mask:0xf bound_ctrl:1
	v_cndmask_b32_e64 v57, v65, v69, s[8:9]
	v_cndmask_b32_e64 v56, v64, v68, s[8:9]
	v_cndmask_b32_e64 v55, v63, v67, s[8:9]
	v_cndmask_b32_e64 v54, v62, v66, s[8:9]
	v_cvt_pk_bf16_f32 v46, v46, v47
	v_cvt_pk_bf16_f32 v47, v48, v49
	v_cvt_pk_bf16_f32 v48, v42, v43
	v_cvt_pk_bf16_f32 v49, v44, v45
	v_cvt_pk_bf16_f32 v38, v38, v39
	v_cvt_pk_bf16_f32 v39, v40, v41
	v_cvt_pk_bf16_f32 v34, v34, v35
	v_cvt_pk_bf16_f32 v35, v36, v37
	v_lshl_add_u64 v[58:59], v[58:59], 0, v[140:141]
	global_store_dwordx4 v[60:61], v[54:57], off
	global_store_dwordx4 v[58:59], v[50:53], off
	v_lshl_add_u64 v[42:43], v[146:147], 0, s[14:15]
	s_mov_b64 vcc, s[8:9]
	v_mov_b32_dpp v50, v38 row_ror:8 row_mask:0xf bank_mask:0xf bound_ctrl:1
	v_mov_b32_dpp v51, v39 row_ror:8 row_mask:0xf bank_mask:0xf bound_ctrl:1
	v_mov_b32_dpp v52, v34 row_ror:8 row_mask:0xf bank_mask:0xf bound_ctrl:1
	v_mov_b32_dpp v53, v35 row_ror:8 row_mask:0xf bank_mask:0xf bound_ctrl:1
	v_lshl_add_u64 v[44:45], v[42:43], 0, v[138:139]
	v_cndmask_b32_dpp v37, v49, v35, vcc row_ror:8 row_mask:0xf bank_mask:0xf bound_ctrl:1
	v_cndmask_b32_dpp v36, v48, v34, vcc row_ror:8 row_mask:0xf bank_mask:0xf bound_ctrl:1
	v_cndmask_b32_dpp v35, v47, v39, vcc row_ror:8 row_mask:0xf bank_mask:0xf bound_ctrl:1
	v_cndmask_b32_dpp v34, v46, v38, vcc row_ror:8 row_mask:0xf bank_mask:0xf bound_ctrl:1
	v_cndmask_b32_e64 v41, v49, v53, s[8:9]
	v_cndmask_b32_e64 v40, v48, v52, s[8:9]
	v_cndmask_b32_e64 v39, v47, v51, s[8:9]
	v_cndmask_b32_e64 v38, v46, v50, s[8:9]
	v_cvt_pk_bf16_f32 v30, v30, v31
	v_cvt_pk_bf16_f32 v31, v32, v33
	v_cvt_pk_bf16_f32 v32, v26, v27
	v_cvt_pk_bf16_f32 v33, v28, v29
	v_cvt_pk_bf16_f32 v22, v22, v23
	v_cvt_pk_bf16_f32 v23, v24, v25
	v_cvt_pk_bf16_f32 v18, v18, v19
	v_cvt_pk_bf16_f32 v19, v20, v21
	v_lshl_add_u64 v[42:43], v[42:43], 0, v[140:141]
	global_store_dwordx4 v[44:45], v[38:41], off
	global_store_dwordx4 v[42:43], v[34:37], off
	v_lshl_add_u64 v[26:27], v[146:147], 0, s[16:17]
	s_mov_b64 vcc, s[8:9]
	v_mov_b32_dpp v34, v22 row_ror:8 row_mask:0xf bank_mask:0xf bound_ctrl:1
	v_mov_b32_dpp v35, v23 row_ror:8 row_mask:0xf bank_mask:0xf bound_ctrl:1
	v_mov_b32_dpp v36, v18 row_ror:8 row_mask:0xf bank_mask:0xf bound_ctrl:1
	v_mov_b32_dpp v37, v19 row_ror:8 row_mask:0xf bank_mask:0xf bound_ctrl:1
	v_lshl_add_u64 v[28:29], v[26:27], 0, v[138:139]
	v_cndmask_b32_dpp v21, v33, v19, vcc row_ror:8 row_mask:0xf bank_mask:0xf bound_ctrl:1
	v_cndmask_b32_dpp v20, v32, v18, vcc row_ror:8 row_mask:0xf bank_mask:0xf bound_ctrl:1
	v_cndmask_b32_dpp v19, v31, v23, vcc row_ror:8 row_mask:0xf bank_mask:0xf bound_ctrl:1
	v_cndmask_b32_dpp v18, v30, v22, vcc row_ror:8 row_mask:0xf bank_mask:0xf bound_ctrl:1
	v_cndmask_b32_e64 v25, v33, v37, s[8:9]
	v_cndmask_b32_e64 v24, v32, v36, s[8:9]
	v_cndmask_b32_e64 v23, v31, v35, s[8:9]
	v_cndmask_b32_e64 v22, v30, v34, s[8:9]
	v_cvt_pk_bf16_f32 v14, v14, v15
	v_cvt_pk_bf16_f32 v15, v16, v17
	v_cvt_pk_bf16_f32 v16, v10, v11
	v_cvt_pk_bf16_f32 v17, v12, v13
	v_cvt_pk_bf16_f32 v6, v6, v7
	v_cvt_pk_bf16_f32 v7, v8, v9
	v_cvt_pk_bf16_f32 v2, v2, v3
	v_cvt_pk_bf16_f32 v3, v4, v5
	v_lshl_add_u64 v[26:27], v[26:27], 0, v[140:141]
	global_store_dwordx4 v[28:29], v[22:25], off
	global_store_dwordx4 v[26:27], v[18:21], off
	v_lshl_add_u64 v[10:11], v[146:147], 0, s[18:19]
	s_mov_b64 vcc, s[8:9]
	v_mov_b32_dpp v18, v6 row_ror:8 row_mask:0xf bank_mask:0xf bound_ctrl:1
	v_mov_b32_dpp v19, v7 row_ror:8 row_mask:0xf bank_mask:0xf bound_ctrl:1
	v_mov_b32_dpp v20, v2 row_ror:8 row_mask:0xf bank_mask:0xf bound_ctrl:1
	v_mov_b32_dpp v21, v3 row_ror:8 row_mask:0xf bank_mask:0xf bound_ctrl:1
	v_lshl_add_u64 v[12:13], v[10:11], 0, v[138:139]
	v_cndmask_b32_dpp v5, v17, v3, vcc row_ror:8 row_mask:0xf bank_mask:0xf bound_ctrl:1
	v_cndmask_b32_dpp v4, v16, v2, vcc row_ror:8 row_mask:0xf bank_mask:0xf bound_ctrl:1
	v_cndmask_b32_dpp v3, v15, v7, vcc row_ror:8 row_mask:0xf bank_mask:0xf bound_ctrl:1
	v_cndmask_b32_dpp v2, v14, v6, vcc row_ror:8 row_mask:0xf bank_mask:0xf bound_ctrl:1
	v_cndmask_b32_e64 v9, v17, v21, s[8:9]
	v_cndmask_b32_e64 v8, v16, v20, s[8:9]
	v_cndmask_b32_e64 v7, v15, v19, s[8:9]
	v_cndmask_b32_e64 v6, v14, v18, s[8:9]
	s_and_b64 vcc, exec, s[10:11]
	s_mov_b64 s[10:11], -1
	v_lshl_add_u64 v[10:11], v[10:11], 0, v[140:141]
	global_store_dwordx4 v[12:13], v[6:9], off
	global_store_dwordx4 v[10:11], v[2:5], off
	s_cbranch_vccnz .LBB0_1714
	s_andn2_b64 vcc, exec, s[2:3]
	s_cbranch_vccnz .LBB0_1713
	s_barrier
	s_branch .LBB0_1713

; __device__ __forceinline__ unsigned pk2(float lo, float hi) { const f32x2 v = {lo, hi}; return __builtin_bit_cast(unsigned, __builtin_convertvector(v, bf16x2_t)); }
; __device__ __forceinline__ u32x4 ror8(u32x4 v) { u32x4 r;
; #pragma unroll
;     for (int i = 0; i < 4; ++i) r[i] = (unsigned)__builtin_amdgcn_mov_dpp((int)v[i], 0x128, 0xf, 0xf, true);
;     return r; }
; __device__ __forceinline__ void store_pair(unsigned char* own, size_t stride8, int hi_off, u32x4 lo, u32x4 hi, bool upper) {
;     const u32x4 tlo = ror8(lo), thi = ror8(hi);
;     const u32x4 A = upper ? thi : lo, B = upper ? hi : tlo;
;     unsigned char* pa = upper ? own - stride8 + hi_off : own;
;     unsigned char* pb = upper ? own + hi_off : own + stride8;
;     *(u32x4*)pa = A; *(u32x4*)pb = B;
; }
;     __device__ __forceinline__ void operator()(const f32x4 (&acc)[2][2][4][2], const Unit& u, int wr, int wc, int fr, int fq) const {
; #pragma unroll
;         for (int ai = 0; ai < 2; ++ai)
; #pragma unroll
;             for (int m = 0; m < 4; ++m) { unsigned char* rowp = (unsigned char*)(H + ((size_t)(u.pm * (FF / 64) + u.pn * 4 + wc) * 256 + (wr * 64 + fr + ai * 128 + m * 16)) * 64 + 8 * fq); u32x4 w[2];
; #pragma unroll
;                 for (int bj = 0; bj < 2; ++bj) { f32x4 v0 = acc[ai][bj][m][0], v1 = acc[ai][bj][m][1];
; #pragma unroll
;                     for (int j = 0; j < 4; ++j) { const float a = fmaxf(v0[j], 0.f), b = fmaxf(v1[j], 0.f); v0[j] = a * a; v1[j] = b * b; }
;                     w[bj].x = pk2(v0[0], v0[1]); w[bj].y = pk2(v0[2], v0[3]); w[bj].z = pk2(v1[0], v1[1]); w[bj].w = pk2(v1[2], v1[3]); }
;                 store_pair(rowp, (size_t)8 * 64 * 2, 64, w[0], w[1], fr >= 8); }
;     }
.LBB0_1845:
	s_lshl_b32 s4, s22, 7
	s_lshl_b32 s5, s24, 2
	s_add_i32 s5, s5, s4
	s_or_b32 s4, s5, s44
	s_ashr_i32 s5, s4, 31
	s_lshl_b64 s[4:5], s[4:5], 15
	s_add_u32 s22, s62, s4
	v_max_f32_e32 v126, 0, v126
	v_max_f32_e32 v122, 0, v122
	v_max_f32_e32 v127, 0, v127
	v_max_f32_e32 v123, 0, v123
	v_max_f32_e32 v128, 0, v128
	v_max_f32_e32 v124, 0, v124
	v_max_f32_e32 v129, 0, v129
	v_max_f32_e32 v125, 0, v125
	v_max_f32_e32 v118, 0, v118
	v_max_f32_e32 v114, 0, v114
	v_max_f32_e32 v119, 0, v119
	v_max_f32_e32 v115, 0, v115
	v_max_f32_e32 v120, 0, v120
	v_max_f32_e32 v116, 0, v116
	v_max_f32_e32 v121, 0, v121
	v_max_f32_e32 v117, 0, v117
	s_addc_u32 s23, s83, s5
	v_pk_mul_f32 v[126:127], v[126:127], v[126:127]
	v_pk_mul_f32 v[122:123], v[122:123], v[122:123]
	v_pk_mul_f32 v[128:129], v[128:129], v[128:129]
	v_pk_mul_f32 v[124:125], v[124:125], v[124:125]
	v_pk_mul_f32 v[118:119], v[118:119], v[118:119]
	v_pk_mul_f32 v[114:115], v[114:115], v[114:115]
	v_pk_mul_f32 v[120:121], v[120:121], v[120:121]
	v_pk_mul_f32 v[116:117], v[116:117], v[116:117]
	v_lshl_add_u64 v[164:165], s[22:23], 0, v[144:145]
	v_cvt_pk_bf16_f32 v126, v126, v127
	v_cvt_pk_bf16_f32 v127, v128, v129
	v_cvt_pk_bf16_f32 v128, v122, v123
	v_cvt_pk_bf16_f32 v129, v124, v125
	v_cvt_pk_bf16_f32 v118, v118, v119
	v_cvt_pk_bf16_f32 v119, v120, v121
	v_cvt_pk_bf16_f32 v114, v114, v115
	v_cvt_pk_bf16_f32 v115, v116, v117
	v_lshl_add_u64 v[122:123], v[164:165], 0, v[138:139]
	s_mov_b64 vcc, s[8:9]
	v_mov_b32_dpp v164, v118 row_ror:8 row_mask:0xf bank_mask:0xf bound_ctrl:1
	v_mov_b32_dpp v165, v119 row_ror:8 row_mask:0xf bank_mask:0xf bound_ctrl:1
	v_mov_b32_dpp v166, v114 row_ror:8 row_mask:0xf bank_mask:0xf bound_ctrl:1
	v_mov_b32_dpp v167, v115 row_ror:8 row_mask:0xf bank_mask:0xf bound_ctrl:1
	v_max_f32_e32 v110, 0, v110
	v_max_f32_e32 v106, 0, v106
	v_max_f32_e32 v111, 0, v111
	v_max_f32_e32 v107, 0, v107
	v_max_f32_e32 v112, 0, v112
	v_max_f32_e32 v108, 0, v108
	v_max_f32_e32 v113, 0, v113
	v_max_f32_e32 v109, 0, v109
	v_max_f32_e32 v102, 0, v102
	v_max_f32_e32 v98, 0, v98
	v_max_f32_e32 v103, 0, v103
	v_max_f32_e32 v99, 0, v99
	v_max_f32_e32 v104, 0, v104
	v_max_f32_e32 v100, 0, v100
	v_max_f32_e32 v105, 0, v105
	v_max_f32_e32 v101, 0, v101
	v_lshl_add_u64 v[124:125], v[122:123], 0, v[140:141]
	v_cndmask_b32_dpp v117, v129, v115, vcc row_ror:8 row_mask:0xf bank_mask:0xf bound_ctrl:1
	v_cndmask_b32_dpp v116, v128, v114, vcc row_ror:8 row_mask:0xf bank_mask:0xf bound_ctrl:1
	v_cndmask_b32_dpp v115, v127, v119, vcc row_ror:8 row_mask:0xf bank_mask:0xf bound_ctrl:1
	v_cndmask_b32_dpp v114, v126, v118, vcc row_ror:8 row_mask:0xf bank_mask:0xf bound_ctrl:1
	v_cndmask_b32_e64 v121, v129, v167, s[8:9]
	v_cndmask_b32_e64 v120, v128, v166, s[8:9]
	v_cndmask_b32_e64 v119, v127, v165, s[8:9]
	v_cndmask_b32_e64 v118, v126, v164, s[8:9]
	v_pk_mul_f32 v[110:111], v[110:111], v[110:111]
	v_pk_mul_f32 v[106:107], v[106:107], v[106:107]
	v_pk_mul_f32 v[112:113], v[112:113], v[112:113]
	v_pk_mul_f32 v[108:109], v[108:109], v[108:109]
	v_pk_mul_f32 v[102:103], v[102:103], v[102:103]
	v_pk_mul_f32 v[98:99], v[98:99], v[98:99]
	v_pk_mul_f32 v[104:105], v[104:105], v[104:105]
	v_pk_mul_f32 v[100:101], v[100:101], v[100:101]
	v_lshl_add_u64 v[122:123], v[122:123], 0, v[142:143]
	global_store_dwordx4 v[124:125], v[118:121], off
	global_store_dwordx4 v[122:123], v[114:117], off
	v_cvt_pk_bf16_f32 v110, v110, v111
	v_cvt_pk_bf16_f32 v111, v112, v113
	v_lshl_add_u64 v[114:115], s[22:23], 0, v[146:147]
	v_cvt_pk_bf16_f32 v112, v106, v107
	v_cvt_pk_bf16_f32 v113, v108, v109
	v_cvt_pk_bf16_f32 v102, v102, v103
	v_cvt_pk_bf16_f32 v103, v104, v105
	v_cvt_pk_bf16_f32 v98, v98, v99
	v_cvt_pk_bf16_f32 v99, v100, v101
	v_lshl_add_u64 v[106:107], v[114:115], 0, v[138:139]
	s_mov_b64 vcc, s[8:9]
	v_mov_b32_dpp v114, v102 row_ror:8 row_mask:0xf bank_mask:0xf bound_ctrl:1
	v_mov_b32_dpp v115, v103 row_ror:8 row_mask:0xf bank_mask:0xf bound_ctrl:1
	v_mov_b32_dpp v116, v98 row_ror:8 row_mask:0xf bank_mask:0xf bound_ctrl:1
	v_mov_b32_dpp v117, v99 row_ror:8 row_mask:0xf bank_mask:0xf bound_ctrl:1
	v_max_f32_e32 v94, 0, v94
	v_max_f32_e32 v90, 0, v90
	v_max_f32_e32 v95, 0, v95
	v_max_f32_e32 v91, 0, v91
	v_max_f32_e32 v96, 0, v96
	v_max_f32_e32 v92, 0, v92
	v_max_f32_e32 v97, 0, v97
	v_max_f32_e32 v93, 0, v93
	v_max_f32_e32 v86, 0, v86
	v_max_f32_e32 v82, 0, v82
	v_max_f32_e32 v87, 0, v87
	v_max_f32_e32 v83, 0, v83
	v_max_f32_e32 v88, 0, v88
	v_max_f32_e32 v84, 0, v84
	v_max_f32_e32 v89, 0, v89
	v_max_f32_e32 v85, 0, v85
	v_lshl_add_u64 v[108:109], v[106:107], 0, v[140:141]
	v_cndmask_b32_dpp v101, v113, v99, vcc row_ror:8 row_mask:0xf bank_mask:0xf bound_ctrl:1
	v_cndmask_b32_dpp v100, v112, v98, vcc row_ror:8 row_mask:0xf bank_mask:0xf bound_ctrl:1
	v_cndmask_b32_dpp v99, v111, v103, vcc row_ror:8 row_mask:0xf bank_mask:0xf bound_ctrl:1
	v_cndmask_b32_dpp v98, v110, v102, vcc row_ror:8 row_mask:0xf bank_mask:0xf bound_ctrl:1
	v_cndmask_b32_e64 v105, v113, v117, s[8:9]
	v_cndmask_b32_e64 v104, v112, v116, s[8:9]
	v_cndmask_b32_e64 v103, v111, v115, s[8:9]
	v_cndmask_b32_e64 v102, v110, v114, s[8:9]
	v_pk_mul_f32 v[94:95], v[94:95], v[94:95]
	v_pk_mul_f32 v[90:91], v[90:91], v[90:91]
	v_pk_mul_f32 v[96:97], v[96:97], v[96:97]
	v_pk_mul_f32 v[92:93], v[92:93], v[92:93]
	v_pk_mul_f32 v[86:87], v[86:87], v[86:87]
	v_pk_mul_f32 v[82:83], v[82:83], v[82:83]
	v_pk_mul_f32 v[88:89], v[88:89], v[88:89]
	v_pk_mul_f32 v[84:85], v[84:85], v[84:85]
	v_lshl_add_u64 v[106:107], v[106:107], 0, v[142:143]
	global_store_dwordx4 v[108:109], v[102:105], off
	global_store_dwordx4 v[106:107], v[98:101], off
	v_cvt_pk_bf16_f32 v94, v94, v95
; __device__ __forceinline__ unsigned pk2(float lo, float hi) { const f32x2 v = {lo, hi}; return __builtin_bit_cast(unsigned, __builtin_convertvector(v, bf16x2_t)); }
; __device__ __forceinline__ u32x4 ror8(u32x4 v) { u32x4 r;
; #pragma unroll
;     for (int i = 0; i < 4; ++i) r[i] = (unsigned)__builtin_amdgcn_mov_dpp((int)v[i], 0x128, 0xf, 0xf, true);
;     return r; }
; __device__ __forceinline__ void store_pair(unsigned char* own, size_t stride8, int hi_off, u32x4 lo, u32x4 hi, bool upper) {
;     const u32x4 tlo = ror8(lo), thi = ror8(hi);
;     const u32x4 A = upper ? thi : lo, B = upper ? hi : tlo;
;     unsigned char* pa = upper ? own - stride8 + hi_off : own;
;     unsigned char* pb = upper ? own + hi_off : own + stride8;
;     *(u32x4*)pa = A; *(u32x4*)pb = B;
;     __device__ __forceinline__ void operator()(const f32x4 (&acc)[2][2][4][2], const Unit& u, int wr, int wc, int fr, int fq) const {
;     ...
;             for (int m = 0; m < 4; ++m) { unsigned char* rowp = (unsigned char*)(H + ((size_t)(u.pm * (FF / 64) + u.pn * 4 + wc) * 256 + (wr * 64 + fr + ai * 128 + m * 16)) * 64 + 8 * fq); u32x4 w[2];
; #pragma unroll
;                 for (int bj = 0; bj < 2; ++bj) { f32x4 v0 = acc[ai][bj][m][0], v1 = acc[ai][bj][m][1];
; #pragma unroll
;                     for (int j = 0; j < 4; ++j) { const float a = fmaxf(v0[j], 0.f), b = fmaxf(v1[j], 0.f); v0[j] = a * a; v1[j] = b * b; }
;                     w[bj].x = pk2(v0[0], v0[1]); w[bj].y = pk2(v0[2], v0[3]); w[bj].z = pk2(v1[0], v1[1]); w[bj].w = pk2(v1[2], v1[3]); }
;                 store_pair(rowp, (size_t)8 * 64 * 2, 64, w[0], w[1], fr >= 8); }
	v_cvt_pk_bf16_f32 v95, v96, v97
	v_lshl_add_u64 v[98:99], s[22:23], 0, v[148:149]
	v_cvt_pk_bf16_f32 v96, v90, v91
	v_cvt_pk_bf16_f32 v97, v92, v93
	v_cvt_pk_bf16_f32 v86, v86, v87
	v_cvt_pk_bf16_f32 v87, v88, v89
	v_cvt_pk_bf16_f32 v82, v82, v83
	v_cvt_pk_bf16_f32 v83, v84, v85
	v_lshl_add_u64 v[90:91], v[98:99], 0, v[138:139]
	s_mov_b64 vcc, s[8:9]
	v_mov_b32_dpp v98, v86 row_ror:8 row_mask:0xf bank_mask:0xf bound_ctrl:1
	v_mov_b32_dpp v99, v87 row_ror:8 row_mask:0xf bank_mask:0xf bound_ctrl:1
	v_mov_b32_dpp v100, v82 row_ror:8 row_mask:0xf bank_mask:0xf bound_ctrl:1
	v_mov_b32_dpp v101, v83 row_ror:8 row_mask:0xf bank_mask:0xf bound_ctrl:1
	v_max_f32_e32 v78, 0, v78
	v_max_f32_e32 v74, 0, v74
	v_max_f32_e32 v79, 0, v79
	v_max_f32_e32 v75, 0, v75
	v_max_f32_e32 v80, 0, v80
	v_max_f32_e32 v76, 0, v76
	v_max_f32_e32 v81, 0, v81
	v_max_f32_e32 v77, 0, v77
	v_max_f32_e32 v70, 0, v70
	v_max_f32_e32 v66, 0, v66
	v_max_f32_e32 v71, 0, v71
	v_max_f32_e32 v67, 0, v67
	v_max_f32_e32 v72, 0, v72
	v_max_f32_e32 v68, 0, v68
	v_max_f32_e32 v73, 0, v73
	v_max_f32_e32 v69, 0, v69
	v_lshl_add_u64 v[92:93], v[90:91], 0, v[140:141]
	v_cndmask_b32_dpp v85, v97, v83, vcc row_ror:8 row_mask:0xf bank_mask:0xf bound_ctrl:1
	v_cndmask_b32_dpp v84, v96, v82, vcc row_ror:8 row_mask:0xf bank_mask:0xf bound_ctrl:1
	v_cndmask_b32_dpp v83, v95, v87, vcc row_ror:8 row_mask:0xf bank_mask:0xf bound_ctrl:1
	v_cndmask_b32_dpp v82, v94, v86, vcc row_ror:8 row_mask:0xf bank_mask:0xf bound_ctrl:1
	v_cndmask_b32_e64 v89, v97, v101, s[8:9]
	v_cndmask_b32_e64 v88, v96, v100, s[8:9]
	v_cndmask_b32_e64 v87, v95, v99, s[8:9]
	v_cndmask_b32_e64 v86, v94, v98, s[8:9]
	v_pk_mul_f32 v[78:79], v[78:79], v[78:79]
	v_pk_mul_f32 v[74:75], v[74:75], v[74:75]
	v_pk_mul_f32 v[80:81], v[80:81], v[80:81]
	v_pk_mul_f32 v[76:77], v[76:77], v[76:77]
	v_pk_mul_f32 v[70:71], v[70:71], v[70:71]
	v_pk_mul_f32 v[66:67], v[66:67], v[66:67]
	v_pk_mul_f32 v[72:73], v[72:73], v[72:73]
	v_pk_mul_f32 v[68:69], v[68:69], v[68:69]
	v_lshl_add_u64 v[90:91], v[90:91], 0, v[142:143]
	global_store_dwordx4 v[92:93], v[86:89], off
	global_store_dwordx4 v[90:91], v[82:85], off
	v_cvt_pk_bf16_f32 v78, v78, v79
	v_cvt_pk_bf16_f32 v79, v80, v81
	v_lshl_add_u64 v[82:83], s[22:23], 0, v[150:151]
	v_cvt_pk_bf16_f32 v80, v74, v75
	v_cvt_pk_bf16_f32 v81, v76, v77
	v_cvt_pk_bf16_f32 v70, v70, v71
	v_cvt_pk_bf16_f32 v71, v72, v73
	v_cvt_pk_bf16_f32 v66, v66, v67
	v_cvt_pk_bf16_f32 v67, v68, v69
	v_lshl_add_u64 v[74:75], v[82:83], 0, v[138:139]
	s_mov_b64 vcc, s[8:9]
	v_mov_b32_dpp v82, v70 row_ror:8 row_mask:0xf bank_mask:0xf bound_ctrl:1
	v_mov_b32_dpp v83, v71 row_ror:8 row_mask:0xf bank_mask:0xf bound_ctrl:1
	v_mov_b32_dpp v84, v66 row_ror:8 row_mask:0xf bank_mask:0xf bound_ctrl:1
	v_mov_b32_dpp v85, v67 row_ror:8 row_mask:0xf bank_mask:0xf bound_ctrl:1
	v_max_f32_e32 v62, 0, v62
	v_max_f32_e32 v58, 0, v58
	v_max_f32_e32 v63, 0, v63
	v_max_f32_e32 v59, 0, v59
	v_max_f32_e32 v64, 0, v64
	v_max_f32_e32 v60, 0, v60
	v_max_f32_e32 v65, 0, v65
	v_max_f32_e32 v61, 0, v61
	v_max_f32_e32 v54, 0, v54
	v_max_f32_e32 v50, 0, v50
	v_max_f32_e32 v55, 0, v55
	v_max_f32_e32 v51, 0, v51
	v_max_f32_e32 v56, 0, v56
	v_max_f32_e32 v52, 0, v52
	v_max_f32_e32 v57, 0, v57
	v_max_f32_e32 v53, 0, v53
	v_lshl_add_u64 v[76:77], v[74:75], 0, v[140:141]
	v_cndmask_b32_dpp v69, v81, v67, vcc row_ror:8 row_mask:0xf bank_mask:0xf bound_ctrl:1
	v_cndmask_b32_dpp v68, v80, v66, vcc row_ror:8 row_mask:0xf bank_mask:0xf bound_ctrl:1
	v_cndmask_b32_dpp v67, v79, v71, vcc row_ror:8 row_mask:0xf bank_mask:0xf bound_ctrl:1
	v_cndmask_b32_dpp v66, v78, v70, vcc row_ror:8 row_mask:0xf bank_mask:0xf bound_ctrl:1
	v_cndmask_b32_e64 v73, v81, v85, s[8:9]
	v_cndmask_b32_e64 v72, v80, v84, s[8:9]
	v_cndmask_b32_e64 v71, v79, v83, s[8:9]
	v_cndmask_b32_e64 v70, v78, v82, s[8:9]
	v_pk_mul_f32 v[62:63], v[62:63], v[62:63]
	v_pk_mul_f32 v[58:59], v[58:59], v[58:59]
	v_pk_mul_f32 v[64:65], v[64:65], v[64:65]
	v_pk_mul_f32 v[60:61], v[60:61], v[60:61]
	v_pk_mul_f32 v[54:55], v[54:55], v[54:55]
	v_pk_mul_f32 v[50:51], v[50:51], v[50:51]
	v_pk_mul_f32 v[56:57], v[56:57], v[56:57]
	v_pk_mul_f32 v[52:53], v[52:53], v[52:53]
	v_lshl_add_u64 v[74:75], v[74:75], 0, v[142:143]
	global_store_dwordx4 v[76:77], v[70:73], off
	global_store_dwordx4 v[74:75], v[66:69], off
	v_cvt_pk_bf16_f32 v62, v62, v63
	v_cvt_pk_bf16_f32 v63, v64, v65
	v_lshl_add_u64 v[66:67], s[22:23], 0, v[152:153]
	v_cvt_pk_bf16_f32 v64, v58, v59
	v_cvt_pk_bf16_f32 v65, v60, v61
	v_cvt_pk_bf16_f32 v54, v54, v55
	v_cvt_pk_bf16_f32 v55, v56, v57
	v_cvt_pk_bf16_f32 v50, v50, v51
	v_cvt_pk_bf16_f32 v51, v52, v53
	v_lshl_add_u64 v[58:59], v[66:67], 0, v[138:139]
	s_mov_b64 vcc, s[8:9]
	v_mov_b32_dpp v66, v54 row_ror:8 row_mask:0xf bank_mask:0xf bound_ctrl:1
	v_mov_b32_dpp v67, v55 row_ror:8 row_mask:0xf bank_mask:0xf bound_ctrl:1
	v_mov_b32_dpp v68, v50 row_ror:8 row_mask:0xf bank_mask:0xf bound_ctrl:1
	v_mov_b32_dpp v69, v51 row_ror:8 row_mask:0xf bank_mask:0xf bound_ctrl:1
	v_max_f32_e32 v46, 0, v46
	v_max_f32_e32 v42, 0, v42
	v_max_f32_e32 v47, 0, v47
	v_max_f32_e32 v43, 0, v43
	v_max_f32_e32 v48, 0, v48
	v_max_f32_e32 v44, 0, v44
	v_max_f32_e32 v49, 0, v49
	v_max_f32_e32 v45, 0, v45
	v_max_f32_e32 v38, 0, v38
	v_max_f32_e32 v34, 0, v34
	v_max_f32_e32 v39, 0, v39
	v_max_f32_e32 v35, 0, v35
	v_max_f32_e32 v40, 0, v40
	v_max_f32_e32 v36, 0, v36
	v_max_f32_e32 v41, 0, v41
	v_max_f32_e32 v37, 0, v37
	v_lshl_add_u64 v[60:61], v[58:59], 0, v[140:141]
	v_cndmask_b32_dpp v53, v65, v51, vcc row_ror:8 row_mask:0xf bank_mask:0xf bound_ctrl:1
	v_cndmask_b32_dpp v52, v64, v50, vcc row_ror:8 row_mask:0xf bank_mask:0xf bound_ctrl:1
; __device__ __forceinline__ unsigned pk2(float lo, float hi) { const f32x2 v = {lo, hi}; return __builtin_bit_cast(unsigned, __builtin_convertvector(v, bf16x2_t)); }
; __device__ __forceinline__ u32x4 ror8(u32x4 v) { u32x4 r;
; #pragma unroll
;     for (int i = 0; i < 4; ++i) r[i] = (unsigned)__builtin_amdgcn_mov_dpp((int)v[i], 0x128, 0xf, 0xf, true);
;     return r; }
; __device__ __forceinline__ void store_pair(unsigned char* own, size_t stride8, int hi_off, u32x4 lo, u32x4 hi, bool upper) {
;     const u32x4 tlo = ror8(lo), thi = ror8(hi);
;     const u32x4 A = upper ? thi : lo, B = upper ? hi : tlo;
;     unsigned char* pa = upper ? own - stride8 + hi_off : own;
;     unsigned char* pb = upper ? own + hi_off : own + stride8;
;     *(u32x4*)pa = A; *(u32x4*)pb = B;
;     __device__ __forceinline__ void operator()(const f32x4 (&acc)[2][2][4][2], const Unit& u, int wr, int wc, int fr, int fq) const {
;     ...
;             for (int m = 0; m < 4; ++m) { unsigned char* rowp = (unsigned char*)(H + ((size_t)(u.pm * (FF / 64) + u.pn * 4 + wc) * 256 + (wr * 64 + fr + ai * 128 + m * 16)) * 64 + 8 * fq); u32x4 w[2];
; #pragma unroll
;                 for (int bj = 0; bj < 2; ++bj) { f32x4 v0 = acc[ai][bj][m][0], v1 = acc[ai][bj][m][1];
; #pragma unroll
;                     for (int j = 0; j < 4; ++j) { const float a = fmaxf(v0[j], 0.f), b = fmaxf(v1[j], 0.f); v0[j] = a * a; v1[j] = b * b; }
;                     w[bj].x = pk2(v0[0], v0[1]); w[bj].y = pk2(v0[2], v0[3]); w[bj].z = pk2(v1[0], v1[1]); w[bj].w = pk2(v1[2], v1[3]); }
;                 store_pair(rowp, (size_t)8 * 64 * 2, 64, w[0], w[1], fr >= 8); }
	v_cndmask_b32_dpp v51, v63, v55, vcc row_ror:8 row_mask:0xf bank_mask:0xf bound_ctrl:1
	v_cndmask_b32_dpp v50, v62, v54, vcc row_ror:8 row_mask:0xf bank_mask:0xf bound_ctrl:1
	v_cndmask_b32_e64 v57, v65, v69, s[8:9]
	v_cndmask_b32_e64 v56, v64, v68, s[8:9]
	v_cndmask_b32_e64 v55, v63, v67, s[8:9]
	v_cndmask_b32_e64 v54, v62, v66, s[8:9]
	v_pk_mul_f32 v[46:47], v[46:47], v[46:47]
	v_pk_mul_f32 v[42:43], v[42:43], v[42:43]
	v_pk_mul_f32 v[48:49], v[48:49], v[48:49]
	v_pk_mul_f32 v[44:45], v[44:45], v[44:45]
	v_pk_mul_f32 v[38:39], v[38:39], v[38:39]
	v_pk_mul_f32 v[34:35], v[34:35], v[34:35]
	v_pk_mul_f32 v[40:41], v[40:41], v[40:41]
	v_pk_mul_f32 v[36:37], v[36:37], v[36:37]
	v_lshl_add_u64 v[58:59], v[58:59], 0, v[142:143]
	global_store_dwordx4 v[60:61], v[54:57], off
	global_store_dwordx4 v[58:59], v[50:53], off
	v_cvt_pk_bf16_f32 v46, v46, v47
	v_cvt_pk_bf16_f32 v47, v48, v49
	v_lshl_add_u64 v[50:51], s[22:23], 0, v[154:155]
	v_cvt_pk_bf16_f32 v48, v42, v43
	v_cvt_pk_bf16_f32 v49, v44, v45
	v_cvt_pk_bf16_f32 v38, v38, v39
	v_cvt_pk_bf16_f32 v39, v40, v41
	v_cvt_pk_bf16_f32 v34, v34, v35
	v_cvt_pk_bf16_f32 v35, v36, v37
	v_lshl_add_u64 v[42:43], v[50:51], 0, v[138:139]
	s_mov_b64 vcc, s[8:9]
	v_mov_b32_dpp v50, v38 row_ror:8 row_mask:0xf bank_mask:0xf bound_ctrl:1
	v_mov_b32_dpp v51, v39 row_ror:8 row_mask:0xf bank_mask:0xf bound_ctrl:1
	v_mov_b32_dpp v52, v34 row_ror:8 row_mask:0xf bank_mask:0xf bound_ctrl:1
	v_mov_b32_dpp v53, v35 row_ror:8 row_mask:0xf bank_mask:0xf bound_ctrl:1
	v_max_f32_e32 v30, 0, v30
	v_max_f32_e32 v26, 0, v26
	v_max_f32_e32 v31, 0, v31
	v_max_f32_e32 v27, 0, v27
	v_max_f32_e32 v32, 0, v32
	v_max_f32_e32 v28, 0, v28
	v_max_f32_e32 v33, 0, v33
	v_max_f32_e32 v29, 0, v29
	v_max_f32_e32 v22, 0, v22
	v_max_f32_e32 v18, 0, v18
	v_max_f32_e32 v23, 0, v23
	v_max_f32_e32 v19, 0, v19
	v_max_f32_e32 v24, 0, v24
	v_max_f32_e32 v20, 0, v20
	v_max_f32_e32 v25, 0, v25
	v_max_f32_e32 v21, 0, v21
	v_lshl_add_u64 v[44:45], v[42:43], 0, v[140:141]
	v_cndmask_b32_dpp v37, v49, v35, vcc row_ror:8 row_mask:0xf bank_mask:0xf bound_ctrl:1
	v_cndmask_b32_dpp v36, v48, v34, vcc row_ror:8 row_mask:0xf bank_mask:0xf bound_ctrl:1
	v_cndmask_b32_dpp v35, v47, v39, vcc row_ror:8 row_mask:0xf bank_mask:0xf bound_ctrl:1
	v_cndmask_b32_dpp v34, v46, v38, vcc row_ror:8 row_mask:0xf bank_mask:0xf bound_ctrl:1
	v_cndmask_b32_e64 v41, v49, v53, s[8:9]
	v_cndmask_b32_e64 v40, v48, v52, s[8:9]
	v_cndmask_b32_e64 v39, v47, v51, s[8:9]
	v_cndmask_b32_e64 v38, v46, v50, s[8:9]
	v_pk_mul_f32 v[30:31], v[30:31], v[30:31]
	v_pk_mul_f32 v[26:27], v[26:27], v[26:27]
	v_pk_mul_f32 v[32:33], v[32:33], v[32:33]
	v_pk_mul_f32 v[28:29], v[28:29], v[28:29]
	v_pk_mul_f32 v[22:23], v[22:23], v[22:23]
	v_pk_mul_f32 v[18:19], v[18:19], v[18:19]
	v_pk_mul_f32 v[24:25], v[24:25], v[24:25]
	v_pk_mul_f32 v[20:21], v[20:21], v[20:21]
	v_lshl_add_u64 v[42:43], v[42:43], 0, v[142:143]
	global_store_dwordx4 v[44:45], v[38:41], off
	global_store_dwordx4 v[42:43], v[34:37], off
	v_cvt_pk_bf16_f32 v30, v30, v31
	v_cvt_pk_bf16_f32 v31, v32, v33
	v_lshl_add_u64 v[34:35], s[22:23], 0, v[156:157]
	v_cvt_pk_bf16_f32 v32, v26, v27
	v_cvt_pk_bf16_f32 v33, v28, v29
	v_cvt_pk_bf16_f32 v22, v22, v23
	v_cvt_pk_bf16_f32 v23, v24, v25
	v_cvt_pk_bf16_f32 v18, v18, v19
	v_cvt_pk_bf16_f32 v19, v20, v21
	v_lshl_add_u64 v[26:27], v[34:35], 0, v[138:139]
	s_mov_b64 vcc, s[8:9]
	v_mov_b32_dpp v34, v22 row_ror:8 row_mask:0xf bank_mask:0xf bound_ctrl:1
	v_mov_b32_dpp v35, v23 row_ror:8 row_mask:0xf bank_mask:0xf bound_ctrl:1
	v_mov_b32_dpp v36, v18 row_ror:8 row_mask:0xf bank_mask:0xf bound_ctrl:1
	v_mov_b32_dpp v37, v19 row_ror:8 row_mask:0xf bank_mask:0xf bound_ctrl:1
	v_max_f32_e32 v14, 0, v14
	v_max_f32_e32 v10, 0, v10
	v_max_f32_e32 v15, 0, v15
	v_max_f32_e32 v11, 0, v11
	v_max_f32_e32 v16, 0, v16
	v_max_f32_e32 v12, 0, v12
	v_max_f32_e32 v17, 0, v17
	v_max_f32_e32 v13, 0, v13
	v_max_f32_e32 v6, 0, v6
	v_max_f32_e32 v2, 0, v2
	v_max_f32_e32 v7, 0, v7
	v_max_f32_e32 v3, 0, v3
	v_max_f32_e32 v8, 0, v8
	v_max_f32_e32 v4, 0, v4
	v_max_f32_e32 v9, 0, v9
	v_max_f32_e32 v5, 0, v5
	v_lshl_add_u64 v[28:29], v[26:27], 0, v[140:141]
	v_cndmask_b32_dpp v21, v33, v19, vcc row_ror:8 row_mask:0xf bank_mask:0xf bound_ctrl:1
	v_cndmask_b32_dpp v20, v32, v18, vcc row_ror:8 row_mask:0xf bank_mask:0xf bound_ctrl:1
	v_cndmask_b32_dpp v19, v31, v23, vcc row_ror:8 row_mask:0xf bank_mask:0xf bound_ctrl:1
	v_cndmask_b32_dpp v18, v30, v22, vcc row_ror:8 row_mask:0xf bank_mask:0xf bound_ctrl:1
	v_cndmask_b32_e64 v25, v33, v37, s[8:9]
	v_cndmask_b32_e64 v24, v32, v36, s[8:9]
	v_cndmask_b32_e64 v23, v31, v35, s[8:9]
	v_cndmask_b32_e64 v22, v30, v34, s[8:9]
	v_pk_mul_f32 v[14:15], v[14:15], v[14:15]
	v_pk_mul_f32 v[10:11], v[10:11], v[10:11]
	v_pk_mul_f32 v[16:17], v[16:17], v[16:17]
	v_pk_mul_f32 v[12:13], v[12:13], v[12:13]
	v_pk_mul_f32 v[6:7], v[6:7], v[6:7]
	v_pk_mul_f32 v[2:3], v[2:3], v[2:3]
	v_pk_mul_f32 v[8:9], v[8:9], v[8:9]
	v_pk_mul_f32 v[4:5], v[4:5], v[4:5]
	v_lshl_add_u64 v[26:27], v[26:27], 0, v[142:143]
	global_store_dwordx4 v[28:29], v[22:25], off
	global_store_dwordx4 v[26:27], v[18:21], off
	v_cvt_pk_bf16_f32 v14, v14, v15
	v_cvt_pk_bf16_f32 v15, v16, v17
	v_lshl_add_u64 v[18:19], s[22:23], 0, v[158:159]
	v_cvt_pk_bf16_f32 v16, v10, v11
	v_cvt_pk_bf16_f32 v17, v12, v13
	v_cvt_pk_bf16_f32 v6, v6, v7
	v_cvt_pk_bf16_f32 v7, v8, v9
	v_cvt_pk_bf16_f32 v2, v2, v3
	v_cvt_pk_bf16_f32 v3, v4, v5
	v_lshl_add_u64 v[10:11], v[18:19], 0, v[138:139]
	s_mov_b64 vcc, s[8:9]
	v_mov_b32_dpp v18, v6 row_ror:8 row_mask:0xf bank_mask:0xf bound_ctrl:1
	v_mov_b32_dpp v19, v7 row_ror:8 row_mask:0xf bank_mask:0xf bound_ctrl:1
	v_mov_b32_dpp v20, v2 row_ror:8 row_mask:0xf bank_mask:0xf bound_ctrl:1
	v_mov_b32_dpp v21, v3 row_ror:8 row_mask:0xf bank_mask:0xf bound_ctrl:1
	v_lshl_add_u64 v[12:13], v[10:11], 0, v[140:141]
	v_cndmask_b32_dpp v5, v17, v3, vcc row_ror:8 row_mask:0xf bank_mask:0xf bound_ctrl:1
	v_cndmask_b32_dpp v4, v16, v2, vcc row_ror:8 row_mask:0xf bank_mask:0xf bound_ctrl:1
	v_cndmask_b32_dpp v3, v15, v7, vcc row_ror:8 row_mask:0xf bank_mask:0xf bound_ctrl:1
	v_cndmask_b32_dpp v2, v14, v6, vcc row_ror:8 row_mask:0xf bank_mask:0xf bound_ctrl:1
	v_cndmask_b32_e64 v9, v17, v21, s[8:9]
	v_cndmask_b32_e64 v8, v16, v20, s[8:9]
	v_cndmask_b32_e64 v7, v15, v19, s[8:9]
	v_cndmask_b32_e64 v6, v14, v18, s[8:9]
	s_andn2_b64 vcc, exec, s[18:19]
	s_mov_b64 s[4:5], -1
	v_lshl_add_u64 v[10:11], v[10:11], 0, v[142:143]
	global_store_dwordx4 v[12:13], v[6:9], off
	global_store_dwordx4 v[10:11], v[2:5], off
	s_cbranch_vccnz .LBB0_1838
	s_andn2_b64 vcc, exec, s[2:3]
	s_cbranch_vccnz .LBB0_1837
	s_barrier
	s_branch .LBB0_1837

; __device__ __forceinline__ unsigned pk2(float lo, float hi) { const f32x2 v = {lo, hi}; return __builtin_bit_cast(unsigned, __builtin_convertvector(v, bf16x2_t)); }
; __device__ __forceinline__ u32x4 ror8(u32x4 v) { u32x4 r;
; #pragma unroll
;     for (int i = 0; i < 4; ++i) r[i] = (unsigned)__builtin_amdgcn_mov_dpp((int)v[i], 0x128, 0xf, 0xf, true);
;     return r; }
; __device__ __forceinline__ void store_pair(unsigned char* own, size_t stride8, int hi_off, u32x4 lo, u32x4 hi, bool upper) {
;     const u32x4 tlo = ror8(lo), thi = ror8(hi);
;     const u32x4 A = upper ? thi : lo, B = upper ? hi : tlo;
;     unsigned char* pa = upper ? own - stride8 + hi_off : own;
;     unsigned char* pb = upper ? own + hi_off : own + stride8;
;     *(u32x4*)pa = A; *(u32x4*)pb = B;
;     __device__ __forceinline__ void operator()(const f32x4 (&acc)[2][2][4][2], const Unit& u, int wr, int wc, int fr, int fq) const {
;         const int row0 = u.pm * 256 + wr * 64 + fr, col0 = u.pn * 256 + wc * 64 + 8 * fq;
;         bf16_t* base = u.part == 0 ? Z + (size_t)row0 * D + col0 : P + ((size_t)(u.part - 1) * MS + (row0 - MP)) * D + col0;
; #pragma unroll
;         for (int ai = 0; ai < 2; ++ai)
; #pragma unroll
;             for (int m = 0; m < 4; ++m) { u32x4 w[2];
; #pragma unroll
;                 for (int bj = 0; bj < 2; ++bj) { const f32x4 v0 = acc[ai][bj][m][0], v1 = acc[ai][bj][m][1]; w[bj].x = pk2(v0[0], v0[1]); w[bj].y = pk2(v0[2], v0[3]); w[bj].z = pk2(v1[0], v1[1]); w[bj].w = pk2(v1[2], v1[3]); }
;                 store_pair((unsigned char*)(base + (size_t)(ai * 128 + m * 16) * D), (size_t)8 * D * 2, 64, w[0], w[1], fr >= 8); }
.LBB0_1910:
	v_lshl_add_u32 v143, s49, 8, v1
	v_add_u32_e32 v144, 0xffffe000, v143
	v_sub_co_u32_e64 v142, vcc, s47, 1
	v_mov_b32_e32 v145, s91
	s_nop 0
	v_cndmask_b32_e32 v144, v144, v143, vcc
	v_ashrrev_i32_e32 v143, 31, v142
	v_lshlrev_b64 v[142:143], 23, v[142:143]
	v_lshl_add_u64 v[142:143], s[12:13], 0, v[142:143]
	v_cndmask_b32_e32 v143, v143, v145, vcc
	v_mov_b32_e32 v145, s90
	v_cndmask_b32_e32 v142, v142, v145, vcc
	v_ashrrev_i32_e32 v145, 31, v144
	v_lshl_or_b32 v152, s78, 8, v147
	v_lshlrev_b64 v[144:145], 12, v[144:145]
	v_lshl_add_u64 v[142:143], v[142:143], 0, v[144:145]
	v_ashrrev_i32_e32 v153, 31, v152
	v_cvt_pk_bf16_f32 v126, v126, v127
	v_cvt_pk_bf16_f32 v127, v128, v129
	v_cvt_pk_bf16_f32 v128, v122, v123
	v_cvt_pk_bf16_f32 v124, v124, v125
	v_cvt_pk_bf16_f32 v118, v118, v119
	v_cvt_pk_bf16_f32 v119, v120, v121
	v_cvt_pk_bf16_f32 v114, v114, v115
	v_cvt_pk_bf16_f32 v115, v116, v117
	v_lshl_add_u64 v[142:143], v[152:153], 1, v[142:143]
	s_mov_b64 vcc, s[8:9]
	v_mov_b32_dpp v125, v118 row_ror:8 row_mask:0xf bank_mask:0xf bound_ctrl:1
	v_mov_b32_dpp v129, v119 row_ror:8 row_mask:0xf bank_mask:0xf bound_ctrl:1
	v_mov_b32_dpp v144, v114 row_ror:8 row_mask:0xf bank_mask:0xf bound_ctrl:1
	v_mov_b32_dpp v145, v115 row_ror:8 row_mask:0xf bank_mask:0xf bound_ctrl:1
	v_lshl_add_u64 v[122:123], v[142:143], 0, v[134:135]
	v_cndmask_b32_dpp v117, v124, v115, vcc row_ror:8 row_mask:0xf bank_mask:0xf bound_ctrl:1
	v_cndmask_b32_dpp v116, v128, v114, vcc row_ror:8 row_mask:0xf bank_mask:0xf bound_ctrl:1
	v_cndmask_b32_dpp v115, v127, v119, vcc row_ror:8 row_mask:0xf bank_mask:0xf bound_ctrl:1
	v_cndmask_b32_dpp v114, v126, v118, vcc row_ror:8 row_mask:0xf bank_mask:0xf bound_ctrl:1
	v_cndmask_b32_e64 v121, v124, v145, s[8:9]
	v_cndmask_b32_e64 v120, v128, v144, s[8:9]
	v_cndmask_b32_e64 v119, v127, v129, s[8:9]
	v_cndmask_b32_e64 v118, v126, v125, s[8:9]
	v_cvt_pk_bf16_f32 v110, v110, v111
	v_cvt_pk_bf16_f32 v111, v112, v113
	v_cvt_pk_bf16_f32 v112, v106, v107
	v_cvt_pk_bf16_f32 v113, v108, v109
	v_cvt_pk_bf16_f32 v102, v102, v103
	v_cvt_pk_bf16_f32 v103, v104, v105
	v_cvt_pk_bf16_f32 v98, v98, v99
	v_cvt_pk_bf16_f32 v99, v100, v101
	s_mov_b64 s[4:5], 0x10000
	v_lshl_add_u64 v[124:125], v[142:143], 0, v[136:137]
	global_store_dwordx4 v[122:123], v[118:121], off
	global_store_dwordx4 v[124:125], v[114:117], off
	v_lshl_add_u64 v[106:107], v[142:143], 0, s[4:5]
	s_mov_b64 vcc, s[8:9]
	v_mov_b32_dpp v114, v102 row_ror:8 row_mask:0xf bank_mask:0xf bound_ctrl:1
	v_mov_b32_dpp v115, v103 row_ror:8 row_mask:0xf bank_mask:0xf bound_ctrl:1
	v_mov_b32_dpp v116, v98 row_ror:8 row_mask:0xf bank_mask:0xf bound_ctrl:1
	v_mov_b32_dpp v117, v99 row_ror:8 row_mask:0xf bank_mask:0xf bound_ctrl:1
	v_lshl_add_u64 v[108:109], v[106:107], 0, v[134:135]
	v_cndmask_b32_dpp v101, v113, v99, vcc row_ror:8 row_mask:0xf bank_mask:0xf bound_ctrl:1
	v_cndmask_b32_dpp v100, v112, v98, vcc row_ror:8 row_mask:0xf bank_mask:0xf bound_ctrl:1
	v_cndmask_b32_dpp v99, v111, v103, vcc row_ror:8 row_mask:0xf bank_mask:0xf bound_ctrl:1
	v_cndmask_b32_dpp v98, v110, v102, vcc row_ror:8 row_mask:0xf bank_mask:0xf bound_ctrl:1
	v_cndmask_b32_e64 v105, v113, v117, s[8:9]
	v_cndmask_b32_e64 v104, v112, v116, s[8:9]
	v_cndmask_b32_e64 v103, v111, v115, s[8:9]
	v_cndmask_b32_e64 v102, v110, v114, s[8:9]
	v_cvt_pk_bf16_f32 v94, v94, v95
	v_cvt_pk_bf16_f32 v95, v96, v97
	v_cvt_pk_bf16_f32 v96, v90, v91
	v_cvt_pk_bf16_f32 v97, v92, v93
	v_cvt_pk_bf16_f32 v86, v86, v87
	v_cvt_pk_bf16_f32 v87, v88, v89
	v_cvt_pk_bf16_f32 v82, v82, v83
	v_cvt_pk_bf16_f32 v83, v84, v85
	s_mov_b64 s[4:5], 0x20000
	v_lshl_add_u64 v[106:107], v[106:107], 0, v[136:137]
	global_store_dwordx4 v[108:109], v[102:105], off
	global_store_dwordx4 v[106:107], v[98:101], off
	v_lshl_add_u64 v[90:91], v[142:143], 0, s[4:5]
	s_mov_b64 vcc, s[8:9]
	v_mov_b32_dpp v98, v86 row_ror:8 row_mask:0xf bank_mask:0xf bound_ctrl:1
	v_mov_b32_dpp v99, v87 row_ror:8 row_mask:0xf bank_mask:0xf bound_ctrl:1
	v_mov_b32_dpp v100, v82 row_ror:8 row_mask:0xf bank_mask:0xf bound_ctrl:1
	v_mov_b32_dpp v101, v83 row_ror:8 row_mask:0xf bank_mask:0xf bound_ctrl:1
	v_lshl_add_u64 v[92:93], v[90:91], 0, v[134:135]
	v_cndmask_b32_dpp v85, v97, v83, vcc row_ror:8 row_mask:0xf bank_mask:0xf bound_ctrl:1
	v_cndmask_b32_dpp v84, v96, v82, vcc row_ror:8 row_mask:0xf bank_mask:0xf bound_ctrl:1
	v_cndmask_b32_dpp v83, v95, v87, vcc row_ror:8 row_mask:0xf bank_mask:0xf bound_ctrl:1
	v_cndmask_b32_dpp v82, v94, v86, vcc row_ror:8 row_mask:0xf bank_mask:0xf bound_ctrl:1
	v_cndmask_b32_e64 v89, v97, v101, s[8:9]
	v_cndmask_b32_e64 v88, v96, v100, s[8:9]
	v_cndmask_b32_e64 v87, v95, v99, s[8:9]
	v_cndmask_b32_e64 v86, v94, v98, s[8:9]
	v_cvt_pk_bf16_f32 v78, v78, v79
	v_cvt_pk_bf16_f32 v79, v80, v81
	v_cvt_pk_bf16_f32 v80, v74, v75
	v_cvt_pk_bf16_f32 v81, v76, v77
	v_cvt_pk_bf16_f32 v70, v70, v71
	v_cvt_pk_bf16_f32 v71, v72, v73
	v_cvt_pk_bf16_f32 v66, v66, v67
	v_cvt_pk_bf16_f32 v67, v68, v69
	v_lshl_add_u64 v[90:91], v[90:91], 0, v[136:137]
	global_store_dwordx4 v[92:93], v[86:89], off
	global_store_dwordx4 v[90:91], v[82:85], off
	v_lshl_add_u64 v[74:75], v[142:143], 0, s[14:15]
	s_mov_b64 vcc, s[8:9]
	v_mov_b32_dpp v82, v70 row_ror:8 row_mask:0xf bank_mask:0xf bound_ctrl:1
	v_mov_b32_dpp v83, v71 row_ror:8 row_mask:0xf bank_mask:0xf bound_ctrl:1
	v_mov_b32_dpp v84, v66 row_ror:8 row_mask:0xf bank_mask:0xf bound_ctrl:1
	v_mov_b32_dpp v85, v67 row_ror:8 row_mask:0xf bank_mask:0xf bound_ctrl:1
	v_lshl_add_u64 v[76:77], v[74:75], 0, v[134:135]
	v_cndmask_b32_dpp v69, v81, v67, vcc row_ror:8 row_mask:0xf bank_mask:0xf bound_ctrl:1
; __device__ __forceinline__ unsigned pk2(float lo, float hi) { const f32x2 v = {lo, hi}; return __builtin_bit_cast(unsigned, __builtin_convertvector(v, bf16x2_t)); }
; __device__ __forceinline__ u32x4 ror8(u32x4 v) { u32x4 r;
; #pragma unroll
;     for (int i = 0; i < 4; ++i) r[i] = (unsigned)__builtin_amdgcn_mov_dpp((int)v[i], 0x128, 0xf, 0xf, true);
;     return r; }
; __device__ __forceinline__ void store_pair(unsigned char* own, size_t stride8, int hi_off, u32x4 lo, u32x4 hi, bool upper) {
;     const u32x4 tlo = ror8(lo), thi = ror8(hi);
;     const u32x4 A = upper ? thi : lo, B = upper ? hi : tlo;
;     unsigned char* pa = upper ? own - stride8 + hi_off : own;
;     unsigned char* pb = upper ? own + hi_off : own + stride8;
;     *(u32x4*)pa = A; *(u32x4*)pb = B;
;     __device__ __forceinline__ void operator()(const f32x4 (&acc)[2][2][4][2], const Unit& u, int wr, int wc, int fr, int fq) const {
;         const int row0 = u.pm * 256 + wr * 64 + fr, col0 = u.pn * 256 + wc * 64 + 8 * fq;
;         bf16_t* base = u.part == 0 ? Z + (size_t)row0 * D + col0 : P + ((size_t)(u.part - 1) * MS + (row0 - MP)) * D + col0;
; #pragma unroll
;         for (int ai = 0; ai < 2; ++ai)
; #pragma unroll
;             for (int m = 0; m < 4; ++m) { u32x4 w[2];
; #pragma unroll
;                 for (int bj = 0; bj < 2; ++bj) { const f32x4 v0 = acc[ai][bj][m][0], v1 = acc[ai][bj][m][1]; w[bj].x = pk2(v0[0], v0[1]); w[bj].y = pk2(v0[2], v0[3]); w[bj].z = pk2(v1[0], v1[1]); w[bj].w = pk2(v1[2], v1[3]); }
;                 store_pair((unsigned char*)(base + (size_t)(ai * 128 + m * 16) * D), (size_t)8 * D * 2, 64, w[0], w[1], fr >= 8); }
	v_cndmask_b32_dpp v68, v80, v66, vcc row_ror:8 row_mask:0xf bank_mask:0xf bound_ctrl:1
	v_cndmask_b32_dpp v67, v79, v71, vcc row_ror:8 row_mask:0xf bank_mask:0xf bound_ctrl:1
	v_cndmask_b32_dpp v66, v78, v70, vcc row_ror:8 row_mask:0xf bank_mask:0xf bound_ctrl:1
	v_cndmask_b32_e64 v73, v81, v85, s[8:9]
	v_cndmask_b32_e64 v72, v80, v84, s[8:9]
	v_cndmask_b32_e64 v71, v79, v83, s[8:9]
	v_cndmask_b32_e64 v70, v78, v82, s[8:9]
	v_cvt_pk_bf16_f32 v62, v62, v63
	v_cvt_pk_bf16_f32 v63, v64, v65
	v_cvt_pk_bf16_f32 v64, v58, v59
	v_cvt_pk_bf16_f32 v65, v60, v61
	v_cvt_pk_bf16_f32 v54, v54, v55
	v_cvt_pk_bf16_f32 v55, v56, v57
	v_cvt_pk_bf16_f32 v50, v50, v51
	v_cvt_pk_bf16_f32 v51, v52, v53
	v_lshl_add_u64 v[74:75], v[74:75], 0, v[136:137]
	global_store_dwordx4 v[76:77], v[70:73], off
	global_store_dwordx4 v[74:75], v[66:69], off
	v_lshl_add_u64 v[58:59], v[142:143], 0, s[16:17]
	s_mov_b64 vcc, s[8:9]
	v_mov_b32_dpp v66, v54 row_ror:8 row_mask:0xf bank_mask:0xf bound_ctrl:1
	v_mov_b32_dpp v67, v55 row_ror:8 row_mask:0xf bank_mask:0xf bound_ctrl:1
	v_mov_b32_dpp v68, v50 row_ror:8 row_mask:0xf bank_mask:0xf bound_ctrl:1
	v_mov_b32_dpp v69, v51 row_ror:8 row_mask:0xf bank_mask:0xf bound_ctrl:1
	v_lshl_add_u64 v[60:61], v[58:59], 0, v[134:135]
	v_cndmask_b32_dpp v53, v65, v51, vcc row_ror:8 row_mask:0xf bank_mask:0xf bound_ctrl:1
	v_cndmask_b32_dpp v52, v64, v50, vcc row_ror:8 row_mask:0xf bank_mask:0xf bound_ctrl:1
	v_cndmask_b32_dpp v51, v63, v55, vcc row_ror:8 row_mask:0xf bank_mask:0xf bound_ctrl:1
	v_cndmask_b32_dpp v50, v62, v54, vcc row_ror:8 row_mask:0xf bank_mask:0xf bound_ctrl:1
	v_cndmask_b32_e64 v57, v65, v69, s[8:9]
	v_cndmask_b32_e64 v56, v64, v68, s[8:9]
	v_cndmask_b32_e64 v55, v63, v67, s[8:9]
	v_cndmask_b32_e64 v54, v62, v66, s[8:9]
	v_cvt_pk_bf16_f32 v46, v46, v47
	v_cvt_pk_bf16_f32 v47, v48, v49
	v_cvt_pk_bf16_f32 v48, v42, v43
	v_cvt_pk_bf16_f32 v49, v44, v45
	v_cvt_pk_bf16_f32 v38, v38, v39
	v_cvt_pk_bf16_f32 v39, v40, v41
	v_cvt_pk_bf16_f32 v34, v34, v35
	v_cvt_pk_bf16_f32 v35, v36, v37
	v_lshl_add_u64 v[58:59], v[58:59], 0, v[136:137]
	global_store_dwordx4 v[60:61], v[54:57], off
	global_store_dwordx4 v[58:59], v[50:53], off
	v_lshl_add_u64 v[42:43], v[142:143], 0, s[18:19]
	s_mov_b64 vcc, s[8:9]
	v_mov_b32_dpp v50, v38 row_ror:8 row_mask:0xf bank_mask:0xf bound_ctrl:1
	v_mov_b32_dpp v51, v39 row_ror:8 row_mask:0xf bank_mask:0xf bound_ctrl:1
	v_mov_b32_dpp v52, v34 row_ror:8 row_mask:0xf bank_mask:0xf bound_ctrl:1
	v_mov_b32_dpp v53, v35 row_ror:8 row_mask:0xf bank_mask:0xf bound_ctrl:1
	v_lshl_add_u64 v[44:45], v[42:43], 0, v[134:135]
	v_cndmask_b32_dpp v37, v49, v35, vcc row_ror:8 row_mask:0xf bank_mask:0xf bound_ctrl:1
	v_cndmask_b32_dpp v36, v48, v34, vcc row_ror:8 row_mask:0xf bank_mask:0xf bound_ctrl:1
	v_cndmask_b32_dpp v35, v47, v39, vcc row_ror:8 row_mask:0xf bank_mask:0xf bound_ctrl:1
	v_cndmask_b32_dpp v34, v46, v38, vcc row_ror:8 row_mask:0xf bank_mask:0xf bound_ctrl:1
	v_cndmask_b32_e64 v41, v49, v53, s[8:9]
	v_cndmask_b32_e64 v40, v48, v52, s[8:9]
	v_cndmask_b32_e64 v39, v47, v51, s[8:9]
	v_cndmask_b32_e64 v38, v46, v50, s[8:9]
	v_cvt_pk_bf16_f32 v30, v30, v31
	v_cvt_pk_bf16_f32 v31, v32, v33
	v_cvt_pk_bf16_f32 v32, v26, v27
	v_cvt_pk_bf16_f32 v33, v28, v29
	v_cvt_pk_bf16_f32 v22, v22, v23
	v_cvt_pk_bf16_f32 v23, v24, v25
	v_cvt_pk_bf16_f32 v18, v18, v19
	v_cvt_pk_bf16_f32 v19, v20, v21
	v_lshl_add_u64 v[42:43], v[42:43], 0, v[136:137]
	global_store_dwordx4 v[44:45], v[38:41], off
	global_store_dwordx4 v[42:43], v[34:37], off
	v_lshl_add_u64 v[26:27], v[142:143], 0, s[20:21]
	s_mov_b64 vcc, s[8:9]
	v_mov_b32_dpp v34, v22 row_ror:8 row_mask:0xf bank_mask:0xf bound_ctrl:1
	v_mov_b32_dpp v35, v23 row_ror:8 row_mask:0xf bank_mask:0xf bound_ctrl:1
	v_mov_b32_dpp v36, v18 row_ror:8 row_mask:0xf bank_mask:0xf bound_ctrl:1
	v_mov_b32_dpp v37, v19 row_ror:8 row_mask:0xf bank_mask:0xf bound_ctrl:1
	v_lshl_add_u64 v[28:29], v[26:27], 0, v[134:135]
	v_cndmask_b32_dpp v21, v33, v19, vcc row_ror:8 row_mask:0xf bank_mask:0xf bound_ctrl:1
	v_cndmask_b32_dpp v20, v32, v18, vcc row_ror:8 row_mask:0xf bank_mask:0xf bound_ctrl:1
	v_cndmask_b32_dpp v19, v31, v23, vcc row_ror:8 row_mask:0xf bank_mask:0xf bound_ctrl:1
	v_cndmask_b32_dpp v18, v30, v22, vcc row_ror:8 row_mask:0xf bank_mask:0xf bound_ctrl:1
	v_cndmask_b32_e64 v25, v33, v37, s[8:9]
	v_cndmask_b32_e64 v24, v32, v36, s[8:9]
	v_cndmask_b32_e64 v23, v31, v35, s[8:9]
	v_cndmask_b32_e64 v22, v30, v34, s[8:9]
	v_cvt_pk_bf16_f32 v14, v14, v15
	v_cvt_pk_bf16_f32 v15, v16, v17
	v_cvt_pk_bf16_f32 v16, v10, v11
	v_cvt_pk_bf16_f32 v17, v12, v13
	v_cvt_pk_bf16_f32 v6, v6, v7
	v_cvt_pk_bf16_f32 v7, v8, v9
	v_cvt_pk_bf16_f32 v2, v2, v3
	v_cvt_pk_bf16_f32 v3, v4, v5
	v_lshl_add_u64 v[26:27], v[26:27], 0, v[136:137]
	global_store_dwordx4 v[28:29], v[22:25], off
	global_store_dwordx4 v[26:27], v[18:21], off
	v_lshl_add_u64 v[10:11], v[142:143], 0, s[22:23]
	s_mov_b64 vcc, s[8:9]
	v_mov_b32_dpp v18, v6 row_ror:8 row_mask:0xf bank_mask:0xf bound_ctrl:1
	v_mov_b32_dpp v19, v7 row_ror:8 row_mask:0xf bank_mask:0xf bound_ctrl:1
	v_mov_b32_dpp v20, v2 row_ror:8 row_mask:0xf bank_mask:0xf bound_ctrl:1
	v_mov_b32_dpp v21, v3 row_ror:8 row_mask:0xf bank_mask:0xf bound_ctrl:1
	v_lshl_add_u64 v[12:13], v[10:11], 0, v[134:135]
	v_cndmask_b32_dpp v5, v17, v3, vcc row_ror:8 row_mask:0xf bank_mask:0xf bound_ctrl:1
	v_cndmask_b32_dpp v4, v16, v2, vcc row_ror:8 row_mask:0xf bank_mask:0xf bound_ctrl:1
	v_cndmask_b32_dpp v3, v15, v7, vcc row_ror:8 row_mask:0xf bank_mask:0xf bound_ctrl:1
	v_cndmask_b32_dpp v2, v14, v6, vcc row_ror:8 row_mask:0xf bank_mask:0xf bound_ctrl:1
	v_cndmask_b32_e64 v9, v17, v21, s[8:9]
	v_cndmask_b32_e64 v8, v16, v20, s[8:9]
	v_cndmask_b32_e64 v7, v15, v19, s[8:9]
	v_cndmask_b32_e64 v6, v14, v18, s[8:9]
	s_and_b64 vcc, exec, s[10:11]
	s_mov_b64 s[10:11], -1
	v_lshl_add_u64 v[10:11], v[10:11], 0, v[136:137]
	global_store_dwordx4 v[12:13], v[6:9], off
	global_store_dwordx4 v[10:11], v[2:5], off
	s_cbranch_vccnz .LBB0_1905
	s_andn2_b64 vcc, exec, s[2:3]
	s_cbranch_vccnz .LBB0_1904
	s_barrier
	s_branch .LBB0_1904

; __device__ __forceinline__ unsigned pk2(float lo, float hi) { const f32x2 v = {lo, hi}; return __builtin_bit_cast(unsigned, __builtin_convertvector(v, bf16x2_t)); }
; __device__ __forceinline__ u32x4 ror8(u32x4 v) { u32x4 r;
; #pragma unroll
;     for (int i = 0; i < 4; ++i) r[i] = (unsigned)__builtin_amdgcn_mov_dpp((int)v[i], 0x128, 0xf, 0xf, true);
;     return r; }
; __device__ __forceinline__ void store_pair(unsigned char* own, size_t stride8, int hi_off, u32x4 lo, u32x4 hi, bool upper) {
;     const u32x4 tlo = ror8(lo), thi = ror8(hi);
;     const u32x4 A = upper ? thi : lo, B = upper ? hi : tlo;
;     unsigned char* pa = upper ? own - stride8 + hi_off : own;
;     unsigned char* pb = upper ? own + hi_off : own + stride8;
;     *(u32x4*)pa = A; *(u32x4*)pb = B;
;     __device__ __forceinline__ void operator()(const f32x4 (&acc)[2][2][4][2], const Unit& u, int wr, int wc, int fr, int fq) const {
;     ...
;             for (int m = 0; m < 4; ++m) { unsigned char* rowp = (unsigned char*)(H + ((size_t)(u.pm * (FF / 64) + u.pn * 4 + wc) * 256 + (wr * 64 + fr + ai * 128 + m * 16)) * 64 + 8 * fq); u32x4 w[2];
; #pragma unroll
;                 for (int bj = 0; bj < 2; ++bj) { f32x4 v0 = acc[ai][bj][m][0], v1 = acc[ai][bj][m][1];
; #pragma unroll
;                     for (int j = 0; j < 4; ++j) { const float a = fmaxf(v0[j], 0.f), b = fmaxf(v1[j], 0.f); v0[j] = a * a; v1[j] = b * b; }
;                     w[bj].x = pk2(v0[0], v0[1]); w[bj].y = pk2(v0[2], v0[3]); w[bj].z = pk2(v1[0], v1[1]); w[bj].w = pk2(v1[2], v1[3]); }
;                 store_pair(rowp, (size_t)8 * 64 * 2, 64, w[0], w[1], fr >= 8); }
.LBB0_2266:
	s_lshl_b32 s4, s22, 7
	s_lshl_b32 s5, s24, 2
	s_add_i32 s5, s5, s4
	s_or_b32 s4, s5, s47
	s_ashr_i32 s5, s4, 31
	s_lshl_b64 s[4:5], s[4:5], 15
	s_add_u32 s22, s1, s4
	v_max_f32_e32 v126, 0, v126
	v_max_f32_e32 v122, 0, v122
	v_max_f32_e32 v127, 0, v127
	v_max_f32_e32 v123, 0, v123
	v_max_f32_e32 v128, 0, v128
	v_max_f32_e32 v124, 0, v124
	v_max_f32_e32 v129, 0, v129
	v_max_f32_e32 v125, 0, v125
	v_max_f32_e32 v118, 0, v118
	v_max_f32_e32 v114, 0, v114
	v_max_f32_e32 v119, 0, v119
	v_max_f32_e32 v115, 0, v115
	v_max_f32_e32 v120, 0, v120
	v_max_f32_e32 v116, 0, v116
	v_max_f32_e32 v121, 0, v121
	v_max_f32_e32 v117, 0, v117
	s_addc_u32 s23, s33, s5
	v_pk_mul_f32 v[126:127], v[126:127], v[126:127]
	v_pk_mul_f32 v[122:123], v[122:123], v[122:123]
	v_pk_mul_f32 v[128:129], v[128:129], v[128:129]
	v_pk_mul_f32 v[124:125], v[124:125], v[124:125]
	v_pk_mul_f32 v[118:119], v[118:119], v[118:119]
	v_pk_mul_f32 v[114:115], v[114:115], v[114:115]
	v_pk_mul_f32 v[120:121], v[120:121], v[120:121]
	v_pk_mul_f32 v[116:117], v[116:117], v[116:117]
	v_lshl_add_u64 v[164:165], s[22:23], 0, v[144:145]
	v_cvt_pk_bf16_f32 v126, v126, v127
	v_cvt_pk_bf16_f32 v127, v128, v129
	v_cvt_pk_bf16_f32 v128, v122, v123
	v_cvt_pk_bf16_f32 v129, v124, v125
	v_cvt_pk_bf16_f32 v118, v118, v119
	v_cvt_pk_bf16_f32 v119, v120, v121
	v_cvt_pk_bf16_f32 v114, v114, v115
	v_cvt_pk_bf16_f32 v115, v116, v117
	v_lshl_add_u64 v[122:123], v[164:165], 0, v[138:139]
	s_mov_b64 vcc, s[2:3]
	v_mov_b32_dpp v164, v118 row_ror:8 row_mask:0xf bank_mask:0xf bound_ctrl:1
	v_mov_b32_dpp v165, v119 row_ror:8 row_mask:0xf bank_mask:0xf bound_ctrl:1
	v_mov_b32_dpp v166, v114 row_ror:8 row_mask:0xf bank_mask:0xf bound_ctrl:1
	v_mov_b32_dpp v167, v115 row_ror:8 row_mask:0xf bank_mask:0xf bound_ctrl:1
	v_max_f32_e32 v110, 0, v110
	v_max_f32_e32 v106, 0, v106
	v_max_f32_e32 v111, 0, v111
	v_max_f32_e32 v107, 0, v107
	v_max_f32_e32 v112, 0, v112
	v_max_f32_e32 v108, 0, v108
	v_max_f32_e32 v113, 0, v113
	v_max_f32_e32 v109, 0, v109
	v_max_f32_e32 v102, 0, v102
	v_max_f32_e32 v98, 0, v98
	v_max_f32_e32 v103, 0, v103
	v_max_f32_e32 v99, 0, v99
	v_max_f32_e32 v104, 0, v104
	v_max_f32_e32 v100, 0, v100
	v_max_f32_e32 v105, 0, v105
	v_max_f32_e32 v101, 0, v101
	v_lshl_add_u64 v[124:125], v[122:123], 0, v[140:141]
	v_cndmask_b32_dpp v117, v129, v115, vcc row_ror:8 row_mask:0xf bank_mask:0xf bound_ctrl:1
	v_cndmask_b32_dpp v116, v128, v114, vcc row_ror:8 row_mask:0xf bank_mask:0xf bound_ctrl:1
	v_cndmask_b32_dpp v115, v127, v119, vcc row_ror:8 row_mask:0xf bank_mask:0xf bound_ctrl:1
	v_cndmask_b32_dpp v114, v126, v118, vcc row_ror:8 row_mask:0xf bank_mask:0xf bound_ctrl:1
	v_cndmask_b32_e64 v121, v129, v167, s[2:3]
	v_cndmask_b32_e64 v120, v128, v166, s[2:3]
	v_cndmask_b32_e64 v119, v127, v165, s[2:3]
	v_cndmask_b32_e64 v118, v126, v164, s[2:3]
	v_pk_mul_f32 v[110:111], v[110:111], v[110:111]
	v_pk_mul_f32 v[106:107], v[106:107], v[106:107]
	v_pk_mul_f32 v[112:113], v[112:113], v[112:113]
	v_pk_mul_f32 v[108:109], v[108:109], v[108:109]
	v_pk_mul_f32 v[102:103], v[102:103], v[102:103]
	v_pk_mul_f32 v[98:99], v[98:99], v[98:99]
	v_pk_mul_f32 v[104:105], v[104:105], v[104:105]
	v_pk_mul_f32 v[100:101], v[100:101], v[100:101]
	v_lshl_add_u64 v[122:123], v[122:123], 0, v[142:143]
	global_store_dwordx4 v[124:125], v[118:121], off
	global_store_dwordx4 v[122:123], v[114:117], off
	v_cvt_pk_bf16_f32 v110, v110, v111
	v_cvt_pk_bf16_f32 v111, v112, v113
	v_lshl_add_u64 v[114:115], s[22:23], 0, v[146:147]
	v_cvt_pk_bf16_f32 v112, v106, v107
	v_cvt_pk_bf16_f32 v113, v108, v109
	v_cvt_pk_bf16_f32 v102, v102, v103
	v_cvt_pk_bf16_f32 v103, v104, v105
	v_cvt_pk_bf16_f32 v98, v98, v99
	v_cvt_pk_bf16_f32 v99, v100, v101
	v_lshl_add_u64 v[106:107], v[114:115], 0, v[138:139]
	s_mov_b64 vcc, s[2:3]
	v_mov_b32_dpp v114, v102 row_ror:8 row_mask:0xf bank_mask:0xf bound_ctrl:1
	v_mov_b32_dpp v115, v103 row_ror:8 row_mask:0xf bank_mask:0xf bound_ctrl:1
	v_mov_b32_dpp v116, v98 row_ror:8 row_mask:0xf bank_mask:0xf bound_ctrl:1
	v_mov_b32_dpp v117, v99 row_ror:8 row_mask:0xf bank_mask:0xf bound_ctrl:1
	v_max_f32_e32 v94, 0, v94
	v_max_f32_e32 v90, 0, v90
	v_max_f32_e32 v95, 0, v95
	v_max_f32_e32 v91, 0, v91
	v_max_f32_e32 v96, 0, v96
	v_max_f32_e32 v92, 0, v92
	v_max_f32_e32 v97, 0, v97
	v_max_f32_e32 v93, 0, v93
	v_max_f32_e32 v86, 0, v86
	v_max_f32_e32 v82, 0, v82
	v_max_f32_e32 v87, 0, v87
	v_max_f32_e32 v83, 0, v83
	v_max_f32_e32 v88, 0, v88
	v_max_f32_e32 v84, 0, v84
	v_max_f32_e32 v89, 0, v89
	v_max_f32_e32 v85, 0, v85
	v_lshl_add_u64 v[108:109], v[106:107], 0, v[140:141]
	v_cndmask_b32_dpp v101, v113, v99, vcc row_ror:8 row_mask:0xf bank_mask:0xf bound_ctrl:1
	v_cndmask_b32_dpp v100, v112, v98, vcc row_ror:8 row_mask:0xf bank_mask:0xf bound_ctrl:1
	v_cndmask_b32_dpp v99, v111, v103, vcc row_ror:8 row_mask:0xf bank_mask:0xf bound_ctrl:1
	v_cndmask_b32_dpp v98, v110, v102, vcc row_ror:8 row_mask:0xf bank_mask:0xf bound_ctrl:1
	v_cndmask_b32_e64 v105, v113, v117, s[2:3]
	v_cndmask_b32_e64 v104, v112, v116, s[2:3]
	v_cndmask_b32_e64 v103, v111, v115, s[2:3]
	v_cndmask_b32_e64 v102, v110, v114, s[2:3]
	v_pk_mul_f32 v[94:95], v[94:95], v[94:95]
	v_pk_mul_f32 v[90:91], v[90:91], v[90:91]
	v_pk_mul_f32 v[96:97], v[96:97], v[96:97]
	v_pk_mul_f32 v[92:93], v[92:93], v[92:93]
	v_pk_mul_f32 v[86:87], v[86:87], v[86:87]
	v_pk_mul_f32 v[82:83], v[82:83], v[82:83]
	v_pk_mul_f32 v[88:89], v[88:89], v[88:89]
	v_pk_mul_f32 v[84:85], v[84:85], v[84:85]
	v_lshl_add_u64 v[106:107], v[106:107], 0, v[142:143]
	global_store_dwordx4 v[108:109], v[102:105], off
	global_store_dwordx4 v[106:107], v[98:101], off
	v_cvt_pk_bf16_f32 v94, v94, v95
; __device__ __forceinline__ unsigned pk2(float lo, float hi) { const f32x2 v = {lo, hi}; return __builtin_bit_cast(unsigned, __builtin_convertvector(v, bf16x2_t)); }
; __device__ __forceinline__ u32x4 ror8(u32x4 v) { u32x4 r;
; #pragma unroll
;     for (int i = 0; i < 4; ++i) r[i] = (unsigned)__builtin_amdgcn_mov_dpp((int)v[i], 0x128, 0xf, 0xf, true);
;     return r; }
; __device__ __forceinline__ void store_pair(unsigned char* own, size_t stride8, int hi_off, u32x4 lo, u32x4 hi, bool upper) {
;     const u32x4 tlo = ror8(lo), thi = ror8(hi);
;     const u32x4 A = upper ? thi : lo, B = upper ? hi : tlo;
;     unsigned char* pa = upper ? own - stride8 + hi_off : own;
;     unsigned char* pb = upper ? own + hi_off : own + stride8;
;     *(u32x4*)pa = A; *(u32x4*)pb = B;
;     __device__ __forceinline__ void operator()(const f32x4 (&acc)[2][2][4][2], const Unit& u, int wr, int wc, int fr, int fq) const {
;     ...
;             for (int m = 0; m < 4; ++m) { unsigned char* rowp = (unsigned char*)(H + ((size_t)(u.pm * (FF / 64) + u.pn * 4 + wc) * 256 + (wr * 64 + fr + ai * 128 + m * 16)) * 64 + 8 * fq); u32x4 w[2];
; #pragma unroll
;                 for (int bj = 0; bj < 2; ++bj) { f32x4 v0 = acc[ai][bj][m][0], v1 = acc[ai][bj][m][1];
; #pragma unroll
;                     for (int j = 0; j < 4; ++j) { const float a = fmaxf(v0[j], 0.f), b = fmaxf(v1[j], 0.f); v0[j] = a * a; v1[j] = b * b; }
;                     w[bj].x = pk2(v0[0], v0[1]); w[bj].y = pk2(v0[2], v0[3]); w[bj].z = pk2(v1[0], v1[1]); w[bj].w = pk2(v1[2], v1[3]); }
;                 store_pair(rowp, (size_t)8 * 64 * 2, 64, w[0], w[1], fr >= 8); }
	v_cvt_pk_bf16_f32 v95, v96, v97
	v_lshl_add_u64 v[98:99], s[22:23], 0, v[148:149]
	v_cvt_pk_bf16_f32 v96, v90, v91
	v_cvt_pk_bf16_f32 v97, v92, v93
	v_cvt_pk_bf16_f32 v86, v86, v87
	v_cvt_pk_bf16_f32 v87, v88, v89
	v_cvt_pk_bf16_f32 v82, v82, v83
	v_cvt_pk_bf16_f32 v83, v84, v85
	v_lshl_add_u64 v[90:91], v[98:99], 0, v[138:139]
	s_mov_b64 vcc, s[2:3]
	v_mov_b32_dpp v98, v86 row_ror:8 row_mask:0xf bank_mask:0xf bound_ctrl:1
	v_mov_b32_dpp v99, v87 row_ror:8 row_mask:0xf bank_mask:0xf bound_ctrl:1
	v_mov_b32_dpp v100, v82 row_ror:8 row_mask:0xf bank_mask:0xf bound_ctrl:1
	v_mov_b32_dpp v101, v83 row_ror:8 row_mask:0xf bank_mask:0xf bound_ctrl:1
	v_max_f32_e32 v78, 0, v78
	v_max_f32_e32 v74, 0, v74
	v_max_f32_e32 v79, 0, v79
	v_max_f32_e32 v75, 0, v75
	v_max_f32_e32 v80, 0, v80
	v_max_f32_e32 v76, 0, v76
	v_max_f32_e32 v81, 0, v81
	v_max_f32_e32 v77, 0, v77
	v_max_f32_e32 v70, 0, v70
	v_max_f32_e32 v66, 0, v66
	v_max_f32_e32 v71, 0, v71
	v_max_f32_e32 v67, 0, v67
	v_max_f32_e32 v72, 0, v72
	v_max_f32_e32 v68, 0, v68
	v_max_f32_e32 v73, 0, v73
	v_max_f32_e32 v69, 0, v69
	v_lshl_add_u64 v[92:93], v[90:91], 0, v[140:141]
	v_cndmask_b32_dpp v85, v97, v83, vcc row_ror:8 row_mask:0xf bank_mask:0xf bound_ctrl:1
	v_cndmask_b32_dpp v84, v96, v82, vcc row_ror:8 row_mask:0xf bank_mask:0xf bound_ctrl:1
	v_cndmask_b32_dpp v83, v95, v87, vcc row_ror:8 row_mask:0xf bank_mask:0xf bound_ctrl:1
	v_cndmask_b32_dpp v82, v94, v86, vcc row_ror:8 row_mask:0xf bank_mask:0xf bound_ctrl:1
	v_cndmask_b32_e64 v89, v97, v101, s[2:3]
	v_cndmask_b32_e64 v88, v96, v100, s[2:3]
	v_cndmask_b32_e64 v87, v95, v99, s[2:3]
	v_cndmask_b32_e64 v86, v94, v98, s[2:3]
	v_pk_mul_f32 v[78:79], v[78:79], v[78:79]
	v_pk_mul_f32 v[74:75], v[74:75], v[74:75]
	v_pk_mul_f32 v[80:81], v[80:81], v[80:81]
	v_pk_mul_f32 v[76:77], v[76:77], v[76:77]
	v_pk_mul_f32 v[70:71], v[70:71], v[70:71]
	v_pk_mul_f32 v[66:67], v[66:67], v[66:67]
	v_pk_mul_f32 v[72:73], v[72:73], v[72:73]
	v_pk_mul_f32 v[68:69], v[68:69], v[68:69]
	v_lshl_add_u64 v[90:91], v[90:91], 0, v[142:143]
	global_store_dwordx4 v[92:93], v[86:89], off
	global_store_dwordx4 v[90:91], v[82:85], off
	v_cvt_pk_bf16_f32 v78, v78, v79
	v_cvt_pk_bf16_f32 v79, v80, v81
	v_lshl_add_u64 v[82:83], s[22:23], 0, v[150:151]
	v_cvt_pk_bf16_f32 v80, v74, v75
	v_cvt_pk_bf16_f32 v81, v76, v77
	v_cvt_pk_bf16_f32 v70, v70, v71
	v_cvt_pk_bf16_f32 v71, v72, v73
	v_cvt_pk_bf16_f32 v66, v66, v67
	v_cvt_pk_bf16_f32 v67, v68, v69
	v_lshl_add_u64 v[74:75], v[82:83], 0, v[138:139]
	s_mov_b64 vcc, s[2:3]
	v_mov_b32_dpp v82, v70 row_ror:8 row_mask:0xf bank_mask:0xf bound_ctrl:1
	v_mov_b32_dpp v83, v71 row_ror:8 row_mask:0xf bank_mask:0xf bound_ctrl:1
	v_mov_b32_dpp v84, v66 row_ror:8 row_mask:0xf bank_mask:0xf bound_ctrl:1
	v_mov_b32_dpp v85, v67 row_ror:8 row_mask:0xf bank_mask:0xf bound_ctrl:1
	v_max_f32_e32 v62, 0, v62
	v_max_f32_e32 v58, 0, v58
	v_max_f32_e32 v63, 0, v63
	v_max_f32_e32 v59, 0, v59
	v_max_f32_e32 v64, 0, v64
	v_max_f32_e32 v60, 0, v60
	v_max_f32_e32 v65, 0, v65
	v_max_f32_e32 v61, 0, v61
	v_max_f32_e32 v54, 0, v54
	v_max_f32_e32 v50, 0, v50
	v_max_f32_e32 v55, 0, v55
	v_max_f32_e32 v51, 0, v51
	v_max_f32_e32 v56, 0, v56
	v_max_f32_e32 v52, 0, v52
	v_max_f32_e32 v57, 0, v57
	v_max_f32_e32 v53, 0, v53
	v_lshl_add_u64 v[76:77], v[74:75], 0, v[140:141]
	v_cndmask_b32_dpp v69, v81, v67, vcc row_ror:8 row_mask:0xf bank_mask:0xf bound_ctrl:1
	v_cndmask_b32_dpp v68, v80, v66, vcc row_ror:8 row_mask:0xf bank_mask:0xf bound_ctrl:1
	v_cndmask_b32_dpp v67, v79, v71, vcc row_ror:8 row_mask:0xf bank_mask:0xf bound_ctrl:1
	v_cndmask_b32_dpp v66, v78, v70, vcc row_ror:8 row_mask:0xf bank_mask:0xf bound_ctrl:1
	v_cndmask_b32_e64 v73, v81, v85, s[2:3]
	v_cndmask_b32_e64 v72, v80, v84, s[2:3]
	v_cndmask_b32_e64 v71, v79, v83, s[2:3]
	v_cndmask_b32_e64 v70, v78, v82, s[2:3]
	v_pk_mul_f32 v[62:63], v[62:63], v[62:63]
	v_pk_mul_f32 v[58:59], v[58:59], v[58:59]
	v_pk_mul_f32 v[64:65], v[64:65], v[64:65]
	v_pk_mul_f32 v[60:61], v[60:61], v[60:61]
	v_pk_mul_f32 v[54:55], v[54:55], v[54:55]
	v_pk_mul_f32 v[50:51], v[50:51], v[50:51]
	v_pk_mul_f32 v[56:57], v[56:57], v[56:57]
	v_pk_mul_f32 v[52:53], v[52:53], v[52:53]
	v_lshl_add_u64 v[74:75], v[74:75], 0, v[142:143]
	global_store_dwordx4 v[76:77], v[70:73], off
	global_store_dwordx4 v[74:75], v[66:69], off
	v_cvt_pk_bf16_f32 v62, v62, v63
	v_cvt_pk_bf16_f32 v63, v64, v65
	v_lshl_add_u64 v[66:67], s[22:23], 0, v[152:153]
	v_cvt_pk_bf16_f32 v64, v58, v59
	v_cvt_pk_bf16_f32 v65, v60, v61
	v_cvt_pk_bf16_f32 v54, v54, v55
	v_cvt_pk_bf16_f32 v55, v56, v57
	v_cvt_pk_bf16_f32 v50, v50, v51
	v_cvt_pk_bf16_f32 v51, v52, v53
	v_lshl_add_u64 v[58:59], v[66:67], 0, v[138:139]
	s_mov_b64 vcc, s[2:3]
	v_mov_b32_dpp v66, v54 row_ror:8 row_mask:0xf bank_mask:0xf bound_ctrl:1
	v_mov_b32_dpp v67, v55 row_ror:8 row_mask:0xf bank_mask:0xf bound_ctrl:1
	v_mov_b32_dpp v68, v50 row_ror:8 row_mask:0xf bank_mask:0xf bound_ctrl:1
	v_mov_b32_dpp v69, v51 row_ror:8 row_mask:0xf bank_mask:0xf bound_ctrl:1
	v_max_f32_e32 v46, 0, v46
	v_max_f32_e32 v42, 0, v42
	v_max_f32_e32 v47, 0, v47
	v_max_f32_e32 v43, 0, v43
	v_max_f32_e32 v48, 0, v48
	v_max_f32_e32 v44, 0, v44
	v_max_f32_e32 v49, 0, v49
	v_max_f32_e32 v45, 0, v45
	v_max_f32_e32 v38, 0, v38
	v_max_f32_e32 v34, 0, v34
	v_max_f32_e32 v39, 0, v39
	v_max_f32_e32 v35, 0, v35
	v_max_f32_e32 v40, 0, v40
	v_max_f32_e32 v36, 0, v36
	v_max_f32_e32 v41, 0, v41
	v_max_f32_e32 v37, 0, v37
	v_lshl_add_u64 v[60:61], v[58:59], 0, v[140:141]
	v_cndmask_b32_dpp v53, v65, v51, vcc row_ror:8 row_mask:0xf bank_mask:0xf bound_ctrl:1
	v_cndmask_b32_dpp v52, v64, v50, vcc row_ror:8 row_mask:0xf bank_mask:0xf bound_ctrl:1
; __device__ __forceinline__ unsigned pk2(float lo, float hi) { const f32x2 v = {lo, hi}; return __builtin_bit_cast(unsigned, __builtin_convertvector(v, bf16x2_t)); }
; __device__ __forceinline__ u32x4 ror8(u32x4 v) { u32x4 r;
; #pragma unroll
;     for (int i = 0; i < 4; ++i) r[i] = (unsigned)__builtin_amdgcn_mov_dpp((int)v[i], 0x128, 0xf, 0xf, true);
;     return r; }
; __device__ __forceinline__ void store_pair(unsigned char* own, size_t stride8, int hi_off, u32x4 lo, u32x4 hi, bool upper) {
;     const u32x4 tlo = ror8(lo), thi = ror8(hi);
;     const u32x4 A = upper ? thi : lo, B = upper ? hi : tlo;
;     unsigned char* pa = upper ? own - stride8 + hi_off : own;
;     unsigned char* pb = upper ? own + hi_off : own + stride8;
;     *(u32x4*)pa = A; *(u32x4*)pb = B;
;     __device__ __forceinline__ void operator()(const f32x4 (&acc)[2][2][4][2], const Unit& u, int wr, int wc, int fr, int fq) const {
;     ...
;             for (int m = 0; m < 4; ++m) { unsigned char* rowp = (unsigned char*)(H + ((size_t)(u.pm * (FF / 64) + u.pn * 4 + wc) * 256 + (wr * 64 + fr + ai * 128 + m * 16)) * 64 + 8 * fq); u32x4 w[2];
; #pragma unroll
;                 for (int bj = 0; bj < 2; ++bj) { f32x4 v0 = acc[ai][bj][m][0], v1 = acc[ai][bj][m][1];
; #pragma unroll
;                     for (int j = 0; j < 4; ++j) { const float a = fmaxf(v0[j], 0.f), b = fmaxf(v1[j], 0.f); v0[j] = a * a; v1[j] = b * b; }
;                     w[bj].x = pk2(v0[0], v0[1]); w[bj].y = pk2(v0[2], v0[3]); w[bj].z = pk2(v1[0], v1[1]); w[bj].w = pk2(v1[2], v1[3]); }
;                 store_pair(rowp, (size_t)8 * 64 * 2, 64, w[0], w[1], fr >= 8); }
	v_cndmask_b32_dpp v51, v63, v55, vcc row_ror:8 row_mask:0xf bank_mask:0xf bound_ctrl:1
	v_cndmask_b32_dpp v50, v62, v54, vcc row_ror:8 row_mask:0xf bank_mask:0xf bound_ctrl:1
	v_cndmask_b32_e64 v57, v65, v69, s[2:3]
	v_cndmask_b32_e64 v56, v64, v68, s[2:3]
	v_cndmask_b32_e64 v55, v63, v67, s[2:3]
	v_cndmask_b32_e64 v54, v62, v66, s[2:3]
	v_pk_mul_f32 v[46:47], v[46:47], v[46:47]
	v_pk_mul_f32 v[42:43], v[42:43], v[42:43]
	v_pk_mul_f32 v[48:49], v[48:49], v[48:49]
	v_pk_mul_f32 v[44:45], v[44:45], v[44:45]
	v_pk_mul_f32 v[38:39], v[38:39], v[38:39]
	v_pk_mul_f32 v[34:35], v[34:35], v[34:35]
	v_pk_mul_f32 v[40:41], v[40:41], v[40:41]
	v_pk_mul_f32 v[36:37], v[36:37], v[36:37]
	v_lshl_add_u64 v[58:59], v[58:59], 0, v[142:143]
	global_store_dwordx4 v[60:61], v[54:57], off
	global_store_dwordx4 v[58:59], v[50:53], off
	v_cvt_pk_bf16_f32 v46, v46, v47
	v_cvt_pk_bf16_f32 v47, v48, v49
	v_lshl_add_u64 v[50:51], s[22:23], 0, v[154:155]
	v_cvt_pk_bf16_f32 v48, v42, v43
	v_cvt_pk_bf16_f32 v49, v44, v45
	v_cvt_pk_bf16_f32 v38, v38, v39
	v_cvt_pk_bf16_f32 v39, v40, v41
	v_cvt_pk_bf16_f32 v34, v34, v35
	v_cvt_pk_bf16_f32 v35, v36, v37
	v_lshl_add_u64 v[42:43], v[50:51], 0, v[138:139]
	s_mov_b64 vcc, s[2:3]
	v_mov_b32_dpp v50, v38 row_ror:8 row_mask:0xf bank_mask:0xf bound_ctrl:1
	v_mov_b32_dpp v51, v39 row_ror:8 row_mask:0xf bank_mask:0xf bound_ctrl:1
	v_mov_b32_dpp v52, v34 row_ror:8 row_mask:0xf bank_mask:0xf bound_ctrl:1
	v_mov_b32_dpp v53, v35 row_ror:8 row_mask:0xf bank_mask:0xf bound_ctrl:1
	v_max_f32_e32 v30, 0, v30
	v_max_f32_e32 v26, 0, v26
	v_max_f32_e32 v31, 0, v31
	v_max_f32_e32 v27, 0, v27
	v_max_f32_e32 v32, 0, v32
	v_max_f32_e32 v28, 0, v28
	v_max_f32_e32 v33, 0, v33
	v_max_f32_e32 v29, 0, v29
	v_max_f32_e32 v22, 0, v22
	v_max_f32_e32 v18, 0, v18
	v_max_f32_e32 v23, 0, v23
	v_max_f32_e32 v19, 0, v19
	v_max_f32_e32 v24, 0, v24
	v_max_f32_e32 v20, 0, v20
	v_max_f32_e32 v25, 0, v25
	v_max_f32_e32 v21, 0, v21
	v_lshl_add_u64 v[44:45], v[42:43], 0, v[140:141]
	v_cndmask_b32_dpp v37, v49, v35, vcc row_ror:8 row_mask:0xf bank_mask:0xf bound_ctrl:1
	v_cndmask_b32_dpp v36, v48, v34, vcc row_ror:8 row_mask:0xf bank_mask:0xf bound_ctrl:1
	v_cndmask_b32_dpp v35, v47, v39, vcc row_ror:8 row_mask:0xf bank_mask:0xf bound_ctrl:1
	v_cndmask_b32_dpp v34, v46, v38, vcc row_ror:8 row_mask:0xf bank_mask:0xf bound_ctrl:1
	v_cndmask_b32_e64 v41, v49, v53, s[2:3]
	v_cndmask_b32_e64 v40, v48, v52, s[2:3]
	v_cndmask_b32_e64 v39, v47, v51, s[2:3]
	v_cndmask_b32_e64 v38, v46, v50, s[2:3]
	v_pk_mul_f32 v[30:31], v[30:31], v[30:31]
	v_pk_mul_f32 v[26:27], v[26:27], v[26:27]
	v_pk_mul_f32 v[32:33], v[32:33], v[32:33]
	v_pk_mul_f32 v[28:29], v[28:29], v[28:29]
	v_pk_mul_f32 v[22:23], v[22:23], v[22:23]
	v_pk_mul_f32 v[18:19], v[18:19], v[18:19]
	v_pk_mul_f32 v[24:25], v[24:25], v[24:25]
	v_pk_mul_f32 v[20:21], v[20:21], v[20:21]
	v_lshl_add_u64 v[42:43], v[42:43], 0, v[142:143]
	global_store_dwordx4 v[44:45], v[38:41], off
	global_store_dwordx4 v[42:43], v[34:37], off
	v_cvt_pk_bf16_f32 v30, v30, v31
	v_cvt_pk_bf16_f32 v31, v32, v33
	v_lshl_add_u64 v[34:35], s[22:23], 0, v[156:157]
	v_cvt_pk_bf16_f32 v32, v26, v27
	v_cvt_pk_bf16_f32 v33, v28, v29
	v_cvt_pk_bf16_f32 v22, v22, v23
	v_cvt_pk_bf16_f32 v23, v24, v25
	v_cvt_pk_bf16_f32 v18, v18, v19
	v_cvt_pk_bf16_f32 v19, v20, v21
	v_lshl_add_u64 v[26:27], v[34:35], 0, v[138:139]
	s_mov_b64 vcc, s[2:3]
	v_mov_b32_dpp v34, v22 row_ror:8 row_mask:0xf bank_mask:0xf bound_ctrl:1
	v_mov_b32_dpp v35, v23 row_ror:8 row_mask:0xf bank_mask:0xf bound_ctrl:1
	v_mov_b32_dpp v36, v18 row_ror:8 row_mask:0xf bank_mask:0xf bound_ctrl:1
	v_mov_b32_dpp v37, v19 row_ror:8 row_mask:0xf bank_mask:0xf bound_ctrl:1
	v_max_f32_e32 v14, 0, v14
	v_max_f32_e32 v10, 0, v10
	v_max_f32_e32 v15, 0, v15
	v_max_f32_e32 v11, 0, v11
	v_max_f32_e32 v16, 0, v16
	v_max_f32_e32 v12, 0, v12
	v_max_f32_e32 v17, 0, v17
	v_max_f32_e32 v13, 0, v13
	v_max_f32_e32 v6, 0, v6
	v_max_f32_e32 v2, 0, v2
	v_max_f32_e32 v7, 0, v7
	v_max_f32_e32 v3, 0, v3
	v_max_f32_e32 v8, 0, v8
	v_max_f32_e32 v4, 0, v4
	v_max_f32_e32 v9, 0, v9
	v_max_f32_e32 v5, 0, v5
	v_lshl_add_u64 v[28:29], v[26:27], 0, v[140:141]
	v_cndmask_b32_dpp v21, v33, v19, vcc row_ror:8 row_mask:0xf bank_mask:0xf bound_ctrl:1
	v_cndmask_b32_dpp v20, v32, v18, vcc row_ror:8 row_mask:0xf bank_mask:0xf bound_ctrl:1
	v_cndmask_b32_dpp v19, v31, v23, vcc row_ror:8 row_mask:0xf bank_mask:0xf bound_ctrl:1
	v_cndmask_b32_dpp v18, v30, v22, vcc row_ror:8 row_mask:0xf bank_mask:0xf bound_ctrl:1
	v_cndmask_b32_e64 v25, v33, v37, s[2:3]
	v_cndmask_b32_e64 v24, v32, v36, s[2:3]
	v_cndmask_b32_e64 v23, v31, v35, s[2:3]
	v_cndmask_b32_e64 v22, v30, v34, s[2:3]
	v_pk_mul_f32 v[14:15], v[14:15], v[14:15]
	v_pk_mul_f32 v[10:11], v[10:11], v[10:11]
	v_pk_mul_f32 v[16:17], v[16:17], v[16:17]
	v_pk_mul_f32 v[12:13], v[12:13], v[12:13]
	v_pk_mul_f32 v[6:7], v[6:7], v[6:7]
	v_pk_mul_f32 v[2:3], v[2:3], v[2:3]
	v_pk_mul_f32 v[8:9], v[8:9], v[8:9]
	v_pk_mul_f32 v[4:5], v[4:5], v[4:5]
	v_lshl_add_u64 v[26:27], v[26:27], 0, v[142:143]
	global_store_dwordx4 v[28:29], v[22:25], off
	global_store_dwordx4 v[26:27], v[18:21], off
	v_cvt_pk_bf16_f32 v14, v14, v15
	v_cvt_pk_bf16_f32 v15, v16, v17
	v_lshl_add_u64 v[18:19], s[22:23], 0, v[158:159]
	v_cvt_pk_bf16_f32 v16, v10, v11
	v_cvt_pk_bf16_f32 v17, v12, v13
	v_cvt_pk_bf16_f32 v6, v6, v7
	v_cvt_pk_bf16_f32 v7, v8, v9
	v_cvt_pk_bf16_f32 v2, v2, v3
	v_cvt_pk_bf16_f32 v3, v4, v5
	v_lshl_add_u64 v[10:11], v[18:19], 0, v[138:139]
	s_mov_b64 vcc, s[2:3]
	v_mov_b32_dpp v18, v6 row_ror:8 row_mask:0xf bank_mask:0xf bound_ctrl:1
	v_mov_b32_dpp v19, v7 row_ror:8 row_mask:0xf bank_mask:0xf bound_ctrl:1
	v_mov_b32_dpp v20, v2 row_ror:8 row_mask:0xf bank_mask:0xf bound_ctrl:1
	v_mov_b32_dpp v21, v3 row_ror:8 row_mask:0xf bank_mask:0xf bound_ctrl:1
	v_lshl_add_u64 v[12:13], v[10:11], 0, v[140:141]
	v_cndmask_b32_dpp v5, v17, v3, vcc row_ror:8 row_mask:0xf bank_mask:0xf bound_ctrl:1
	v_cndmask_b32_dpp v4, v16, v2, vcc row_ror:8 row_mask:0xf bank_mask:0xf bound_ctrl:1
	v_cndmask_b32_dpp v3, v15, v7, vcc row_ror:8 row_mask:0xf bank_mask:0xf bound_ctrl:1
	v_cndmask_b32_dpp v2, v14, v6, vcc row_ror:8 row_mask:0xf bank_mask:0xf bound_ctrl:1
	v_cndmask_b32_e64 v9, v17, v21, s[2:3]
	v_cndmask_b32_e64 v8, v16, v20, s[2:3]
	v_cndmask_b32_e64 v7, v15, v19, s[2:3]
	v_cndmask_b32_e64 v6, v14, v18, s[2:3]
	s_andn2_b64 vcc, exec, s[18:19]
	s_mov_b64 s[4:5], -1
	v_lshl_add_u64 v[10:11], v[10:11], 0, v[142:143]
	global_store_dwordx4 v[12:13], v[6:9], off
	global_store_dwordx4 v[10:11], v[2:5], off
	s_cbranch_vccnz .LBB0_2259
	s_andn2_b64 vcc, exec, s[6:7]
	s_cbranch_vccnz .LBB0_2258
	s_barrier
	s_branch .LBB0_2258

; __device__ __forceinline__ unsigned pk2(float lo, float hi) { const f32x2 v = {lo, hi}; return __builtin_bit_cast(unsigned, __builtin_convertvector(v, bf16x2_t)); }
; __device__ __forceinline__ u32x4 ror8(u32x4 v) { u32x4 r;
; #pragma unroll
;     for (int i = 0; i < 4; ++i) r[i] = (unsigned)__builtin_amdgcn_mov_dpp((int)v[i], 0x128, 0xf, 0xf, true);
;     return r; }
; __device__ __forceinline__ void store_pair(unsigned char* own, size_t stride8, int hi_off, u32x4 lo, u32x4 hi, bool upper) {
;     const u32x4 tlo = ror8(lo), thi = ror8(hi);
;     const u32x4 A = upper ? thi : lo, B = upper ? hi : tlo;
;     unsigned char* pa = upper ? own - stride8 + hi_off : own;
;     unsigned char* pb = upper ? own + hi_off : own + stride8;
;     *(u32x4*)pa = A; *(u32x4*)pb = B;
;     __device__ __forceinline__ void operator()(const f32x4 (&acc)[2][2][4][2], const Unit& u, int wr, int wc, int fr, int fq) const {
;         const int row0 = u.pm * 256 + wr * 64 + fr, col0 = u.pn * 256 + wc * 64 + 8 * fq;
;         bf16_t* base = u.part == 0 ? Z + (size_t)row0 * D + col0 : P + ((size_t)(u.part - 1) * MS + (row0 - MP)) * D + col0;
; #pragma unroll
;         for (int ai = 0; ai < 2; ++ai)
; #pragma unroll
;             for (int m = 0; m < 4; ++m) { u32x4 w[2];
; #pragma unroll
;                 for (int bj = 0; bj < 2; ++bj) { const f32x4 v0 = acc[ai][bj][m][0], v1 = acc[ai][bj][m][1]; w[bj].x = pk2(v0[0], v0[1]); w[bj].y = pk2(v0[2], v0[3]); w[bj].z = pk2(v1[0], v1[1]); w[bj].w = pk2(v1[2], v1[3]); }
;                 store_pair((unsigned char*)(base + (size_t)(ai * 128 + m * 16) * D), (size_t)8 * D * 2, 64, w[0], w[1], fr >= 8); }
.LBB0_2331:
	v_lshl_add_u32 v143, s82, 8, v1
	v_add_u32_e32 v144, 0xffffe000, v143
	v_sub_co_u32_e64 v142, vcc, s55, 1
	v_mov_b32_e32 v145, s9
	s_nop 0
	v_cndmask_b32_e32 v144, v144, v143, vcc
	v_ashrrev_i32_e32 v143, 31, v142
	v_lshlrev_b64 v[142:143], 23, v[142:143]
	v_lshl_add_u64 v[142:143], s[12:13], 0, v[142:143]
	v_cndmask_b32_e32 v143, v143, v145, vcc
	v_mov_b32_e32 v145, s8
	v_cndmask_b32_e32 v142, v142, v145, vcc
	v_ashrrev_i32_e32 v145, 31, v144
	v_lshl_or_b32 v152, s78, 8, v147
	v_lshlrev_b64 v[144:145], 12, v[144:145]
	v_lshl_add_u64 v[142:143], v[142:143], 0, v[144:145]
	v_ashrrev_i32_e32 v153, 31, v152
	v_cvt_pk_bf16_f32 v126, v126, v127
	v_cvt_pk_bf16_f32 v127, v128, v129
	v_cvt_pk_bf16_f32 v128, v122, v123
	v_cvt_pk_bf16_f32 v124, v124, v125
	v_cvt_pk_bf16_f32 v118, v118, v119
	v_cvt_pk_bf16_f32 v119, v120, v121
	v_cvt_pk_bf16_f32 v114, v114, v115
	v_cvt_pk_bf16_f32 v115, v116, v117
	v_lshl_add_u64 v[142:143], v[152:153], 1, v[142:143]
	s_mov_b64 vcc, s[2:3]
	v_mov_b32_dpp v125, v118 row_ror:8 row_mask:0xf bank_mask:0xf bound_ctrl:1
	v_mov_b32_dpp v129, v119 row_ror:8 row_mask:0xf bank_mask:0xf bound_ctrl:1
	v_mov_b32_dpp v144, v114 row_ror:8 row_mask:0xf bank_mask:0xf bound_ctrl:1
	v_mov_b32_dpp v145, v115 row_ror:8 row_mask:0xf bank_mask:0xf bound_ctrl:1
	v_lshl_add_u64 v[122:123], v[142:143], 0, v[134:135]
	v_cndmask_b32_dpp v117, v124, v115, vcc row_ror:8 row_mask:0xf bank_mask:0xf bound_ctrl:1
	v_cndmask_b32_dpp v116, v128, v114, vcc row_ror:8 row_mask:0xf bank_mask:0xf bound_ctrl:1
	v_cndmask_b32_dpp v115, v127, v119, vcc row_ror:8 row_mask:0xf bank_mask:0xf bound_ctrl:1
	v_cndmask_b32_dpp v114, v126, v118, vcc row_ror:8 row_mask:0xf bank_mask:0xf bound_ctrl:1
	v_cndmask_b32_e64 v121, v124, v145, s[2:3]
	v_cndmask_b32_e64 v120, v128, v144, s[2:3]
	v_cndmask_b32_e64 v119, v127, v129, s[2:3]
	v_cndmask_b32_e64 v118, v126, v125, s[2:3]
	v_cvt_pk_bf16_f32 v110, v110, v111
	v_cvt_pk_bf16_f32 v111, v112, v113
	v_cvt_pk_bf16_f32 v112, v106, v107
	v_cvt_pk_bf16_f32 v113, v108, v109
	v_cvt_pk_bf16_f32 v102, v102, v103
	v_cvt_pk_bf16_f32 v103, v104, v105
	v_cvt_pk_bf16_f32 v98, v98, v99
	v_cvt_pk_bf16_f32 v99, v100, v101
	v_lshl_add_u64 v[124:125], v[142:143], 0, v[136:137]
	global_store_dwordx4 v[122:123], v[118:121], off
	global_store_dwordx4 v[124:125], v[114:117], off
	v_lshl_add_u64 v[106:107], v[142:143], 0, s[16:17]
	s_mov_b64 vcc, s[2:3]
	v_mov_b32_dpp v114, v102 row_ror:8 row_mask:0xf bank_mask:0xf bound_ctrl:1
	v_mov_b32_dpp v115, v103 row_ror:8 row_mask:0xf bank_mask:0xf bound_ctrl:1
	v_mov_b32_dpp v116, v98 row_ror:8 row_mask:0xf bank_mask:0xf bound_ctrl:1
	v_mov_b32_dpp v117, v99 row_ror:8 row_mask:0xf bank_mask:0xf bound_ctrl:1
	v_lshl_add_u64 v[108:109], v[106:107], 0, v[134:135]
	v_cndmask_b32_dpp v101, v113, v99, vcc row_ror:8 row_mask:0xf bank_mask:0xf bound_ctrl:1
	v_cndmask_b32_dpp v100, v112, v98, vcc row_ror:8 row_mask:0xf bank_mask:0xf bound_ctrl:1
	v_cndmask_b32_dpp v99, v111, v103, vcc row_ror:8 row_mask:0xf bank_mask:0xf bound_ctrl:1
	v_cndmask_b32_dpp v98, v110, v102, vcc row_ror:8 row_mask:0xf bank_mask:0xf bound_ctrl:1
	v_cndmask_b32_e64 v105, v113, v117, s[2:3]
	v_cndmask_b32_e64 v104, v112, v116, s[2:3]
	v_cndmask_b32_e64 v103, v111, v115, s[2:3]
	v_cndmask_b32_e64 v102, v110, v114, s[2:3]
	v_cvt_pk_bf16_f32 v94, v94, v95
	v_cvt_pk_bf16_f32 v95, v96, v97
	v_cvt_pk_bf16_f32 v96, v90, v91
	v_cvt_pk_bf16_f32 v97, v92, v93
	v_cvt_pk_bf16_f32 v86, v86, v87
	v_cvt_pk_bf16_f32 v87, v88, v89
	v_cvt_pk_bf16_f32 v82, v82, v83
	v_cvt_pk_bf16_f32 v83, v84, v85
	v_lshl_add_u64 v[106:107], v[106:107], 0, v[136:137]
	global_store_dwordx4 v[108:109], v[102:105], off
	global_store_dwordx4 v[106:107], v[98:101], off
	v_lshl_add_u64 v[90:91], v[142:143], 0, s[18:19]
	s_mov_b64 vcc, s[2:3]
	v_mov_b32_dpp v98, v86 row_ror:8 row_mask:0xf bank_mask:0xf bound_ctrl:1
	v_mov_b32_dpp v99, v87 row_ror:8 row_mask:0xf bank_mask:0xf bound_ctrl:1
	v_mov_b32_dpp v100, v82 row_ror:8 row_mask:0xf bank_mask:0xf bound_ctrl:1
	v_mov_b32_dpp v101, v83 row_ror:8 row_mask:0xf bank_mask:0xf bound_ctrl:1
	v_lshl_add_u64 v[92:93], v[90:91], 0, v[134:135]
	v_cndmask_b32_dpp v85, v97, v83, vcc row_ror:8 row_mask:0xf bank_mask:0xf bound_ctrl:1
	v_cndmask_b32_dpp v84, v96, v82, vcc row_ror:8 row_mask:0xf bank_mask:0xf bound_ctrl:1
	v_cndmask_b32_dpp v83, v95, v87, vcc row_ror:8 row_mask:0xf bank_mask:0xf bound_ctrl:1
	v_cndmask_b32_dpp v82, v94, v86, vcc row_ror:8 row_mask:0xf bank_mask:0xf bound_ctrl:1
	v_cndmask_b32_e64 v89, v97, v101, s[2:3]
	v_cndmask_b32_e64 v88, v96, v100, s[2:3]
	v_cndmask_b32_e64 v87, v95, v99, s[2:3]
	v_cndmask_b32_e64 v86, v94, v98, s[2:3]
	v_cvt_pk_bf16_f32 v78, v78, v79
	v_cvt_pk_bf16_f32 v79, v80, v81
	v_cvt_pk_bf16_f32 v80, v74, v75
	v_cvt_pk_bf16_f32 v81, v76, v77
	v_cvt_pk_bf16_f32 v70, v70, v71
	v_cvt_pk_bf16_f32 v71, v72, v73
	v_cvt_pk_bf16_f32 v66, v66, v67
	v_cvt_pk_bf16_f32 v67, v68, v69
	v_lshl_add_u64 v[90:91], v[90:91], 0, v[136:137]
	global_store_dwordx4 v[92:93], v[86:89], off
	global_store_dwordx4 v[90:91], v[82:85], off
	v_lshl_add_u64 v[74:75], v[142:143], 0, s[20:21]
	s_mov_b64 vcc, s[2:3]
	v_mov_b32_dpp v82, v70 row_ror:8 row_mask:0xf bank_mask:0xf bound_ctrl:1
	v_mov_b32_dpp v83, v71 row_ror:8 row_mask:0xf bank_mask:0xf bound_ctrl:1
	v_mov_b32_dpp v84, v66 row_ror:8 row_mask:0xf bank_mask:0xf bound_ctrl:1
	v_mov_b32_dpp v85, v67 row_ror:8 row_mask:0xf bank_mask:0xf bound_ctrl:1
	v_lshl_add_u64 v[76:77], v[74:75], 0, v[134:135]
	v_cndmask_b32_dpp v69, v81, v67, vcc row_ror:8 row_mask:0xf bank_mask:0xf bound_ctrl:1
	v_cndmask_b32_dpp v68, v80, v66, vcc row_ror:8 row_mask:0xf bank_mask:0xf bound_ctrl:1
; __device__ __forceinline__ unsigned pk2(float lo, float hi) { const f32x2 v = {lo, hi}; return __builtin_bit_cast(unsigned, __builtin_convertvector(v, bf16x2_t)); }
; __device__ __forceinline__ u32x4 ror8(u32x4 v) { u32x4 r;
; #pragma unroll
;     for (int i = 0; i < 4; ++i) r[i] = (unsigned)__builtin_amdgcn_mov_dpp((int)v[i], 0x128, 0xf, 0xf, true);
;     return r; }
; __device__ __forceinline__ void store_pair(unsigned char* own, size_t stride8, int hi_off, u32x4 lo, u32x4 hi, bool upper) {
;     const u32x4 tlo = ror8(lo), thi = ror8(hi);
;     const u32x4 A = upper ? thi : lo, B = upper ? hi : tlo;
;     unsigned char* pa = upper ? own - stride8 + hi_off : own;
;     unsigned char* pb = upper ? own + hi_off : own + stride8;
;     *(u32x4*)pa = A; *(u32x4*)pb = B;
;     __device__ __forceinline__ void operator()(const f32x4 (&acc)[2][2][4][2], const Unit& u, int wr, int wc, int fr, int fq) const {
;         const int row0 = u.pm * 256 + wr * 64 + fr, col0 = u.pn * 256 + wc * 64 + 8 * fq;
;         bf16_t* base = u.part == 0 ? Z + (size_t)row0 * D + col0 : P + ((size_t)(u.part - 1) * MS + (row0 - MP)) * D + col0;
; #pragma unroll
;         for (int ai = 0; ai < 2; ++ai)
; #pragma unroll
;             for (int m = 0; m < 4; ++m) { u32x4 w[2];
; #pragma unroll
;                 for (int bj = 0; bj < 2; ++bj) { const f32x4 v0 = acc[ai][bj][m][0], v1 = acc[ai][bj][m][1]; w[bj].x = pk2(v0[0], v0[1]); w[bj].y = pk2(v0[2], v0[3]); w[bj].z = pk2(v1[0], v1[1]); w[bj].w = pk2(v1[2], v1[3]); }
;                 store_pair((unsigned char*)(base + (size_t)(ai * 128 + m * 16) * D), (size_t)8 * D * 2, 64, w[0], w[1], fr >= 8); }
	v_cndmask_b32_dpp v67, v79, v71, vcc row_ror:8 row_mask:0xf bank_mask:0xf bound_ctrl:1
	v_cndmask_b32_dpp v66, v78, v70, vcc row_ror:8 row_mask:0xf bank_mask:0xf bound_ctrl:1
	v_cndmask_b32_e64 v73, v81, v85, s[2:3]
	v_cndmask_b32_e64 v72, v80, v84, s[2:3]
	v_cndmask_b32_e64 v71, v79, v83, s[2:3]
	v_cndmask_b32_e64 v70, v78, v82, s[2:3]
	v_cvt_pk_bf16_f32 v62, v62, v63
	v_cvt_pk_bf16_f32 v63, v64, v65
	v_cvt_pk_bf16_f32 v64, v58, v59
	v_cvt_pk_bf16_f32 v65, v60, v61
	v_cvt_pk_bf16_f32 v54, v54, v55
	v_cvt_pk_bf16_f32 v55, v56, v57
	v_cvt_pk_bf16_f32 v50, v50, v51
	v_cvt_pk_bf16_f32 v51, v52, v53
	v_lshl_add_u64 v[74:75], v[74:75], 0, v[136:137]
	global_store_dwordx4 v[76:77], v[70:73], off
	global_store_dwordx4 v[74:75], v[66:69], off
	v_lshl_add_u64 v[58:59], v[142:143], 0, s[22:23]
	s_mov_b64 vcc, s[2:3]
	v_mov_b32_dpp v66, v54 row_ror:8 row_mask:0xf bank_mask:0xf bound_ctrl:1
	v_mov_b32_dpp v67, v55 row_ror:8 row_mask:0xf bank_mask:0xf bound_ctrl:1
	v_mov_b32_dpp v68, v50 row_ror:8 row_mask:0xf bank_mask:0xf bound_ctrl:1
	v_mov_b32_dpp v69, v51 row_ror:8 row_mask:0xf bank_mask:0xf bound_ctrl:1
	v_lshl_add_u64 v[60:61], v[58:59], 0, v[134:135]
	v_cndmask_b32_dpp v53, v65, v51, vcc row_ror:8 row_mask:0xf bank_mask:0xf bound_ctrl:1
	v_cndmask_b32_dpp v52, v64, v50, vcc row_ror:8 row_mask:0xf bank_mask:0xf bound_ctrl:1
	v_cndmask_b32_dpp v51, v63, v55, vcc row_ror:8 row_mask:0xf bank_mask:0xf bound_ctrl:1
	v_cndmask_b32_dpp v50, v62, v54, vcc row_ror:8 row_mask:0xf bank_mask:0xf bound_ctrl:1
	v_cndmask_b32_e64 v57, v65, v69, s[2:3]
	v_cndmask_b32_e64 v56, v64, v68, s[2:3]
	v_cndmask_b32_e64 v55, v63, v67, s[2:3]
	v_cndmask_b32_e64 v54, v62, v66, s[2:3]
	v_cvt_pk_bf16_f32 v46, v46, v47
	v_cvt_pk_bf16_f32 v47, v48, v49
	v_cvt_pk_bf16_f32 v48, v42, v43
	v_cvt_pk_bf16_f32 v49, v44, v45
	v_cvt_pk_bf16_f32 v38, v38, v39
	v_cvt_pk_bf16_f32 v39, v40, v41
	v_cvt_pk_bf16_f32 v34, v34, v35
	v_cvt_pk_bf16_f32 v35, v36, v37
	v_lshl_add_u64 v[58:59], v[58:59], 0, v[136:137]
	global_store_dwordx4 v[60:61], v[54:57], off
	global_store_dwordx4 v[58:59], v[50:53], off
	v_lshl_add_u64 v[42:43], v[142:143], 0, s[24:25]
	s_mov_b64 vcc, s[2:3]
	v_mov_b32_dpp v50, v38 row_ror:8 row_mask:0xf bank_mask:0xf bound_ctrl:1
	v_mov_b32_dpp v51, v39 row_ror:8 row_mask:0xf bank_mask:0xf bound_ctrl:1
	v_mov_b32_dpp v52, v34 row_ror:8 row_mask:0xf bank_mask:0xf bound_ctrl:1
	v_mov_b32_dpp v53, v35 row_ror:8 row_mask:0xf bank_mask:0xf bound_ctrl:1
	v_lshl_add_u64 v[44:45], v[42:43], 0, v[134:135]
	v_cndmask_b32_dpp v37, v49, v35, vcc row_ror:8 row_mask:0xf bank_mask:0xf bound_ctrl:1
	v_cndmask_b32_dpp v36, v48, v34, vcc row_ror:8 row_mask:0xf bank_mask:0xf bound_ctrl:1
	v_cndmask_b32_dpp v35, v47, v39, vcc row_ror:8 row_mask:0xf bank_mask:0xf bound_ctrl:1
	v_cndmask_b32_dpp v34, v46, v38, vcc row_ror:8 row_mask:0xf bank_mask:0xf bound_ctrl:1
	v_cndmask_b32_e64 v41, v49, v53, s[2:3]
	v_cndmask_b32_e64 v40, v48, v52, s[2:3]
	v_cndmask_b32_e64 v39, v47, v51, s[2:3]
	v_cndmask_b32_e64 v38, v46, v50, s[2:3]
	v_cvt_pk_bf16_f32 v30, v30, v31
	v_cvt_pk_bf16_f32 v31, v32, v33
	v_cvt_pk_bf16_f32 v32, v26, v27
	v_cvt_pk_bf16_f32 v33, v28, v29
	v_cvt_pk_bf16_f32 v22, v22, v23
	v_cvt_pk_bf16_f32 v23, v24, v25
	v_cvt_pk_bf16_f32 v18, v18, v19
	v_cvt_pk_bf16_f32 v19, v20, v21
	v_lshl_add_u64 v[42:43], v[42:43], 0, v[136:137]
	global_store_dwordx4 v[44:45], v[38:41], off
	global_store_dwordx4 v[42:43], v[34:37], off
	v_lshl_add_u64 v[26:27], v[142:143], 0, s[26:27]
	s_mov_b64 vcc, s[2:3]
	v_mov_b32_dpp v34, v22 row_ror:8 row_mask:0xf bank_mask:0xf bound_ctrl:1
	v_mov_b32_dpp v35, v23 row_ror:8 row_mask:0xf bank_mask:0xf bound_ctrl:1
	v_mov_b32_dpp v36, v18 row_ror:8 row_mask:0xf bank_mask:0xf bound_ctrl:1
	v_mov_b32_dpp v37, v19 row_ror:8 row_mask:0xf bank_mask:0xf bound_ctrl:1
	v_lshl_add_u64 v[28:29], v[26:27], 0, v[134:135]
	v_cndmask_b32_dpp v21, v33, v19, vcc row_ror:8 row_mask:0xf bank_mask:0xf bound_ctrl:1
	v_cndmask_b32_dpp v20, v32, v18, vcc row_ror:8 row_mask:0xf bank_mask:0xf bound_ctrl:1
	v_cndmask_b32_dpp v19, v31, v23, vcc row_ror:8 row_mask:0xf bank_mask:0xf bound_ctrl:1
	v_cndmask_b32_dpp v18, v30, v22, vcc row_ror:8 row_mask:0xf bank_mask:0xf bound_ctrl:1
	v_cndmask_b32_e64 v25, v33, v37, s[2:3]
	v_cndmask_b32_e64 v24, v32, v36, s[2:3]
	v_cndmask_b32_e64 v23, v31, v35, s[2:3]
	v_cndmask_b32_e64 v22, v30, v34, s[2:3]
	v_cvt_pk_bf16_f32 v14, v14, v15
	v_cvt_pk_bf16_f32 v15, v16, v17
	v_cvt_pk_bf16_f32 v16, v10, v11
	v_cvt_pk_bf16_f32 v17, v12, v13
	v_cvt_pk_bf16_f32 v6, v6, v7
	v_cvt_pk_bf16_f32 v7, v8, v9
	v_cvt_pk_bf16_f32 v2, v2, v3
	v_cvt_pk_bf16_f32 v3, v4, v5
	v_lshl_add_u64 v[26:27], v[26:27], 0, v[136:137]
	global_store_dwordx4 v[28:29], v[22:25], off
	global_store_dwordx4 v[26:27], v[18:21], off
	v_lshl_add_u64 v[10:11], v[142:143], 0, s[28:29]
	s_mov_b64 vcc, s[2:3]
	v_mov_b32_dpp v18, v6 row_ror:8 row_mask:0xf bank_mask:0xf bound_ctrl:1
	v_mov_b32_dpp v19, v7 row_ror:8 row_mask:0xf bank_mask:0xf bound_ctrl:1
	v_mov_b32_dpp v20, v2 row_ror:8 row_mask:0xf bank_mask:0xf bound_ctrl:1
	v_mov_b32_dpp v21, v3 row_ror:8 row_mask:0xf bank_mask:0xf bound_ctrl:1
	v_lshl_add_u64 v[12:13], v[10:11], 0, v[134:135]
	v_cndmask_b32_dpp v5, v17, v3, vcc row_ror:8 row_mask:0xf bank_mask:0xf bound_ctrl:1
	v_cndmask_b32_dpp v4, v16, v2, vcc row_ror:8 row_mask:0xf bank_mask:0xf bound_ctrl:1
	v_cndmask_b32_dpp v3, v15, v7, vcc row_ror:8 row_mask:0xf bank_mask:0xf bound_ctrl:1
	v_cndmask_b32_dpp v2, v14, v6, vcc row_ror:8 row_mask:0xf bank_mask:0xf bound_ctrl:1
	v_cndmask_b32_e64 v9, v17, v21, s[2:3]
	v_cndmask_b32_e64 v8, v16, v20, s[2:3]
	v_cndmask_b32_e64 v7, v15, v19, s[2:3]
	v_cndmask_b32_e64 v6, v14, v18, s[2:3]
	s_and_b64 vcc, exec, s[6:7]
	s_mov_b64 s[6:7], -1
	v_lshl_add_u64 v[10:11], v[10:11], 0, v[136:137]
	global_store_dwordx4 v[12:13], v[6:9], off
	global_store_dwordx4 v[10:11], v[2:5], off
	s_cbranch_vccnz .LBB0_2326
	s_andn2_b64 vcc, exec, s[10:11]
	s_cbranch_vccnz .LBB0_2325
	s_barrier
	s_branch .LBB0_2325
